# in-proj: peeled first and last K-steps of each tile re-emitted in the pipelined loop shape (no serialised LDS reads); next-tile staging folded under K-step 15
# baseline (speedup 1.0000x reference)
; template <int EPI>
; DI void gemm_phase(const P& p, int l, const u16* __restrict__ A, const u16* __restrict__ Bt, int mpx, char* lds) {
;     ...
;   const int tn = t + 1;
;   int m1 = 0, n1 = 0;
;   const bool has_next = tile_coords<EPI>(tn, mpx, m1, n1);
;   const u16* Agn = A + (size_t)m1 * 1024;
;   const u16* Bgn = Bt + (size_t)n1 * 1024;
;   f32x4 acc[8][4];
; #pragma unroll
;   for (int i = 0; i < 8; ++i)
; #pragma unroll
;     for (int j = 0; j < 4; ++j) acc[i][j] = zero4();
;   {
;   const int lane = tid & 63, w = tid >> 6, r = lane & 15, g = lane >> 4, wm = w >> 2, wn = w & 3;
;   __syncthreads();
;   GLOAD(Ag, Bg, 64)
;   __builtin_amdgcn_sched_barrier(0);
;   GCOMPUTE_KS(As0, Bs0, 0)
;   __builtin_amdgcn_sched_barrier(0);
;   GSTORE(As1, Bs1)
;   GLOAD(Ag, Bg, 128)
;   __builtin_amdgcn_sched_barrier(0);
;   GCOMPUTE_KS(As0, Bs0, 1)
;   __builtin_amdgcn_sched_barrier(0);
.LBB0_81:
	s_mov_b32 s57, s3
	s_lshl_b64 s[42:43], s[56:57], 11
	s_lshl_b32 s2, s51, 11
	s_add_u32 s58, s16, s42
	s_addc_u32 s59, s17, s43
	s_add_u32 s60, s24, s2
	s_addc_u32 s61, s25, 0
	v_add_u32_e32 v208, s33, v196
	v_add_u32_e32 v209, s35, v196
	v_add_u32_e32 v210, s39, v196
	global_load_dwordx4 v[162:165], v196, s[40:41] offset:128
	global_load_dwordx4 v[166:169], v208, s[40:41] offset:128
	global_load_dwordx4 v[170:173], v209, s[40:41] offset:128
	global_load_dwordx4 v[174:177], v210, s[40:41] offset:128
	global_load_dwordx4 v[178:181], v196, s[0:1] offset:128
	global_load_dwordx4 v[182:185], v208, s[0:1] offset:128
	global_load_dwordx4 v[186:189], v209, s[0:1] offset:128
	global_load_dwordx4 v[190:193], v210, s[0:1] offset:128
	s_waitcnt lgkmcnt(0)
	s_barrier
	ds_read_b128 v[212:215], v204 offset:32768
	ds_read_b128 v[216:219], v204 offset:34816
	ds_read_b128 v[220:223], v204 offset:36864
	ds_read_b128 v[234:237], v204 offset:38912
	ds_read_b128 v[238:241], v205
	ds_read_b128 v[242:245], v205 offset:2048
	ds_read_b128 v[246:249], v205 offset:4096
	ds_read_b128 v[250:253], v205 offset:6144
	s_waitcnt lgkmcnt(3)
	v_mfma_f32_16x16x32_bf16 v[6:9], v[238:241], v[212:215], 0
	v_mfma_f32_16x16x32_bf16 v[10:13], v[238:241], v[216:219], 0
	v_mfma_f32_16x16x32_bf16 v[14:17], v[238:241], v[220:223], 0
	v_mfma_f32_16x16x32_bf16 v[18:21], v[238:241], v[234:237], 0
	ds_read_b128 v[238:241], v205 offset:8192
	global_load_dwordx4 v[130:133], v196, s[40:41] offset:256
	s_waitcnt vmcnt(8)
	ds_write_b128 v202, v[162:165]
	s_waitcnt lgkmcnt(4)
	v_mfma_f32_16x16x32_bf16 v[22:25], v[242:245], v[212:215], 0
	v_mfma_f32_16x16x32_bf16 v[26:29], v[242:245], v[216:219], 0
	v_mfma_f32_16x16x32_bf16 v[30:33], v[242:245], v[220:223], 0
	v_mfma_f32_16x16x32_bf16 v[34:37], v[242:245], v[234:237], 0
	ds_read_b128 v[242:245], v205 offset:10240
	global_load_dwordx4 v[134:137], v208, s[40:41] offset:256
	s_waitcnt vmcnt(8)
	ds_write_b128 v227, v[166:169]
	ds_read_b128 v[162:165], v206 offset:32768
	s_waitcnt lgkmcnt(6)
	v_mfma_f32_16x16x32_bf16 v[38:41], v[246:249], v[212:215], 0
	v_mfma_f32_16x16x32_bf16 v[42:45], v[246:249], v[216:219], 0
	v_mfma_f32_16x16x32_bf16 v[46:49], v[246:249], v[220:223], 0
	v_mfma_f32_16x16x32_bf16 v[50:53], v[246:249], v[234:237], 0
	ds_read_b128 v[246:249], v205 offset:12288
	global_load_dwordx4 v[138:141], v209, s[40:41] offset:256
	s_waitcnt vmcnt(8)
	ds_write_b128 v228, v[170:173]
	ds_read_b128 v[166:169], v206 offset:34816
	s_waitcnt lgkmcnt(8)
	v_mfma_f32_16x16x32_bf16 v[54:57], v[250:253], v[212:215], 0
	v_mfma_f32_16x16x32_bf16 v[58:61], v[250:253], v[216:219], 0
	v_mfma_f32_16x16x32_bf16 v[62:65], v[250:253], v[220:223], 0
	v_mfma_f32_16x16x32_bf16 v[66:69], v[250:253], v[234:237], 0
	ds_read_b128 v[250:253], v205 offset:14336
	global_load_dwordx4 v[142:145], v210, s[40:41] offset:256
	s_waitcnt vmcnt(8)
	ds_write_b128 v229, v[174:177]
	ds_read_b128 v[170:173], v206 offset:36864
	s_waitcnt lgkmcnt(10)
	v_mfma_f32_16x16x32_bf16 v[70:73], v[238:241], v[212:215], 0
	v_mfma_f32_16x16x32_bf16 v[74:77], v[238:241], v[216:219], 0
	v_mfma_f32_16x16x32_bf16 v[78:81], v[238:241], v[220:223], 0
	v_mfma_f32_16x16x32_bf16 v[82:85], v[238:241], v[234:237], 0
	ds_read_b128 v[238:241], v207
	global_load_dwordx4 v[146:149], v196, s[0:1] offset:256
	s_waitcnt vmcnt(8)
	ds_write_b128 v203, v[178:181]
	ds_read_b128 v[174:177], v206 offset:38912
	s_waitcnt lgkmcnt(11)
	v_mfma_f32_16x16x32_bf16 v[86:89], v[242:245], v[212:215], 0
	v_mfma_f32_16x16x32_bf16 v[90:93], v[242:245], v[216:219], 0
	v_mfma_f32_16x16x32_bf16 v[94:97], v[242:245], v[220:223], 0
	v_mfma_f32_16x16x32_bf16 v[98:101], v[242:245], v[234:237], 0
	ds_read_b128 v[242:245], v207 offset:2048
	global_load_dwordx4 v[150:153], v208, s[0:1] offset:256
	s_waitcnt vmcnt(8)
	ds_write_b128 v230, v[182:185]
	s_waitcnt lgkmcnt(10)
	v_mfma_f32_16x16x32_bf16 v[102:105], v[246:249], v[212:215], 0
	v_mfma_f32_16x16x32_bf16 v[106:109], v[246:249], v[216:219], 0
	v_mfma_f32_16x16x32_bf16 v[110:113], v[246:249], v[220:223], 0
	v_mfma_f32_16x16x32_bf16 v[114:117], v[246:249], v[234:237], 0
	ds_read_b128 v[246:249], v207 offset:4096
	global_load_dwordx4 v[154:157], v209, s[0:1] offset:256
	s_waitcnt vmcnt(8)
	ds_write_b128 v231, v[186:189]
	s_waitcnt lgkmcnt(9)
	v_mfma_f32_16x16x32_bf16 v[118:121], v[250:253], v[212:215], 0
	v_mfma_f32_16x16x32_bf16 v[122:125], v[250:253], v[216:219], 0
	v_mfma_f32_16x16x32_bf16 v[126:129], v[250:253], v[220:223], 0
	v_mfma_f32_16x16x32_bf16 v[2:5], v[250:253], v[234:237], 0
	ds_read_b128 v[250:253], v207 offset:6144
	global_load_dwordx4 v[158:161], v210, s[0:1] offset:256
	s_waitcnt vmcnt(8)
	ds_write_b128 v232, v[190:193]
	s_waitcnt lgkmcnt(6)
	v_mfma_f32_16x16x32_bf16 v[6:9], v[238:241], v[162:165], v[6:9]
	v_mfma_f32_16x16x32_bf16 v[10:13], v[238:241], v[166:169], v[10:13]
	v_mfma_f32_16x16x32_bf16 v[14:17], v[238:241], v[170:173], v[14:17]
	v_mfma_f32_16x16x32_bf16 v[18:21], v[238:241], v[174:177], v[18:21]
	ds_read_b128 v[238:241], v207 offset:8192
	s_waitcnt lgkmcnt(6)
	v_mfma_f32_16x16x32_bf16 v[22:25], v[242:245], v[162:165], v[22:25]
	v_mfma_f32_16x16x32_bf16 v[26:29], v[242:245], v[166:169], v[26:29]
	v_mfma_f32_16x16x32_bf16 v[30:33], v[242:245], v[170:173], v[30:33]
	v_mfma_f32_16x16x32_bf16 v[34:37], v[242:245], v[174:177], v[34:37]
	ds_read_b128 v[242:245], v207 offset:10240
	s_waitcnt lgkmcnt(5)
	v_mfma_f32_16x16x32_bf16 v[38:41], v[246:249], v[162:165], v[38:41]
	v_mfma_f32_16x16x32_bf16 v[42:45], v[246:249], v[166:169], v[42:45]
	v_mfma_f32_16x16x32_bf16 v[46:49], v[246:249], v[170:173], v[46:49]
	v_mfma_f32_16x16x32_bf16 v[50:53], v[246:249], v[174:177], v[50:53]
	ds_read_b128 v[246:249], v207 offset:12288
	s_waitcnt lgkmcnt(4)
	v_mfma_f32_16x16x32_bf16 v[54:57], v[250:253], v[162:165], v[54:57]
	v_mfma_f32_16x16x32_bf16 v[58:61], v[250:253], v[166:169], v[58:61]
	v_mfma_f32_16x16x32_bf16 v[62:65], v[250:253], v[170:173], v[62:65]
	v_mfma_f32_16x16x32_bf16 v[66:69], v[250:253], v[174:177], v[66:69]
	ds_read_b128 v[250:253], v207 offset:14336
	s_waitcnt lgkmcnt(3)
	v_mfma_f32_16x16x32_bf16 v[70:73], v[238:241], v[162:165], v[70:73]
	v_mfma_f32_16x16x32_bf16 v[74:77], v[238:241], v[166:169], v[74:77]
	v_mfma_f32_16x16x32_bf16 v[78:81], v[238:241], v[170:173], v[78:81]
	v_mfma_f32_16x16x32_bf16 v[82:85], v[238:241], v[174:177], v[82:85]
	s_waitcnt lgkmcnt(2)
	v_mfma_f32_16x16x32_bf16 v[86:89], v[242:245], v[162:165], v[86:89]
	v_mfma_f32_16x16x32_bf16 v[90:93], v[242:245], v[166:169], v[90:93]
	v_mfma_f32_16x16x32_bf16 v[94:97], v[242:245], v[170:173], v[94:97]
	v_mfma_f32_16x16x32_bf16 v[98:101], v[242:245], v[174:177], v[98:101]
	s_waitcnt lgkmcnt(0)
	s_mov_b32 s49, 1
	s_movk_i32 s47, 0x100
	s_mov_b64 s[42:43], s[0:1]
	s_mov_b64 s[44:45], s[40:41]
	s_barrier
; #define GCOMPUTE(AS, BS) GCOMPUTE_KS(AS, BS, 0) GCOMPUTE_KS(AS, BS, 1)
; template <int EPI>
; DI void gemm_phase(const P& p, int l, const u16* __restrict__ A, const u16* __restrict__ Bt, int mpx, char* lds) {
;     ...
;   for (int kk = 1; kk < 15; kk += 2) {
;     __syncthreads();
;     GSTORE(As0, Bs0)
;     GLOAD(Ag, Bg, (kk + 2) * 64)
;     __builtin_amdgcn_sched_barrier(0);
;     GCOMPUTE(As1, Bs1)
	ds_read_b128 v[212:215], v198
	ds_read_b128 v[216:219], v198 offset:2048
	ds_read_b128 v[220:223], v198 offset:4096
	ds_read_b128 v[234:237], v198 offset:6144
	ds_read_b128 v[238:241], v199
	ds_read_b128 v[242:245], v199 offset:2048
	v_mfma_f32_16x16x32_bf16 v[102:105], v[246:249], v[162:165], v[102:105]
	v_mfma_f32_16x16x32_bf16 v[106:109], v[246:249], v[166:169], v[106:109]
	v_mfma_f32_16x16x32_bf16 v[110:113], v[246:249], v[170:173], v[110:113]
	v_mfma_f32_16x16x32_bf16 v[114:117], v[246:249], v[174:177], v[114:117]
	ds_read_b128 v[246:249], v199 offset:4096
	v_mfma_f32_16x16x32_bf16 v[118:121], v[250:253], v[162:165], v[118:121]
	v_mfma_f32_16x16x32_bf16 v[122:125], v[250:253], v[166:169], v[122:125]
	v_mfma_f32_16x16x32_bf16 v[126:129], v[250:253], v[170:173], v[126:129]
	v_mfma_f32_16x16x32_bf16 v[2:5], v[250:253], v[174:177], v[2:5]
	ds_read_b128 v[250:253], v199 offset:6144

; #define GCOMPUTE(AS, BS) GCOMPUTE_KS(AS, BS, 0) GCOMPUTE_KS(AS, BS, 1)
; template <int EPI>
; DI void gemm_phase(const P& p, int l, const u16* __restrict__ A, const u16* __restrict__ Bt, int mpx, char* lds) {
;     ...
;   __syncthreads();
;   __builtin_amdgcn_sched_barrier(0);
;   GCOMPUTE(As1, Bs1)
;   __builtin_amdgcn_sched_barrier(0);
;   }
;   __syncthreads();
;   GSTORE(As0, Bs0)
.Lgemm_in_exit:
	s_barrier
	ds_read_b128 v[212:215], v198
	ds_read_b128 v[216:219], v198 offset:2048
	ds_read_b128 v[220:223], v198 offset:4096
	ds_read_b128 v[234:237], v198 offset:6144
	ds_read_b128 v[238:241], v199
	ds_read_b128 v[242:245], v199 offset:2048
	v_mfma_f32_16x16x32_bf16 v[102:105], v[246:249], v[162:165], v[102:105]
	v_mfma_f32_16x16x32_bf16 v[106:109], v[246:249], v[166:169], v[106:109]
	v_mfma_f32_16x16x32_bf16 v[110:113], v[246:249], v[170:173], v[110:113]
	v_mfma_f32_16x16x32_bf16 v[114:117], v[246:249], v[174:177], v[114:117]
	ds_read_b128 v[246:249], v199 offset:4096
	v_mfma_f32_16x16x32_bf16 v[118:121], v[250:253], v[162:165], v[118:121]
	v_mfma_f32_16x16x32_bf16 v[122:125], v[250:253], v[166:169], v[122:125]
	v_mfma_f32_16x16x32_bf16 v[126:129], v[250:253], v[170:173], v[126:129]
	v_mfma_f32_16x16x32_bf16 v[2:5], v[250:253], v[174:177], v[2:5]
	ds_read_b128 v[250:253], v199 offset:6144
	s_waitcnt lgkmcnt(3)
	v_mfma_f32_16x16x32_bf16 v[6:9], v[238:241], v[212:215], v[6:9]
	v_mfma_f32_16x16x32_bf16 v[10:13], v[238:241], v[216:219], v[10:13]
	v_mfma_f32_16x16x32_bf16 v[14:17], v[238:241], v[220:223], v[14:17]
	v_mfma_f32_16x16x32_bf16 v[18:21], v[238:241], v[234:237], v[18:21]
	ds_read_b128 v[238:241], v199 offset:8192
	s_waitcnt vmcnt(7)
	ds_write_b128 v201, v[130:133]
	s_waitcnt lgkmcnt(4)
	v_mfma_f32_16x16x32_bf16 v[22:25], v[242:245], v[212:215], v[22:25]
	v_mfma_f32_16x16x32_bf16 v[26:29], v[242:245], v[216:219], v[26:29]
	v_mfma_f32_16x16x32_bf16 v[30:33], v[242:245], v[220:223], v[30:33]
	v_mfma_f32_16x16x32_bf16 v[34:37], v[242:245], v[234:237], v[34:37]
	ds_read_b128 v[242:245], v199 offset:10240
	s_waitcnt vmcnt(6)
	ds_write_b128 v201, v[134:137] offset:8192
	ds_read_b128 v[130:133], v200
	s_waitcnt lgkmcnt(6)
	v_mfma_f32_16x16x32_bf16 v[38:41], v[246:249], v[212:215], v[38:41]
	v_mfma_f32_16x16x32_bf16 v[42:45], v[246:249], v[216:219], v[42:45]
	v_mfma_f32_16x16x32_bf16 v[46:49], v[246:249], v[220:223], v[46:49]
	v_mfma_f32_16x16x32_bf16 v[50:53], v[246:249], v[234:237], v[50:53]
	ds_read_b128 v[246:249], v199 offset:12288
	s_waitcnt vmcnt(5)
	ds_write_b128 v201, v[138:141] offset:16384
	ds_read_b128 v[134:137], v200 offset:2048
	s_waitcnt lgkmcnt(8)
	v_mfma_f32_16x16x32_bf16 v[54:57], v[250:253], v[212:215], v[54:57]
	v_mfma_f32_16x16x32_bf16 v[58:61], v[250:253], v[216:219], v[58:61]
	v_mfma_f32_16x16x32_bf16 v[62:65], v[250:253], v[220:223], v[62:65]
	v_mfma_f32_16x16x32_bf16 v[66:69], v[250:253], v[234:237], v[66:69]
	ds_read_b128 v[250:253], v199 offset:14336
	s_waitcnt vmcnt(4)
	ds_write_b128 v201, v[142:145] offset:24576
	ds_read_b128 v[138:141], v200 offset:4096
	s_waitcnt lgkmcnt(10)
	v_mfma_f32_16x16x32_bf16 v[70:73], v[238:241], v[212:215], v[70:73]
	v_mfma_f32_16x16x32_bf16 v[74:77], v[238:241], v[216:219], v[74:77]
	v_mfma_f32_16x16x32_bf16 v[78:81], v[238:241], v[220:223], v[78:81]
	v_mfma_f32_16x16x32_bf16 v[82:85], v[238:241], v[234:237], v[82:85]
	ds_read_b128 v[238:241], v233
	s_waitcnt vmcnt(3)
	ds_write_b128 v201, v[146:149] offset:32768
	ds_read_b128 v[142:145], v200 offset:6144
	s_waitcnt lgkmcnt(11)
	v_mfma_f32_16x16x32_bf16 v[86:89], v[242:245], v[212:215], v[86:89]
	v_mfma_f32_16x16x32_bf16 v[90:93], v[242:245], v[216:219], v[90:93]
	v_mfma_f32_16x16x32_bf16 v[94:97], v[242:245], v[220:223], v[94:97]
	v_mfma_f32_16x16x32_bf16 v[98:101], v[242:245], v[234:237], v[98:101]
	ds_read_b128 v[242:245], v233 offset:2048
	s_waitcnt vmcnt(2)
	ds_write_b128 v201, v[150:153] offset:40960
	s_waitcnt lgkmcnt(10)
	v_mfma_f32_16x16x32_bf16 v[102:105], v[246:249], v[212:215], v[102:105]
	v_mfma_f32_16x16x32_bf16 v[106:109], v[246:249], v[216:219], v[106:109]
	v_mfma_f32_16x16x32_bf16 v[110:113], v[246:249], v[220:223], v[110:113]
	v_mfma_f32_16x16x32_bf16 v[114:117], v[246:249], v[234:237], v[114:117]
	ds_read_b128 v[246:249], v233 offset:4096
	s_waitcnt vmcnt(1)
	ds_write_b128 v201, v[154:157] offset:49152
	s_waitcnt lgkmcnt(9)
	v_mfma_f32_16x16x32_bf16 v[118:121], v[250:253], v[212:215], v[118:121]
	v_mfma_f32_16x16x32_bf16 v[122:125], v[250:253], v[216:219], v[122:125]
	v_mfma_f32_16x16x32_bf16 v[126:129], v[250:253], v[220:223], v[126:129]
	v_mfma_f32_16x16x32_bf16 v[2:5], v[250:253], v[234:237], v[2:5]
	ds_read_b128 v[250:253], v233 offset:6144
	s_waitcnt vmcnt(0)
	ds_write_b128 v201, v[158:161] offset:57344
	s_waitcnt lgkmcnt(6)
	v_mfma_f32_16x16x32_bf16 v[6:9], v[238:241], v[130:133], v[6:9]
	v_mfma_f32_16x16x32_bf16 v[10:13], v[238:241], v[134:137], v[10:13]
	v_mfma_f32_16x16x32_bf16 v[14:17], v[238:241], v[138:141], v[14:17]
	v_mfma_f32_16x16x32_bf16 v[18:21], v[238:241], v[142:145], v[18:21]
	ds_read_b128 v[238:241], v233 offset:8192
	s_waitcnt lgkmcnt(6)
	v_mfma_f32_16x16x32_bf16 v[22:25], v[242:245], v[130:133], v[22:25]
	v_mfma_f32_16x16x32_bf16 v[26:29], v[242:245], v[134:137], v[26:29]
	v_mfma_f32_16x16x32_bf16 v[30:33], v[242:245], v[138:141], v[30:33]
	v_mfma_f32_16x16x32_bf16 v[34:37], v[242:245], v[142:145], v[34:37]
	ds_read_b128 v[242:245], v233 offset:10240
	s_waitcnt lgkmcnt(5)
	v_mfma_f32_16x16x32_bf16 v[38:41], v[246:249], v[130:133], v[38:41]
	v_mfma_f32_16x16x32_bf16 v[42:45], v[246:249], v[134:137], v[42:45]
	v_mfma_f32_16x16x32_bf16 v[46:49], v[246:249], v[138:141], v[46:49]
	v_mfma_f32_16x16x32_bf16 v[50:53], v[246:249], v[142:145], v[50:53]
	ds_read_b128 v[246:249], v233 offset:12288
	s_waitcnt lgkmcnt(4)
	v_mfma_f32_16x16x32_bf16 v[54:57], v[250:253], v[130:133], v[54:57]
	v_mfma_f32_16x16x32_bf16 v[58:61], v[250:253], v[134:137], v[58:61]
	v_mfma_f32_16x16x32_bf16 v[62:65], v[250:253], v[138:141], v[62:65]
	v_mfma_f32_16x16x32_bf16 v[66:69], v[250:253], v[142:145], v[66:69]
	ds_read_b128 v[250:253], v233 offset:14336
	s_waitcnt lgkmcnt(3)
	v_mfma_f32_16x16x32_bf16 v[70:73], v[238:241], v[130:133], v[70:73]
	v_mfma_f32_16x16x32_bf16 v[74:77], v[238:241], v[134:137], v[74:77]
	v_mfma_f32_16x16x32_bf16 v[78:81], v[238:241], v[138:141], v[78:81]
	v_mfma_f32_16x16x32_bf16 v[82:85], v[238:241], v[142:145], v[82:85]
	s_waitcnt lgkmcnt(2)
	v_mfma_f32_16x16x32_bf16 v[86:89], v[242:245], v[130:133], v[86:89]
	v_mfma_f32_16x16x32_bf16 v[90:93], v[242:245], v[134:137], v[90:93]
	v_mfma_f32_16x16x32_bf16 v[94:97], v[242:245], v[138:141], v[94:97]
	v_mfma_f32_16x16x32_bf16 v[98:101], v[242:245], v[142:145], v[98:101]
	s_waitcnt lgkmcnt(0)
	s_barrier
; #define GCOMPUTE(AS, BS) GCOMPUTE_KS(AS, BS, 0) GCOMPUTE_KS(AS, BS, 1)
; template <int EPI>
; DI void gemm_phase(const P& p, int l, const u16* __restrict__ A, const u16* __restrict__ Bt, int mpx, char* lds) {
;     ...
;   GCOMPUTE(As1, Bs1)
;   __builtin_amdgcn_sched_barrier(0);
;     ...
;     const int cb = n0 + wn * 64;
;     const bool isctx = m0 >= MLAT;
;     const int b = isctx ? ((m0 - MLAT) >> 8) : (m0 >> 11);
;     const int tokw = (isctx ? 2048 + ((m0 - MLAT) & 255) : (m0 & 2047)) + wm * 128;
;     u16* Tl = (u16*)(lds + 65536) + w * (64 * 72);
;     int kind = 0;
;     int tr = 0;
;     bool donorm = false;
;     if (cb >= 2816) { kind = 2; tr = 1; }
;     else if (cb < 256) tr = 1;
;     else if (cb < 512) tr = 0;
;     else if (cb < 1024) tr = 2;
;     else if (cb < 1408) { tr = 3; donorm = true; }
;     else if (cb < 1536) kind = 1;
;     else if (cb < 2048) tr = isctx ? 0 : 4;
;     else if (cb < 2304) kind = 1;
;     else if (cb < 2688) tr = isctx ? 0 : 3;
;     else kind = 1;
	v_mfma_f32_16x16x32_bf16 v[102:105], v[246:249], v[130:133], v[102:105]
	v_mfma_f32_16x16x32_bf16 v[106:109], v[246:249], v[134:137], v[106:109]
	v_mfma_f32_16x16x32_bf16 v[110:113], v[246:249], v[138:141], v[110:113]
	v_mfma_f32_16x16x32_bf16 v[114:117], v[246:249], v[142:145], v[114:117]
	v_mfma_f32_16x16x32_bf16 v[118:121], v[250:253], v[130:133], v[118:121]
	v_mfma_f32_16x16x32_bf16 v[122:125], v[250:253], v[134:137], v[122:125]
	v_mfma_f32_16x16x32_bf16 v[126:129], v[250:253], v[138:141], v[126:129]
	v_mfma_f32_16x16x32_bf16 v[2:5], v[250:253], v[142:145], v[2:5]
	s_nop 0
	v_readfirstlane_b32 s40, v195
	s_lshr_b32 s40, s40, 6
	s_and_b32 s41, s40, 3
	s_lshr_b32 s42, s40, 2
	s_lshr_b32 s43, s46, 6
	s_add_i32 s43, s43, s41
	s_cmp_ge_u32 s66, 0x8000
	s_cselect_b32 s67, 1, 0
	s_mov_b32 s44, 0xffff
	s_mov_b32 s45, 0
	s_bitcmp1_b64 s[44:45], s43
	s_cbranch_scc1 .Lfe_kind0
	s_mov_b32 s44, 0xc00000
	s_mov_b32 s45, 0xc0f
	s_bitcmp1_b64 s[44:45], s43
	s_cbranch_scc1 .Lfe_kind1
	s_cmp_ge_u32 s43, 44
	s_cbranch_scc1 .Lfe_kind2
	s_branch .Lfe_kind0

; DI float silu(float v) { return v * __builtin_amdgcn_rcpf(1.f + __builtin_amdgcn_exp2f(-1.4426950408889634f * v)); }
; template <int EPI>
; DI void gemm_phase(const P& p, int l, const u16* __restrict__ A, const u16* __restrict__ Bt, int mpx, char* lds) {
;     ...
;           float v0 = acc[hf * 4 + mi][0][j], v1 = acc[hf * 4 + mi][1][j], v2 = acc[hf * 4 + mi][2][j], v3 = acc[hf * 4 + mi][3][j];
;           const int rowl = mi * 16 + g * 4 + j;
;           const int s = tokw + hf * 64 + rowl;
;           if (tr == 1) {
;             v0 = silu(v0); v1 = silu(v1); v2 = silu(v2); v3 = silu(v3);
;     ...
;             Tl[rowl * 72 + 0 * 16 + r] = (u16)u01;
;             Tl[rowl * 72 + 1 * 16 + r] = (u16)(u01 >> 16);
;             Tl[rowl * 72 + 2 * 16 + r] = (u16)u23;
;             Tl[rowl * 72 + 3 * 16 + r] = (u16)(u23 >> 16);
.Lfe_k0_silu:
	s_add_u32 s62, s44, 0x1000
	s_addc_u32 s63, s45, 0
	v_mul_f32_e32 v174, 0xbfb8aa3b, v6
	v_mul_f32_e32 v175, 0xbfb8aa3b, v10
	v_mul_f32_e32 v176, 0xbfb8aa3b, v14
	v_mul_f32_e32 v177, 0xbfb8aa3b, v18
	v_exp_f32_e32 v174, v174
	v_exp_f32_e32 v175, v175
	v_exp_f32_e32 v176, v176
	v_exp_f32_e32 v177, v177
	v_add_f32_e32 v174, 1.0, v174
	v_add_f32_e32 v175, 1.0, v175
	v_add_f32_e32 v176, 1.0, v176
	v_add_f32_e32 v177, 1.0, v177
	v_rcp_f32_e32 v174, v174
	v_rcp_f32_e32 v175, v175
	v_rcp_f32_e32 v176, v176
	v_rcp_f32_e32 v177, v177
	v_mul_f32_e32 v174, v6, v174
	v_mul_f32_e32 v175, v10, v175
	v_mul_f32_e32 v176, v14, v176
	v_mul_f32_e32 v177, v18, v177
	v_cvt_pk_bf16_f32 v178, v174, v175
	v_cvt_pk_bf16_f32 v179, v176, v177
	ds_write_b16 v170, v178 offset:0
	ds_write_b16_d16_hi v170, v178 offset:32
	ds_write_b16 v170, v179 offset:64
	ds_write_b16_d16_hi v170, v179 offset:96
	v_mul_f32_e32 v180, 0xbfb8aa3b, v7
	v_mul_f32_e32 v181, 0xbfb8aa3b, v11
	v_mul_f32_e32 v182, 0xbfb8aa3b, v15
	v_mul_f32_e32 v183, 0xbfb8aa3b, v19
	v_exp_f32_e32 v180, v180
	v_exp_f32_e32 v181, v181
	v_exp_f32_e32 v182, v182
	v_exp_f32_e32 v183, v183
	v_add_f32_e32 v180, 1.0, v180
	v_add_f32_e32 v181, 1.0, v181
	v_add_f32_e32 v182, 1.0, v182
	v_add_f32_e32 v183, 1.0, v183
	v_rcp_f32_e32 v180, v180
	v_rcp_f32_e32 v181, v181
	v_rcp_f32_e32 v182, v182
	v_rcp_f32_e32 v183, v183
	v_mul_f32_e32 v180, v7, v180
	v_mul_f32_e32 v181, v11, v181
	v_mul_f32_e32 v182, v15, v182
	v_mul_f32_e32 v183, v19, v183
	v_cvt_pk_bf16_f32 v184, v180, v181
	v_cvt_pk_bf16_f32 v185, v182, v183
	ds_write_b16 v170, v184 offset:144
	ds_write_b16_d16_hi v170, v184 offset:176
	ds_write_b16 v170, v185 offset:208
	ds_write_b16_d16_hi v170, v185 offset:240
	v_mul_f32_e32 v186, 0xbfb8aa3b, v8
	v_mul_f32_e32 v187, 0xbfb8aa3b, v12
	v_mul_f32_e32 v188, 0xbfb8aa3b, v16
	v_mul_f32_e32 v189, 0xbfb8aa3b, v20
	v_exp_f32_e32 v186, v186
	v_exp_f32_e32 v187, v187
	v_exp_f32_e32 v188, v188
	v_exp_f32_e32 v189, v189
	v_add_f32_e32 v186, 1.0, v186
	v_add_f32_e32 v187, 1.0, v187
	v_add_f32_e32 v188, 1.0, v188
	v_add_f32_e32 v189, 1.0, v189
	v_rcp_f32_e32 v186, v186
	v_rcp_f32_e32 v187, v187
	v_rcp_f32_e32 v188, v188
	v_rcp_f32_e32 v189, v189
	v_mul_f32_e32 v186, v8, v186
	v_mul_f32_e32 v187, v12, v187
	v_mul_f32_e32 v188, v16, v188
	v_mul_f32_e32 v189, v20, v189
	v_cvt_pk_bf16_f32 v190, v186, v187
	v_cvt_pk_bf16_f32 v191, v188, v189
	ds_write_b16 v170, v190 offset:288
	ds_write_b16_d16_hi v170, v190 offset:320
	ds_write_b16 v170, v191 offset:352
	ds_write_b16_d16_hi v170, v191 offset:384
	v_mul_f32_e32 v192, 0xbfb8aa3b, v9
	v_mul_f32_e32 v193, 0xbfb8aa3b, v13
	v_mul_f32_e32 v174, 0xbfb8aa3b, v17
	v_mul_f32_e32 v175, 0xbfb8aa3b, v21
	v_exp_f32_e32 v192, v192
	v_exp_f32_e32 v193, v193
	v_exp_f32_e32 v174, v174
	v_exp_f32_e32 v175, v175
	v_add_f32_e32 v192, 1.0, v192
	v_add_f32_e32 v193, 1.0, v193
	v_add_f32_e32 v174, 1.0, v174
	v_add_f32_e32 v175, 1.0, v175
	v_rcp_f32_e32 v192, v192
	v_rcp_f32_e32 v193, v193
	v_rcp_f32_e32 v174, v174
	v_rcp_f32_e32 v175, v175
	v_mul_f32_e32 v192, v9, v192
	v_mul_f32_e32 v193, v13, v193
	v_mul_f32_e32 v174, v17, v174
	v_mul_f32_e32 v175, v21, v175
	v_cvt_pk_bf16_f32 v176, v192, v193
	v_cvt_pk_bf16_f32 v177, v174, v175
	ds_write_b16 v170, v176 offset:432
	ds_write_b16_d16_hi v170, v176 offset:464
	ds_write_b16 v170, v177 offset:496
	ds_write_b16_d16_hi v170, v177 offset:528
	v_mul_f32_e32 v178, 0xbfb8aa3b, v22
	v_mul_f32_e32 v179, 0xbfb8aa3b, v26
	v_mul_f32_e32 v180, 0xbfb8aa3b, v30
	v_mul_f32_e32 v181, 0xbfb8aa3b, v34
	v_exp_f32_e32 v178, v178
	v_exp_f32_e32 v179, v179
	v_exp_f32_e32 v180, v180
	v_exp_f32_e32 v181, v181
	v_add_f32_e32 v178, 1.0, v178
	v_add_f32_e32 v179, 1.0, v179
	v_add_f32_e32 v180, 1.0, v180
	v_add_f32_e32 v181, 1.0, v181
	v_rcp_f32_e32 v178, v178
	v_rcp_f32_e32 v179, v179
	v_rcp_f32_e32 v180, v180
	v_rcp_f32_e32 v181, v181
	v_mul_f32_e32 v178, v22, v178
	v_mul_f32_e32 v179, v26, v179
	v_mul_f32_e32 v180, v30, v180
	v_mul_f32_e32 v181, v34, v181
	v_cvt_pk_bf16_f32 v182, v178, v179
	v_cvt_pk_bf16_f32 v183, v180, v181
	ds_write_b16 v170, v182 offset:2304
	ds_write_b16_d16_hi v170, v182 offset:2336
	ds_write_b16 v170, v183 offset:2368
	ds_write_b16_d16_hi v170, v183 offset:2400
	v_mul_f32_e32 v184, 0xbfb8aa3b, v23
	v_mul_f32_e32 v185, 0xbfb8aa3b, v27
	v_mul_f32_e32 v186, 0xbfb8aa3b, v31
	v_mul_f32_e32 v187, 0xbfb8aa3b, v35
	v_exp_f32_e32 v184, v184
	v_exp_f32_e32 v185, v185
	v_exp_f32_e32 v186, v186
	v_exp_f32_e32 v187, v187
	v_add_f32_e32 v184, 1.0, v184
	v_add_f32_e32 v185, 1.0, v185
	v_add_f32_e32 v186, 1.0, v186
	v_add_f32_e32 v187, 1.0, v187
	v_rcp_f32_e32 v184, v184
	v_rcp_f32_e32 v185, v185
	v_rcp_f32_e32 v186, v186
	v_rcp_f32_e32 v187, v187
	v_mul_f32_e32 v184, v23, v184
	v_mul_f32_e32 v185, v27, v185
	v_mul_f32_e32 v186, v31, v186
	v_mul_f32_e32 v187, v35, v187
	v_cvt_pk_bf16_f32 v188, v184, v185
	v_cvt_pk_bf16_f32 v189, v186, v187
	ds_write_b16 v170, v188 offset:2448
	ds_write_b16_d16_hi v170, v188 offset:2480
	ds_write_b16 v170, v189 offset:2512
	ds_write_b16_d16_hi v170, v189 offset:2544
	v_mul_f32_e32 v190, 0xbfb8aa3b, v24
	v_mul_f32_e32 v191, 0xbfb8aa3b, v28
	v_mul_f32_e32 v192, 0xbfb8aa3b, v32
	v_mul_f32_e32 v193, 0xbfb8aa3b, v36
	v_exp_f32_e32 v190, v190
	v_exp_f32_e32 v191, v191
	v_exp_f32_e32 v192, v192
	v_exp_f32_e32 v193, v193
	v_add_f32_e32 v190, 1.0, v190
	v_add_f32_e32 v191, 1.0, v191
	v_add_f32_e32 v192, 1.0, v192
	v_add_f32_e32 v193, 1.0, v193
	v_rcp_f32_e32 v190, v190
	v_rcp_f32_e32 v191, v191
	v_rcp_f32_e32 v192, v192
	v_rcp_f32_e32 v193, v193
	v_mul_f32_e32 v190, v24, v190
	v_mul_f32_e32 v191, v28, v191
	v_mul_f32_e32 v192, v32, v192
; DI float silu(float v) { return v * __builtin_amdgcn_rcpf(1.f + __builtin_amdgcn_exp2f(-1.4426950408889634f * v)); }
; template <int EPI>
; DI void gemm_phase(const P& p, int l, const u16* __restrict__ A, const u16* __restrict__ Bt, int mpx, char* lds) {
;     ...
;           float v0 = acc[hf * 4 + mi][0][j], v1 = acc[hf * 4 + mi][1][j], v2 = acc[hf * 4 + mi][2][j], v3 = acc[hf * 4 + mi][3][j];
;           const int rowl = mi * 16 + g * 4 + j;
;           const int s = tokw + hf * 64 + rowl;
;           if (tr == 1) {
;             v0 = silu(v0); v1 = silu(v1); v2 = silu(v2); v3 = silu(v3);
;     ...
;             Tl[rowl * 72 + 0 * 16 + r] = (u16)u01;
;             Tl[rowl * 72 + 1 * 16 + r] = (u16)(u01 >> 16);
;             Tl[rowl * 72 + 2 * 16 + r] = (u16)u23;
;             Tl[rowl * 72 + 3 * 16 + r] = (u16)(u23 >> 16);
	v_mul_f32_e32 v193, v36, v193
	v_cvt_pk_bf16_f32 v174, v190, v191
	v_cvt_pk_bf16_f32 v175, v192, v193
	ds_write_b16 v170, v174 offset:2592
	ds_write_b16_d16_hi v170, v174 offset:2624
	ds_write_b16 v170, v175 offset:2656
	ds_write_b16_d16_hi v170, v175 offset:2688
	v_mul_f32_e32 v176, 0xbfb8aa3b, v25
	v_mul_f32_e32 v177, 0xbfb8aa3b, v29
	v_mul_f32_e32 v178, 0xbfb8aa3b, v33
	v_mul_f32_e32 v179, 0xbfb8aa3b, v37
	v_exp_f32_e32 v176, v176
	v_exp_f32_e32 v177, v177
	v_exp_f32_e32 v178, v178
	v_exp_f32_e32 v179, v179
	v_add_f32_e32 v176, 1.0, v176
	v_add_f32_e32 v177, 1.0, v177
	v_add_f32_e32 v178, 1.0, v178
	v_add_f32_e32 v179, 1.0, v179
	v_rcp_f32_e32 v176, v176
	v_rcp_f32_e32 v177, v177
	v_rcp_f32_e32 v178, v178
	v_rcp_f32_e32 v179, v179
	v_mul_f32_e32 v176, v25, v176
	v_mul_f32_e32 v177, v29, v177
	v_mul_f32_e32 v178, v33, v178
	v_mul_f32_e32 v179, v37, v179
	v_cvt_pk_bf16_f32 v180, v176, v177
	v_cvt_pk_bf16_f32 v181, v178, v179
	ds_write_b16 v170, v180 offset:2736
	ds_write_b16_d16_hi v170, v180 offset:2768
	ds_write_b16 v170, v181 offset:2800
	ds_write_b16_d16_hi v170, v181 offset:2832
	v_mul_f32_e32 v182, 0xbfb8aa3b, v38
	v_mul_f32_e32 v183, 0xbfb8aa3b, v42
	v_mul_f32_e32 v184, 0xbfb8aa3b, v46
	v_mul_f32_e32 v185, 0xbfb8aa3b, v50
	v_exp_f32_e32 v182, v182
	v_exp_f32_e32 v183, v183
	v_exp_f32_e32 v184, v184
	v_exp_f32_e32 v185, v185
	v_add_f32_e32 v182, 1.0, v182
	v_add_f32_e32 v183, 1.0, v183
	v_add_f32_e32 v184, 1.0, v184
	v_add_f32_e32 v185, 1.0, v185
	v_rcp_f32_e32 v182, v182
	v_rcp_f32_e32 v183, v183
	v_rcp_f32_e32 v184, v184
	v_rcp_f32_e32 v185, v185
	v_mul_f32_e32 v182, v38, v182
	v_mul_f32_e32 v183, v42, v183
	v_mul_f32_e32 v184, v46, v184
	v_mul_f32_e32 v185, v50, v185
	v_cvt_pk_bf16_f32 v186, v182, v183
	v_cvt_pk_bf16_f32 v187, v184, v185
	ds_write_b16 v170, v186 offset:4608
	ds_write_b16_d16_hi v170, v186 offset:4640
	ds_write_b16 v170, v187 offset:4672
	ds_write_b16_d16_hi v170, v187 offset:4704
	v_mul_f32_e32 v188, 0xbfb8aa3b, v39
	v_mul_f32_e32 v189, 0xbfb8aa3b, v43
	v_mul_f32_e32 v190, 0xbfb8aa3b, v47
	v_mul_f32_e32 v191, 0xbfb8aa3b, v51
	v_exp_f32_e32 v188, v188
	v_exp_f32_e32 v189, v189
	v_exp_f32_e32 v190, v190
	v_exp_f32_e32 v191, v191
	v_add_f32_e32 v188, 1.0, v188
	v_add_f32_e32 v189, 1.0, v189
	v_add_f32_e32 v190, 1.0, v190
	v_add_f32_e32 v191, 1.0, v191
	v_rcp_f32_e32 v188, v188
	v_rcp_f32_e32 v189, v189
	v_rcp_f32_e32 v190, v190
	v_rcp_f32_e32 v191, v191
	v_mul_f32_e32 v188, v39, v188
	v_mul_f32_e32 v189, v43, v189
	v_mul_f32_e32 v190, v47, v190
	v_mul_f32_e32 v191, v51, v191
	v_cvt_pk_bf16_f32 v192, v188, v189
	v_cvt_pk_bf16_f32 v193, v190, v191
	ds_write_b16 v170, v192 offset:4752
	ds_write_b16_d16_hi v170, v192 offset:4784
	ds_write_b16 v170, v193 offset:4816
	ds_write_b16_d16_hi v170, v193 offset:4848
	v_mul_f32_e32 v174, 0xbfb8aa3b, v40
	v_mul_f32_e32 v175, 0xbfb8aa3b, v44
	v_mul_f32_e32 v176, 0xbfb8aa3b, v48
	v_mul_f32_e32 v177, 0xbfb8aa3b, v52
	v_exp_f32_e32 v174, v174
	v_exp_f32_e32 v175, v175
	v_exp_f32_e32 v176, v176
	v_exp_f32_e32 v177, v177
	v_add_f32_e32 v174, 1.0, v174
	v_add_f32_e32 v175, 1.0, v175
	v_add_f32_e32 v176, 1.0, v176
	v_add_f32_e32 v177, 1.0, v177
	v_rcp_f32_e32 v174, v174
	v_rcp_f32_e32 v175, v175
	v_rcp_f32_e32 v176, v176
	v_rcp_f32_e32 v177, v177
	v_mul_f32_e32 v174, v40, v174
	v_mul_f32_e32 v175, v44, v175
	v_mul_f32_e32 v176, v48, v176
	v_mul_f32_e32 v177, v52, v177
	v_cvt_pk_bf16_f32 v178, v174, v175
	v_cvt_pk_bf16_f32 v179, v176, v177
	ds_write_b16 v170, v178 offset:4896
	ds_write_b16_d16_hi v170, v178 offset:4928
	ds_write_b16 v170, v179 offset:4960
	ds_write_b16_d16_hi v170, v179 offset:4992
	v_mul_f32_e32 v180, 0xbfb8aa3b, v41
	v_mul_f32_e32 v181, 0xbfb8aa3b, v45
	v_mul_f32_e32 v182, 0xbfb8aa3b, v49
	v_mul_f32_e32 v183, 0xbfb8aa3b, v53
	v_exp_f32_e32 v180, v180
	v_exp_f32_e32 v181, v181
	v_exp_f32_e32 v182, v182
	v_exp_f32_e32 v183, v183
	v_add_f32_e32 v180, 1.0, v180
	v_add_f32_e32 v181, 1.0, v181
	v_add_f32_e32 v182, 1.0, v182
	v_add_f32_e32 v183, 1.0, v183
	v_rcp_f32_e32 v180, v180
	v_rcp_f32_e32 v181, v181
	v_rcp_f32_e32 v182, v182
	v_rcp_f32_e32 v183, v183
	v_mul_f32_e32 v180, v41, v180
	v_mul_f32_e32 v181, v45, v181
	v_mul_f32_e32 v182, v49, v182
	v_mul_f32_e32 v183, v53, v183
	v_cvt_pk_bf16_f32 v184, v180, v181
	v_cvt_pk_bf16_f32 v185, v182, v183
	ds_write_b16 v170, v184 offset:5040
	ds_write_b16_d16_hi v170, v184 offset:5072
	ds_write_b16 v170, v185 offset:5104
	ds_write_b16_d16_hi v170, v185 offset:5136
	v_mul_f32_e32 v186, 0xbfb8aa3b, v54
	v_mul_f32_e32 v187, 0xbfb8aa3b, v58
	v_mul_f32_e32 v188, 0xbfb8aa3b, v62
	v_mul_f32_e32 v189, 0xbfb8aa3b, v66
	v_exp_f32_e32 v186, v186
	v_exp_f32_e32 v187, v187
	v_exp_f32_e32 v188, v188
	v_exp_f32_e32 v189, v189
	v_add_f32_e32 v186, 1.0, v186
	v_add_f32_e32 v187, 1.0, v187
	v_add_f32_e32 v188, 1.0, v188
	v_add_f32_e32 v189, 1.0, v189
	v_rcp_f32_e32 v186, v186
	v_rcp_f32_e32 v187, v187
	v_rcp_f32_e32 v188, v188
	v_rcp_f32_e32 v189, v189
	v_mul_f32_e32 v186, v54, v186
	v_mul_f32_e32 v187, v58, v187
	v_mul_f32_e32 v188, v62, v188
	v_mul_f32_e32 v189, v66, v189
	v_cvt_pk_bf16_f32 v190, v186, v187
	v_cvt_pk_bf16_f32 v191, v188, v189
	ds_write_b16 v170, v190 offset:6912
	ds_write_b16_d16_hi v170, v190 offset:6944
	ds_write_b16 v170, v191 offset:6976
	ds_write_b16_d16_hi v170, v191 offset:7008
	v_mul_f32_e32 v192, 0xbfb8aa3b, v55
	v_mul_f32_e32 v193, 0xbfb8aa3b, v59
	v_mul_f32_e32 v174, 0xbfb8aa3b, v63
	v_mul_f32_e32 v175, 0xbfb8aa3b, v67
	v_exp_f32_e32 v192, v192
	v_exp_f32_e32 v193, v193
	v_exp_f32_e32 v174, v174
	v_exp_f32_e32 v175, v175
	v_add_f32_e32 v192, 1.0, v192
	v_add_f32_e32 v193, 1.0, v193
	v_add_f32_e32 v174, 1.0, v174
; template <int EPI>
; DI void gemm_phase(const P& p, int l, const u16* __restrict__ A, const u16* __restrict__ Bt, int mpx, char* lds) {
;     ...
;           if (tr == 1) {
;             v0 = silu(v0); v1 = silu(v1); v2 = silu(v2); v3 = silu(v3);
;           } else if (tr == 3) {
;             if (donorm) {
;               float ss = v0 * v0 + v1 * v1 + v2 * v2 + v3 * v3;
;               ss += __shfl_xor(ss, 1);
;               ss += __shfl_xor(ss, 2);
;               ss += __shfl_xor(ss, 4);
;               ss += __shfl_xor(ss, 8);
;               const float inv = rsqrtf(ss * (1.f / 64.f) + 1e-6f);
;               v0 *= inv * gv0; v1 *= inv * gv1; v2 *= inv * gv2; v3 *= inv * gv3;
;             }
;             if (dorope) {
;               float sr, cr, sc, cc;
;               sincos_rev((float)(s >> 6) * invf64, sr, cr);
;               sincos_rev((float)(s & 63) * invf64, sc, cc);
;               const float a1 = v0, a2 = v1, b1 = v2, b2 = v3;
;               v0 = a1 * cr - a2 * sr;
;               v1 = a2 * cr + a1 * sr;
;               v2 = b1 * cc - b2 * sc;
;               v3 = b2 * cc + b1 * sc;
;             }
;           } else if (tr == 4) {
;             float sr, cr, sc, cc;
;             sincos_rev((float)(s >> 6) * invf32, sr, cr);
;             sincos_rev((float)(s & 63) * invf32, sc, cc);
;             const float p0 = __shfl_xor(v0, 8), p1 = __shfl_xor(v1, 8), p2 = __shfl_xor(v2, 8), p3 = __shfl_xor(v3, 8);
;             v0 = lo8 ? (v0 * cr - p0 * sr) : (v0 * cr + p0 * sr);
;             v1 = lo8 ? (v1 * cc - p1 * sc) : (v1 * cc + p1 * sc);
;             v2 = lo8 ? (v2 * cr - p2 * sr) : (v2 * cr + p2 * sr);
;             v3 = lo8 ? (v3 * cc - p3 * sc) : (v3 * cc + p3 * sc);
;           }
;           const unsigned u01 = pack2(v0, v1), u23 = pack2(v2, v3);
;           if (kind == 1) {
;             Tl[(0 * 16 + r) * 72 + rowl] = (u16)u01;
;             Tl[(1 * 16 + r) * 72 + rowl] = (u16)(u01 >> 16);
;             Tl[(2 * 16 + r) * 72 + rowl] = (u16)u23;
;             Tl[(3 * 16 + r) * 72 + rowl] = (u16)(u23 >> 16);
;           } else if (tr == 2) {
;             Tl[rowl * 72 + 0 * 16 + r] = f2h(v0);
;             Tl[rowl * 72 + 1 * 16 + r] = f2h(v1);
;             Tl[rowl * 72 + 2 * 16 + r] = f2h(v2);
;             Tl[rowl * 72 + 3 * 16 + r] = f2h(v3);
;           } else {
;             Tl[rowl * 72 + 0 * 16 + r] = (u16)u01;
	v_add_f32_e32 v175, 1.0, v175
	v_rcp_f32_e32 v192, v192
	v_rcp_f32_e32 v193, v193
	v_rcp_f32_e32 v174, v174
	v_rcp_f32_e32 v175, v175
	v_mul_f32_e32 v192, v55, v192
	v_mul_f32_e32 v193, v59, v193
	v_mul_f32_e32 v174, v63, v174
	v_mul_f32_e32 v175, v67, v175
	v_cvt_pk_bf16_f32 v176, v192, v193
	v_cvt_pk_bf16_f32 v177, v174, v175
	ds_write_b16 v170, v176 offset:7056
	ds_write_b16_d16_hi v170, v176 offset:7088
	ds_write_b16 v170, v177 offset:7120
	ds_write_b16_d16_hi v170, v177 offset:7152
	v_mul_f32_e32 v178, 0xbfb8aa3b, v56
	v_mul_f32_e32 v179, 0xbfb8aa3b, v60
	v_mul_f32_e32 v180, 0xbfb8aa3b, v64
	v_mul_f32_e32 v181, 0xbfb8aa3b, v68
	v_exp_f32_e32 v178, v178
	v_exp_f32_e32 v179, v179
	v_exp_f32_e32 v180, v180
	v_exp_f32_e32 v181, v181
	v_add_f32_e32 v178, 1.0, v178
	v_add_f32_e32 v179, 1.0, v179
	v_add_f32_e32 v180, 1.0, v180
	v_add_f32_e32 v181, 1.0, v181
	v_rcp_f32_e32 v178, v178
	v_rcp_f32_e32 v179, v179
	v_rcp_f32_e32 v180, v180
	v_rcp_f32_e32 v181, v181
	v_mul_f32_e32 v178, v56, v178
	v_mul_f32_e32 v179, v60, v179
	v_mul_f32_e32 v180, v64, v180
	v_mul_f32_e32 v181, v68, v181
	v_cvt_pk_bf16_f32 v182, v178, v179
	v_cvt_pk_bf16_f32 v183, v180, v181
	ds_write_b16 v170, v182 offset:7200
	ds_write_b16_d16_hi v170, v182 offset:7232
	ds_write_b16 v170, v183 offset:7264
	ds_write_b16_d16_hi v170, v183 offset:7296
	v_mul_f32_e32 v184, 0xbfb8aa3b, v57
	v_mul_f32_e32 v185, 0xbfb8aa3b, v61
	v_mul_f32_e32 v186, 0xbfb8aa3b, v65
	v_mul_f32_e32 v187, 0xbfb8aa3b, v69
	v_exp_f32_e32 v184, v184
	v_exp_f32_e32 v185, v185
	v_exp_f32_e32 v186, v186
	v_exp_f32_e32 v187, v187
	v_add_f32_e32 v184, 1.0, v184
	v_add_f32_e32 v185, 1.0, v185
	v_add_f32_e32 v186, 1.0, v186
	v_add_f32_e32 v187, 1.0, v187
	v_rcp_f32_e32 v184, v184
	v_rcp_f32_e32 v185, v185
	v_rcp_f32_e32 v186, v186
	v_rcp_f32_e32 v187, v187
	v_mul_f32_e32 v184, v57, v184
	v_mul_f32_e32 v185, v61, v185
	v_mul_f32_e32 v186, v65, v186
	v_mul_f32_e32 v187, v69, v187
	v_cvt_pk_bf16_f32 v188, v184, v185
	v_cvt_pk_bf16_f32 v189, v186, v187
	ds_write_b16 v170, v188 offset:7344
	ds_write_b16_d16_hi v170, v188 offset:7376
	ds_write_b16 v170, v189 offset:7408
	ds_write_b16_d16_hi v170, v189 offset:7440
	ds_read_b128 v[130:133], v171 offset:0
	ds_read_b128 v[134:137], v171 offset:1152
	ds_read_b128 v[138:141], v171 offset:2304
	ds_read_b128 v[142:145], v171 offset:3456
	ds_read_b128 v[146:149], v171 offset:4608
	ds_read_b128 v[150:153], v171 offset:5760
	ds_read_b128 v[154:157], v171 offset:6912
	ds_read_b128 v[158:161], v171 offset:8064
	s_waitcnt lgkmcnt(7)
	global_store_dwordx4 v172, v[130:133], s[44:45] offset:0 sc1
	s_waitcnt lgkmcnt(6)
	global_store_dwordx4 v172, v[134:137], s[44:45] offset:1024 sc1
	s_waitcnt lgkmcnt(5)
	global_store_dwordx4 v172, v[138:141], s[44:45] offset:2048 sc1
	s_waitcnt lgkmcnt(4)
	global_store_dwordx4 v172, v[142:145], s[44:45] offset:3072 sc1
	s_waitcnt lgkmcnt(3)
	global_store_dwordx4 v172, v[146:149], s[62:63] offset:0 sc1
	s_waitcnt lgkmcnt(2)
	global_store_dwordx4 v172, v[150:153], s[62:63] offset:1024 sc1
	s_waitcnt lgkmcnt(1)
	global_store_dwordx4 v172, v[154:157], s[62:63] offset:2048 sc1
	s_waitcnt lgkmcnt(0)
	global_store_dwordx4 v172, v[158:161], s[62:63] offset:3072 sc1
	s_add_u32 s44, s44, 0x2000
	s_addc_u32 s45, s45, 0
	s_add_u32 s62, s62, 0x2000
	s_addc_u32 s63, s63, 0
	v_mul_f32_e32 v174, 0xbfb8aa3b, v70
	v_mul_f32_e32 v175, 0xbfb8aa3b, v74
	v_mul_f32_e32 v176, 0xbfb8aa3b, v78
	v_mul_f32_e32 v177, 0xbfb8aa3b, v82
	v_exp_f32_e32 v174, v174
	v_exp_f32_e32 v175, v175
	v_exp_f32_e32 v176, v176
	v_exp_f32_e32 v177, v177
	v_add_f32_e32 v174, 1.0, v174
	v_add_f32_e32 v175, 1.0, v175
	v_add_f32_e32 v176, 1.0, v176
	v_add_f32_e32 v177, 1.0, v177
	v_rcp_f32_e32 v174, v174
	v_rcp_f32_e32 v175, v175
	v_rcp_f32_e32 v176, v176
	v_rcp_f32_e32 v177, v177
	v_mul_f32_e32 v174, v70, v174
	v_mul_f32_e32 v175, v74, v175
	v_mul_f32_e32 v176, v78, v176
	v_mul_f32_e32 v177, v82, v177
	v_cvt_pk_bf16_f32 v178, v174, v175
	v_cvt_pk_bf16_f32 v179, v176, v177
	ds_write_b16 v170, v178 offset:0
	ds_write_b16_d16_hi v170, v178 offset:32
	ds_write_b16 v170, v179 offset:64
	ds_write_b16_d16_hi v170, v179 offset:96
	v_mul_f32_e32 v180, 0xbfb8aa3b, v71
	v_mul_f32_e32 v181, 0xbfb8aa3b, v75
	v_mul_f32_e32 v182, 0xbfb8aa3b, v79
	v_mul_f32_e32 v183, 0xbfb8aa3b, v83
	v_exp_f32_e32 v180, v180
	v_exp_f32_e32 v181, v181
	v_exp_f32_e32 v182, v182
	v_exp_f32_e32 v183, v183
	v_add_f32_e32 v180, 1.0, v180
	v_add_f32_e32 v181, 1.0, v181
	v_add_f32_e32 v182, 1.0, v182
	v_add_f32_e32 v183, 1.0, v183
	v_rcp_f32_e32 v180, v180
	v_rcp_f32_e32 v181, v181
	v_rcp_f32_e32 v182, v182
	v_rcp_f32_e32 v183, v183
	v_mul_f32_e32 v180, v71, v180
	v_mul_f32_e32 v181, v75, v181
	v_mul_f32_e32 v182, v79, v182
	v_mul_f32_e32 v183, v83, v183
	v_cvt_pk_bf16_f32 v184, v180, v181
	v_cvt_pk_bf16_f32 v185, v182, v183
	ds_write_b16 v170, v184 offset:144
	ds_write_b16_d16_hi v170, v184 offset:176
	ds_write_b16 v170, v185 offset:208
	ds_write_b16_d16_hi v170, v185 offset:240
	v_mul_f32_e32 v186, 0xbfb8aa3b, v72
	v_mul_f32_e32 v187, 0xbfb8aa3b, v76
	v_mul_f32_e32 v188, 0xbfb8aa3b, v80
	v_mul_f32_e32 v189, 0xbfb8aa3b, v84
	v_exp_f32_e32 v186, v186
	v_exp_f32_e32 v187, v187
	v_exp_f32_e32 v188, v188
	v_exp_f32_e32 v189, v189
	v_add_f32_e32 v186, 1.0, v186
	v_add_f32_e32 v187, 1.0, v187
	v_add_f32_e32 v188, 1.0, v188
	v_add_f32_e32 v189, 1.0, v189
	v_rcp_f32_e32 v186, v186
	v_rcp_f32_e32 v187, v187
	v_rcp_f32_e32 v188, v188
	v_rcp_f32_e32 v189, v189
	v_mul_f32_e32 v186, v72, v186
	v_mul_f32_e32 v187, v76, v187
	v_mul_f32_e32 v188, v80, v188
	v_mul_f32_e32 v189, v84, v189
	v_cvt_pk_bf16_f32 v190, v186, v187
	v_cvt_pk_bf16_f32 v191, v188, v189
; DI float silu(float v) { return v * __builtin_amdgcn_rcpf(1.f + __builtin_amdgcn_exp2f(-1.4426950408889634f * v)); }
; template <int EPI>
; DI void gemm_phase(const P& p, int l, const u16* __restrict__ A, const u16* __restrict__ Bt, int mpx, char* lds) {
;     ...
;           float v0 = acc[hf * 4 + mi][0][j], v1 = acc[hf * 4 + mi][1][j], v2 = acc[hf * 4 + mi][2][j], v3 = acc[hf * 4 + mi][3][j];
;           const int rowl = mi * 16 + g * 4 + j;
;           const int s = tokw + hf * 64 + rowl;
;           if (tr == 1) {
;             v0 = silu(v0); v1 = silu(v1); v2 = silu(v2); v3 = silu(v3);
;     ...
;             Tl[rowl * 72 + 0 * 16 + r] = (u16)u01;
;             Tl[rowl * 72 + 1 * 16 + r] = (u16)(u01 >> 16);
;             Tl[rowl * 72 + 2 * 16 + r] = (u16)u23;
;             Tl[rowl * 72 + 3 * 16 + r] = (u16)(u23 >> 16);
	ds_write_b16 v170, v190 offset:288
	ds_write_b16_d16_hi v170, v190 offset:320
	ds_write_b16 v170, v191 offset:352
	ds_write_b16_d16_hi v170, v191 offset:384
	v_mul_f32_e32 v192, 0xbfb8aa3b, v73
	v_mul_f32_e32 v193, 0xbfb8aa3b, v77
	v_mul_f32_e32 v174, 0xbfb8aa3b, v81
	v_mul_f32_e32 v175, 0xbfb8aa3b, v85
	v_exp_f32_e32 v192, v192
	v_exp_f32_e32 v193, v193
	v_exp_f32_e32 v174, v174
	v_exp_f32_e32 v175, v175
	v_add_f32_e32 v192, 1.0, v192
	v_add_f32_e32 v193, 1.0, v193
	v_add_f32_e32 v174, 1.0, v174
	v_add_f32_e32 v175, 1.0, v175
	v_rcp_f32_e32 v192, v192
	v_rcp_f32_e32 v193, v193
	v_rcp_f32_e32 v174, v174
	v_rcp_f32_e32 v175, v175
	v_mul_f32_e32 v192, v73, v192
	v_mul_f32_e32 v193, v77, v193
	v_mul_f32_e32 v174, v81, v174
	v_mul_f32_e32 v175, v85, v175
	v_cvt_pk_bf16_f32 v176, v192, v193
	v_cvt_pk_bf16_f32 v177, v174, v175
	ds_write_b16 v170, v176 offset:432
	ds_write_b16_d16_hi v170, v176 offset:464
	ds_write_b16 v170, v177 offset:496
	ds_write_b16_d16_hi v170, v177 offset:528
	v_mul_f32_e32 v178, 0xbfb8aa3b, v86
	v_mul_f32_e32 v179, 0xbfb8aa3b, v90
	v_mul_f32_e32 v180, 0xbfb8aa3b, v94
	v_mul_f32_e32 v181, 0xbfb8aa3b, v98
	v_exp_f32_e32 v178, v178
	v_exp_f32_e32 v179, v179
	v_exp_f32_e32 v180, v180
	v_exp_f32_e32 v181, v181
	v_add_f32_e32 v178, 1.0, v178
	v_add_f32_e32 v179, 1.0, v179
	v_add_f32_e32 v180, 1.0, v180
	v_add_f32_e32 v181, 1.0, v181
	v_rcp_f32_e32 v178, v178
	v_rcp_f32_e32 v179, v179
	v_rcp_f32_e32 v180, v180
	v_rcp_f32_e32 v181, v181
	v_mul_f32_e32 v178, v86, v178
	v_mul_f32_e32 v179, v90, v179
	v_mul_f32_e32 v180, v94, v180
	v_mul_f32_e32 v181, v98, v181
	v_cvt_pk_bf16_f32 v182, v178, v179
	v_cvt_pk_bf16_f32 v183, v180, v181
	ds_write_b16 v170, v182 offset:2304
	ds_write_b16_d16_hi v170, v182 offset:2336
	ds_write_b16 v170, v183 offset:2368
	ds_write_b16_d16_hi v170, v183 offset:2400
	v_mul_f32_e32 v184, 0xbfb8aa3b, v87
	v_mul_f32_e32 v185, 0xbfb8aa3b, v91
	v_mul_f32_e32 v186, 0xbfb8aa3b, v95
	v_mul_f32_e32 v187, 0xbfb8aa3b, v99
	v_exp_f32_e32 v184, v184
	v_exp_f32_e32 v185, v185
	v_exp_f32_e32 v186, v186
	v_exp_f32_e32 v187, v187
	v_add_f32_e32 v184, 1.0, v184
	v_add_f32_e32 v185, 1.0, v185
	v_add_f32_e32 v186, 1.0, v186
	v_add_f32_e32 v187, 1.0, v187
	v_rcp_f32_e32 v184, v184
	v_rcp_f32_e32 v185, v185
	v_rcp_f32_e32 v186, v186
	v_rcp_f32_e32 v187, v187
	v_mul_f32_e32 v184, v87, v184
	v_mul_f32_e32 v185, v91, v185
	v_mul_f32_e32 v186, v95, v186
	v_mul_f32_e32 v187, v99, v187
	v_cvt_pk_bf16_f32 v188, v184, v185
	v_cvt_pk_bf16_f32 v189, v186, v187
	ds_write_b16 v170, v188 offset:2448
	ds_write_b16_d16_hi v170, v188 offset:2480
	ds_write_b16 v170, v189 offset:2512
	ds_write_b16_d16_hi v170, v189 offset:2544
	v_mul_f32_e32 v190, 0xbfb8aa3b, v88
	v_mul_f32_e32 v191, 0xbfb8aa3b, v92
	v_mul_f32_e32 v192, 0xbfb8aa3b, v96
	v_mul_f32_e32 v193, 0xbfb8aa3b, v100
	v_exp_f32_e32 v190, v190
	v_exp_f32_e32 v191, v191
	v_exp_f32_e32 v192, v192
	v_exp_f32_e32 v193, v193
	v_add_f32_e32 v190, 1.0, v190
	v_add_f32_e32 v191, 1.0, v191
	v_add_f32_e32 v192, 1.0, v192
	v_add_f32_e32 v193, 1.0, v193
	v_rcp_f32_e32 v190, v190
	v_rcp_f32_e32 v191, v191
	v_rcp_f32_e32 v192, v192
	v_rcp_f32_e32 v193, v193
	v_mul_f32_e32 v190, v88, v190
	v_mul_f32_e32 v191, v92, v191
	v_mul_f32_e32 v192, v96, v192
	v_mul_f32_e32 v193, v100, v193
	v_cvt_pk_bf16_f32 v174, v190, v191
	v_cvt_pk_bf16_f32 v175, v192, v193
	ds_write_b16 v170, v174 offset:2592
	ds_write_b16_d16_hi v170, v174 offset:2624
	ds_write_b16 v170, v175 offset:2656
	ds_write_b16_d16_hi v170, v175 offset:2688
	v_mul_f32_e32 v176, 0xbfb8aa3b, v89
	v_mul_f32_e32 v177, 0xbfb8aa3b, v93
	v_mul_f32_e32 v178, 0xbfb8aa3b, v97
	v_mul_f32_e32 v179, 0xbfb8aa3b, v101
	v_exp_f32_e32 v176, v176
	v_exp_f32_e32 v177, v177
	v_exp_f32_e32 v178, v178
	v_exp_f32_e32 v179, v179
	v_add_f32_e32 v176, 1.0, v176
	v_add_f32_e32 v177, 1.0, v177
	v_add_f32_e32 v178, 1.0, v178
	v_add_f32_e32 v179, 1.0, v179
	v_rcp_f32_e32 v176, v176
	v_rcp_f32_e32 v177, v177
	v_rcp_f32_e32 v178, v178
	v_rcp_f32_e32 v179, v179
	v_mul_f32_e32 v176, v89, v176
	v_mul_f32_e32 v177, v93, v177
	v_mul_f32_e32 v178, v97, v178
	v_mul_f32_e32 v179, v101, v179
	v_cvt_pk_bf16_f32 v180, v176, v177
	v_cvt_pk_bf16_f32 v181, v178, v179
	ds_write_b16 v170, v180 offset:2736
	ds_write_b16_d16_hi v170, v180 offset:2768
	ds_write_b16 v170, v181 offset:2800
	ds_write_b16_d16_hi v170, v181 offset:2832
	v_mul_f32_e32 v182, 0xbfb8aa3b, v102
	v_mul_f32_e32 v183, 0xbfb8aa3b, v106
	v_mul_f32_e32 v184, 0xbfb8aa3b, v110
	v_mul_f32_e32 v185, 0xbfb8aa3b, v114
	v_exp_f32_e32 v182, v182
	v_exp_f32_e32 v183, v183
	v_exp_f32_e32 v184, v184
	v_exp_f32_e32 v185, v185
	v_add_f32_e32 v182, 1.0, v182
	v_add_f32_e32 v183, 1.0, v183
	v_add_f32_e32 v184, 1.0, v184
	v_add_f32_e32 v185, 1.0, v185
	v_rcp_f32_e32 v182, v182
	v_rcp_f32_e32 v183, v183
	v_rcp_f32_e32 v184, v184
	v_rcp_f32_e32 v185, v185
	v_mul_f32_e32 v182, v102, v182
	v_mul_f32_e32 v183, v106, v183
	v_mul_f32_e32 v184, v110, v184
	v_mul_f32_e32 v185, v114, v185
	v_cvt_pk_bf16_f32 v186, v182, v183
	v_cvt_pk_bf16_f32 v187, v184, v185
	ds_write_b16 v170, v186 offset:4608
	ds_write_b16_d16_hi v170, v186 offset:4640
	ds_write_b16 v170, v187 offset:4672
	ds_write_b16_d16_hi v170, v187 offset:4704
	v_mul_f32_e32 v188, 0xbfb8aa3b, v103
	v_mul_f32_e32 v189, 0xbfb8aa3b, v107
	v_mul_f32_e32 v190, 0xbfb8aa3b, v111
	v_mul_f32_e32 v191, 0xbfb8aa3b, v115
	v_exp_f32_e32 v188, v188
	v_exp_f32_e32 v189, v189
	v_exp_f32_e32 v190, v190
	v_exp_f32_e32 v191, v191
	v_add_f32_e32 v188, 1.0, v188
	v_add_f32_e32 v189, 1.0, v189
	v_add_f32_e32 v190, 1.0, v190
	v_add_f32_e32 v191, 1.0, v191
	v_rcp_f32_e32 v188, v188
	v_rcp_f32_e32 v189, v189
	v_rcp_f32_e32 v190, v190
; template <int EPI>
; DI void gemm_phase(const P& p, int l, const u16* __restrict__ A, const u16* __restrict__ Bt, int mpx, char* lds) {
;     ...
;           if (tr == 1) {
;             v0 = silu(v0); v1 = silu(v1); v2 = silu(v2); v3 = silu(v3);
;           } else if (tr == 3) {
;             if (donorm) {
;               float ss = v0 * v0 + v1 * v1 + v2 * v2 + v3 * v3;
;               ss += __shfl_xor(ss, 1);
;               ss += __shfl_xor(ss, 2);
;               ss += __shfl_xor(ss, 4);
;               ss += __shfl_xor(ss, 8);
;               const float inv = rsqrtf(ss * (1.f / 64.f) + 1e-6f);
;               v0 *= inv * gv0; v1 *= inv * gv1; v2 *= inv * gv2; v3 *= inv * gv3;
;             }
;             if (dorope) {
;               float sr, cr, sc, cc;
;               sincos_rev((float)(s >> 6) * invf64, sr, cr);
;               sincos_rev((float)(s & 63) * invf64, sc, cc);
;               const float a1 = v0, a2 = v1, b1 = v2, b2 = v3;
;               v0 = a1 * cr - a2 * sr;
;               v1 = a2 * cr + a1 * sr;
;               v2 = b1 * cc - b2 * sc;
;               v3 = b2 * cc + b1 * sc;
;             }
;           } else if (tr == 4) {
;             float sr, cr, sc, cc;
;             sincos_rev((float)(s >> 6) * invf32, sr, cr);
;             sincos_rev((float)(s & 63) * invf32, sc, cc);
;             const float p0 = __shfl_xor(v0, 8), p1 = __shfl_xor(v1, 8), p2 = __shfl_xor(v2, 8), p3 = __shfl_xor(v3, 8);
;             v0 = lo8 ? (v0 * cr - p0 * sr) : (v0 * cr + p0 * sr);
;             v1 = lo8 ? (v1 * cc - p1 * sc) : (v1 * cc + p1 * sc);
;             v2 = lo8 ? (v2 * cr - p2 * sr) : (v2 * cr + p2 * sr);
;             v3 = lo8 ? (v3 * cc - p3 * sc) : (v3 * cc + p3 * sc);
;           }
;           const unsigned u01 = pack2(v0, v1), u23 = pack2(v2, v3);
;           if (kind == 1) {
;             Tl[(0 * 16 + r) * 72 + rowl] = (u16)u01;
;             Tl[(1 * 16 + r) * 72 + rowl] = (u16)(u01 >> 16);
;             Tl[(2 * 16 + r) * 72 + rowl] = (u16)u23;
;             Tl[(3 * 16 + r) * 72 + rowl] = (u16)(u23 >> 16);
;           } else if (tr == 2) {
;             Tl[rowl * 72 + 0 * 16 + r] = f2h(v0);
;             Tl[rowl * 72 + 1 * 16 + r] = f2h(v1);
;             Tl[rowl * 72 + 2 * 16 + r] = f2h(v2);
;             Tl[rowl * 72 + 3 * 16 + r] = f2h(v3);
;           } else {
;             Tl[rowl * 72 + 0 * 16 + r] = (u16)u01;
	v_rcp_f32_e32 v191, v191
	v_mul_f32_e32 v188, v103, v188
	v_mul_f32_e32 v189, v107, v189
	v_mul_f32_e32 v190, v111, v190
	v_mul_f32_e32 v191, v115, v191
	v_cvt_pk_bf16_f32 v192, v188, v189
	v_cvt_pk_bf16_f32 v193, v190, v191
	ds_write_b16 v170, v192 offset:4752
	ds_write_b16_d16_hi v170, v192 offset:4784
	ds_write_b16 v170, v193 offset:4816
	ds_write_b16_d16_hi v170, v193 offset:4848
	v_mul_f32_e32 v174, 0xbfb8aa3b, v104
	v_mul_f32_e32 v175, 0xbfb8aa3b, v108
	v_mul_f32_e32 v176, 0xbfb8aa3b, v112
	v_mul_f32_e32 v177, 0xbfb8aa3b, v116
	v_exp_f32_e32 v174, v174
	v_exp_f32_e32 v175, v175
	v_exp_f32_e32 v176, v176
	v_exp_f32_e32 v177, v177
	v_add_f32_e32 v174, 1.0, v174
	v_add_f32_e32 v175, 1.0, v175
	v_add_f32_e32 v176, 1.0, v176
	v_add_f32_e32 v177, 1.0, v177
	v_rcp_f32_e32 v174, v174
	v_rcp_f32_e32 v175, v175
	v_rcp_f32_e32 v176, v176
	v_rcp_f32_e32 v177, v177
	v_mul_f32_e32 v174, v104, v174
	v_mul_f32_e32 v175, v108, v175
	v_mul_f32_e32 v176, v112, v176
	v_mul_f32_e32 v177, v116, v177
	v_cvt_pk_bf16_f32 v178, v174, v175
	v_cvt_pk_bf16_f32 v179, v176, v177
	ds_write_b16 v170, v178 offset:4896
	ds_write_b16_d16_hi v170, v178 offset:4928
	ds_write_b16 v170, v179 offset:4960
	ds_write_b16_d16_hi v170, v179 offset:4992
	v_mul_f32_e32 v180, 0xbfb8aa3b, v105
	v_mul_f32_e32 v181, 0xbfb8aa3b, v109
	v_mul_f32_e32 v182, 0xbfb8aa3b, v113
	v_mul_f32_e32 v183, 0xbfb8aa3b, v117
	v_exp_f32_e32 v180, v180
	v_exp_f32_e32 v181, v181
	v_exp_f32_e32 v182, v182
	v_exp_f32_e32 v183, v183
	v_add_f32_e32 v180, 1.0, v180
	v_add_f32_e32 v181, 1.0, v181
	v_add_f32_e32 v182, 1.0, v182
	v_add_f32_e32 v183, 1.0, v183
	v_rcp_f32_e32 v180, v180
	v_rcp_f32_e32 v181, v181
	v_rcp_f32_e32 v182, v182
	v_rcp_f32_e32 v183, v183
	v_mul_f32_e32 v180, v105, v180
	v_mul_f32_e32 v181, v109, v181
	v_mul_f32_e32 v182, v113, v182
	v_mul_f32_e32 v183, v117, v183
	v_cvt_pk_bf16_f32 v184, v180, v181
	v_cvt_pk_bf16_f32 v185, v182, v183
	ds_write_b16 v170, v184 offset:5040
	ds_write_b16_d16_hi v170, v184 offset:5072
	ds_write_b16 v170, v185 offset:5104
	ds_write_b16_d16_hi v170, v185 offset:5136
	v_mul_f32_e32 v186, 0xbfb8aa3b, v118
	v_mul_f32_e32 v187, 0xbfb8aa3b, v122
	v_mul_f32_e32 v188, 0xbfb8aa3b, v126
	v_mul_f32_e32 v189, 0xbfb8aa3b, v2
	v_exp_f32_e32 v186, v186
	v_exp_f32_e32 v187, v187
	v_exp_f32_e32 v188, v188
	v_exp_f32_e32 v189, v189
	v_add_f32_e32 v186, 1.0, v186
	v_add_f32_e32 v187, 1.0, v187
	v_add_f32_e32 v188, 1.0, v188
	v_add_f32_e32 v189, 1.0, v189
	v_rcp_f32_e32 v186, v186
	v_rcp_f32_e32 v187, v187
	v_rcp_f32_e32 v188, v188
	v_rcp_f32_e32 v189, v189
	v_mul_f32_e32 v186, v118, v186
	v_mul_f32_e32 v187, v122, v187
	v_mul_f32_e32 v188, v126, v188
	v_mul_f32_e32 v189, v2, v189
	v_cvt_pk_bf16_f32 v190, v186, v187
	v_cvt_pk_bf16_f32 v191, v188, v189
	ds_write_b16 v170, v190 offset:6912
	ds_write_b16_d16_hi v170, v190 offset:6944
	ds_write_b16 v170, v191 offset:6976
	ds_write_b16_d16_hi v170, v191 offset:7008
	v_mul_f32_e32 v192, 0xbfb8aa3b, v119
	v_mul_f32_e32 v193, 0xbfb8aa3b, v123
	v_mul_f32_e32 v174, 0xbfb8aa3b, v127
	v_mul_f32_e32 v175, 0xbfb8aa3b, v3
	v_exp_f32_e32 v192, v192
	v_exp_f32_e32 v193, v193
	v_exp_f32_e32 v174, v174
	v_exp_f32_e32 v175, v175
	v_add_f32_e32 v192, 1.0, v192
	v_add_f32_e32 v193, 1.0, v193
	v_add_f32_e32 v174, 1.0, v174
	v_add_f32_e32 v175, 1.0, v175
	v_rcp_f32_e32 v192, v192
	v_rcp_f32_e32 v193, v193
	v_rcp_f32_e32 v174, v174
	v_rcp_f32_e32 v175, v175
	v_mul_f32_e32 v192, v119, v192
	v_mul_f32_e32 v193, v123, v193
	v_mul_f32_e32 v174, v127, v174
	v_mul_f32_e32 v175, v3, v175
	v_cvt_pk_bf16_f32 v176, v192, v193
	v_cvt_pk_bf16_f32 v177, v174, v175
	ds_write_b16 v170, v176 offset:7056
	ds_write_b16_d16_hi v170, v176 offset:7088
	ds_write_b16 v170, v177 offset:7120
	ds_write_b16_d16_hi v170, v177 offset:7152
	v_mul_f32_e32 v178, 0xbfb8aa3b, v120
	v_mul_f32_e32 v179, 0xbfb8aa3b, v124
	v_mul_f32_e32 v180, 0xbfb8aa3b, v128
	v_mul_f32_e32 v181, 0xbfb8aa3b, v4
	v_exp_f32_e32 v178, v178
	v_exp_f32_e32 v179, v179
	v_exp_f32_e32 v180, v180
	v_exp_f32_e32 v181, v181
	v_add_f32_e32 v178, 1.0, v178
	v_add_f32_e32 v179, 1.0, v179
	v_add_f32_e32 v180, 1.0, v180
	v_add_f32_e32 v181, 1.0, v181
	v_rcp_f32_e32 v178, v178
	v_rcp_f32_e32 v179, v179
	v_rcp_f32_e32 v180, v180
	v_rcp_f32_e32 v181, v181
	v_mul_f32_e32 v178, v120, v178
	v_mul_f32_e32 v179, v124, v179
	v_mul_f32_e32 v180, v128, v180
	v_mul_f32_e32 v181, v4, v181
	v_cvt_pk_bf16_f32 v182, v178, v179
	v_cvt_pk_bf16_f32 v183, v180, v181
	ds_write_b16 v170, v182 offset:7200
	ds_write_b16_d16_hi v170, v182 offset:7232
	ds_write_b16 v170, v183 offset:7264
	ds_write_b16_d16_hi v170, v183 offset:7296
	v_mul_f32_e32 v184, 0xbfb8aa3b, v121
	v_mul_f32_e32 v185, 0xbfb8aa3b, v125
	v_mul_f32_e32 v186, 0xbfb8aa3b, v129
	v_mul_f32_e32 v187, 0xbfb8aa3b, v5
	v_exp_f32_e32 v184, v184
	v_exp_f32_e32 v185, v185
	v_exp_f32_e32 v186, v186
	v_exp_f32_e32 v187, v187
	v_add_f32_e32 v184, 1.0, v184
	v_add_f32_e32 v185, 1.0, v185
	v_add_f32_e32 v186, 1.0, v186
	v_add_f32_e32 v187, 1.0, v187
	v_rcp_f32_e32 v184, v184
	v_rcp_f32_e32 v185, v185
	v_rcp_f32_e32 v186, v186
	v_rcp_f32_e32 v187, v187
	v_mul_f32_e32 v184, v121, v184
	v_mul_f32_e32 v185, v125, v185
	v_mul_f32_e32 v186, v129, v186
	v_mul_f32_e32 v187, v5, v187
	v_cvt_pk_bf16_f32 v188, v184, v185
	v_cvt_pk_bf16_f32 v189, v186, v187
	ds_write_b16 v170, v188 offset:7344
	ds_write_b16_d16_hi v170, v188 offset:7376
	ds_write_b16 v170, v189 offset:7408
	ds_write_b16_d16_hi v170, v189 offset:7440
	ds_read_b128 v[130:133], v171 offset:0
	ds_read_b128 v[134:137], v171 offset:1152
	ds_read_b128 v[138:141], v171 offset:2304
	ds_read_b128 v[142:145], v171 offset:3456
	ds_read_b128 v[146:149], v171 offset:4608
	ds_read_b128 v[150:153], v171 offset:5760
	ds_read_b128 v[154:157], v171 offset:6912
	ds_read_b128 v[158:161], v171 offset:8064
	s_waitcnt lgkmcnt(7)
	global_store_dwordx4 v172, v[130:133], s[44:45] offset:0 sc1
	s_waitcnt lgkmcnt(6)
	global_store_dwordx4 v172, v[134:137], s[44:45] offset:1024 sc1
	s_waitcnt lgkmcnt(5)
	global_store_dwordx4 v172, v[138:141], s[44:45] offset:2048 sc1
	s_waitcnt lgkmcnt(4)
	global_store_dwordx4 v172, v[142:145], s[44:45] offset:3072 sc1
	s_waitcnt lgkmcnt(3)
	global_store_dwordx4 v172, v[146:149], s[62:63] offset:0 sc1
	s_waitcnt lgkmcnt(2)
	global_store_dwordx4 v172, v[150:153], s[62:63] offset:1024 sc1
	s_waitcnt lgkmcnt(1)
	global_store_dwordx4 v172, v[154:157], s[62:63] offset:2048 sc1
	s_waitcnt lgkmcnt(0)
	global_store_dwordx4 v172, v[158:161], s[62:63] offset:3072 sc1
	s_branch .Lfe_done
; template <int EPI>
; DI void gemm_phase(const P& p, int l, const u16* __restrict__ A, const u16* __restrict__ Bt, int mpx, char* lds) {
;     ...
;           const unsigned u01 = pack2(v0, v1), u23 = pack2(v2, v3);
;           if (kind == 1) {
;             Tl[(0 * 16 + r) * 72 + rowl] = (u16)u01;
;             Tl[(1 * 16 + r) * 72 + rowl] = (u16)(u01 >> 16);
;             Tl[(2 * 16 + r) * 72 + rowl] = (u16)u23;
;             Tl[(3 * 16 + r) * 72 + rowl] = (u16)(u23 >> 16);
;           } else if (tr == 2) {
;             Tl[rowl * 72 + 0 * 16 + r] = f2h(v0);
;             Tl[rowl * 72 + 1 * 16 + r] = f2h(v1);
;             Tl[rowl * 72 + 2 * 16 + r] = f2h(v2);
;             Tl[rowl * 72 + 3 * 16 + r] = f2h(v3);
;           } else {
;             Tl[rowl * 72 + 0 * 16 + r] = (u16)u01;
;             Tl[rowl * 72 + 1 * 16 + r] = (u16)(u01 >> 16);
;             Tl[rowl * 72 + 2 * 16 + r] = (u16)u23;
;             Tl[rowl * 72 + 3 * 16 + r] = (u16)(u23 >> 16);
;           }
;         }
;       }
;       __builtin_amdgcn_fence(__ATOMIC_RELEASE, "wavefront");
;       u16* dh = (kind == 1) ? dst + hf * 64 : dst + (size_t)(hf * 64) * rstride;
; #pragma unroll
;       for (int i = 0; i < 8; ++i) {
;         const int c = lane + i * 64;
;         const int row = c >> 3, cc = c & 7;
;         uint4 v = *(const uint4*)&Tl[row * 72 + cc * 8];
;         *(uint4*)(dh + (size_t)row * rstride + cc * 8) = v;
;       }
.Lfe_k0_plain:
	s_add_u32 s62, s44, 0x1000
	s_addc_u32 s63, s45, 0
	v_cvt_pk_bf16_f32 v178, v6, v10
	v_cvt_pk_bf16_f32 v179, v14, v18
	ds_write_b16 v170, v178 offset:0
	ds_write_b16_d16_hi v170, v178 offset:32
	ds_write_b16 v170, v179 offset:64
	ds_write_b16_d16_hi v170, v179 offset:96
	v_cvt_pk_bf16_f32 v184, v7, v11
	v_cvt_pk_bf16_f32 v185, v15, v19
	ds_write_b16 v170, v184 offset:144
	ds_write_b16_d16_hi v170, v184 offset:176
	ds_write_b16 v170, v185 offset:208
	ds_write_b16_d16_hi v170, v185 offset:240
	v_cvt_pk_bf16_f32 v190, v8, v12
	v_cvt_pk_bf16_f32 v191, v16, v20
	ds_write_b16 v170, v190 offset:288
	ds_write_b16_d16_hi v170, v190 offset:320
	ds_write_b16 v170, v191 offset:352
	ds_write_b16_d16_hi v170, v191 offset:384
	v_cvt_pk_bf16_f32 v176, v9, v13
	v_cvt_pk_bf16_f32 v177, v17, v21
	ds_write_b16 v170, v176 offset:432
	ds_write_b16_d16_hi v170, v176 offset:464
	ds_write_b16 v170, v177 offset:496
	ds_write_b16_d16_hi v170, v177 offset:528
	v_cvt_pk_bf16_f32 v182, v22, v26
	v_cvt_pk_bf16_f32 v183, v30, v34
	ds_write_b16 v170, v182 offset:2304
	ds_write_b16_d16_hi v170, v182 offset:2336
	ds_write_b16 v170, v183 offset:2368
	ds_write_b16_d16_hi v170, v183 offset:2400
	v_cvt_pk_bf16_f32 v188, v23, v27
	v_cvt_pk_bf16_f32 v189, v31, v35
	ds_write_b16 v170, v188 offset:2448
	ds_write_b16_d16_hi v170, v188 offset:2480
	ds_write_b16 v170, v189 offset:2512
	ds_write_b16_d16_hi v170, v189 offset:2544
	v_cvt_pk_bf16_f32 v174, v24, v28
	v_cvt_pk_bf16_f32 v175, v32, v36
	ds_write_b16 v170, v174 offset:2592
	ds_write_b16_d16_hi v170, v174 offset:2624
	ds_write_b16 v170, v175 offset:2656
	ds_write_b16_d16_hi v170, v175 offset:2688
	v_cvt_pk_bf16_f32 v180, v25, v29
	v_cvt_pk_bf16_f32 v181, v33, v37
	ds_write_b16 v170, v180 offset:2736
	ds_write_b16_d16_hi v170, v180 offset:2768
	ds_write_b16 v170, v181 offset:2800
	ds_write_b16_d16_hi v170, v181 offset:2832
	v_cvt_pk_bf16_f32 v186, v38, v42
	v_cvt_pk_bf16_f32 v187, v46, v50
	ds_write_b16 v170, v186 offset:4608
	ds_write_b16_d16_hi v170, v186 offset:4640
	ds_write_b16 v170, v187 offset:4672
	ds_write_b16_d16_hi v170, v187 offset:4704
	v_cvt_pk_bf16_f32 v192, v39, v43
	v_cvt_pk_bf16_f32 v193, v47, v51
	ds_write_b16 v170, v192 offset:4752
	ds_write_b16_d16_hi v170, v192 offset:4784
	ds_write_b16 v170, v193 offset:4816
	ds_write_b16_d16_hi v170, v193 offset:4848
	v_cvt_pk_bf16_f32 v178, v40, v44
	v_cvt_pk_bf16_f32 v179, v48, v52
	ds_write_b16 v170, v178 offset:4896
	ds_write_b16_d16_hi v170, v178 offset:4928
	ds_write_b16 v170, v179 offset:4960
	ds_write_b16_d16_hi v170, v179 offset:4992
	v_cvt_pk_bf16_f32 v184, v41, v45
	v_cvt_pk_bf16_f32 v185, v49, v53
	ds_write_b16 v170, v184 offset:5040
	ds_write_b16_d16_hi v170, v184 offset:5072
	ds_write_b16 v170, v185 offset:5104
	ds_write_b16_d16_hi v170, v185 offset:5136
	v_cvt_pk_bf16_f32 v190, v54, v58
	v_cvt_pk_bf16_f32 v191, v62, v66
	ds_write_b16 v170, v190 offset:6912
	ds_write_b16_d16_hi v170, v190 offset:6944
	ds_write_b16 v170, v191 offset:6976
	ds_write_b16_d16_hi v170, v191 offset:7008
	v_cvt_pk_bf16_f32 v176, v55, v59
	v_cvt_pk_bf16_f32 v177, v63, v67
	ds_write_b16 v170, v176 offset:7056
	ds_write_b16_d16_hi v170, v176 offset:7088
	ds_write_b16 v170, v177 offset:7120
	ds_write_b16_d16_hi v170, v177 offset:7152
	v_cvt_pk_bf16_f32 v182, v56, v60
	v_cvt_pk_bf16_f32 v183, v64, v68
	ds_write_b16 v170, v182 offset:7200
	ds_write_b16_d16_hi v170, v182 offset:7232
	ds_write_b16 v170, v183 offset:7264
	ds_write_b16_d16_hi v170, v183 offset:7296
	v_cvt_pk_bf16_f32 v188, v57, v61
	v_cvt_pk_bf16_f32 v189, v65, v69
	ds_write_b16 v170, v188 offset:7344
	ds_write_b16_d16_hi v170, v188 offset:7376
	ds_write_b16 v170, v189 offset:7408
	ds_write_b16_d16_hi v170, v189 offset:7440
	ds_read_b128 v[130:133], v171 offset:0
	ds_read_b128 v[134:137], v171 offset:1152
	ds_read_b128 v[138:141], v171 offset:2304
	ds_read_b128 v[142:145], v171 offset:3456
	ds_read_b128 v[146:149], v171 offset:4608
	ds_read_b128 v[150:153], v171 offset:5760
	ds_read_b128 v[154:157], v171 offset:6912
	ds_read_b128 v[158:161], v171 offset:8064
	s_waitcnt lgkmcnt(7)
	global_store_dwordx4 v172, v[130:133], s[44:45] offset:0 sc1
	s_waitcnt lgkmcnt(6)
	global_store_dwordx4 v172, v[134:137], s[44:45] offset:1024 sc1
	s_waitcnt lgkmcnt(5)
	global_store_dwordx4 v172, v[138:141], s[44:45] offset:2048 sc1
	s_waitcnt lgkmcnt(4)
	global_store_dwordx4 v172, v[142:145], s[44:45] offset:3072 sc1
	s_waitcnt lgkmcnt(3)
	global_store_dwordx4 v172, v[146:149], s[62:63] offset:0 sc1
	s_waitcnt lgkmcnt(2)
	global_store_dwordx4 v172, v[150:153], s[62:63] offset:1024 sc1
	s_waitcnt lgkmcnt(1)
	global_store_dwordx4 v172, v[154:157], s[62:63] offset:2048 sc1
	s_waitcnt lgkmcnt(0)
; template <int EPI>
; DI void gemm_phase(const P& p, int l, const u16* __restrict__ A, const u16* __restrict__ Bt, int mpx, char* lds) {
;     ...
;           const unsigned u01 = pack2(v0, v1), u23 = pack2(v2, v3);
;           if (kind == 1) {
;             Tl[(0 * 16 + r) * 72 + rowl] = (u16)u01;
;             Tl[(1 * 16 + r) * 72 + rowl] = (u16)(u01 >> 16);
;             Tl[(2 * 16 + r) * 72 + rowl] = (u16)u23;
;             Tl[(3 * 16 + r) * 72 + rowl] = (u16)(u23 >> 16);
;           } else if (tr == 2) {
;             Tl[rowl * 72 + 0 * 16 + r] = f2h(v0);
;             Tl[rowl * 72 + 1 * 16 + r] = f2h(v1);
;             Tl[rowl * 72 + 2 * 16 + r] = f2h(v2);
;             Tl[rowl * 72 + 3 * 16 + r] = f2h(v3);
;           } else {
;             Tl[rowl * 72 + 0 * 16 + r] = (u16)u01;
;             Tl[rowl * 72 + 1 * 16 + r] = (u16)(u01 >> 16);
;             Tl[rowl * 72 + 2 * 16 + r] = (u16)u23;
;             Tl[rowl * 72 + 3 * 16 + r] = (u16)(u23 >> 16);
;           }
;         }
;       }
;       __builtin_amdgcn_fence(__ATOMIC_RELEASE, "wavefront");
;       u16* dh = (kind == 1) ? dst + hf * 64 : dst + (size_t)(hf * 64) * rstride;
; #pragma unroll
;       for (int i = 0; i < 8; ++i) {
;         const int c = lane + i * 64;
;         const int row = c >> 3, cc = c & 7;
;         uint4 v = *(const uint4*)&Tl[row * 72 + cc * 8];
;         *(uint4*)(dh + (size_t)row * rstride + cc * 8) = v;
;       }
	global_store_dwordx4 v172, v[158:161], s[62:63] offset:3072 sc1
	s_add_u32 s44, s44, 0x2000
	s_addc_u32 s45, s45, 0
	s_add_u32 s62, s62, 0x2000
	s_addc_u32 s63, s63, 0
	v_cvt_pk_bf16_f32 v178, v70, v74
	v_cvt_pk_bf16_f32 v179, v78, v82
	ds_write_b16 v170, v178 offset:0
	ds_write_b16_d16_hi v170, v178 offset:32
	ds_write_b16 v170, v179 offset:64
	ds_write_b16_d16_hi v170, v179 offset:96
	v_cvt_pk_bf16_f32 v184, v71, v75
	v_cvt_pk_bf16_f32 v185, v79, v83
	ds_write_b16 v170, v184 offset:144
	ds_write_b16_d16_hi v170, v184 offset:176
	ds_write_b16 v170, v185 offset:208
	ds_write_b16_d16_hi v170, v185 offset:240
	v_cvt_pk_bf16_f32 v190, v72, v76
	v_cvt_pk_bf16_f32 v191, v80, v84
	ds_write_b16 v170, v190 offset:288
	ds_write_b16_d16_hi v170, v190 offset:320
	ds_write_b16 v170, v191 offset:352
	ds_write_b16_d16_hi v170, v191 offset:384
	v_cvt_pk_bf16_f32 v176, v73, v77
	v_cvt_pk_bf16_f32 v177, v81, v85
	ds_write_b16 v170, v176 offset:432
	ds_write_b16_d16_hi v170, v176 offset:464
	ds_write_b16 v170, v177 offset:496
	ds_write_b16_d16_hi v170, v177 offset:528
	v_cvt_pk_bf16_f32 v182, v86, v90
	v_cvt_pk_bf16_f32 v183, v94, v98
	ds_write_b16 v170, v182 offset:2304
	ds_write_b16_d16_hi v170, v182 offset:2336
	ds_write_b16 v170, v183 offset:2368
	ds_write_b16_d16_hi v170, v183 offset:2400
	v_cvt_pk_bf16_f32 v188, v87, v91
	v_cvt_pk_bf16_f32 v189, v95, v99
	ds_write_b16 v170, v188 offset:2448
	ds_write_b16_d16_hi v170, v188 offset:2480
	ds_write_b16 v170, v189 offset:2512
	ds_write_b16_d16_hi v170, v189 offset:2544
	v_cvt_pk_bf16_f32 v174, v88, v92
	v_cvt_pk_bf16_f32 v175, v96, v100
	ds_write_b16 v170, v174 offset:2592
	ds_write_b16_d16_hi v170, v174 offset:2624
	ds_write_b16 v170, v175 offset:2656
	ds_write_b16_d16_hi v170, v175 offset:2688
	v_cvt_pk_bf16_f32 v180, v89, v93
	v_cvt_pk_bf16_f32 v181, v97, v101
	ds_write_b16 v170, v180 offset:2736
	ds_write_b16_d16_hi v170, v180 offset:2768
	ds_write_b16 v170, v181 offset:2800
	ds_write_b16_d16_hi v170, v181 offset:2832
	v_cvt_pk_bf16_f32 v186, v102, v106
	v_cvt_pk_bf16_f32 v187, v110, v114
	ds_write_b16 v170, v186 offset:4608
	ds_write_b16_d16_hi v170, v186 offset:4640
	ds_write_b16 v170, v187 offset:4672
	ds_write_b16_d16_hi v170, v187 offset:4704
	v_cvt_pk_bf16_f32 v192, v103, v107
	v_cvt_pk_bf16_f32 v193, v111, v115
	ds_write_b16 v170, v192 offset:4752
	ds_write_b16_d16_hi v170, v192 offset:4784
	ds_write_b16 v170, v193 offset:4816
	ds_write_b16_d16_hi v170, v193 offset:4848
	v_cvt_pk_bf16_f32 v178, v104, v108
	v_cvt_pk_bf16_f32 v179, v112, v116
	ds_write_b16 v170, v178 offset:4896
	ds_write_b16_d16_hi v170, v178 offset:4928
	ds_write_b16 v170, v179 offset:4960
	ds_write_b16_d16_hi v170, v179 offset:4992
	v_cvt_pk_bf16_f32 v184, v105, v109
	v_cvt_pk_bf16_f32 v185, v113, v117
	ds_write_b16 v170, v184 offset:5040
	ds_write_b16_d16_hi v170, v184 offset:5072
	ds_write_b16 v170, v185 offset:5104
	ds_write_b16_d16_hi v170, v185 offset:5136
	v_cvt_pk_bf16_f32 v190, v118, v122
	v_cvt_pk_bf16_f32 v191, v126, v2
	ds_write_b16 v170, v190 offset:6912
	ds_write_b16_d16_hi v170, v190 offset:6944
	ds_write_b16 v170, v191 offset:6976
	ds_write_b16_d16_hi v170, v191 offset:7008
	v_cvt_pk_bf16_f32 v176, v119, v123
	v_cvt_pk_bf16_f32 v177, v127, v3
	ds_write_b16 v170, v176 offset:7056
	ds_write_b16_d16_hi v170, v176 offset:7088
	ds_write_b16 v170, v177 offset:7120
	ds_write_b16_d16_hi v170, v177 offset:7152
	v_cvt_pk_bf16_f32 v182, v120, v124
	v_cvt_pk_bf16_f32 v183, v128, v4
	ds_write_b16 v170, v182 offset:7200
	ds_write_b16_d16_hi v170, v182 offset:7232
	ds_write_b16 v170, v183 offset:7264
	ds_write_b16_d16_hi v170, v183 offset:7296
	v_cvt_pk_bf16_f32 v188, v121, v125
	v_cvt_pk_bf16_f32 v189, v129, v5
	ds_write_b16 v170, v188 offset:7344
	ds_write_b16_d16_hi v170, v188 offset:7376
	ds_write_b16 v170, v189 offset:7408
	ds_write_b16_d16_hi v170, v189 offset:7440
	ds_read_b128 v[130:133], v171 offset:0
	ds_read_b128 v[134:137], v171 offset:1152
	ds_read_b128 v[138:141], v171 offset:2304
	ds_read_b128 v[142:145], v171 offset:3456
	ds_read_b128 v[146:149], v171 offset:4608
	ds_read_b128 v[150:153], v171 offset:5760
	ds_read_b128 v[154:157], v171 offset:6912
	ds_read_b128 v[158:161], v171 offset:8064
	s_waitcnt lgkmcnt(7)
	global_store_dwordx4 v172, v[130:133], s[44:45] offset:0 sc1
	s_waitcnt lgkmcnt(6)
	global_store_dwordx4 v172, v[134:137], s[44:45] offset:1024 sc1
	s_waitcnt lgkmcnt(5)
	global_store_dwordx4 v172, v[138:141], s[44:45] offset:2048 sc1
	s_waitcnt lgkmcnt(4)
	global_store_dwordx4 v172, v[142:145], s[44:45] offset:3072 sc1
	s_waitcnt lgkmcnt(3)
	global_store_dwordx4 v172, v[146:149], s[62:63] offset:0 sc1
	s_waitcnt lgkmcnt(2)
	global_store_dwordx4 v172, v[150:153], s[62:63] offset:1024 sc1
	s_waitcnt lgkmcnt(1)
	global_store_dwordx4 v172, v[154:157], s[62:63] offset:2048 sc1
	s_waitcnt lgkmcnt(0)
	global_store_dwordx4 v172, v[158:161], s[62:63] offset:3072 sc1
	s_branch .Lfe_done
; template <int EPI>
; DI void gemm_phase(const P& p, int l, const u16* __restrict__ A, const u16* __restrict__ Bt, int mpx, char* lds) {
;     ...
;           } else if (tr == 2) {
;             Tl[rowl * 72 + 0 * 16 + r] = f2h(v0);
;             Tl[rowl * 72 + 1 * 16 + r] = f2h(v1);
;             Tl[rowl * 72 + 2 * 16 + r] = f2h(v2);
;             Tl[rowl * 72 + 3 * 16 + r] = f2h(v3);
;           } else {
;             Tl[rowl * 72 + 0 * 16 + r] = (u16)u01;
;             Tl[rowl * 72 + 1 * 16 + r] = (u16)(u01 >> 16);
;             Tl[rowl * 72 + 2 * 16 + r] = (u16)u23;
;             Tl[rowl * 72 + 3 * 16 + r] = (u16)(u23 >> 16);
;           }
;         }
;       }
;       __builtin_amdgcn_fence(__ATOMIC_RELEASE, "wavefront");
;       u16* dh = (kind == 1) ? dst + hf * 64 : dst + (size_t)(hf * 64) * rstride;
; #pragma unroll
;       for (int i = 0; i < 8; ++i) {
;         const int c = lane + i * 64;
;         const int row = c >> 3, cc = c & 7;
;         uint4 v = *(const uint4*)&Tl[row * 72 + cc * 8];
;         *(uint4*)(dh + (size_t)row * rstride + cc * 8) = v;
;       }
.Lfe_k0_fp16:
	s_add_u32 s62, s44, 0x1000
	s_addc_u32 s63, s45, 0
	v_cvt_f16_f32_e32 v174, v6
	v_cvt_f16_f32_e32 v175, v10
	v_cvt_f16_f32_e32 v176, v14
	v_cvt_f16_f32_e32 v177, v18
	ds_write_b16 v170, v174 offset:0
	ds_write_b16 v170, v175 offset:32
	ds_write_b16 v170, v176 offset:64
	ds_write_b16 v170, v177 offset:96
	v_cvt_f16_f32_e32 v180, v7
	v_cvt_f16_f32_e32 v181, v11
	v_cvt_f16_f32_e32 v182, v15
	v_cvt_f16_f32_e32 v183, v19
	ds_write_b16 v170, v180 offset:144
	ds_write_b16 v170, v181 offset:176
	ds_write_b16 v170, v182 offset:208
	ds_write_b16 v170, v183 offset:240
	v_cvt_f16_f32_e32 v186, v8
	v_cvt_f16_f32_e32 v187, v12
	v_cvt_f16_f32_e32 v188, v16
	v_cvt_f16_f32_e32 v189, v20
	ds_write_b16 v170, v186 offset:288
	ds_write_b16 v170, v187 offset:320
	ds_write_b16 v170, v188 offset:352
	ds_write_b16 v170, v189 offset:384
	v_cvt_f16_f32_e32 v192, v9
	v_cvt_f16_f32_e32 v193, v13
	v_cvt_f16_f32_e32 v174, v17
	v_cvt_f16_f32_e32 v175, v21
	ds_write_b16 v170, v192 offset:432
	ds_write_b16 v170, v193 offset:464
	ds_write_b16 v170, v174 offset:496
	ds_write_b16 v170, v175 offset:528
	v_cvt_f16_f32_e32 v178, v22
	v_cvt_f16_f32_e32 v179, v26
	v_cvt_f16_f32_e32 v180, v30
	v_cvt_f16_f32_e32 v181, v34
	ds_write_b16 v170, v178 offset:2304
	ds_write_b16 v170, v179 offset:2336
	ds_write_b16 v170, v180 offset:2368
	ds_write_b16 v170, v181 offset:2400
	v_cvt_f16_f32_e32 v184, v23
	v_cvt_f16_f32_e32 v185, v27
	v_cvt_f16_f32_e32 v186, v31
	v_cvt_f16_f32_e32 v187, v35
	ds_write_b16 v170, v184 offset:2448
	ds_write_b16 v170, v185 offset:2480
	ds_write_b16 v170, v186 offset:2512
	ds_write_b16 v170, v187 offset:2544
	v_cvt_f16_f32_e32 v190, v24
	v_cvt_f16_f32_e32 v191, v28
	v_cvt_f16_f32_e32 v192, v32
	v_cvt_f16_f32_e32 v193, v36
	ds_write_b16 v170, v190 offset:2592
	ds_write_b16 v170, v191 offset:2624
	ds_write_b16 v170, v192 offset:2656
	ds_write_b16 v170, v193 offset:2688
	v_cvt_f16_f32_e32 v176, v25
	v_cvt_f16_f32_e32 v177, v29
	v_cvt_f16_f32_e32 v178, v33
	v_cvt_f16_f32_e32 v179, v37
	ds_write_b16 v170, v176 offset:2736
	ds_write_b16 v170, v177 offset:2768
	ds_write_b16 v170, v178 offset:2800
	ds_write_b16 v170, v179 offset:2832
	v_cvt_f16_f32_e32 v182, v38
	v_cvt_f16_f32_e32 v183, v42
	v_cvt_f16_f32_e32 v184, v46
	v_cvt_f16_f32_e32 v185, v50
	ds_write_b16 v170, v182 offset:4608
	ds_write_b16 v170, v183 offset:4640
	ds_write_b16 v170, v184 offset:4672
	ds_write_b16 v170, v185 offset:4704
	v_cvt_f16_f32_e32 v188, v39
	v_cvt_f16_f32_e32 v189, v43
	v_cvt_f16_f32_e32 v190, v47
	v_cvt_f16_f32_e32 v191, v51
	ds_write_b16 v170, v188 offset:4752
	ds_write_b16 v170, v189 offset:4784
	ds_write_b16 v170, v190 offset:4816
	ds_write_b16 v170, v191 offset:4848
	v_cvt_f16_f32_e32 v174, v40
	v_cvt_f16_f32_e32 v175, v44
	v_cvt_f16_f32_e32 v176, v48
	v_cvt_f16_f32_e32 v177, v52
	ds_write_b16 v170, v174 offset:4896
	ds_write_b16 v170, v175 offset:4928
	ds_write_b16 v170, v176 offset:4960
	ds_write_b16 v170, v177 offset:4992
	v_cvt_f16_f32_e32 v180, v41
	v_cvt_f16_f32_e32 v181, v45
	v_cvt_f16_f32_e32 v182, v49
	v_cvt_f16_f32_e32 v183, v53
	ds_write_b16 v170, v180 offset:5040
	ds_write_b16 v170, v181 offset:5072
	ds_write_b16 v170, v182 offset:5104
	ds_write_b16 v170, v183 offset:5136
	v_cvt_f16_f32_e32 v186, v54
	v_cvt_f16_f32_e32 v187, v58
	v_cvt_f16_f32_e32 v188, v62
	v_cvt_f16_f32_e32 v189, v66
	ds_write_b16 v170, v186 offset:6912
	ds_write_b16 v170, v187 offset:6944
	ds_write_b16 v170, v188 offset:6976
	ds_write_b16 v170, v189 offset:7008
	v_cvt_f16_f32_e32 v192, v55
	v_cvt_f16_f32_e32 v193, v59
	v_cvt_f16_f32_e32 v174, v63
	v_cvt_f16_f32_e32 v175, v67
	ds_write_b16 v170, v192 offset:7056
	ds_write_b16 v170, v193 offset:7088
	ds_write_b16 v170, v174 offset:7120
	ds_write_b16 v170, v175 offset:7152
	v_cvt_f16_f32_e32 v178, v56
	v_cvt_f16_f32_e32 v179, v60
	v_cvt_f16_f32_e32 v180, v64
	v_cvt_f16_f32_e32 v181, v68
	ds_write_b16 v170, v178 offset:7200
	ds_write_b16 v170, v179 offset:7232
	ds_write_b16 v170, v180 offset:7264
	ds_write_b16 v170, v181 offset:7296
	v_cvt_f16_f32_e32 v184, v57
	v_cvt_f16_f32_e32 v185, v61
	v_cvt_f16_f32_e32 v186, v65
	v_cvt_f16_f32_e32 v187, v69
	ds_write_b16 v170, v184 offset:7344
	ds_write_b16 v170, v185 offset:7376
	ds_write_b16 v170, v186 offset:7408
	ds_write_b16 v170, v187 offset:7440
	ds_read_b128 v[130:133], v171 offset:0
	ds_read_b128 v[134:137], v171 offset:1152
	ds_read_b128 v[138:141], v171 offset:2304
	ds_read_b128 v[142:145], v171 offset:3456
	ds_read_b128 v[146:149], v171 offset:4608
	ds_read_b128 v[150:153], v171 offset:5760
	ds_read_b128 v[154:157], v171 offset:6912
	ds_read_b128 v[158:161], v171 offset:8064
	s_waitcnt lgkmcnt(7)
	global_store_dwordx4 v172, v[130:133], s[44:45] offset:0 sc1
	s_waitcnt lgkmcnt(6)
	global_store_dwordx4 v172, v[134:137], s[44:45] offset:1024 sc1
	s_waitcnt lgkmcnt(5)
	global_store_dwordx4 v172, v[138:141], s[44:45] offset:2048 sc1
	s_waitcnt lgkmcnt(4)
	global_store_dwordx4 v172, v[142:145], s[44:45] offset:3072 sc1
	s_waitcnt lgkmcnt(3)
	global_store_dwordx4 v172, v[146:149], s[62:63] offset:0 sc1
	s_waitcnt lgkmcnt(2)
	global_store_dwordx4 v172, v[150:153], s[62:63] offset:1024 sc1
	s_waitcnt lgkmcnt(1)
	global_store_dwordx4 v172, v[154:157], s[62:63] offset:2048 sc1
	s_waitcnt lgkmcnt(0)
; template <int EPI>
; DI void gemm_phase(const P& p, int l, const u16* __restrict__ A, const u16* __restrict__ Bt, int mpx, char* lds) {
;     ...
;           } else if (tr == 2) {
;             Tl[rowl * 72 + 0 * 16 + r] = f2h(v0);
;             Tl[rowl * 72 + 1 * 16 + r] = f2h(v1);
;             Tl[rowl * 72 + 2 * 16 + r] = f2h(v2);
;             Tl[rowl * 72 + 3 * 16 + r] = f2h(v3);
;           } else {
;             Tl[rowl * 72 + 0 * 16 + r] = (u16)u01;
;             Tl[rowl * 72 + 1 * 16 + r] = (u16)(u01 >> 16);
;             Tl[rowl * 72 + 2 * 16 + r] = (u16)u23;
;             Tl[rowl * 72 + 3 * 16 + r] = (u16)(u23 >> 16);
;           }
;         }
;       }
;       __builtin_amdgcn_fence(__ATOMIC_RELEASE, "wavefront");
;       u16* dh = (kind == 1) ? dst + hf * 64 : dst + (size_t)(hf * 64) * rstride;
; #pragma unroll
;       for (int i = 0; i < 8; ++i) {
;         const int c = lane + i * 64;
;         const int row = c >> 3, cc = c & 7;
;         uint4 v = *(const uint4*)&Tl[row * 72 + cc * 8];
;         *(uint4*)(dh + (size_t)row * rstride + cc * 8) = v;
;       }
	global_store_dwordx4 v172, v[158:161], s[62:63] offset:3072 sc1
	s_add_u32 s44, s44, 0x2000
	s_addc_u32 s45, s45, 0
	s_add_u32 s62, s62, 0x2000
	s_addc_u32 s63, s63, 0
	v_cvt_f16_f32_e32 v174, v70
	v_cvt_f16_f32_e32 v175, v74
	v_cvt_f16_f32_e32 v176, v78
	v_cvt_f16_f32_e32 v177, v82
	ds_write_b16 v170, v174 offset:0
	ds_write_b16 v170, v175 offset:32
	ds_write_b16 v170, v176 offset:64
	ds_write_b16 v170, v177 offset:96
	v_cvt_f16_f32_e32 v180, v71
	v_cvt_f16_f32_e32 v181, v75
	v_cvt_f16_f32_e32 v182, v79
	v_cvt_f16_f32_e32 v183, v83
	ds_write_b16 v170, v180 offset:144
	ds_write_b16 v170, v181 offset:176
	ds_write_b16 v170, v182 offset:208
	ds_write_b16 v170, v183 offset:240
	v_cvt_f16_f32_e32 v186, v72
	v_cvt_f16_f32_e32 v187, v76
	v_cvt_f16_f32_e32 v188, v80
	v_cvt_f16_f32_e32 v189, v84
	ds_write_b16 v170, v186 offset:288
	ds_write_b16 v170, v187 offset:320
	ds_write_b16 v170, v188 offset:352
	ds_write_b16 v170, v189 offset:384
	v_cvt_f16_f32_e32 v192, v73
	v_cvt_f16_f32_e32 v193, v77
	v_cvt_f16_f32_e32 v174, v81
	v_cvt_f16_f32_e32 v175, v85
	ds_write_b16 v170, v192 offset:432
	ds_write_b16 v170, v193 offset:464
	ds_write_b16 v170, v174 offset:496
	ds_write_b16 v170, v175 offset:528
	v_cvt_f16_f32_e32 v178, v86
	v_cvt_f16_f32_e32 v179, v90
	v_cvt_f16_f32_e32 v180, v94
	v_cvt_f16_f32_e32 v181, v98
	ds_write_b16 v170, v178 offset:2304
	ds_write_b16 v170, v179 offset:2336
	ds_write_b16 v170, v180 offset:2368
	ds_write_b16 v170, v181 offset:2400
	v_cvt_f16_f32_e32 v184, v87
	v_cvt_f16_f32_e32 v185, v91
	v_cvt_f16_f32_e32 v186, v95
	v_cvt_f16_f32_e32 v187, v99
	ds_write_b16 v170, v184 offset:2448
	ds_write_b16 v170, v185 offset:2480
	ds_write_b16 v170, v186 offset:2512
	ds_write_b16 v170, v187 offset:2544
	v_cvt_f16_f32_e32 v190, v88
	v_cvt_f16_f32_e32 v191, v92
	v_cvt_f16_f32_e32 v192, v96
	v_cvt_f16_f32_e32 v193, v100
	ds_write_b16 v170, v190 offset:2592
	ds_write_b16 v170, v191 offset:2624
	ds_write_b16 v170, v192 offset:2656
	ds_write_b16 v170, v193 offset:2688
	v_cvt_f16_f32_e32 v176, v89
	v_cvt_f16_f32_e32 v177, v93
	v_cvt_f16_f32_e32 v178, v97
	v_cvt_f16_f32_e32 v179, v101
	ds_write_b16 v170, v176 offset:2736
	ds_write_b16 v170, v177 offset:2768
	ds_write_b16 v170, v178 offset:2800
	ds_write_b16 v170, v179 offset:2832
	v_cvt_f16_f32_e32 v182, v102
	v_cvt_f16_f32_e32 v183, v106
	v_cvt_f16_f32_e32 v184, v110
	v_cvt_f16_f32_e32 v185, v114
	ds_write_b16 v170, v182 offset:4608
	ds_write_b16 v170, v183 offset:4640
	ds_write_b16 v170, v184 offset:4672
	ds_write_b16 v170, v185 offset:4704
	v_cvt_f16_f32_e32 v188, v103
	v_cvt_f16_f32_e32 v189, v107
	v_cvt_f16_f32_e32 v190, v111
	v_cvt_f16_f32_e32 v191, v115
	ds_write_b16 v170, v188 offset:4752
	ds_write_b16 v170, v189 offset:4784
	ds_write_b16 v170, v190 offset:4816
	ds_write_b16 v170, v191 offset:4848
	v_cvt_f16_f32_e32 v174, v104
	v_cvt_f16_f32_e32 v175, v108
	v_cvt_f16_f32_e32 v176, v112
	v_cvt_f16_f32_e32 v177, v116
	ds_write_b16 v170, v174 offset:4896
	ds_write_b16 v170, v175 offset:4928
	ds_write_b16 v170, v176 offset:4960
	ds_write_b16 v170, v177 offset:4992
	v_cvt_f16_f32_e32 v180, v105
	v_cvt_f16_f32_e32 v181, v109
	v_cvt_f16_f32_e32 v182, v113
	v_cvt_f16_f32_e32 v183, v117
	ds_write_b16 v170, v180 offset:5040
	ds_write_b16 v170, v181 offset:5072
	ds_write_b16 v170, v182 offset:5104
	ds_write_b16 v170, v183 offset:5136
	v_cvt_f16_f32_e32 v186, v118
	v_cvt_f16_f32_e32 v187, v122
	v_cvt_f16_f32_e32 v188, v126
	v_cvt_f16_f32_e32 v189, v2
	ds_write_b16 v170, v186 offset:6912
	ds_write_b16 v170, v187 offset:6944
	ds_write_b16 v170, v188 offset:6976
	ds_write_b16 v170, v189 offset:7008
	v_cvt_f16_f32_e32 v192, v119
	v_cvt_f16_f32_e32 v193, v123
	v_cvt_f16_f32_e32 v174, v127
	v_cvt_f16_f32_e32 v175, v3
	ds_write_b16 v170, v192 offset:7056
	ds_write_b16 v170, v193 offset:7088
	ds_write_b16 v170, v174 offset:7120
	ds_write_b16 v170, v175 offset:7152
	v_cvt_f16_f32_e32 v178, v120
	v_cvt_f16_f32_e32 v179, v124
	v_cvt_f16_f32_e32 v180, v128
	v_cvt_f16_f32_e32 v181, v4
	ds_write_b16 v170, v178 offset:7200
	ds_write_b16 v170, v179 offset:7232
	ds_write_b16 v170, v180 offset:7264
	ds_write_b16 v170, v181 offset:7296
	v_cvt_f16_f32_e32 v184, v121
	v_cvt_f16_f32_e32 v185, v125
	v_cvt_f16_f32_e32 v186, v129
	v_cvt_f16_f32_e32 v187, v5
	ds_write_b16 v170, v184 offset:7344
	ds_write_b16 v170, v185 offset:7376
	ds_write_b16 v170, v186 offset:7408
	ds_write_b16 v170, v187 offset:7440
	ds_read_b128 v[130:133], v171 offset:0
	ds_read_b128 v[134:137], v171 offset:1152
	ds_read_b128 v[138:141], v171 offset:2304
	ds_read_b128 v[142:145], v171 offset:3456
	ds_read_b128 v[146:149], v171 offset:4608
	ds_read_b128 v[150:153], v171 offset:5760
	ds_read_b128 v[154:157], v171 offset:6912
	ds_read_b128 v[158:161], v171 offset:8064
	s_waitcnt lgkmcnt(7)
	global_store_dwordx4 v172, v[130:133], s[44:45] offset:0 sc1
	s_waitcnt lgkmcnt(6)
	global_store_dwordx4 v172, v[134:137], s[44:45] offset:1024 sc1
	s_waitcnt lgkmcnt(5)
	global_store_dwordx4 v172, v[138:141], s[44:45] offset:2048 sc1
	s_waitcnt lgkmcnt(4)
	global_store_dwordx4 v172, v[142:145], s[44:45] offset:3072 sc1
	s_waitcnt lgkmcnt(3)
	global_store_dwordx4 v172, v[146:149], s[62:63] offset:0 sc1
	s_waitcnt lgkmcnt(2)
	global_store_dwordx4 v172, v[150:153], s[62:63] offset:1024 sc1
	s_waitcnt lgkmcnt(1)
	global_store_dwordx4 v172, v[154:157], s[62:63] offset:2048 sc1
	s_waitcnt lgkmcnt(0)
	global_store_dwordx4 v172, v[158:161], s[62:63] offset:3072 sc1
	s_branch .Lfe_done
; DI void sincos_rev(float ang, float& s, float& c) {
;   float rev = ang * 0.15915494309189535f;
;   rev -= rintf(rev);
;   s = __builtin_amdgcn_sinf(rev);
;   c = __builtin_amdgcn_cosf(rev);
; }
; template <int EPI>
; DI void gemm_phase(const P& p, int l, const u16* __restrict__ A, const u16* __restrict__ Bt, int mpx, char* lds) {
;     ...
;             if (dorope) {
;               float sr, cr, sc, cc;
;               sincos_rev((float)(s >> 6) * invf64, sr, cr);
;               sincos_rev((float)(s & 63) * invf64, sc, cc);
;               const float a1 = v0, a2 = v1, b1 = v2, b2 = v3;
;               v0 = a1 * cr - a2 * sr;
;               v1 = a2 * cr + a1 * sr;
;               v2 = b1 * cc - b2 * sc;
;               v3 = b2 * cc + b1 * sc;
;             }
.Lfe_k0_rope64:
	v_and_b32_e32 v0, 15, v226
	v_cvt_f32_ubyte0_e32 v0, v0
	v_mul_f32_e32 v0, 0xc1549a78, v0
	v_mul_f32_e32 v0, 0x3d800000, v0
	v_exp_f32_e32 v174, v0
	v_lshrrev_b32_e32 v0, 4, v226
	v_lshlrev_b32_e32 v0, 2, v0
	v_add_u32_e32 v182, 0, v0
	v_cvt_f32_i32_e32 v182, v182
	v_mul_f32_e32 v182, v174, v182
	v_mul_f32_e32 v183, 0.15915494, v182
	v_rndne_f32_e32 v183, v183
	v_fma_f32 v183, v182, 0.15915494, -v183
	v_sin_f32_e32 v212, v183
	v_cos_f32_e32 v238, v183
	v_add_u32_e32 v182, 1, v0
	v_cvt_f32_i32_e32 v182, v182
	v_mul_f32_e32 v182, v174, v182
	v_mul_f32_e32 v183, 0.15915494, v182
	v_rndne_f32_e32 v183, v183
	v_fma_f32 v183, v182, 0.15915494, -v183
	v_sin_f32_e32 v213, v183
	v_cos_f32_e32 v239, v183
	v_add_u32_e32 v182, 2, v0
	v_cvt_f32_i32_e32 v182, v182
	v_mul_f32_e32 v182, v174, v182
	v_mul_f32_e32 v183, 0.15915494, v182
	v_rndne_f32_e32 v183, v183
	v_fma_f32 v183, v182, 0.15915494, -v183
	v_sin_f32_e32 v214, v183
	v_cos_f32_e32 v240, v183
	v_add_u32_e32 v182, 3, v0
	v_cvt_f32_i32_e32 v182, v182
	v_mul_f32_e32 v182, v174, v182
	v_mul_f32_e32 v183, 0.15915494, v182
	v_rndne_f32_e32 v183, v183
	v_fma_f32 v183, v182, 0.15915494, -v183
	v_sin_f32_e32 v215, v183
	v_cos_f32_e32 v241, v183
	v_add_u32_e32 v182, 16, v0
	v_cvt_f32_i32_e32 v182, v182
	v_mul_f32_e32 v182, v174, v182
	v_mul_f32_e32 v183, 0.15915494, v182
	v_rndne_f32_e32 v183, v183
	v_fma_f32 v183, v182, 0.15915494, -v183
	v_sin_f32_e32 v216, v183
	v_cos_f32_e32 v242, v183
	v_add_u32_e32 v182, 17, v0
	v_cvt_f32_i32_e32 v182, v182
	v_mul_f32_e32 v182, v174, v182
	v_mul_f32_e32 v183, 0.15915494, v182
	v_rndne_f32_e32 v183, v183
	v_fma_f32 v183, v182, 0.15915494, -v183
	v_sin_f32_e32 v217, v183
	v_cos_f32_e32 v243, v183
	v_add_u32_e32 v182, 18, v0
	v_cvt_f32_i32_e32 v182, v182
	v_mul_f32_e32 v182, v174, v182
	v_mul_f32_e32 v183, 0.15915494, v182
	v_rndne_f32_e32 v183, v183
	v_fma_f32 v183, v182, 0.15915494, -v183
	v_sin_f32_e32 v218, v183
	v_cos_f32_e32 v244, v183
	v_add_u32_e32 v182, 19, v0
	v_cvt_f32_i32_e32 v182, v182
	v_mul_f32_e32 v182, v174, v182
	v_mul_f32_e32 v183, 0.15915494, v182
	v_rndne_f32_e32 v183, v183
	v_fma_f32 v183, v182, 0.15915494, -v183
	v_sin_f32_e32 v219, v183
	v_cos_f32_e32 v245, v183
	v_add_u32_e32 v182, 32, v0
	v_cvt_f32_i32_e32 v182, v182
	v_mul_f32_e32 v182, v174, v182
	v_mul_f32_e32 v183, 0.15915494, v182
	v_rndne_f32_e32 v183, v183
	v_fma_f32 v183, v182, 0.15915494, -v183
	v_sin_f32_e32 v220, v183
	v_cos_f32_e32 v246, v183
	v_add_u32_e32 v182, 33, v0
	v_cvt_f32_i32_e32 v182, v182
	v_mul_f32_e32 v182, v174, v182
	v_mul_f32_e32 v183, 0.15915494, v182
	v_rndne_f32_e32 v183, v183
	v_fma_f32 v183, v182, 0.15915494, -v183
	v_sin_f32_e32 v221, v183
	v_cos_f32_e32 v247, v183
	v_add_u32_e32 v182, 34, v0
	v_cvt_f32_i32_e32 v182, v182
	v_mul_f32_e32 v182, v174, v182
	v_mul_f32_e32 v183, 0.15915494, v182
	v_rndne_f32_e32 v183, v183
	v_fma_f32 v183, v182, 0.15915494, -v183
	v_sin_f32_e32 v222, v183
	v_cos_f32_e32 v248, v183
	v_add_u32_e32 v182, 35, v0
	v_cvt_f32_i32_e32 v182, v182
	v_mul_f32_e32 v182, v174, v182
	v_mul_f32_e32 v183, 0.15915494, v182
	v_rndne_f32_e32 v183, v183
	v_fma_f32 v183, v182, 0.15915494, -v183
	v_sin_f32_e32 v223, v183
	v_cos_f32_e32 v249, v183
	v_add_u32_e32 v182, 48, v0
	v_cvt_f32_i32_e32 v182, v182
	v_mul_f32_e32 v182, v174, v182
	v_mul_f32_e32 v183, 0.15915494, v182
	v_rndne_f32_e32 v183, v183
	v_fma_f32 v183, v182, 0.15915494, -v183
	v_sin_f32_e32 v234, v183
	v_cos_f32_e32 v250, v183
	v_add_u32_e32 v182, 49, v0
	v_cvt_f32_i32_e32 v182, v182
	v_mul_f32_e32 v182, v174, v182
	v_mul_f32_e32 v183, 0.15915494, v182
	v_rndne_f32_e32 v183, v183
	v_fma_f32 v183, v182, 0.15915494, -v183
	v_sin_f32_e32 v235, v183
	v_cos_f32_e32 v251, v183
	v_add_u32_e32 v182, 50, v0
	v_cvt_f32_i32_e32 v182, v182
	v_mul_f32_e32 v182, v174, v182
	v_mul_f32_e32 v183, 0.15915494, v182
	v_rndne_f32_e32 v183, v183
	v_fma_f32 v183, v182, 0.15915494, -v183
	v_sin_f32_e32 v236, v183
	v_cos_f32_e32 v252, v183
	v_add_u32_e32 v182, 51, v0
	v_cvt_f32_i32_e32 v182, v182
	v_mul_f32_e32 v182, v174, v182
	v_mul_f32_e32 v183, 0.15915494, v182
	v_rndne_f32_e32 v183, v183
	v_fma_f32 v183, v182, 0.15915494, -v183
	v_sin_f32_e32 v237, v183
	v_cos_f32_e32 v253, v183
	s_add_u32 s62, s44, 0x1000
	s_addc_u32 s63, s45, 0
	s_lshr_b32 s70, s69, 6
	v_cvt_f32_i32_e32 v182, s70
	v_mul_f32_e32 v182, v174, v182
	v_mul_f32_e32 v183, 0.15915494, v182
	v_rndne_f32_e32 v183, v183
	v_fma_f32 v183, v182, 0.15915494, -v183
	v_sin_f32_e32 v175, v183
	v_cos_f32_e32 v176, v183
	v_mul_f32_e32 v186, v175, v10
	v_mul_f32_e32 v187, v176, v10
	v_fma_f32 v188, v176, v6, -v186
	v_fma_f32 v189, v175, v6, v187
	v_mul_f32_e32 v186, v212, v18
	v_mul_f32_e32 v187, v238, v18
	v_fma_f32 v190, v238, v14, -v186
	v_fma_f32 v191, v212, v14, v187
	v_cvt_pk_bf16_f32 v192, v188, v189
	v_cvt_pk_bf16_f32 v193, v190, v191
	ds_write_b16 v170, v192 offset:0
	ds_write_b16_d16_hi v170, v192 offset:32
	ds_write_b16 v170, v193 offset:64
	ds_write_b16_d16_hi v170, v193 offset:96
	v_mul_f32_e32 v186, v175, v11
	v_mul_f32_e32 v187, v176, v11
	v_fma_f32 v188, v176, v7, -v186
	v_fma_f32 v189, v175, v7, v187
	v_mul_f32_e32 v186, v213, v19
	v_mul_f32_e32 v187, v239, v19
	v_fma_f32 v190, v239, v15, -v186
	v_fma_f32 v191, v213, v15, v187
	v_cvt_pk_bf16_f32 v192, v188, v189
	v_cvt_pk_bf16_f32 v193, v190, v191
	ds_write_b16 v170, v192 offset:144
	ds_write_b16_d16_hi v170, v192 offset:176
	ds_write_b16 v170, v193 offset:208
	ds_write_b16_d16_hi v170, v193 offset:240
	v_mul_f32_e32 v186, v175, v12
	v_mul_f32_e32 v187, v176, v12
	v_fma_f32 v188, v176, v8, -v186
	v_fma_f32 v189, v175, v8, v187
	v_mul_f32_e32 v186, v214, v20
; template <int EPI>
; DI void gemm_phase(const P& p, int l, const u16* __restrict__ A, const u16* __restrict__ Bt, int mpx, char* lds) {
;     ...
;             if (dorope) {
;               float sr, cr, sc, cc;
;               sincos_rev((float)(s >> 6) * invf64, sr, cr);
;               sincos_rev((float)(s & 63) * invf64, sc, cc);
;               const float a1 = v0, a2 = v1, b1 = v2, b2 = v3;
;               v0 = a1 * cr - a2 * sr;
;               v1 = a2 * cr + a1 * sr;
;               v2 = b1 * cc - b2 * sc;
;               v3 = b2 * cc + b1 * sc;
;             }
;     ...
;             Tl[rowl * 72 + 0 * 16 + r] = (u16)u01;
;             Tl[rowl * 72 + 1 * 16 + r] = (u16)(u01 >> 16);
;             Tl[rowl * 72 + 2 * 16 + r] = (u16)u23;
;             Tl[rowl * 72 + 3 * 16 + r] = (u16)(u23 >> 16);
	v_mul_f32_e32 v187, v240, v20
	v_fma_f32 v190, v240, v16, -v186
	v_fma_f32 v191, v214, v16, v187
	v_cvt_pk_bf16_f32 v192, v188, v189
	v_cvt_pk_bf16_f32 v193, v190, v191
	ds_write_b16 v170, v192 offset:288
	ds_write_b16_d16_hi v170, v192 offset:320
	ds_write_b16 v170, v193 offset:352
	ds_write_b16_d16_hi v170, v193 offset:384
	v_mul_f32_e32 v186, v175, v13
	v_mul_f32_e32 v187, v176, v13
	v_fma_f32 v188, v176, v9, -v186
	v_fma_f32 v189, v175, v9, v187
	v_mul_f32_e32 v186, v215, v21
	v_mul_f32_e32 v187, v241, v21
	v_fma_f32 v190, v241, v17, -v186
	v_fma_f32 v191, v215, v17, v187
	v_cvt_pk_bf16_f32 v192, v188, v189
	v_cvt_pk_bf16_f32 v193, v190, v191
	ds_write_b16 v170, v192 offset:432
	ds_write_b16_d16_hi v170, v192 offset:464
	ds_write_b16 v170, v193 offset:496
	ds_write_b16_d16_hi v170, v193 offset:528
	v_mul_f32_e32 v186, v175, v26
	v_mul_f32_e32 v187, v176, v26
	v_fma_f32 v188, v176, v22, -v186
	v_fma_f32 v189, v175, v22, v187
	v_mul_f32_e32 v186, v216, v34
	v_mul_f32_e32 v187, v242, v34
	v_fma_f32 v190, v242, v30, -v186
	v_fma_f32 v191, v216, v30, v187
	v_cvt_pk_bf16_f32 v192, v188, v189
	v_cvt_pk_bf16_f32 v193, v190, v191
	ds_write_b16 v170, v192 offset:2304
	ds_write_b16_d16_hi v170, v192 offset:2336
	ds_write_b16 v170, v193 offset:2368
	ds_write_b16_d16_hi v170, v193 offset:2400
	v_mul_f32_e32 v186, v175, v27
	v_mul_f32_e32 v187, v176, v27
	v_fma_f32 v188, v176, v23, -v186
	v_fma_f32 v189, v175, v23, v187
	v_mul_f32_e32 v186, v217, v35
	v_mul_f32_e32 v187, v243, v35
	v_fma_f32 v190, v243, v31, -v186
	v_fma_f32 v191, v217, v31, v187
	v_cvt_pk_bf16_f32 v192, v188, v189
	v_cvt_pk_bf16_f32 v193, v190, v191
	ds_write_b16 v170, v192 offset:2448
	ds_write_b16_d16_hi v170, v192 offset:2480
	ds_write_b16 v170, v193 offset:2512
	ds_write_b16_d16_hi v170, v193 offset:2544
	v_mul_f32_e32 v186, v175, v28
	v_mul_f32_e32 v187, v176, v28
	v_fma_f32 v188, v176, v24, -v186
	v_fma_f32 v189, v175, v24, v187
	v_mul_f32_e32 v186, v218, v36
	v_mul_f32_e32 v187, v244, v36
	v_fma_f32 v190, v244, v32, -v186
	v_fma_f32 v191, v218, v32, v187
	v_cvt_pk_bf16_f32 v192, v188, v189
	v_cvt_pk_bf16_f32 v193, v190, v191
	ds_write_b16 v170, v192 offset:2592
	ds_write_b16_d16_hi v170, v192 offset:2624
	ds_write_b16 v170, v193 offset:2656
	ds_write_b16_d16_hi v170, v193 offset:2688
	v_mul_f32_e32 v186, v175, v29
	v_mul_f32_e32 v187, v176, v29
	v_fma_f32 v188, v176, v25, -v186
	v_fma_f32 v189, v175, v25, v187
	v_mul_f32_e32 v186, v219, v37
	v_mul_f32_e32 v187, v245, v37
	v_fma_f32 v190, v245, v33, -v186
	v_fma_f32 v191, v219, v33, v187
	v_cvt_pk_bf16_f32 v192, v188, v189
	v_cvt_pk_bf16_f32 v193, v190, v191
	ds_write_b16 v170, v192 offset:2736
	ds_write_b16_d16_hi v170, v192 offset:2768
	ds_write_b16 v170, v193 offset:2800
	ds_write_b16_d16_hi v170, v193 offset:2832
	v_mul_f32_e32 v186, v175, v42
	v_mul_f32_e32 v187, v176, v42
	v_fma_f32 v188, v176, v38, -v186
	v_fma_f32 v189, v175, v38, v187
	v_mul_f32_e32 v186, v220, v50
	v_mul_f32_e32 v187, v246, v50
	v_fma_f32 v190, v246, v46, -v186
	v_fma_f32 v191, v220, v46, v187
	v_cvt_pk_bf16_f32 v192, v188, v189
	v_cvt_pk_bf16_f32 v193, v190, v191
	ds_write_b16 v170, v192 offset:4608
	ds_write_b16_d16_hi v170, v192 offset:4640
	ds_write_b16 v170, v193 offset:4672
	ds_write_b16_d16_hi v170, v193 offset:4704
	v_mul_f32_e32 v186, v175, v43
	v_mul_f32_e32 v187, v176, v43
	v_fma_f32 v188, v176, v39, -v186
	v_fma_f32 v189, v175, v39, v187
	v_mul_f32_e32 v186, v221, v51
	v_mul_f32_e32 v187, v247, v51
	v_fma_f32 v190, v247, v47, -v186
	v_fma_f32 v191, v221, v47, v187
	v_cvt_pk_bf16_f32 v192, v188, v189
	v_cvt_pk_bf16_f32 v193, v190, v191
	ds_write_b16 v170, v192 offset:4752
	ds_write_b16_d16_hi v170, v192 offset:4784
	ds_write_b16 v170, v193 offset:4816
	ds_write_b16_d16_hi v170, v193 offset:4848
	v_mul_f32_e32 v186, v175, v44
	v_mul_f32_e32 v187, v176, v44
	v_fma_f32 v188, v176, v40, -v186
	v_fma_f32 v189, v175, v40, v187
	v_mul_f32_e32 v186, v222, v52
	v_mul_f32_e32 v187, v248, v52
	v_fma_f32 v190, v248, v48, -v186
	v_fma_f32 v191, v222, v48, v187
	v_cvt_pk_bf16_f32 v192, v188, v189
	v_cvt_pk_bf16_f32 v193, v190, v191
	ds_write_b16 v170, v192 offset:4896
	ds_write_b16_d16_hi v170, v192 offset:4928
	ds_write_b16 v170, v193 offset:4960
	ds_write_b16_d16_hi v170, v193 offset:4992
	v_mul_f32_e32 v186, v175, v45
	v_mul_f32_e32 v187, v176, v45
	v_fma_f32 v188, v176, v41, -v186
	v_fma_f32 v189, v175, v41, v187
	v_mul_f32_e32 v186, v223, v53
	v_mul_f32_e32 v187, v249, v53
	v_fma_f32 v190, v249, v49, -v186
	v_fma_f32 v191, v223, v49, v187
	v_cvt_pk_bf16_f32 v192, v188, v189
	v_cvt_pk_bf16_f32 v193, v190, v191
	ds_write_b16 v170, v192 offset:5040
	ds_write_b16_d16_hi v170, v192 offset:5072
	ds_write_b16 v170, v193 offset:5104
	ds_write_b16_d16_hi v170, v193 offset:5136
	v_mul_f32_e32 v186, v175, v58
	v_mul_f32_e32 v187, v176, v58
	v_fma_f32 v188, v176, v54, -v186
	v_fma_f32 v189, v175, v54, v187
	v_mul_f32_e32 v186, v234, v66
	v_mul_f32_e32 v187, v250, v66
	v_fma_f32 v190, v250, v62, -v186
	v_fma_f32 v191, v234, v62, v187
	v_cvt_pk_bf16_f32 v192, v188, v189
	v_cvt_pk_bf16_f32 v193, v190, v191
	ds_write_b16 v170, v192 offset:6912
	ds_write_b16_d16_hi v170, v192 offset:6944
	ds_write_b16 v170, v193 offset:6976
	ds_write_b16_d16_hi v170, v193 offset:7008
	v_mul_f32_e32 v186, v175, v59
	v_mul_f32_e32 v187, v176, v59
	v_fma_f32 v188, v176, v55, -v186
	v_fma_f32 v189, v175, v55, v187
	v_mul_f32_e32 v186, v235, v67
	v_mul_f32_e32 v187, v251, v67
	v_fma_f32 v190, v251, v63, -v186
	v_fma_f32 v191, v235, v63, v187
	v_cvt_pk_bf16_f32 v192, v188, v189
	v_cvt_pk_bf16_f32 v193, v190, v191
	ds_write_b16 v170, v192 offset:7056
	ds_write_b16_d16_hi v170, v192 offset:7088
; template <int EPI>
; DI void gemm_phase(const P& p, int l, const u16* __restrict__ A, const u16* __restrict__ Bt, int mpx, char* lds) {
;     ...
;             if (dorope) {
;               float sr, cr, sc, cc;
;               sincos_rev((float)(s >> 6) * invf64, sr, cr);
;               sincos_rev((float)(s & 63) * invf64, sc, cc);
;               const float a1 = v0, a2 = v1, b1 = v2, b2 = v3;
;               v0 = a1 * cr - a2 * sr;
;               v1 = a2 * cr + a1 * sr;
;               v2 = b1 * cc - b2 * sc;
;               v3 = b2 * cc + b1 * sc;
;             }
;           } else if (tr == 4) {
;             float sr, cr, sc, cc;
;             sincos_rev((float)(s >> 6) * invf32, sr, cr);
;             sincos_rev((float)(s & 63) * invf32, sc, cc);
;             const float p0 = __shfl_xor(v0, 8), p1 = __shfl_xor(v1, 8), p2 = __shfl_xor(v2, 8), p3 = __shfl_xor(v3, 8);
;             v0 = lo8 ? (v0 * cr - p0 * sr) : (v0 * cr + p0 * sr);
;             v1 = lo8 ? (v1 * cc - p1 * sc) : (v1 * cc + p1 * sc);
;             v2 = lo8 ? (v2 * cr - p2 * sr) : (v2 * cr + p2 * sr);
;             v3 = lo8 ? (v3 * cc - p3 * sc) : (v3 * cc + p3 * sc);
;           }
;           const unsigned u01 = pack2(v0, v1), u23 = pack2(v2, v3);
;           if (kind == 1) {
;             Tl[(0 * 16 + r) * 72 + rowl] = (u16)u01;
;             Tl[(1 * 16 + r) * 72 + rowl] = (u16)(u01 >> 16);
;             Tl[(2 * 16 + r) * 72 + rowl] = (u16)u23;
;             Tl[(3 * 16 + r) * 72 + rowl] = (u16)(u23 >> 16);
;           } else if (tr == 2) {
;             Tl[rowl * 72 + 0 * 16 + r] = f2h(v0);
;             Tl[rowl * 72 + 1 * 16 + r] = f2h(v1);
;             Tl[rowl * 72 + 2 * 16 + r] = f2h(v2);
;             Tl[rowl * 72 + 3 * 16 + r] = f2h(v3);
;           } else {
;             Tl[rowl * 72 + 0 * 16 + r] = (u16)u01;
;             Tl[rowl * 72 + 1 * 16 + r] = (u16)(u01 >> 16);
;             Tl[rowl * 72 + 2 * 16 + r] = (u16)u23;
;             Tl[rowl * 72 + 3 * 16 + r] = (u16)(u23 >> 16);
;           }
;         }
;       }
;       __builtin_amdgcn_fence(__ATOMIC_RELEASE, "wavefront");
;       u16* dh = (kind == 1) ? dst + hf * 64 : dst + (size_t)(hf * 64) * rstride;
; #pragma unroll
;       for (int i = 0; i < 8; ++i) {
;         const int c = lane + i * 64;
;         const int row = c >> 3, cc = c & 7;
;         uint4 v = *(const uint4*)&Tl[row * 72 + cc * 8];
	ds_write_b16 v170, v193 offset:7120
	ds_write_b16_d16_hi v170, v193 offset:7152
	v_mul_f32_e32 v186, v175, v60
	v_mul_f32_e32 v187, v176, v60
	v_fma_f32 v188, v176, v56, -v186
	v_fma_f32 v189, v175, v56, v187
	v_mul_f32_e32 v186, v236, v68
	v_mul_f32_e32 v187, v252, v68
	v_fma_f32 v190, v252, v64, -v186
	v_fma_f32 v191, v236, v64, v187
	v_cvt_pk_bf16_f32 v192, v188, v189
	v_cvt_pk_bf16_f32 v193, v190, v191
	ds_write_b16 v170, v192 offset:7200
	ds_write_b16_d16_hi v170, v192 offset:7232
	ds_write_b16 v170, v193 offset:7264
	ds_write_b16_d16_hi v170, v193 offset:7296
	v_mul_f32_e32 v186, v175, v61
	v_mul_f32_e32 v187, v176, v61
	v_fma_f32 v188, v176, v57, -v186
	v_fma_f32 v189, v175, v57, v187
	v_mul_f32_e32 v186, v237, v69
	v_mul_f32_e32 v187, v253, v69
	v_fma_f32 v190, v253, v65, -v186
	v_fma_f32 v191, v237, v65, v187
	v_cvt_pk_bf16_f32 v192, v188, v189
	v_cvt_pk_bf16_f32 v193, v190, v191
	ds_write_b16 v170, v192 offset:7344
	ds_write_b16_d16_hi v170, v192 offset:7376
	ds_write_b16 v170, v193 offset:7408
	ds_write_b16_d16_hi v170, v193 offset:7440
	ds_read_b128 v[130:133], v171 offset:0
	ds_read_b128 v[134:137], v171 offset:1152
	ds_read_b128 v[138:141], v171 offset:2304
	ds_read_b128 v[142:145], v171 offset:3456
	ds_read_b128 v[146:149], v171 offset:4608
	ds_read_b128 v[150:153], v171 offset:5760
	ds_read_b128 v[154:157], v171 offset:6912
	ds_read_b128 v[158:161], v171 offset:8064
	s_waitcnt lgkmcnt(7)
	global_store_dwordx4 v172, v[130:133], s[44:45] offset:0 sc1
	s_waitcnt lgkmcnt(6)
	global_store_dwordx4 v172, v[134:137], s[44:45] offset:1024 sc1
	s_waitcnt lgkmcnt(5)
	global_store_dwordx4 v172, v[138:141], s[44:45] offset:2048 sc1
	s_waitcnt lgkmcnt(4)
	global_store_dwordx4 v172, v[142:145], s[44:45] offset:3072 sc1
	s_waitcnt lgkmcnt(3)
	global_store_dwordx4 v172, v[146:149], s[62:63] offset:0 sc1
	s_waitcnt lgkmcnt(2)
	global_store_dwordx4 v172, v[150:153], s[62:63] offset:1024 sc1
	s_waitcnt lgkmcnt(1)
	global_store_dwordx4 v172, v[154:157], s[62:63] offset:2048 sc1
	s_waitcnt lgkmcnt(0)
	global_store_dwordx4 v172, v[158:161], s[62:63] offset:3072 sc1
	s_add_u32 s44, s44, 0x2000
	s_addc_u32 s45, s45, 0
	s_add_u32 s62, s62, 0x2000
	s_addc_u32 s63, s63, 0
	s_lshr_b32 s70, s69, 6
	s_add_i32 s70, s70, 1
	v_cvt_f32_i32_e32 v182, s70
	v_mul_f32_e32 v182, v174, v182
	v_mul_f32_e32 v183, 0.15915494, v182
	v_rndne_f32_e32 v183, v183
	v_fma_f32 v183, v182, 0.15915494, -v183
	v_sin_f32_e32 v175, v183
	v_cos_f32_e32 v176, v183
	v_mul_f32_e32 v186, v175, v74
	v_mul_f32_e32 v187, v176, v74
	v_fma_f32 v188, v176, v70, -v186
	v_fma_f32 v189, v175, v70, v187
	v_mul_f32_e32 v186, v212, v82
	v_mul_f32_e32 v187, v238, v82
	v_fma_f32 v190, v238, v78, -v186
	v_fma_f32 v191, v212, v78, v187
	v_cvt_pk_bf16_f32 v192, v188, v189
	v_cvt_pk_bf16_f32 v193, v190, v191
	ds_write_b16 v170, v192 offset:0
	ds_write_b16_d16_hi v170, v192 offset:32
	ds_write_b16 v170, v193 offset:64
	ds_write_b16_d16_hi v170, v193 offset:96
	v_mul_f32_e32 v186, v175, v75
	v_mul_f32_e32 v187, v176, v75
	v_fma_f32 v188, v176, v71, -v186
	v_fma_f32 v189, v175, v71, v187
	v_mul_f32_e32 v186, v213, v83
	v_mul_f32_e32 v187, v239, v83
	v_fma_f32 v190, v239, v79, -v186
	v_fma_f32 v191, v213, v79, v187
	v_cvt_pk_bf16_f32 v192, v188, v189
	v_cvt_pk_bf16_f32 v193, v190, v191
	ds_write_b16 v170, v192 offset:144
	ds_write_b16_d16_hi v170, v192 offset:176
	ds_write_b16 v170, v193 offset:208
	ds_write_b16_d16_hi v170, v193 offset:240
	v_mul_f32_e32 v186, v175, v76
	v_mul_f32_e32 v187, v176, v76
	v_fma_f32 v188, v176, v72, -v186
	v_fma_f32 v189, v175, v72, v187
	v_mul_f32_e32 v186, v214, v84
	v_mul_f32_e32 v187, v240, v84
	v_fma_f32 v190, v240, v80, -v186
	v_fma_f32 v191, v214, v80, v187
	v_cvt_pk_bf16_f32 v192, v188, v189
	v_cvt_pk_bf16_f32 v193, v190, v191
	ds_write_b16 v170, v192 offset:288
	ds_write_b16_d16_hi v170, v192 offset:320
	ds_write_b16 v170, v193 offset:352
	ds_write_b16_d16_hi v170, v193 offset:384
	v_mul_f32_e32 v186, v175, v77
	v_mul_f32_e32 v187, v176, v77
	v_fma_f32 v188, v176, v73, -v186
	v_fma_f32 v189, v175, v73, v187
	v_mul_f32_e32 v186, v215, v85
	v_mul_f32_e32 v187, v241, v85
	v_fma_f32 v190, v241, v81, -v186
	v_fma_f32 v191, v215, v81, v187
	v_cvt_pk_bf16_f32 v192, v188, v189
	v_cvt_pk_bf16_f32 v193, v190, v191
	ds_write_b16 v170, v192 offset:432
	ds_write_b16_d16_hi v170, v192 offset:464
	ds_write_b16 v170, v193 offset:496
	ds_write_b16_d16_hi v170, v193 offset:528
	v_mul_f32_e32 v186, v175, v90
	v_mul_f32_e32 v187, v176, v90
	v_fma_f32 v188, v176, v86, -v186
	v_fma_f32 v189, v175, v86, v187
	v_mul_f32_e32 v186, v216, v98
	v_mul_f32_e32 v187, v242, v98
	v_fma_f32 v190, v242, v94, -v186
	v_fma_f32 v191, v216, v94, v187
	v_cvt_pk_bf16_f32 v192, v188, v189
	v_cvt_pk_bf16_f32 v193, v190, v191
	ds_write_b16 v170, v192 offset:2304
	ds_write_b16_d16_hi v170, v192 offset:2336
	ds_write_b16 v170, v193 offset:2368
	ds_write_b16_d16_hi v170, v193 offset:2400
	v_mul_f32_e32 v186, v175, v91
	v_mul_f32_e32 v187, v176, v91
	v_fma_f32 v188, v176, v87, -v186
	v_fma_f32 v189, v175, v87, v187
	v_mul_f32_e32 v186, v217, v99
	v_mul_f32_e32 v187, v243, v99
	v_fma_f32 v190, v243, v95, -v186
	v_fma_f32 v191, v217, v95, v187
	v_cvt_pk_bf16_f32 v192, v188, v189
	v_cvt_pk_bf16_f32 v193, v190, v191
	ds_write_b16 v170, v192 offset:2448
	ds_write_b16_d16_hi v170, v192 offset:2480
	ds_write_b16 v170, v193 offset:2512
	ds_write_b16_d16_hi v170, v193 offset:2544
	v_mul_f32_e32 v186, v175, v92
	v_mul_f32_e32 v187, v176, v92
	v_fma_f32 v188, v176, v88, -v186
	v_fma_f32 v189, v175, v88, v187
	v_mul_f32_e32 v186, v218, v100
	v_mul_f32_e32 v187, v244, v100
	v_fma_f32 v190, v244, v96, -v186
; template <int EPI>
; DI void gemm_phase(const P& p, int l, const u16* __restrict__ A, const u16* __restrict__ Bt, int mpx, char* lds) {
;     ...
;             if (dorope) {
;               float sr, cr, sc, cc;
;               sincos_rev((float)(s >> 6) * invf64, sr, cr);
;               sincos_rev((float)(s & 63) * invf64, sc, cc);
;               const float a1 = v0, a2 = v1, b1 = v2, b2 = v3;
;               v0 = a1 * cr - a2 * sr;
;               v1 = a2 * cr + a1 * sr;
;               v2 = b1 * cc - b2 * sc;
;               v3 = b2 * cc + b1 * sc;
;             }
;           } else if (tr == 4) {
;             float sr, cr, sc, cc;
;             sincos_rev((float)(s >> 6) * invf32, sr, cr);
;             sincos_rev((float)(s & 63) * invf32, sc, cc);
;             const float p0 = __shfl_xor(v0, 8), p1 = __shfl_xor(v1, 8), p2 = __shfl_xor(v2, 8), p3 = __shfl_xor(v3, 8);
;             v0 = lo8 ? (v0 * cr - p0 * sr) : (v0 * cr + p0 * sr);
;             v1 = lo8 ? (v1 * cc - p1 * sc) : (v1 * cc + p1 * sc);
;             v2 = lo8 ? (v2 * cr - p2 * sr) : (v2 * cr + p2 * sr);
;             v3 = lo8 ? (v3 * cc - p3 * sc) : (v3 * cc + p3 * sc);
;           }
;           const unsigned u01 = pack2(v0, v1), u23 = pack2(v2, v3);
;           if (kind == 1) {
;             Tl[(0 * 16 + r) * 72 + rowl] = (u16)u01;
;             Tl[(1 * 16 + r) * 72 + rowl] = (u16)(u01 >> 16);
;             Tl[(2 * 16 + r) * 72 + rowl] = (u16)u23;
;             Tl[(3 * 16 + r) * 72 + rowl] = (u16)(u23 >> 16);
;           } else if (tr == 2) {
;             Tl[rowl * 72 + 0 * 16 + r] = f2h(v0);
;             Tl[rowl * 72 + 1 * 16 + r] = f2h(v1);
;             Tl[rowl * 72 + 2 * 16 + r] = f2h(v2);
;             Tl[rowl * 72 + 3 * 16 + r] = f2h(v3);
;           } else {
;             Tl[rowl * 72 + 0 * 16 + r] = (u16)u01;
;             Tl[rowl * 72 + 1 * 16 + r] = (u16)(u01 >> 16);
;             Tl[rowl * 72 + 2 * 16 + r] = (u16)u23;
;             Tl[rowl * 72 + 3 * 16 + r] = (u16)(u23 >> 16);
;           }
;         }
;       }
;       __builtin_amdgcn_fence(__ATOMIC_RELEASE, "wavefront");
;       u16* dh = (kind == 1) ? dst + hf * 64 : dst + (size_t)(hf * 64) * rstride;
; #pragma unroll
;       for (int i = 0; i < 8; ++i) {
;         const int c = lane + i * 64;
;         const int row = c >> 3, cc = c & 7;
;         uint4 v = *(const uint4*)&Tl[row * 72 + cc * 8];
	v_fma_f32 v191, v218, v96, v187
	v_cvt_pk_bf16_f32 v192, v188, v189
	v_cvt_pk_bf16_f32 v193, v190, v191
	ds_write_b16 v170, v192 offset:2592
	ds_write_b16_d16_hi v170, v192 offset:2624
	ds_write_b16 v170, v193 offset:2656
	ds_write_b16_d16_hi v170, v193 offset:2688
	v_mul_f32_e32 v186, v175, v93
	v_mul_f32_e32 v187, v176, v93
	v_fma_f32 v188, v176, v89, -v186
	v_fma_f32 v189, v175, v89, v187
	v_mul_f32_e32 v186, v219, v101
	v_mul_f32_e32 v187, v245, v101
	v_fma_f32 v190, v245, v97, -v186
	v_fma_f32 v191, v219, v97, v187
	v_cvt_pk_bf16_f32 v192, v188, v189
	v_cvt_pk_bf16_f32 v193, v190, v191
	ds_write_b16 v170, v192 offset:2736
	ds_write_b16_d16_hi v170, v192 offset:2768
	ds_write_b16 v170, v193 offset:2800
	ds_write_b16_d16_hi v170, v193 offset:2832
	v_mul_f32_e32 v186, v175, v106
	v_mul_f32_e32 v187, v176, v106
	v_fma_f32 v188, v176, v102, -v186
	v_fma_f32 v189, v175, v102, v187
	v_mul_f32_e32 v186, v220, v114
	v_mul_f32_e32 v187, v246, v114
	v_fma_f32 v190, v246, v110, -v186
	v_fma_f32 v191, v220, v110, v187
	v_cvt_pk_bf16_f32 v192, v188, v189
	v_cvt_pk_bf16_f32 v193, v190, v191
	ds_write_b16 v170, v192 offset:4608
	ds_write_b16_d16_hi v170, v192 offset:4640
	ds_write_b16 v170, v193 offset:4672
	ds_write_b16_d16_hi v170, v193 offset:4704
	v_mul_f32_e32 v186, v175, v107
	v_mul_f32_e32 v187, v176, v107
	v_fma_f32 v188, v176, v103, -v186
	v_fma_f32 v189, v175, v103, v187
	v_mul_f32_e32 v186, v221, v115
	v_mul_f32_e32 v187, v247, v115
	v_fma_f32 v190, v247, v111, -v186
	v_fma_f32 v191, v221, v111, v187
	v_cvt_pk_bf16_f32 v192, v188, v189
	v_cvt_pk_bf16_f32 v193, v190, v191
	ds_write_b16 v170, v192 offset:4752
	ds_write_b16_d16_hi v170, v192 offset:4784
	ds_write_b16 v170, v193 offset:4816
	ds_write_b16_d16_hi v170, v193 offset:4848
	v_mul_f32_e32 v186, v175, v108
	v_mul_f32_e32 v187, v176, v108
	v_fma_f32 v188, v176, v104, -v186
	v_fma_f32 v189, v175, v104, v187
	v_mul_f32_e32 v186, v222, v116
	v_mul_f32_e32 v187, v248, v116
	v_fma_f32 v190, v248, v112, -v186
	v_fma_f32 v191, v222, v112, v187
	v_cvt_pk_bf16_f32 v192, v188, v189
	v_cvt_pk_bf16_f32 v193, v190, v191
	ds_write_b16 v170, v192 offset:4896
	ds_write_b16_d16_hi v170, v192 offset:4928
	ds_write_b16 v170, v193 offset:4960
	ds_write_b16_d16_hi v170, v193 offset:4992
	v_mul_f32_e32 v186, v175, v109
	v_mul_f32_e32 v187, v176, v109
	v_fma_f32 v188, v176, v105, -v186
	v_fma_f32 v189, v175, v105, v187
	v_mul_f32_e32 v186, v223, v117
	v_mul_f32_e32 v187, v249, v117
	v_fma_f32 v190, v249, v113, -v186
	v_fma_f32 v191, v223, v113, v187
	v_cvt_pk_bf16_f32 v192, v188, v189
	v_cvt_pk_bf16_f32 v193, v190, v191
	ds_write_b16 v170, v192 offset:5040
	ds_write_b16_d16_hi v170, v192 offset:5072
	ds_write_b16 v170, v193 offset:5104
	ds_write_b16_d16_hi v170, v193 offset:5136
	v_mul_f32_e32 v186, v175, v122
	v_mul_f32_e32 v187, v176, v122
	v_fma_f32 v188, v176, v118, -v186
	v_fma_f32 v189, v175, v118, v187
	v_mul_f32_e32 v186, v234, v2
	v_mul_f32_e32 v187, v250, v2
	v_fma_f32 v190, v250, v126, -v186
	v_fma_f32 v191, v234, v126, v187
	v_cvt_pk_bf16_f32 v192, v188, v189
	v_cvt_pk_bf16_f32 v193, v190, v191
	ds_write_b16 v170, v192 offset:6912
	ds_write_b16_d16_hi v170, v192 offset:6944
	ds_write_b16 v170, v193 offset:6976
	ds_write_b16_d16_hi v170, v193 offset:7008
	v_mul_f32_e32 v186, v175, v123
	v_mul_f32_e32 v187, v176, v123
	v_fma_f32 v188, v176, v119, -v186
	v_fma_f32 v189, v175, v119, v187
	v_mul_f32_e32 v186, v235, v3
	v_mul_f32_e32 v187, v251, v3
	v_fma_f32 v190, v251, v127, -v186
	v_fma_f32 v191, v235, v127, v187
	v_cvt_pk_bf16_f32 v192, v188, v189
	v_cvt_pk_bf16_f32 v193, v190, v191
	ds_write_b16 v170, v192 offset:7056
	ds_write_b16_d16_hi v170, v192 offset:7088
	ds_write_b16 v170, v193 offset:7120
	ds_write_b16_d16_hi v170, v193 offset:7152
	v_mul_f32_e32 v186, v175, v124
	v_mul_f32_e32 v187, v176, v124
	v_fma_f32 v188, v176, v120, -v186
	v_fma_f32 v189, v175, v120, v187
	v_mul_f32_e32 v186, v236, v4
	v_mul_f32_e32 v187, v252, v4
	v_fma_f32 v190, v252, v128, -v186
	v_fma_f32 v191, v236, v128, v187
	v_cvt_pk_bf16_f32 v192, v188, v189
	v_cvt_pk_bf16_f32 v193, v190, v191
	ds_write_b16 v170, v192 offset:7200
	ds_write_b16_d16_hi v170, v192 offset:7232
	ds_write_b16 v170, v193 offset:7264
	ds_write_b16_d16_hi v170, v193 offset:7296
	v_mul_f32_e32 v186, v175, v125
	v_mul_f32_e32 v187, v176, v125
	v_fma_f32 v188, v176, v121, -v186
	v_fma_f32 v189, v175, v121, v187
	v_mul_f32_e32 v186, v237, v5
	v_mul_f32_e32 v187, v253, v5
	v_fma_f32 v190, v253, v129, -v186
	v_fma_f32 v191, v237, v129, v187
	v_cvt_pk_bf16_f32 v192, v188, v189
	v_cvt_pk_bf16_f32 v193, v190, v191
	ds_write_b16 v170, v192 offset:7344
	ds_write_b16_d16_hi v170, v192 offset:7376
	ds_write_b16 v170, v193 offset:7408
	ds_write_b16_d16_hi v170, v193 offset:7440
	ds_read_b128 v[130:133], v171 offset:0
	ds_read_b128 v[134:137], v171 offset:1152
	ds_read_b128 v[138:141], v171 offset:2304
	ds_read_b128 v[142:145], v171 offset:3456
	ds_read_b128 v[146:149], v171 offset:4608
	ds_read_b128 v[150:153], v171 offset:5760
	ds_read_b128 v[154:157], v171 offset:6912
	ds_read_b128 v[158:161], v171 offset:8064
	s_waitcnt lgkmcnt(7)
	global_store_dwordx4 v172, v[130:133], s[44:45] offset:0 sc1
	s_waitcnt lgkmcnt(6)
	global_store_dwordx4 v172, v[134:137], s[44:45] offset:1024 sc1
	s_waitcnt lgkmcnt(5)
	global_store_dwordx4 v172, v[138:141], s[44:45] offset:2048 sc1
	s_waitcnt lgkmcnt(4)
	global_store_dwordx4 v172, v[142:145], s[44:45] offset:3072 sc1
	s_waitcnt lgkmcnt(3)
	global_store_dwordx4 v172, v[146:149], s[62:63] offset:0 sc1
	s_waitcnt lgkmcnt(2)
	global_store_dwordx4 v172, v[150:153], s[62:63] offset:1024 sc1
	s_waitcnt lgkmcnt(1)
	global_store_dwordx4 v172, v[154:157], s[62:63] offset:2048 sc1
	s_waitcnt lgkmcnt(0)
	global_store_dwordx4 v172, v[158:161], s[62:63] offset:3072 sc1
	s_branch .Lfe_done
; DI void sincos_rev(float ang, float& s, float& c) {
;   float rev = ang * 0.15915494309189535f;
;   rev -= rintf(rev);
;   s = __builtin_amdgcn_sinf(rev);
;   c = __builtin_amdgcn_cosf(rev);
; }
; template <int EPI>
; DI void gemm_phase(const P& p, int l, const u16* __restrict__ A, const u16* __restrict__ Bt, int mpx, char* lds) {
;     ...
;           } else if (tr == 4) {
;             float sr, cr, sc, cc;
;             sincos_rev((float)(s >> 6) * invf32, sr, cr);
;             sincos_rev((float)(s & 63) * invf32, sc, cc);
;             const float p0 = __shfl_xor(v0, 8), p1 = __shfl_xor(v1, 8), p2 = __shfl_xor(v2, 8), p3 = __shfl_xor(v3, 8);
;             v0 = lo8 ? (v0 * cr - p0 * sr) : (v0 * cr + p0 * sr);
;             v1 = lo8 ? (v1 * cc - p1 * sc) : (v1 * cc + p1 * sc);
;             v2 = lo8 ? (v2 * cr - p2 * sr) : (v2 * cr + p2 * sr);
;             v3 = lo8 ? (v3 * cc - p3 * sc) : (v3 * cc + p3 * sc);
;           }
.Lfe_k0_rope32:
	v_and_b32_e32 v0, 7, v226
	v_cvt_f32_ubyte0_e32 v0, v0
	v_mul_f32_e32 v0, 0xc1549a78, v0
	v_mul_f32_e32 v0, 0x3e000000, v0
	v_exp_f32_e32 v174, v0
	v_lshrrev_b32_e32 v0, 4, v226
	v_lshlrev_b32_e32 v0, 2, v0
	v_add_u32_e32 v182, 0, v0
	v_cvt_f32_i32_e32 v182, v182
	v_mul_f32_e32 v182, v174, v182
	v_mul_f32_e32 v183, 0.15915494, v182
	v_rndne_f32_e32 v183, v183
	v_fma_f32 v183, v182, 0.15915494, -v183
	v_sin_f32_e32 v212, v183
	v_cos_f32_e32 v238, v183
	v_add_u32_e32 v182, 1, v0
	v_cvt_f32_i32_e32 v182, v182
	v_mul_f32_e32 v182, v174, v182
	v_mul_f32_e32 v183, 0.15915494, v182
	v_rndne_f32_e32 v183, v183
	v_fma_f32 v183, v182, 0.15915494, -v183
	v_sin_f32_e32 v213, v183
	v_cos_f32_e32 v239, v183
	v_add_u32_e32 v182, 2, v0
	v_cvt_f32_i32_e32 v182, v182
	v_mul_f32_e32 v182, v174, v182
	v_mul_f32_e32 v183, 0.15915494, v182
	v_rndne_f32_e32 v183, v183
	v_fma_f32 v183, v182, 0.15915494, -v183
	v_sin_f32_e32 v214, v183
	v_cos_f32_e32 v240, v183
	v_add_u32_e32 v182, 3, v0
	v_cvt_f32_i32_e32 v182, v182
	v_mul_f32_e32 v182, v174, v182
	v_mul_f32_e32 v183, 0.15915494, v182
	v_rndne_f32_e32 v183, v183
	v_fma_f32 v183, v182, 0.15915494, -v183
	v_sin_f32_e32 v215, v183
	v_cos_f32_e32 v241, v183
	v_add_u32_e32 v182, 16, v0
	v_cvt_f32_i32_e32 v182, v182
	v_mul_f32_e32 v182, v174, v182
	v_mul_f32_e32 v183, 0.15915494, v182
	v_rndne_f32_e32 v183, v183
	v_fma_f32 v183, v182, 0.15915494, -v183
	v_sin_f32_e32 v216, v183
	v_cos_f32_e32 v242, v183
	v_add_u32_e32 v182, 17, v0
	v_cvt_f32_i32_e32 v182, v182
	v_mul_f32_e32 v182, v174, v182
	v_mul_f32_e32 v183, 0.15915494, v182
	v_rndne_f32_e32 v183, v183
	v_fma_f32 v183, v182, 0.15915494, -v183
	v_sin_f32_e32 v217, v183
	v_cos_f32_e32 v243, v183
	v_add_u32_e32 v182, 18, v0
	v_cvt_f32_i32_e32 v182, v182
	v_mul_f32_e32 v182, v174, v182
	v_mul_f32_e32 v183, 0.15915494, v182
	v_rndne_f32_e32 v183, v183
	v_fma_f32 v183, v182, 0.15915494, -v183
	v_sin_f32_e32 v218, v183
	v_cos_f32_e32 v244, v183
	v_add_u32_e32 v182, 19, v0
	v_cvt_f32_i32_e32 v182, v182
	v_mul_f32_e32 v182, v174, v182
	v_mul_f32_e32 v183, 0.15915494, v182
	v_rndne_f32_e32 v183, v183
	v_fma_f32 v183, v182, 0.15915494, -v183
	v_sin_f32_e32 v219, v183
	v_cos_f32_e32 v245, v183
	v_add_u32_e32 v182, 32, v0
	v_cvt_f32_i32_e32 v182, v182
	v_mul_f32_e32 v182, v174, v182
	v_mul_f32_e32 v183, 0.15915494, v182
	v_rndne_f32_e32 v183, v183
	v_fma_f32 v183, v182, 0.15915494, -v183
	v_sin_f32_e32 v220, v183
	v_cos_f32_e32 v246, v183
	v_add_u32_e32 v182, 33, v0
	v_cvt_f32_i32_e32 v182, v182
	v_mul_f32_e32 v182, v174, v182
	v_mul_f32_e32 v183, 0.15915494, v182
	v_rndne_f32_e32 v183, v183
	v_fma_f32 v183, v182, 0.15915494, -v183
	v_sin_f32_e32 v221, v183
	v_cos_f32_e32 v247, v183
	v_add_u32_e32 v182, 34, v0
	v_cvt_f32_i32_e32 v182, v182
	v_mul_f32_e32 v182, v174, v182
	v_mul_f32_e32 v183, 0.15915494, v182
	v_rndne_f32_e32 v183, v183
	v_fma_f32 v183, v182, 0.15915494, -v183
	v_sin_f32_e32 v222, v183
	v_cos_f32_e32 v248, v183
	v_add_u32_e32 v182, 35, v0
	v_cvt_f32_i32_e32 v182, v182
	v_mul_f32_e32 v182, v174, v182
	v_mul_f32_e32 v183, 0.15915494, v182
	v_rndne_f32_e32 v183, v183
	v_fma_f32 v183, v182, 0.15915494, -v183
	v_sin_f32_e32 v223, v183
	v_cos_f32_e32 v249, v183
	v_add_u32_e32 v182, 48, v0
	v_cvt_f32_i32_e32 v182, v182
	v_mul_f32_e32 v182, v174, v182
	v_mul_f32_e32 v183, 0.15915494, v182
	v_rndne_f32_e32 v183, v183
	v_fma_f32 v183, v182, 0.15915494, -v183
	v_sin_f32_e32 v234, v183
	v_cos_f32_e32 v250, v183
	v_add_u32_e32 v182, 49, v0
	v_cvt_f32_i32_e32 v182, v182
	v_mul_f32_e32 v182, v174, v182
	v_mul_f32_e32 v183, 0.15915494, v182
	v_rndne_f32_e32 v183, v183
	v_fma_f32 v183, v182, 0.15915494, -v183
	v_sin_f32_e32 v235, v183
	v_cos_f32_e32 v251, v183
	v_add_u32_e32 v182, 50, v0
	v_cvt_f32_i32_e32 v182, v182
	v_mul_f32_e32 v182, v174, v182
	v_mul_f32_e32 v183, 0.15915494, v182
	v_rndne_f32_e32 v183, v183
	v_fma_f32 v183, v182, 0.15915494, -v183
	v_sin_f32_e32 v236, v183
	v_cos_f32_e32 v252, v183
	v_add_u32_e32 v182, 51, v0
	v_cvt_f32_i32_e32 v182, v182
	v_mul_f32_e32 v182, v174, v182
	v_mul_f32_e32 v183, 0.15915494, v182
	v_rndne_f32_e32 v183, v183
	v_fma_f32 v183, v182, 0.15915494, -v183
	v_sin_f32_e32 v237, v183
	v_cos_f32_e32 v253, v183
	v_and_b32_e32 v0, 8, v226
	v_cmp_eq_u32_e32 vcc, 0, v0
	s_nop 1
	v_cndmask_b32_e64 v212, v212, -v212, vcc
	v_cndmask_b32_e64 v213, v213, -v213, vcc
	v_cndmask_b32_e64 v214, v214, -v214, vcc
	v_cndmask_b32_e64 v215, v215, -v215, vcc
	v_cndmask_b32_e64 v216, v216, -v216, vcc
	v_cndmask_b32_e64 v217, v217, -v217, vcc
	v_cndmask_b32_e64 v218, v218, -v218, vcc
	v_cndmask_b32_e64 v219, v219, -v219, vcc
	v_cndmask_b32_e64 v220, v220, -v220, vcc
	v_cndmask_b32_e64 v221, v221, -v221, vcc
	v_cndmask_b32_e64 v222, v222, -v222, vcc
	v_cndmask_b32_e64 v223, v223, -v223, vcc
	v_cndmask_b32_e64 v234, v234, -v234, vcc
	v_cndmask_b32_e64 v235, v235, -v235, vcc
	v_cndmask_b32_e64 v236, v236, -v236, vcc
	v_cndmask_b32_e64 v237, v237, -v237, vcc
	s_add_u32 s62, s44, 0x1000
	s_addc_u32 s63, s45, 0
	s_lshr_b32 s70, s69, 6
	v_cvt_f32_i32_e32 v182, s70
	v_mul_f32_e32 v182, v174, v182
	v_mul_f32_e32 v183, 0.15915494, v182
	v_rndne_f32_e32 v183, v183
	v_fma_f32 v183, v182, 0.15915494, -v183
	v_sin_f32_e32 v175, v183
	v_cos_f32_e32 v176, v183
	s_nop 0
	v_cndmask_b32_e64 v177, v175, -v175, vcc
	v_mul_f32_dpp v182, v6, v177 row_ror:8 row_mask:0xf bank_mask:0xf
	v_mul_f32_dpp v183, v10, v212 row_ror:8 row_mask:0xf bank_mask:0xf
	v_mul_f32_dpp v184, v14, v177 row_ror:8 row_mask:0xf bank_mask:0xf
	v_mul_f32_dpp v185, v18, v212 row_ror:8 row_mask:0xf bank_mask:0xf
	v_fma_f32 v186, v6, v176, v182
	v_fma_f32 v187, v10, v238, v183
; template <int EPI>
; DI void gemm_phase(const P& p, int l, const u16* __restrict__ A, const u16* __restrict__ Bt, int mpx, char* lds) {
;     ...
;           } else if (tr == 4) {
;             float sr, cr, sc, cc;
;             sincos_rev((float)(s >> 6) * invf32, sr, cr);
;             sincos_rev((float)(s & 63) * invf32, sc, cc);
;             const float p0 = __shfl_xor(v0, 8), p1 = __shfl_xor(v1, 8), p2 = __shfl_xor(v2, 8), p3 = __shfl_xor(v3, 8);
;             v0 = lo8 ? (v0 * cr - p0 * sr) : (v0 * cr + p0 * sr);
;             v1 = lo8 ? (v1 * cc - p1 * sc) : (v1 * cc + p1 * sc);
;             v2 = lo8 ? (v2 * cr - p2 * sr) : (v2 * cr + p2 * sr);
;             v3 = lo8 ? (v3 * cc - p3 * sc) : (v3 * cc + p3 * sc);
;           }
;           const unsigned u01 = pack2(v0, v1), u23 = pack2(v2, v3);
;           if (kind == 1) {
;             Tl[(0 * 16 + r) * 72 + rowl] = (u16)u01;
;             Tl[(1 * 16 + r) * 72 + rowl] = (u16)(u01 >> 16);
;             Tl[(2 * 16 + r) * 72 + rowl] = (u16)u23;
;             Tl[(3 * 16 + r) * 72 + rowl] = (u16)(u23 >> 16);
;           } else if (tr == 2) {
;             Tl[rowl * 72 + 0 * 16 + r] = f2h(v0);
;             Tl[rowl * 72 + 1 * 16 + r] = f2h(v1);
;             Tl[rowl * 72 + 2 * 16 + r] = f2h(v2);
;             Tl[rowl * 72 + 3 * 16 + r] = f2h(v3);
;           } else {
;             Tl[rowl * 72 + 0 * 16 + r] = (u16)u01;
;             Tl[rowl * 72 + 1 * 16 + r] = (u16)(u01 >> 16);
;             Tl[rowl * 72 + 2 * 16 + r] = (u16)u23;
;             Tl[rowl * 72 + 3 * 16 + r] = (u16)(u23 >> 16);
	v_fma_f32 v188, v14, v176, v184
	v_fma_f32 v189, v18, v238, v185
	v_cvt_pk_bf16_f32 v192, v186, v187
	v_cvt_pk_bf16_f32 v193, v188, v189
	ds_write_b16 v170, v192 offset:0
	ds_write_b16_d16_hi v170, v192 offset:32
	ds_write_b16 v170, v193 offset:64
	ds_write_b16_d16_hi v170, v193 offset:96
	v_mul_f32_dpp v182, v7, v177 row_ror:8 row_mask:0xf bank_mask:0xf
	v_mul_f32_dpp v183, v11, v213 row_ror:8 row_mask:0xf bank_mask:0xf
	v_mul_f32_dpp v184, v15, v177 row_ror:8 row_mask:0xf bank_mask:0xf
	v_mul_f32_dpp v185, v19, v213 row_ror:8 row_mask:0xf bank_mask:0xf
	v_fma_f32 v186, v7, v176, v182
	v_fma_f32 v187, v11, v239, v183
	v_fma_f32 v188, v15, v176, v184
	v_fma_f32 v189, v19, v239, v185
	v_cvt_pk_bf16_f32 v192, v186, v187
	v_cvt_pk_bf16_f32 v193, v188, v189
	ds_write_b16 v170, v192 offset:144
	ds_write_b16_d16_hi v170, v192 offset:176
	ds_write_b16 v170, v193 offset:208
	ds_write_b16_d16_hi v170, v193 offset:240
	v_mul_f32_dpp v182, v8, v177 row_ror:8 row_mask:0xf bank_mask:0xf
	v_mul_f32_dpp v183, v12, v214 row_ror:8 row_mask:0xf bank_mask:0xf
	v_mul_f32_dpp v184, v16, v177 row_ror:8 row_mask:0xf bank_mask:0xf
	v_mul_f32_dpp v185, v20, v214 row_ror:8 row_mask:0xf bank_mask:0xf
	v_fma_f32 v186, v8, v176, v182
	v_fma_f32 v187, v12, v240, v183
	v_fma_f32 v188, v16, v176, v184
	v_fma_f32 v189, v20, v240, v185
	v_cvt_pk_bf16_f32 v192, v186, v187
	v_cvt_pk_bf16_f32 v193, v188, v189
	ds_write_b16 v170, v192 offset:288
	ds_write_b16_d16_hi v170, v192 offset:320
	ds_write_b16 v170, v193 offset:352
	ds_write_b16_d16_hi v170, v193 offset:384
	v_mul_f32_dpp v182, v9, v177 row_ror:8 row_mask:0xf bank_mask:0xf
	v_mul_f32_dpp v183, v13, v215 row_ror:8 row_mask:0xf bank_mask:0xf
	v_mul_f32_dpp v184, v17, v177 row_ror:8 row_mask:0xf bank_mask:0xf
	v_mul_f32_dpp v185, v21, v215 row_ror:8 row_mask:0xf bank_mask:0xf
	v_fma_f32 v186, v9, v176, v182
	v_fma_f32 v187, v13, v241, v183
	v_fma_f32 v188, v17, v176, v184
	v_fma_f32 v189, v21, v241, v185
	v_cvt_pk_bf16_f32 v192, v186, v187
	v_cvt_pk_bf16_f32 v193, v188, v189
	ds_write_b16 v170, v192 offset:432
	ds_write_b16_d16_hi v170, v192 offset:464
	ds_write_b16 v170, v193 offset:496
	ds_write_b16_d16_hi v170, v193 offset:528
	v_mul_f32_dpp v182, v22, v177 row_ror:8 row_mask:0xf bank_mask:0xf
	v_mul_f32_dpp v183, v26, v216 row_ror:8 row_mask:0xf bank_mask:0xf
	v_mul_f32_dpp v184, v30, v177 row_ror:8 row_mask:0xf bank_mask:0xf
	v_mul_f32_dpp v185, v34, v216 row_ror:8 row_mask:0xf bank_mask:0xf
	v_fma_f32 v186, v22, v176, v182
	v_fma_f32 v187, v26, v242, v183
	v_fma_f32 v188, v30, v176, v184
	v_fma_f32 v189, v34, v242, v185
	v_cvt_pk_bf16_f32 v192, v186, v187
	v_cvt_pk_bf16_f32 v193, v188, v189
	ds_write_b16 v170, v192 offset:2304
	ds_write_b16_d16_hi v170, v192 offset:2336
	ds_write_b16 v170, v193 offset:2368
	ds_write_b16_d16_hi v170, v193 offset:2400
	v_mul_f32_dpp v182, v23, v177 row_ror:8 row_mask:0xf bank_mask:0xf
	v_mul_f32_dpp v183, v27, v217 row_ror:8 row_mask:0xf bank_mask:0xf
	v_mul_f32_dpp v184, v31, v177 row_ror:8 row_mask:0xf bank_mask:0xf
	v_mul_f32_dpp v185, v35, v217 row_ror:8 row_mask:0xf bank_mask:0xf
	v_fma_f32 v186, v23, v176, v182
	v_fma_f32 v187, v27, v243, v183
	v_fma_f32 v188, v31, v176, v184
	v_fma_f32 v189, v35, v243, v185
	v_cvt_pk_bf16_f32 v192, v186, v187
	v_cvt_pk_bf16_f32 v193, v188, v189
	ds_write_b16 v170, v192 offset:2448
	ds_write_b16_d16_hi v170, v192 offset:2480
	ds_write_b16 v170, v193 offset:2512
	ds_write_b16_d16_hi v170, v193 offset:2544
	v_mul_f32_dpp v182, v24, v177 row_ror:8 row_mask:0xf bank_mask:0xf
	v_mul_f32_dpp v183, v28, v218 row_ror:8 row_mask:0xf bank_mask:0xf
	v_mul_f32_dpp v184, v32, v177 row_ror:8 row_mask:0xf bank_mask:0xf
	v_mul_f32_dpp v185, v36, v218 row_ror:8 row_mask:0xf bank_mask:0xf
	v_fma_f32 v186, v24, v176, v182
	v_fma_f32 v187, v28, v244, v183
	v_fma_f32 v188, v32, v176, v184
	v_fma_f32 v189, v36, v244, v185
	v_cvt_pk_bf16_f32 v192, v186, v187
	v_cvt_pk_bf16_f32 v193, v188, v189
	ds_write_b16 v170, v192 offset:2592
	ds_write_b16_d16_hi v170, v192 offset:2624
	ds_write_b16 v170, v193 offset:2656
	ds_write_b16_d16_hi v170, v193 offset:2688
	v_mul_f32_dpp v182, v25, v177 row_ror:8 row_mask:0xf bank_mask:0xf
	v_mul_f32_dpp v183, v29, v219 row_ror:8 row_mask:0xf bank_mask:0xf
	v_mul_f32_dpp v184, v33, v177 row_ror:8 row_mask:0xf bank_mask:0xf
	v_mul_f32_dpp v185, v37, v219 row_ror:8 row_mask:0xf bank_mask:0xf
	v_fma_f32 v186, v25, v176, v182
	v_fma_f32 v187, v29, v245, v183
	v_fma_f32 v188, v33, v176, v184
	v_fma_f32 v189, v37, v245, v185
	v_cvt_pk_bf16_f32 v192, v186, v187
	v_cvt_pk_bf16_f32 v193, v188, v189
	ds_write_b16 v170, v192 offset:2736
	ds_write_b16_d16_hi v170, v192 offset:2768
	ds_write_b16 v170, v193 offset:2800
	ds_write_b16_d16_hi v170, v193 offset:2832
	v_mul_f32_dpp v182, v38, v177 row_ror:8 row_mask:0xf bank_mask:0xf
	v_mul_f32_dpp v183, v42, v220 row_ror:8 row_mask:0xf bank_mask:0xf
	v_mul_f32_dpp v184, v46, v177 row_ror:8 row_mask:0xf bank_mask:0xf
	v_mul_f32_dpp v185, v50, v220 row_ror:8 row_mask:0xf bank_mask:0xf
	v_fma_f32 v186, v38, v176, v182
	v_fma_f32 v187, v42, v246, v183
	v_fma_f32 v188, v46, v176, v184
	v_fma_f32 v189, v50, v246, v185
	v_cvt_pk_bf16_f32 v192, v186, v187
	v_cvt_pk_bf16_f32 v193, v188, v189
	ds_write_b16 v170, v192 offset:4608
	ds_write_b16_d16_hi v170, v192 offset:4640
	ds_write_b16 v170, v193 offset:4672
	ds_write_b16_d16_hi v170, v193 offset:4704
	v_mul_f32_dpp v182, v39, v177 row_ror:8 row_mask:0xf bank_mask:0xf
	v_mul_f32_dpp v183, v43, v221 row_ror:8 row_mask:0xf bank_mask:0xf
	v_mul_f32_dpp v184, v47, v177 row_ror:8 row_mask:0xf bank_mask:0xf
	v_mul_f32_dpp v185, v51, v221 row_ror:8 row_mask:0xf bank_mask:0xf
; template <int EPI>
; DI void gemm_phase(const P& p, int l, const u16* __restrict__ A, const u16* __restrict__ Bt, int mpx, char* lds) {
;     ...
;           } else if (tr == 4) {
;             float sr, cr, sc, cc;
;             sincos_rev((float)(s >> 6) * invf32, sr, cr);
;             sincos_rev((float)(s & 63) * invf32, sc, cc);
;             const float p0 = __shfl_xor(v0, 8), p1 = __shfl_xor(v1, 8), p2 = __shfl_xor(v2, 8), p3 = __shfl_xor(v3, 8);
;             v0 = lo8 ? (v0 * cr - p0 * sr) : (v0 * cr + p0 * sr);
;             v1 = lo8 ? (v1 * cc - p1 * sc) : (v1 * cc + p1 * sc);
;             v2 = lo8 ? (v2 * cr - p2 * sr) : (v2 * cr + p2 * sr);
;             v3 = lo8 ? (v3 * cc - p3 * sc) : (v3 * cc + p3 * sc);
;           }
;           const unsigned u01 = pack2(v0, v1), u23 = pack2(v2, v3);
;           if (kind == 1) {
;             Tl[(0 * 16 + r) * 72 + rowl] = (u16)u01;
;             Tl[(1 * 16 + r) * 72 + rowl] = (u16)(u01 >> 16);
;             Tl[(2 * 16 + r) * 72 + rowl] = (u16)u23;
;             Tl[(3 * 16 + r) * 72 + rowl] = (u16)(u23 >> 16);
;           } else if (tr == 2) {
;             Tl[rowl * 72 + 0 * 16 + r] = f2h(v0);
;             Tl[rowl * 72 + 1 * 16 + r] = f2h(v1);
;             Tl[rowl * 72 + 2 * 16 + r] = f2h(v2);
;             Tl[rowl * 72 + 3 * 16 + r] = f2h(v3);
;           } else {
;             Tl[rowl * 72 + 0 * 16 + r] = (u16)u01;
;             Tl[rowl * 72 + 1 * 16 + r] = (u16)(u01 >> 16);
;             Tl[rowl * 72 + 2 * 16 + r] = (u16)u23;
;             Tl[rowl * 72 + 3 * 16 + r] = (u16)(u23 >> 16);
;           }
;         }
;       }
;       __builtin_amdgcn_fence(__ATOMIC_RELEASE, "wavefront");
;       u16* dh = (kind == 1) ? dst + hf * 64 : dst + (size_t)(hf * 64) * rstride;
; #pragma unroll
;       for (int i = 0; i < 8; ++i) {
;         const int c = lane + i * 64;
;         const int row = c >> 3, cc = c & 7;
;         uint4 v = *(const uint4*)&Tl[row * 72 + cc * 8];
;         *(uint4*)(dh + (size_t)row * rstride + cc * 8) = v;
;       }
	v_fma_f32 v186, v39, v176, v182
	v_fma_f32 v187, v43, v247, v183
	v_fma_f32 v188, v47, v176, v184
	v_fma_f32 v189, v51, v247, v185
	v_cvt_pk_bf16_f32 v192, v186, v187
	v_cvt_pk_bf16_f32 v193, v188, v189
	ds_write_b16 v170, v192 offset:4752
	ds_write_b16_d16_hi v170, v192 offset:4784
	ds_write_b16 v170, v193 offset:4816
	ds_write_b16_d16_hi v170, v193 offset:4848
	v_mul_f32_dpp v182, v40, v177 row_ror:8 row_mask:0xf bank_mask:0xf
	v_mul_f32_dpp v183, v44, v222 row_ror:8 row_mask:0xf bank_mask:0xf
	v_mul_f32_dpp v184, v48, v177 row_ror:8 row_mask:0xf bank_mask:0xf
	v_mul_f32_dpp v185, v52, v222 row_ror:8 row_mask:0xf bank_mask:0xf
	v_fma_f32 v186, v40, v176, v182
	v_fma_f32 v187, v44, v248, v183
	v_fma_f32 v188, v48, v176, v184
	v_fma_f32 v189, v52, v248, v185
	v_cvt_pk_bf16_f32 v192, v186, v187
	v_cvt_pk_bf16_f32 v193, v188, v189
	ds_write_b16 v170, v192 offset:4896
	ds_write_b16_d16_hi v170, v192 offset:4928
	ds_write_b16 v170, v193 offset:4960
	ds_write_b16_d16_hi v170, v193 offset:4992
	v_mul_f32_dpp v182, v41, v177 row_ror:8 row_mask:0xf bank_mask:0xf
	v_mul_f32_dpp v183, v45, v223 row_ror:8 row_mask:0xf bank_mask:0xf
	v_mul_f32_dpp v184, v49, v177 row_ror:8 row_mask:0xf bank_mask:0xf
	v_mul_f32_dpp v185, v53, v223 row_ror:8 row_mask:0xf bank_mask:0xf
	v_fma_f32 v186, v41, v176, v182
	v_fma_f32 v187, v45, v249, v183
	v_fma_f32 v188, v49, v176, v184
	v_fma_f32 v189, v53, v249, v185
	v_cvt_pk_bf16_f32 v192, v186, v187
	v_cvt_pk_bf16_f32 v193, v188, v189
	ds_write_b16 v170, v192 offset:5040
	ds_write_b16_d16_hi v170, v192 offset:5072
	ds_write_b16 v170, v193 offset:5104
	ds_write_b16_d16_hi v170, v193 offset:5136
	v_mul_f32_dpp v182, v54, v177 row_ror:8 row_mask:0xf bank_mask:0xf
	v_mul_f32_dpp v183, v58, v234 row_ror:8 row_mask:0xf bank_mask:0xf
	v_mul_f32_dpp v184, v62, v177 row_ror:8 row_mask:0xf bank_mask:0xf
	v_mul_f32_dpp v185, v66, v234 row_ror:8 row_mask:0xf bank_mask:0xf
	v_fma_f32 v186, v54, v176, v182
	v_fma_f32 v187, v58, v250, v183
	v_fma_f32 v188, v62, v176, v184
	v_fma_f32 v189, v66, v250, v185
	v_cvt_pk_bf16_f32 v192, v186, v187
	v_cvt_pk_bf16_f32 v193, v188, v189
	ds_write_b16 v170, v192 offset:6912
	ds_write_b16_d16_hi v170, v192 offset:6944
	ds_write_b16 v170, v193 offset:6976
	ds_write_b16_d16_hi v170, v193 offset:7008
	v_mul_f32_dpp v182, v55, v177 row_ror:8 row_mask:0xf bank_mask:0xf
	v_mul_f32_dpp v183, v59, v235 row_ror:8 row_mask:0xf bank_mask:0xf
	v_mul_f32_dpp v184, v63, v177 row_ror:8 row_mask:0xf bank_mask:0xf
	v_mul_f32_dpp v185, v67, v235 row_ror:8 row_mask:0xf bank_mask:0xf
	v_fma_f32 v186, v55, v176, v182
	v_fma_f32 v187, v59, v251, v183
	v_fma_f32 v188, v63, v176, v184
	v_fma_f32 v189, v67, v251, v185
	v_cvt_pk_bf16_f32 v192, v186, v187
	v_cvt_pk_bf16_f32 v193, v188, v189
	ds_write_b16 v170, v192 offset:7056
	ds_write_b16_d16_hi v170, v192 offset:7088
	ds_write_b16 v170, v193 offset:7120
	ds_write_b16_d16_hi v170, v193 offset:7152
	v_mul_f32_dpp v182, v56, v177 row_ror:8 row_mask:0xf bank_mask:0xf
	v_mul_f32_dpp v183, v60, v236 row_ror:8 row_mask:0xf bank_mask:0xf
	v_mul_f32_dpp v184, v64, v177 row_ror:8 row_mask:0xf bank_mask:0xf
	v_mul_f32_dpp v185, v68, v236 row_ror:8 row_mask:0xf bank_mask:0xf
	v_fma_f32 v186, v56, v176, v182
	v_fma_f32 v187, v60, v252, v183
	v_fma_f32 v188, v64, v176, v184
	v_fma_f32 v189, v68, v252, v185
	v_cvt_pk_bf16_f32 v192, v186, v187
	v_cvt_pk_bf16_f32 v193, v188, v189
	ds_write_b16 v170, v192 offset:7200
	ds_write_b16_d16_hi v170, v192 offset:7232
	ds_write_b16 v170, v193 offset:7264
	ds_write_b16_d16_hi v170, v193 offset:7296
	v_mul_f32_dpp v182, v57, v177 row_ror:8 row_mask:0xf bank_mask:0xf
	v_mul_f32_dpp v183, v61, v237 row_ror:8 row_mask:0xf bank_mask:0xf
	v_mul_f32_dpp v184, v65, v177 row_ror:8 row_mask:0xf bank_mask:0xf
	v_mul_f32_dpp v185, v69, v237 row_ror:8 row_mask:0xf bank_mask:0xf
	v_fma_f32 v186, v57, v176, v182
	v_fma_f32 v187, v61, v253, v183
	v_fma_f32 v188, v65, v176, v184
	v_fma_f32 v189, v69, v253, v185
	v_cvt_pk_bf16_f32 v192, v186, v187
	v_cvt_pk_bf16_f32 v193, v188, v189
	ds_write_b16 v170, v192 offset:7344
	ds_write_b16_d16_hi v170, v192 offset:7376
	ds_write_b16 v170, v193 offset:7408
	ds_write_b16_d16_hi v170, v193 offset:7440
	ds_read_b128 v[130:133], v171 offset:0
	ds_read_b128 v[134:137], v171 offset:1152
	ds_read_b128 v[138:141], v171 offset:2304
	ds_read_b128 v[142:145], v171 offset:3456
	ds_read_b128 v[146:149], v171 offset:4608
	ds_read_b128 v[150:153], v171 offset:5760
	ds_read_b128 v[154:157], v171 offset:6912
	ds_read_b128 v[158:161], v171 offset:8064
	s_waitcnt lgkmcnt(7)
	global_store_dwordx4 v172, v[130:133], s[44:45] offset:0 sc1
	s_waitcnt lgkmcnt(6)
	global_store_dwordx4 v172, v[134:137], s[44:45] offset:1024 sc1
	s_waitcnt lgkmcnt(5)
	global_store_dwordx4 v172, v[138:141], s[44:45] offset:2048 sc1
	s_waitcnt lgkmcnt(4)
	global_store_dwordx4 v172, v[142:145], s[44:45] offset:3072 sc1
	s_waitcnt lgkmcnt(3)
	global_store_dwordx4 v172, v[146:149], s[62:63] offset:0 sc1
	s_waitcnt lgkmcnt(2)
	global_store_dwordx4 v172, v[150:153], s[62:63] offset:1024 sc1
	s_waitcnt lgkmcnt(1)
	global_store_dwordx4 v172, v[154:157], s[62:63] offset:2048 sc1
	s_waitcnt lgkmcnt(0)
; template <int EPI>
; DI void gemm_phase(const P& p, int l, const u16* __restrict__ A, const u16* __restrict__ Bt, int mpx, char* lds) {
;     ...
;           } else if (tr == 4) {
;             float sr, cr, sc, cc;
;             sincos_rev((float)(s >> 6) * invf32, sr, cr);
;             sincos_rev((float)(s & 63) * invf32, sc, cc);
;             const float p0 = __shfl_xor(v0, 8), p1 = __shfl_xor(v1, 8), p2 = __shfl_xor(v2, 8), p3 = __shfl_xor(v3, 8);
;             v0 = lo8 ? (v0 * cr - p0 * sr) : (v0 * cr + p0 * sr);
;             v1 = lo8 ? (v1 * cc - p1 * sc) : (v1 * cc + p1 * sc);
;             v2 = lo8 ? (v2 * cr - p2 * sr) : (v2 * cr + p2 * sr);
;             v3 = lo8 ? (v3 * cc - p3 * sc) : (v3 * cc + p3 * sc);
;           }
;           const unsigned u01 = pack2(v0, v1), u23 = pack2(v2, v3);
;           if (kind == 1) {
;             Tl[(0 * 16 + r) * 72 + rowl] = (u16)u01;
;             Tl[(1 * 16 + r) * 72 + rowl] = (u16)(u01 >> 16);
;             Tl[(2 * 16 + r) * 72 + rowl] = (u16)u23;
;             Tl[(3 * 16 + r) * 72 + rowl] = (u16)(u23 >> 16);
;           } else if (tr == 2) {
;             Tl[rowl * 72 + 0 * 16 + r] = f2h(v0);
;             Tl[rowl * 72 + 1 * 16 + r] = f2h(v1);
;             Tl[rowl * 72 + 2 * 16 + r] = f2h(v2);
;             Tl[rowl * 72 + 3 * 16 + r] = f2h(v3);
;           } else {
;             Tl[rowl * 72 + 0 * 16 + r] = (u16)u01;
;             Tl[rowl * 72 + 1 * 16 + r] = (u16)(u01 >> 16);
;             Tl[rowl * 72 + 2 * 16 + r] = (u16)u23;
;             Tl[rowl * 72 + 3 * 16 + r] = (u16)(u23 >> 16);
;     ...
;       u16* dh = (kind == 1) ? dst + hf * 64 : dst + (size_t)(hf * 64) * rstride;
; #pragma unroll
;       for (int i = 0; i < 8; ++i) {
;         const int c = lane + i * 64;
;         const int row = c >> 3, cc = c & 7;
;         uint4 v = *(const uint4*)&Tl[row * 72 + cc * 8];
;         *(uint4*)(dh + (size_t)row * rstride + cc * 8) = v;
;       }
	global_store_dwordx4 v172, v[158:161], s[62:63] offset:3072 sc1
	s_add_u32 s44, s44, 0x2000
	s_addc_u32 s45, s45, 0
	s_add_u32 s62, s62, 0x2000
	s_addc_u32 s63, s63, 0
	s_lshr_b32 s70, s69, 6
	s_add_i32 s70, s70, 1
	v_cvt_f32_i32_e32 v182, s70
	v_mul_f32_e32 v182, v174, v182
	v_mul_f32_e32 v183, 0.15915494, v182
	v_rndne_f32_e32 v183, v183
	v_fma_f32 v183, v182, 0.15915494, -v183
	v_sin_f32_e32 v175, v183
	v_cos_f32_e32 v176, v183
	s_nop 0
	v_cndmask_b32_e64 v177, v175, -v175, vcc
	v_mul_f32_dpp v182, v70, v177 row_ror:8 row_mask:0xf bank_mask:0xf
	v_mul_f32_dpp v183, v74, v212 row_ror:8 row_mask:0xf bank_mask:0xf
	v_mul_f32_dpp v184, v78, v177 row_ror:8 row_mask:0xf bank_mask:0xf
	v_mul_f32_dpp v185, v82, v212 row_ror:8 row_mask:0xf bank_mask:0xf
	v_fma_f32 v186, v70, v176, v182
	v_fma_f32 v187, v74, v238, v183
	v_fma_f32 v188, v78, v176, v184
	v_fma_f32 v189, v82, v238, v185
	v_cvt_pk_bf16_f32 v192, v186, v187
	v_cvt_pk_bf16_f32 v193, v188, v189
	ds_write_b16 v170, v192 offset:0
	ds_write_b16_d16_hi v170, v192 offset:32
	ds_write_b16 v170, v193 offset:64
	ds_write_b16_d16_hi v170, v193 offset:96
	v_mul_f32_dpp v182, v71, v177 row_ror:8 row_mask:0xf bank_mask:0xf
	v_mul_f32_dpp v183, v75, v213 row_ror:8 row_mask:0xf bank_mask:0xf
	v_mul_f32_dpp v184, v79, v177 row_ror:8 row_mask:0xf bank_mask:0xf
	v_mul_f32_dpp v185, v83, v213 row_ror:8 row_mask:0xf bank_mask:0xf
	v_fma_f32 v186, v71, v176, v182
	v_fma_f32 v187, v75, v239, v183
	v_fma_f32 v188, v79, v176, v184
	v_fma_f32 v189, v83, v239, v185
	v_cvt_pk_bf16_f32 v192, v186, v187
	v_cvt_pk_bf16_f32 v193, v188, v189
	ds_write_b16 v170, v192 offset:144
	ds_write_b16_d16_hi v170, v192 offset:176
	ds_write_b16 v170, v193 offset:208
	ds_write_b16_d16_hi v170, v193 offset:240
	v_mul_f32_dpp v182, v72, v177 row_ror:8 row_mask:0xf bank_mask:0xf
	v_mul_f32_dpp v183, v76, v214 row_ror:8 row_mask:0xf bank_mask:0xf
	v_mul_f32_dpp v184, v80, v177 row_ror:8 row_mask:0xf bank_mask:0xf
	v_mul_f32_dpp v185, v84, v214 row_ror:8 row_mask:0xf bank_mask:0xf
	v_fma_f32 v186, v72, v176, v182
	v_fma_f32 v187, v76, v240, v183
	v_fma_f32 v188, v80, v176, v184
	v_fma_f32 v189, v84, v240, v185
	v_cvt_pk_bf16_f32 v192, v186, v187
	v_cvt_pk_bf16_f32 v193, v188, v189
	ds_write_b16 v170, v192 offset:288
	ds_write_b16_d16_hi v170, v192 offset:320
	ds_write_b16 v170, v193 offset:352
	ds_write_b16_d16_hi v170, v193 offset:384
	v_mul_f32_dpp v182, v73, v177 row_ror:8 row_mask:0xf bank_mask:0xf
	v_mul_f32_dpp v183, v77, v215 row_ror:8 row_mask:0xf bank_mask:0xf
	v_mul_f32_dpp v184, v81, v177 row_ror:8 row_mask:0xf bank_mask:0xf
	v_mul_f32_dpp v185, v85, v215 row_ror:8 row_mask:0xf bank_mask:0xf
	v_fma_f32 v186, v73, v176, v182
	v_fma_f32 v187, v77, v241, v183
	v_fma_f32 v188, v81, v176, v184
	v_fma_f32 v189, v85, v241, v185
	v_cvt_pk_bf16_f32 v192, v186, v187
	v_cvt_pk_bf16_f32 v193, v188, v189
	ds_write_b16 v170, v192 offset:432
	ds_write_b16_d16_hi v170, v192 offset:464
	ds_write_b16 v170, v193 offset:496
	ds_write_b16_d16_hi v170, v193 offset:528
	v_mul_f32_dpp v182, v86, v177 row_ror:8 row_mask:0xf bank_mask:0xf
	v_mul_f32_dpp v183, v90, v216 row_ror:8 row_mask:0xf bank_mask:0xf
	v_mul_f32_dpp v184, v94, v177 row_ror:8 row_mask:0xf bank_mask:0xf
	v_mul_f32_dpp v185, v98, v216 row_ror:8 row_mask:0xf bank_mask:0xf
	v_fma_f32 v186, v86, v176, v182
	v_fma_f32 v187, v90, v242, v183
	v_fma_f32 v188, v94, v176, v184
	v_fma_f32 v189, v98, v242, v185
	v_cvt_pk_bf16_f32 v192, v186, v187
	v_cvt_pk_bf16_f32 v193, v188, v189
	ds_write_b16 v170, v192 offset:2304
	ds_write_b16_d16_hi v170, v192 offset:2336
	ds_write_b16 v170, v193 offset:2368
	ds_write_b16_d16_hi v170, v193 offset:2400
	v_mul_f32_dpp v182, v87, v177 row_ror:8 row_mask:0xf bank_mask:0xf
	v_mul_f32_dpp v183, v91, v217 row_ror:8 row_mask:0xf bank_mask:0xf
	v_mul_f32_dpp v184, v95, v177 row_ror:8 row_mask:0xf bank_mask:0xf
	v_mul_f32_dpp v185, v99, v217 row_ror:8 row_mask:0xf bank_mask:0xf
	v_fma_f32 v186, v87, v176, v182
	v_fma_f32 v187, v91, v243, v183
	v_fma_f32 v188, v95, v176, v184
	v_fma_f32 v189, v99, v243, v185
	v_cvt_pk_bf16_f32 v192, v186, v187
	v_cvt_pk_bf16_f32 v193, v188, v189
	ds_write_b16 v170, v192 offset:2448
	ds_write_b16_d16_hi v170, v192 offset:2480
	ds_write_b16 v170, v193 offset:2512
	ds_write_b16_d16_hi v170, v193 offset:2544
	v_mul_f32_dpp v182, v88, v177 row_ror:8 row_mask:0xf bank_mask:0xf
	v_mul_f32_dpp v183, v92, v218 row_ror:8 row_mask:0xf bank_mask:0xf
	v_mul_f32_dpp v184, v96, v177 row_ror:8 row_mask:0xf bank_mask:0xf
	v_mul_f32_dpp v185, v100, v218 row_ror:8 row_mask:0xf bank_mask:0xf
	v_fma_f32 v186, v88, v176, v182
	v_fma_f32 v187, v92, v244, v183
	v_fma_f32 v188, v96, v176, v184
	v_fma_f32 v189, v100, v244, v185
	v_cvt_pk_bf16_f32 v192, v186, v187
	v_cvt_pk_bf16_f32 v193, v188, v189
	ds_write_b16 v170, v192 offset:2592
	ds_write_b16_d16_hi v170, v192 offset:2624
	ds_write_b16 v170, v193 offset:2656
	ds_write_b16_d16_hi v170, v193 offset:2688
	v_mul_f32_dpp v182, v89, v177 row_ror:8 row_mask:0xf bank_mask:0xf
	v_mul_f32_dpp v183, v93, v219 row_ror:8 row_mask:0xf bank_mask:0xf
	v_mul_f32_dpp v184, v97, v177 row_ror:8 row_mask:0xf bank_mask:0xf
	v_mul_f32_dpp v185, v101, v219 row_ror:8 row_mask:0xf bank_mask:0xf
	v_fma_f32 v186, v89, v176, v182
	v_fma_f32 v187, v93, v245, v183
	v_fma_f32 v188, v97, v176, v184
	v_fma_f32 v189, v101, v245, v185
	v_cvt_pk_bf16_f32 v192, v186, v187
	v_cvt_pk_bf16_f32 v193, v188, v189
	ds_write_b16 v170, v192 offset:2736
	ds_write_b16_d16_hi v170, v192 offset:2768
	ds_write_b16 v170, v193 offset:2800
	ds_write_b16_d16_hi v170, v193 offset:2832
	v_mul_f32_dpp v182, v102, v177 row_ror:8 row_mask:0xf bank_mask:0xf
; template <int EPI>
; DI void gemm_phase(const P& p, int l, const u16* __restrict__ A, const u16* __restrict__ Bt, int mpx, char* lds) {
;     ...
;           } else if (tr == 4) {
;             float sr, cr, sc, cc;
;             sincos_rev((float)(s >> 6) * invf32, sr, cr);
;             sincos_rev((float)(s & 63) * invf32, sc, cc);
;             const float p0 = __shfl_xor(v0, 8), p1 = __shfl_xor(v1, 8), p2 = __shfl_xor(v2, 8), p3 = __shfl_xor(v3, 8);
;             v0 = lo8 ? (v0 * cr - p0 * sr) : (v0 * cr + p0 * sr);
;             v1 = lo8 ? (v1 * cc - p1 * sc) : (v1 * cc + p1 * sc);
;             v2 = lo8 ? (v2 * cr - p2 * sr) : (v2 * cr + p2 * sr);
;             v3 = lo8 ? (v3 * cc - p3 * sc) : (v3 * cc + p3 * sc);
;           }
;           const unsigned u01 = pack2(v0, v1), u23 = pack2(v2, v3);
;           if (kind == 1) {
;             Tl[(0 * 16 + r) * 72 + rowl] = (u16)u01;
;             Tl[(1 * 16 + r) * 72 + rowl] = (u16)(u01 >> 16);
;             Tl[(2 * 16 + r) * 72 + rowl] = (u16)u23;
;             Tl[(3 * 16 + r) * 72 + rowl] = (u16)(u23 >> 16);
;           } else if (tr == 2) {
;             Tl[rowl * 72 + 0 * 16 + r] = f2h(v0);
;             Tl[rowl * 72 + 1 * 16 + r] = f2h(v1);
;             Tl[rowl * 72 + 2 * 16 + r] = f2h(v2);
;             Tl[rowl * 72 + 3 * 16 + r] = f2h(v3);
;           } else {
;             Tl[rowl * 72 + 0 * 16 + r] = (u16)u01;
;             Tl[rowl * 72 + 1 * 16 + r] = (u16)(u01 >> 16);
;             Tl[rowl * 72 + 2 * 16 + r] = (u16)u23;
;             Tl[rowl * 72 + 3 * 16 + r] = (u16)(u23 >> 16);
;           }
;         }
;       }
;       __builtin_amdgcn_fence(__ATOMIC_RELEASE, "wavefront");
;       u16* dh = (kind == 1) ? dst + hf * 64 : dst + (size_t)(hf * 64) * rstride;
; #pragma unroll
;       for (int i = 0; i < 8; ++i) {
;         const int c = lane + i * 64;
;         const int row = c >> 3, cc = c & 7;
;         uint4 v = *(const uint4*)&Tl[row * 72 + cc * 8];
;         *(uint4*)(dh + (size_t)row * rstride + cc * 8) = v;
;       }
	v_mul_f32_dpp v183, v106, v220 row_ror:8 row_mask:0xf bank_mask:0xf
	v_mul_f32_dpp v184, v110, v177 row_ror:8 row_mask:0xf bank_mask:0xf
	v_mul_f32_dpp v185, v114, v220 row_ror:8 row_mask:0xf bank_mask:0xf
	v_fma_f32 v186, v102, v176, v182
	v_fma_f32 v187, v106, v246, v183
	v_fma_f32 v188, v110, v176, v184
	v_fma_f32 v189, v114, v246, v185
	v_cvt_pk_bf16_f32 v192, v186, v187
	v_cvt_pk_bf16_f32 v193, v188, v189
	ds_write_b16 v170, v192 offset:4608
	ds_write_b16_d16_hi v170, v192 offset:4640
	ds_write_b16 v170, v193 offset:4672
	ds_write_b16_d16_hi v170, v193 offset:4704
	v_mul_f32_dpp v182, v103, v177 row_ror:8 row_mask:0xf bank_mask:0xf
	v_mul_f32_dpp v183, v107, v221 row_ror:8 row_mask:0xf bank_mask:0xf
	v_mul_f32_dpp v184, v111, v177 row_ror:8 row_mask:0xf bank_mask:0xf
	v_mul_f32_dpp v185, v115, v221 row_ror:8 row_mask:0xf bank_mask:0xf
	v_fma_f32 v186, v103, v176, v182
	v_fma_f32 v187, v107, v247, v183
	v_fma_f32 v188, v111, v176, v184
	v_fma_f32 v189, v115, v247, v185
	v_cvt_pk_bf16_f32 v192, v186, v187
	v_cvt_pk_bf16_f32 v193, v188, v189
	ds_write_b16 v170, v192 offset:4752
	ds_write_b16_d16_hi v170, v192 offset:4784
	ds_write_b16 v170, v193 offset:4816
	ds_write_b16_d16_hi v170, v193 offset:4848
	v_mul_f32_dpp v182, v104, v177 row_ror:8 row_mask:0xf bank_mask:0xf
	v_mul_f32_dpp v183, v108, v222 row_ror:8 row_mask:0xf bank_mask:0xf
	v_mul_f32_dpp v184, v112, v177 row_ror:8 row_mask:0xf bank_mask:0xf
	v_mul_f32_dpp v185, v116, v222 row_ror:8 row_mask:0xf bank_mask:0xf
	v_fma_f32 v186, v104, v176, v182
	v_fma_f32 v187, v108, v248, v183
	v_fma_f32 v188, v112, v176, v184
	v_fma_f32 v189, v116, v248, v185
	v_cvt_pk_bf16_f32 v192, v186, v187
	v_cvt_pk_bf16_f32 v193, v188, v189
	ds_write_b16 v170, v192 offset:4896
	ds_write_b16_d16_hi v170, v192 offset:4928
	ds_write_b16 v170, v193 offset:4960
	ds_write_b16_d16_hi v170, v193 offset:4992
	v_mul_f32_dpp v182, v105, v177 row_ror:8 row_mask:0xf bank_mask:0xf
	v_mul_f32_dpp v183, v109, v223 row_ror:8 row_mask:0xf bank_mask:0xf
	v_mul_f32_dpp v184, v113, v177 row_ror:8 row_mask:0xf bank_mask:0xf
	v_mul_f32_dpp v185, v117, v223 row_ror:8 row_mask:0xf bank_mask:0xf
	v_fma_f32 v186, v105, v176, v182
	v_fma_f32 v187, v109, v249, v183
	v_fma_f32 v188, v113, v176, v184
	v_fma_f32 v189, v117, v249, v185
	v_cvt_pk_bf16_f32 v192, v186, v187
	v_cvt_pk_bf16_f32 v193, v188, v189
	ds_write_b16 v170, v192 offset:5040
	ds_write_b16_d16_hi v170, v192 offset:5072
	ds_write_b16 v170, v193 offset:5104
	ds_write_b16_d16_hi v170, v193 offset:5136
	v_mul_f32_dpp v182, v118, v177 row_ror:8 row_mask:0xf bank_mask:0xf
	v_mul_f32_dpp v183, v122, v234 row_ror:8 row_mask:0xf bank_mask:0xf
	v_mul_f32_dpp v184, v126, v177 row_ror:8 row_mask:0xf bank_mask:0xf
	v_mul_f32_dpp v185, v2, v234 row_ror:8 row_mask:0xf bank_mask:0xf
	v_fma_f32 v186, v118, v176, v182
	v_fma_f32 v187, v122, v250, v183
	v_fma_f32 v188, v126, v176, v184
	v_fma_f32 v189, v2, v250, v185
	v_cvt_pk_bf16_f32 v192, v186, v187
	v_cvt_pk_bf16_f32 v193, v188, v189
	ds_write_b16 v170, v192 offset:6912
	ds_write_b16_d16_hi v170, v192 offset:6944
	ds_write_b16 v170, v193 offset:6976
	ds_write_b16_d16_hi v170, v193 offset:7008
	v_mul_f32_dpp v182, v119, v177 row_ror:8 row_mask:0xf bank_mask:0xf
	v_mul_f32_dpp v183, v123, v235 row_ror:8 row_mask:0xf bank_mask:0xf
	v_mul_f32_dpp v184, v127, v177 row_ror:8 row_mask:0xf bank_mask:0xf
	v_mul_f32_dpp v185, v3, v235 row_ror:8 row_mask:0xf bank_mask:0xf
	v_fma_f32 v186, v119, v176, v182
	v_fma_f32 v187, v123, v251, v183
	v_fma_f32 v188, v127, v176, v184
	v_fma_f32 v189, v3, v251, v185
	v_cvt_pk_bf16_f32 v192, v186, v187
	v_cvt_pk_bf16_f32 v193, v188, v189
	ds_write_b16 v170, v192 offset:7056
	ds_write_b16_d16_hi v170, v192 offset:7088
	ds_write_b16 v170, v193 offset:7120
	ds_write_b16_d16_hi v170, v193 offset:7152
	v_mul_f32_dpp v182, v120, v177 row_ror:8 row_mask:0xf bank_mask:0xf
	v_mul_f32_dpp v183, v124, v236 row_ror:8 row_mask:0xf bank_mask:0xf
	v_mul_f32_dpp v184, v128, v177 row_ror:8 row_mask:0xf bank_mask:0xf
	v_mul_f32_dpp v185, v4, v236 row_ror:8 row_mask:0xf bank_mask:0xf
	v_fma_f32 v186, v120, v176, v182
	v_fma_f32 v187, v124, v252, v183
	v_fma_f32 v188, v128, v176, v184
	v_fma_f32 v189, v4, v252, v185
	v_cvt_pk_bf16_f32 v192, v186, v187
	v_cvt_pk_bf16_f32 v193, v188, v189
	ds_write_b16 v170, v192 offset:7200
	ds_write_b16_d16_hi v170, v192 offset:7232
	ds_write_b16 v170, v193 offset:7264
	ds_write_b16_d16_hi v170, v193 offset:7296
	v_mul_f32_dpp v182, v121, v177 row_ror:8 row_mask:0xf bank_mask:0xf
	v_mul_f32_dpp v183, v125, v237 row_ror:8 row_mask:0xf bank_mask:0xf
	v_mul_f32_dpp v184, v129, v177 row_ror:8 row_mask:0xf bank_mask:0xf
	v_mul_f32_dpp v185, v5, v237 row_ror:8 row_mask:0xf bank_mask:0xf
	v_fma_f32 v186, v121, v176, v182
	v_fma_f32 v187, v125, v253, v183
	v_fma_f32 v188, v129, v176, v184
	v_fma_f32 v189, v5, v253, v185
	v_cvt_pk_bf16_f32 v192, v186, v187
	v_cvt_pk_bf16_f32 v193, v188, v189
	ds_write_b16 v170, v192 offset:7344
	ds_write_b16_d16_hi v170, v192 offset:7376
	ds_write_b16 v170, v193 offset:7408
	ds_write_b16_d16_hi v170, v193 offset:7440
	ds_read_b128 v[130:133], v171 offset:0
	ds_read_b128 v[134:137], v171 offset:1152
	ds_read_b128 v[138:141], v171 offset:2304
	ds_read_b128 v[142:145], v171 offset:3456
	ds_read_b128 v[146:149], v171 offset:4608
	ds_read_b128 v[150:153], v171 offset:5760
	ds_read_b128 v[154:157], v171 offset:6912
	ds_read_b128 v[158:161], v171 offset:8064
	s_waitcnt lgkmcnt(7)
	global_store_dwordx4 v172, v[130:133], s[44:45] offset:0 sc1
	s_waitcnt lgkmcnt(6)
	global_store_dwordx4 v172, v[134:137], s[44:45] offset:1024 sc1
	s_waitcnt lgkmcnt(5)
	global_store_dwordx4 v172, v[138:141], s[44:45] offset:2048 sc1
	s_waitcnt lgkmcnt(4)
	global_store_dwordx4 v172, v[142:145], s[44:45] offset:3072 sc1
	s_waitcnt lgkmcnt(3)
	global_store_dwordx4 v172, v[146:149], s[62:63] offset:0 sc1
	s_waitcnt lgkmcnt(2)
	global_store_dwordx4 v172, v[150:153], s[62:63] offset:1024 sc1
	s_waitcnt lgkmcnt(1)
	global_store_dwordx4 v172, v[154:157], s[62:63] offset:2048 sc1
	s_waitcnt lgkmcnt(0)
	global_store_dwordx4 v172, v[158:161], s[62:63] offset:3072 sc1
	s_branch .Lfe_done
; template <int EPI>
; DI void gemm_phase(const P& p, int l, const u16* __restrict__ A, const u16* __restrict__ Bt, int mpx, char* lds) {
;     ...
;     const float* gw = (cb < 1280 ? p.ga_qn : p.ga_kn) + l * 64;
;     float gv0 = 1.f, gv1 = 1.f, gv2 = 1.f, gv3 = 1.f;
;     if (donorm) { gv0 = gw[r]; gv1 = gw[16 + r]; gv2 = gw[32 + r]; gv3 = gw[48 + r]; }
;     const bool dorope = (tr == 3) && !isctx;
;     const float invf64 = exp2f(-13.287712379549449f * (float)r * (1.f / 16.f));
;     const float invf32 = exp2f(-13.287712379549449f * (float)(r & 7) * (1.f / 8.f));
;     ...
;             if (dorope) {
;               float sr, cr, sc, cc;
;               sincos_rev((float)(s >> 6) * invf64, sr, cr);
;               sincos_rev((float)(s & 63) * invf64, sc, cc);
.Lfe_k0_normrope:
	s_cmp_lt_u32 s43, 20
	s_movk_i32 s70, 0x68
	s_cselect_b32 s70, 0x60, s70
	s_add_u32 s70, s96, s70
	s_addc_u32 s71, s97, 0
	s_load_dwordx2 s[70:71], s[70:71], 0x0
	v_and_b32_e32 v0, 15, v226
	v_lshlrev_b32_e32 v0, 2, v0
	v_mov_b32_e32 v173, 0x358637bd
	s_waitcnt lgkmcnt(0)
	s_lshl_b32 s63, s52, 2
	s_add_u32 s70, s70, s63
	s_addc_u32 s71, s71, 0
	global_load_dword v178, v0, s[70:71] offset:0
	global_load_dword v179, v0, s[70:71] offset:64
	global_load_dword v180, v0, s[70:71] offset:128
	global_load_dword v181, v0, s[70:71] offset:192
	v_and_b32_e32 v0, 15, v226
	v_cvt_f32_ubyte0_e32 v0, v0
	v_mul_f32_e32 v0, 0xc1549a78, v0
	v_mul_f32_e32 v0, 0x3d800000, v0
	v_exp_f32_e32 v174, v0
	v_lshrrev_b32_e32 v0, 4, v226
	v_lshlrev_b32_e32 v0, 2, v0
	v_add_u32_e32 v182, 0, v0
	v_cvt_f32_i32_e32 v182, v182
	v_mul_f32_e32 v182, v174, v182
	v_mul_f32_e32 v183, 0.15915494, v182
	v_rndne_f32_e32 v183, v183
	v_fma_f32 v183, v182, 0.15915494, -v183
	v_sin_f32_e32 v212, v183
	v_cos_f32_e32 v238, v183
	v_add_u32_e32 v182, 1, v0
	v_cvt_f32_i32_e32 v182, v182
	v_mul_f32_e32 v182, v174, v182
	v_mul_f32_e32 v183, 0.15915494, v182
	v_rndne_f32_e32 v183, v183
	v_fma_f32 v183, v182, 0.15915494, -v183
	v_sin_f32_e32 v213, v183
	v_cos_f32_e32 v239, v183
	v_add_u32_e32 v182, 2, v0
	v_cvt_f32_i32_e32 v182, v182
	v_mul_f32_e32 v182, v174, v182
	v_mul_f32_e32 v183, 0.15915494, v182
	v_rndne_f32_e32 v183, v183
	v_fma_f32 v183, v182, 0.15915494, -v183
	v_sin_f32_e32 v214, v183
	v_cos_f32_e32 v240, v183
	v_add_u32_e32 v182, 3, v0
	v_cvt_f32_i32_e32 v182, v182
	v_mul_f32_e32 v182, v174, v182
	v_mul_f32_e32 v183, 0.15915494, v182
	v_rndne_f32_e32 v183, v183
	v_fma_f32 v183, v182, 0.15915494, -v183
	v_sin_f32_e32 v215, v183
	v_cos_f32_e32 v241, v183
	v_add_u32_e32 v182, 16, v0
	v_cvt_f32_i32_e32 v182, v182
	v_mul_f32_e32 v182, v174, v182
	v_mul_f32_e32 v183, 0.15915494, v182
	v_rndne_f32_e32 v183, v183
	v_fma_f32 v183, v182, 0.15915494, -v183
	v_sin_f32_e32 v216, v183
	v_cos_f32_e32 v242, v183
	v_add_u32_e32 v182, 17, v0
	v_cvt_f32_i32_e32 v182, v182
	v_mul_f32_e32 v182, v174, v182
	v_mul_f32_e32 v183, 0.15915494, v182
	v_rndne_f32_e32 v183, v183
	v_fma_f32 v183, v182, 0.15915494, -v183
	v_sin_f32_e32 v217, v183
	v_cos_f32_e32 v243, v183
	v_add_u32_e32 v182, 18, v0
	v_cvt_f32_i32_e32 v182, v182
	v_mul_f32_e32 v182, v174, v182
	v_mul_f32_e32 v183, 0.15915494, v182
	v_rndne_f32_e32 v183, v183
	v_fma_f32 v183, v182, 0.15915494, -v183
	v_sin_f32_e32 v218, v183
	v_cos_f32_e32 v244, v183
	v_add_u32_e32 v182, 19, v0
	v_cvt_f32_i32_e32 v182, v182
	v_mul_f32_e32 v182, v174, v182
	v_mul_f32_e32 v183, 0.15915494, v182
	v_rndne_f32_e32 v183, v183
	v_fma_f32 v183, v182, 0.15915494, -v183
	v_sin_f32_e32 v219, v183
	v_cos_f32_e32 v245, v183
	v_add_u32_e32 v182, 32, v0
	v_cvt_f32_i32_e32 v182, v182
	v_mul_f32_e32 v182, v174, v182
	v_mul_f32_e32 v183, 0.15915494, v182
	v_rndne_f32_e32 v183, v183
	v_fma_f32 v183, v182, 0.15915494, -v183
	v_sin_f32_e32 v220, v183
	v_cos_f32_e32 v246, v183
	v_add_u32_e32 v182, 33, v0
	v_cvt_f32_i32_e32 v182, v182
	v_mul_f32_e32 v182, v174, v182
	v_mul_f32_e32 v183, 0.15915494, v182
	v_rndne_f32_e32 v183, v183
	v_fma_f32 v183, v182, 0.15915494, -v183
	v_sin_f32_e32 v221, v183
	v_cos_f32_e32 v247, v183
	v_add_u32_e32 v182, 34, v0
	v_cvt_f32_i32_e32 v182, v182
	v_mul_f32_e32 v182, v174, v182
	v_mul_f32_e32 v183, 0.15915494, v182
	v_rndne_f32_e32 v183, v183
	v_fma_f32 v183, v182, 0.15915494, -v183
	v_sin_f32_e32 v222, v183
	v_cos_f32_e32 v248, v183
	v_add_u32_e32 v182, 35, v0
	v_cvt_f32_i32_e32 v182, v182
	v_mul_f32_e32 v182, v174, v182
	v_mul_f32_e32 v183, 0.15915494, v182
	v_rndne_f32_e32 v183, v183
	v_fma_f32 v183, v182, 0.15915494, -v183
	v_sin_f32_e32 v223, v183
	v_cos_f32_e32 v249, v183
	v_add_u32_e32 v182, 48, v0
	v_cvt_f32_i32_e32 v182, v182
	v_mul_f32_e32 v182, v174, v182
	v_mul_f32_e32 v183, 0.15915494, v182
	v_rndne_f32_e32 v183, v183
	v_fma_f32 v183, v182, 0.15915494, -v183
	v_sin_f32_e32 v234, v183
	v_cos_f32_e32 v250, v183
	v_add_u32_e32 v182, 49, v0
	v_cvt_f32_i32_e32 v182, v182
	v_mul_f32_e32 v182, v174, v182
	v_mul_f32_e32 v183, 0.15915494, v182
	v_rndne_f32_e32 v183, v183
	v_fma_f32 v183, v182, 0.15915494, -v183
	v_sin_f32_e32 v235, v183
	v_cos_f32_e32 v251, v183
	v_add_u32_e32 v182, 50, v0
	v_cvt_f32_i32_e32 v182, v182
	v_mul_f32_e32 v182, v174, v182
	v_mul_f32_e32 v183, 0.15915494, v182
	v_rndne_f32_e32 v183, v183
	v_fma_f32 v183, v182, 0.15915494, -v183
	v_sin_f32_e32 v236, v183
	v_cos_f32_e32 v252, v183
	v_add_u32_e32 v182, 51, v0
	v_cvt_f32_i32_e32 v182, v182
	v_mul_f32_e32 v182, v174, v182
	v_mul_f32_e32 v183, 0.15915494, v182
	v_rndne_f32_e32 v183, v183
	v_fma_f32 v183, v182, 0.15915494, -v183
	v_sin_f32_e32 v237, v183
	v_cos_f32_e32 v253, v183
	s_waitcnt vmcnt(0)
; template <int EPI>
; DI void gemm_phase(const P& p, int l, const u16* __restrict__ A, const u16* __restrict__ Bt, int mpx, char* lds) {
;     ...
;           } else if (tr == 3) {
;             if (donorm) {
;               float ss = v0 * v0 + v1 * v1 + v2 * v2 + v3 * v3;
;               ss += __shfl_xor(ss, 1);
;               ss += __shfl_xor(ss, 2);
;               ss += __shfl_xor(ss, 4);
;               ss += __shfl_xor(ss, 8);
;               const float inv = rsqrtf(ss * (1.f / 64.f) + 1e-6f);
;               v0 *= inv * gv0; v1 *= inv * gv1; v2 *= inv * gv2; v3 *= inv * gv3;
;             }
;             if (dorope) {
;               float sr, cr, sc, cc;
;               sincos_rev((float)(s >> 6) * invf64, sr, cr);
;               sincos_rev((float)(s & 63) * invf64, sc, cc);
;               const float a1 = v0, a2 = v1, b1 = v2, b2 = v3;
;               v0 = a1 * cr - a2 * sr;
;               v1 = a2 * cr + a1 * sr;
;               v2 = b1 * cc - b2 * sc;
;               v3 = b2 * cc + b1 * sc;
;             }
;           } else if (tr == 4) {
;             float sr, cr, sc, cc;
;             sincos_rev((float)(s >> 6) * invf32, sr, cr);
;             sincos_rev((float)(s & 63) * invf32, sc, cc);
;             const float p0 = __shfl_xor(v0, 8), p1 = __shfl_xor(v1, 8), p2 = __shfl_xor(v2, 8), p3 = __shfl_xor(v3, 8);
;             v0 = lo8 ? (v0 * cr - p0 * sr) : (v0 * cr + p0 * sr);
;             v1 = lo8 ? (v1 * cc - p1 * sc) : (v1 * cc + p1 * sc);
;             v2 = lo8 ? (v2 * cr - p2 * sr) : (v2 * cr + p2 * sr);
;             v3 = lo8 ? (v3 * cc - p3 * sc) : (v3 * cc + p3 * sc);
;           }
;           const unsigned u01 = pack2(v0, v1), u23 = pack2(v2, v3);
;           if (kind == 1) {
;             Tl[(0 * 16 + r) * 72 + rowl] = (u16)u01;
;             Tl[(1 * 16 + r) * 72 + rowl] = (u16)(u01 >> 16);
;             Tl[(2 * 16 + r) * 72 + rowl] = (u16)u23;
;             Tl[(3 * 16 + r) * 72 + rowl] = (u16)(u23 >> 16);
;           } else if (tr == 2) {
;             Tl[rowl * 72 + 0 * 16 + r] = f2h(v0);
;             Tl[rowl * 72 + 1 * 16 + r] = f2h(v1);
;             Tl[rowl * 72 + 2 * 16 + r] = f2h(v2);
;             Tl[rowl * 72 + 3 * 16 + r] = f2h(v3);
;           } else {
;             Tl[rowl * 72 + 0 * 16 + r] = (u16)u01;
;             Tl[rowl * 72 + 1 * 16 + r] = (u16)(u01 >> 16);
;             Tl[rowl * 72 + 2 * 16 + r] = (u16)u23;
	s_add_u32 s62, s44, 0x1000
	s_addc_u32 s63, s45, 0
	s_lshr_b32 s70, s69, 6
	v_cvt_f32_i32_e32 v182, s70
	v_mul_f32_e32 v182, v174, v182
	v_mul_f32_e32 v183, 0.15915494, v182
	v_rndne_f32_e32 v183, v183
	v_fma_f32 v183, v182, 0.15915494, -v183
	v_sin_f32_e32 v175, v183
	v_cos_f32_e32 v176, v183
	v_mul_f32_e32 v182, v6, v6
	v_mul_f32_e32 v183, v10, v10
	v_mul_f32_e32 v184, v14, v14
	v_mul_f32_e32 v185, v18, v18
	v_add_f32_e32 v186, v182, v183
	v_add_f32_e32 v186, v186, v184
	v_add_f32_e32 v186, v186, v185
	s_nop 1
	v_add_f32_dpp v186, v186, v186 quad_perm:[1,0,3,2] row_mask:0xf bank_mask:0xf
	s_nop 1
	v_add_f32_dpp v186, v186, v186 quad_perm:[2,3,0,1] row_mask:0xf bank_mask:0xf
	s_nop 1
	v_add_f32_dpp v186, v186, v186 row_half_mirror row_mask:0xf bank_mask:0xf
	s_nop 1
	v_add_f32_dpp v186, v186, v186 row_mirror row_mask:0xf bank_mask:0xf
	v_fmamk_f32 v186, v186, 0x3c800000, v173
	v_rsq_f32_e32 v186, v186
	s_nop 0
	v_mul_f32_e32 v187, v178, v186
	v_mul_f32_e32 v188, v179, v186
	v_mul_f32_e32 v189, v180, v186
	v_mul_f32_e32 v190, v181, v186
	v_mul_f32_e32 v182, v6, v187
	v_mul_f32_e32 v183, v10, v188
	v_mul_f32_e32 v184, v14, v189
	v_mul_f32_e32 v185, v18, v190
	v_mul_f32_e32 v186, v175, v183
	v_mul_f32_e32 v187, v176, v183
	v_fma_f32 v188, v176, v182, -v186
	v_fma_f32 v189, v175, v182, v187
	v_mul_f32_e32 v186, v212, v185
	v_mul_f32_e32 v187, v238, v185
	v_fma_f32 v190, v238, v184, -v186
	v_fma_f32 v191, v212, v184, v187
	v_cvt_pk_bf16_f32 v192, v188, v189
	v_cvt_pk_bf16_f32 v193, v190, v191
	ds_write_b16 v170, v192 offset:0
	ds_write_b16_d16_hi v170, v192 offset:32
	ds_write_b16 v170, v193 offset:64
	ds_write_b16_d16_hi v170, v193 offset:96
	v_mul_f32_e32 v182, v7, v7
	v_mul_f32_e32 v183, v11, v11
	v_mul_f32_e32 v184, v15, v15
	v_mul_f32_e32 v185, v19, v19
	v_add_f32_e32 v186, v182, v183
	v_add_f32_e32 v186, v186, v184
	v_add_f32_e32 v186, v186, v185
	s_nop 1
	v_add_f32_dpp v186, v186, v186 quad_perm:[1,0,3,2] row_mask:0xf bank_mask:0xf
	s_nop 1
	v_add_f32_dpp v186, v186, v186 quad_perm:[2,3,0,1] row_mask:0xf bank_mask:0xf
	s_nop 1
	v_add_f32_dpp v186, v186, v186 row_half_mirror row_mask:0xf bank_mask:0xf
	s_nop 1
	v_add_f32_dpp v186, v186, v186 row_mirror row_mask:0xf bank_mask:0xf
	v_fmamk_f32 v186, v186, 0x3c800000, v173
	v_rsq_f32_e32 v186, v186
	s_nop 0
	v_mul_f32_e32 v187, v178, v186
	v_mul_f32_e32 v188, v179, v186
	v_mul_f32_e32 v189, v180, v186
	v_mul_f32_e32 v190, v181, v186
	v_mul_f32_e32 v182, v7, v187
	v_mul_f32_e32 v183, v11, v188
	v_mul_f32_e32 v184, v15, v189
	v_mul_f32_e32 v185, v19, v190
	v_mul_f32_e32 v186, v175, v183
	v_mul_f32_e32 v187, v176, v183
	v_fma_f32 v188, v176, v182, -v186
	v_fma_f32 v189, v175, v182, v187
	v_mul_f32_e32 v186, v213, v185
	v_mul_f32_e32 v187, v239, v185
	v_fma_f32 v190, v239, v184, -v186
	v_fma_f32 v191, v213, v184, v187
	v_cvt_pk_bf16_f32 v192, v188, v189
	v_cvt_pk_bf16_f32 v193, v190, v191
	ds_write_b16 v170, v192 offset:144
	ds_write_b16_d16_hi v170, v192 offset:176
	ds_write_b16 v170, v193 offset:208
	ds_write_b16_d16_hi v170, v193 offset:240
	v_mul_f32_e32 v182, v8, v8
	v_mul_f32_e32 v183, v12, v12
	v_mul_f32_e32 v184, v16, v16
	v_mul_f32_e32 v185, v20, v20
	v_add_f32_e32 v186, v182, v183
	v_add_f32_e32 v186, v186, v184
	v_add_f32_e32 v186, v186, v185
	s_nop 1
	v_add_f32_dpp v186, v186, v186 quad_perm:[1,0,3,2] row_mask:0xf bank_mask:0xf
	s_nop 1
	v_add_f32_dpp v186, v186, v186 quad_perm:[2,3,0,1] row_mask:0xf bank_mask:0xf
	s_nop 1
	v_add_f32_dpp v186, v186, v186 row_half_mirror row_mask:0xf bank_mask:0xf
	s_nop 1
	v_add_f32_dpp v186, v186, v186 row_mirror row_mask:0xf bank_mask:0xf
	v_fmamk_f32 v186, v186, 0x3c800000, v173
	v_rsq_f32_e32 v186, v186
	s_nop 0
	v_mul_f32_e32 v187, v178, v186
	v_mul_f32_e32 v188, v179, v186
	v_mul_f32_e32 v189, v180, v186
	v_mul_f32_e32 v190, v181, v186
	v_mul_f32_e32 v182, v8, v187
	v_mul_f32_e32 v183, v12, v188
	v_mul_f32_e32 v184, v16, v189
	v_mul_f32_e32 v185, v20, v190
	v_mul_f32_e32 v186, v175, v183
	v_mul_f32_e32 v187, v176, v183
	v_fma_f32 v188, v176, v182, -v186
	v_fma_f32 v189, v175, v182, v187
	v_mul_f32_e32 v186, v214, v185
	v_mul_f32_e32 v187, v240, v185
	v_fma_f32 v190, v240, v184, -v186
	v_fma_f32 v191, v214, v184, v187
	v_cvt_pk_bf16_f32 v192, v188, v189
	v_cvt_pk_bf16_f32 v193, v190, v191
	ds_write_b16 v170, v192 offset:288
	ds_write_b16_d16_hi v170, v192 offset:320
	ds_write_b16 v170, v193 offset:352
	ds_write_b16_d16_hi v170, v193 offset:384
	v_mul_f32_e32 v182, v9, v9
	v_mul_f32_e32 v183, v13, v13
	v_mul_f32_e32 v184, v17, v17
	v_mul_f32_e32 v185, v21, v21
	v_add_f32_e32 v186, v182, v183
	v_add_f32_e32 v186, v186, v184
	v_add_f32_e32 v186, v186, v185
	s_nop 1
	v_add_f32_dpp v186, v186, v186 quad_perm:[1,0,3,2] row_mask:0xf bank_mask:0xf
	s_nop 1
	v_add_f32_dpp v186, v186, v186 quad_perm:[2,3,0,1] row_mask:0xf bank_mask:0xf
	s_nop 1
	v_add_f32_dpp v186, v186, v186 row_half_mirror row_mask:0xf bank_mask:0xf
	s_nop 1
	v_add_f32_dpp v186, v186, v186 row_mirror row_mask:0xf bank_mask:0xf
	v_fmamk_f32 v186, v186, 0x3c800000, v173
	v_rsq_f32_e32 v186, v186
	s_nop 0
	v_mul_f32_e32 v187, v178, v186
	v_mul_f32_e32 v188, v179, v186
	v_mul_f32_e32 v189, v180, v186
	v_mul_f32_e32 v190, v181, v186
	v_mul_f32_e32 v182, v9, v187
	v_mul_f32_e32 v183, v13, v188
	v_mul_f32_e32 v184, v17, v189
	v_mul_f32_e32 v185, v21, v190
	v_mul_f32_e32 v186, v175, v183
	v_mul_f32_e32 v187, v176, v183
	v_fma_f32 v188, v176, v182, -v186
	v_fma_f32 v189, v175, v182, v187
	v_mul_f32_e32 v186, v215, v185
	v_mul_f32_e32 v187, v241, v185
	v_fma_f32 v190, v241, v184, -v186
	v_fma_f32 v191, v215, v184, v187
	v_cvt_pk_bf16_f32 v192, v188, v189
	v_cvt_pk_bf16_f32 v193, v190, v191
; template <int EPI>
; DI void gemm_phase(const P& p, int l, const u16* __restrict__ A, const u16* __restrict__ Bt, int mpx, char* lds) {
;     ...
;           } else if (tr == 3) {
;             if (donorm) {
;               float ss = v0 * v0 + v1 * v1 + v2 * v2 + v3 * v3;
;               ss += __shfl_xor(ss, 1);
;               ss += __shfl_xor(ss, 2);
;               ss += __shfl_xor(ss, 4);
;               ss += __shfl_xor(ss, 8);
;               const float inv = rsqrtf(ss * (1.f / 64.f) + 1e-6f);
;               v0 *= inv * gv0; v1 *= inv * gv1; v2 *= inv * gv2; v3 *= inv * gv3;
;             }
;             if (dorope) {
;               float sr, cr, sc, cc;
;               sincos_rev((float)(s >> 6) * invf64, sr, cr);
;               sincos_rev((float)(s & 63) * invf64, sc, cc);
;               const float a1 = v0, a2 = v1, b1 = v2, b2 = v3;
;               v0 = a1 * cr - a2 * sr;
;               v1 = a2 * cr + a1 * sr;
;               v2 = b1 * cc - b2 * sc;
;               v3 = b2 * cc + b1 * sc;
;             }
;           } else if (tr == 4) {
;             float sr, cr, sc, cc;
;             sincos_rev((float)(s >> 6) * invf32, sr, cr);
;             sincos_rev((float)(s & 63) * invf32, sc, cc);
;             const float p0 = __shfl_xor(v0, 8), p1 = __shfl_xor(v1, 8), p2 = __shfl_xor(v2, 8), p3 = __shfl_xor(v3, 8);
;             v0 = lo8 ? (v0 * cr - p0 * sr) : (v0 * cr + p0 * sr);
;             v1 = lo8 ? (v1 * cc - p1 * sc) : (v1 * cc + p1 * sc);
;             v2 = lo8 ? (v2 * cr - p2 * sr) : (v2 * cr + p2 * sr);
;             v3 = lo8 ? (v3 * cc - p3 * sc) : (v3 * cc + p3 * sc);
;           }
;           const unsigned u01 = pack2(v0, v1), u23 = pack2(v2, v3);
;           if (kind == 1) {
;             Tl[(0 * 16 + r) * 72 + rowl] = (u16)u01;
;             Tl[(1 * 16 + r) * 72 + rowl] = (u16)(u01 >> 16);
;             Tl[(2 * 16 + r) * 72 + rowl] = (u16)u23;
;             Tl[(3 * 16 + r) * 72 + rowl] = (u16)(u23 >> 16);
;           } else if (tr == 2) {
;             Tl[rowl * 72 + 0 * 16 + r] = f2h(v0);
;             Tl[rowl * 72 + 1 * 16 + r] = f2h(v1);
;             Tl[rowl * 72 + 2 * 16 + r] = f2h(v2);
;             Tl[rowl * 72 + 3 * 16 + r] = f2h(v3);
;           } else {
;             Tl[rowl * 72 + 0 * 16 + r] = (u16)u01;
;             Tl[rowl * 72 + 1 * 16 + r] = (u16)(u01 >> 16);
;             Tl[rowl * 72 + 2 * 16 + r] = (u16)u23;
	ds_write_b16 v170, v192 offset:432
	ds_write_b16_d16_hi v170, v192 offset:464
	ds_write_b16 v170, v193 offset:496
	ds_write_b16_d16_hi v170, v193 offset:528
	v_mul_f32_e32 v182, v22, v22
	v_mul_f32_e32 v183, v26, v26
	v_mul_f32_e32 v184, v30, v30
	v_mul_f32_e32 v185, v34, v34
	v_add_f32_e32 v186, v182, v183
	v_add_f32_e32 v186, v186, v184
	v_add_f32_e32 v186, v186, v185
	s_nop 1
	v_add_f32_dpp v186, v186, v186 quad_perm:[1,0,3,2] row_mask:0xf bank_mask:0xf
	s_nop 1
	v_add_f32_dpp v186, v186, v186 quad_perm:[2,3,0,1] row_mask:0xf bank_mask:0xf
	s_nop 1
	v_add_f32_dpp v186, v186, v186 row_half_mirror row_mask:0xf bank_mask:0xf
	s_nop 1
	v_add_f32_dpp v186, v186, v186 row_mirror row_mask:0xf bank_mask:0xf
	v_fmamk_f32 v186, v186, 0x3c800000, v173
	v_rsq_f32_e32 v186, v186
	s_nop 0
	v_mul_f32_e32 v187, v178, v186
	v_mul_f32_e32 v188, v179, v186
	v_mul_f32_e32 v189, v180, v186
	v_mul_f32_e32 v190, v181, v186
	v_mul_f32_e32 v182, v22, v187
	v_mul_f32_e32 v183, v26, v188
	v_mul_f32_e32 v184, v30, v189
	v_mul_f32_e32 v185, v34, v190
	v_mul_f32_e32 v186, v175, v183
	v_mul_f32_e32 v187, v176, v183
	v_fma_f32 v188, v176, v182, -v186
	v_fma_f32 v189, v175, v182, v187
	v_mul_f32_e32 v186, v216, v185
	v_mul_f32_e32 v187, v242, v185
	v_fma_f32 v190, v242, v184, -v186
	v_fma_f32 v191, v216, v184, v187
	v_cvt_pk_bf16_f32 v192, v188, v189
	v_cvt_pk_bf16_f32 v193, v190, v191
	ds_write_b16 v170, v192 offset:2304
	ds_write_b16_d16_hi v170, v192 offset:2336
	ds_write_b16 v170, v193 offset:2368
	ds_write_b16_d16_hi v170, v193 offset:2400
	v_mul_f32_e32 v182, v23, v23
	v_mul_f32_e32 v183, v27, v27
	v_mul_f32_e32 v184, v31, v31
	v_mul_f32_e32 v185, v35, v35
	v_add_f32_e32 v186, v182, v183
	v_add_f32_e32 v186, v186, v184
	v_add_f32_e32 v186, v186, v185
	s_nop 1
	v_add_f32_dpp v186, v186, v186 quad_perm:[1,0,3,2] row_mask:0xf bank_mask:0xf
	s_nop 1
	v_add_f32_dpp v186, v186, v186 quad_perm:[2,3,0,1] row_mask:0xf bank_mask:0xf
	s_nop 1
	v_add_f32_dpp v186, v186, v186 row_half_mirror row_mask:0xf bank_mask:0xf
	s_nop 1
	v_add_f32_dpp v186, v186, v186 row_mirror row_mask:0xf bank_mask:0xf
	v_fmamk_f32 v186, v186, 0x3c800000, v173
	v_rsq_f32_e32 v186, v186
	s_nop 0
	v_mul_f32_e32 v187, v178, v186
	v_mul_f32_e32 v188, v179, v186
	v_mul_f32_e32 v189, v180, v186
	v_mul_f32_e32 v190, v181, v186
	v_mul_f32_e32 v182, v23, v187
	v_mul_f32_e32 v183, v27, v188
	v_mul_f32_e32 v184, v31, v189
	v_mul_f32_e32 v185, v35, v190
	v_mul_f32_e32 v186, v175, v183
	v_mul_f32_e32 v187, v176, v183
	v_fma_f32 v188, v176, v182, -v186
	v_fma_f32 v189, v175, v182, v187
	v_mul_f32_e32 v186, v217, v185
	v_mul_f32_e32 v187, v243, v185
	v_fma_f32 v190, v243, v184, -v186
	v_fma_f32 v191, v217, v184, v187
	v_cvt_pk_bf16_f32 v192, v188, v189
	v_cvt_pk_bf16_f32 v193, v190, v191
	ds_write_b16 v170, v192 offset:2448
	ds_write_b16_d16_hi v170, v192 offset:2480
	ds_write_b16 v170, v193 offset:2512
	ds_write_b16_d16_hi v170, v193 offset:2544
	v_mul_f32_e32 v182, v24, v24
	v_mul_f32_e32 v183, v28, v28
	v_mul_f32_e32 v184, v32, v32
	v_mul_f32_e32 v185, v36, v36
	v_add_f32_e32 v186, v182, v183
	v_add_f32_e32 v186, v186, v184
	v_add_f32_e32 v186, v186, v185
	s_nop 1
	v_add_f32_dpp v186, v186, v186 quad_perm:[1,0,3,2] row_mask:0xf bank_mask:0xf
	s_nop 1
	v_add_f32_dpp v186, v186, v186 quad_perm:[2,3,0,1] row_mask:0xf bank_mask:0xf
	s_nop 1
	v_add_f32_dpp v186, v186, v186 row_half_mirror row_mask:0xf bank_mask:0xf
	s_nop 1
	v_add_f32_dpp v186, v186, v186 row_mirror row_mask:0xf bank_mask:0xf
	v_fmamk_f32 v186, v186, 0x3c800000, v173
	v_rsq_f32_e32 v186, v186
	s_nop 0
	v_mul_f32_e32 v187, v178, v186
	v_mul_f32_e32 v188, v179, v186
	v_mul_f32_e32 v189, v180, v186
	v_mul_f32_e32 v190, v181, v186
	v_mul_f32_e32 v182, v24, v187
	v_mul_f32_e32 v183, v28, v188
	v_mul_f32_e32 v184, v32, v189
	v_mul_f32_e32 v185, v36, v190
	v_mul_f32_e32 v186, v175, v183
	v_mul_f32_e32 v187, v176, v183
	v_fma_f32 v188, v176, v182, -v186
	v_fma_f32 v189, v175, v182, v187
	v_mul_f32_e32 v186, v218, v185
	v_mul_f32_e32 v187, v244, v185
	v_fma_f32 v190, v244, v184, -v186
	v_fma_f32 v191, v218, v184, v187
	v_cvt_pk_bf16_f32 v192, v188, v189
	v_cvt_pk_bf16_f32 v193, v190, v191
	ds_write_b16 v170, v192 offset:2592
	ds_write_b16_d16_hi v170, v192 offset:2624
	ds_write_b16 v170, v193 offset:2656
	ds_write_b16_d16_hi v170, v193 offset:2688
	v_mul_f32_e32 v182, v25, v25
	v_mul_f32_e32 v183, v29, v29
	v_mul_f32_e32 v184, v33, v33
	v_mul_f32_e32 v185, v37, v37
	v_add_f32_e32 v186, v182, v183
	v_add_f32_e32 v186, v186, v184
	v_add_f32_e32 v186, v186, v185
	s_nop 1
	v_add_f32_dpp v186, v186, v186 quad_perm:[1,0,3,2] row_mask:0xf bank_mask:0xf
	s_nop 1
	v_add_f32_dpp v186, v186, v186 quad_perm:[2,3,0,1] row_mask:0xf bank_mask:0xf
	s_nop 1
	v_add_f32_dpp v186, v186, v186 row_half_mirror row_mask:0xf bank_mask:0xf
	s_nop 1
	v_add_f32_dpp v186, v186, v186 row_mirror row_mask:0xf bank_mask:0xf
	v_fmamk_f32 v186, v186, 0x3c800000, v173
	v_rsq_f32_e32 v186, v186
	s_nop 0
	v_mul_f32_e32 v187, v178, v186
	v_mul_f32_e32 v188, v179, v186
	v_mul_f32_e32 v189, v180, v186
	v_mul_f32_e32 v190, v181, v186
	v_mul_f32_e32 v182, v25, v187
	v_mul_f32_e32 v183, v29, v188
	v_mul_f32_e32 v184, v33, v189
	v_mul_f32_e32 v185, v37, v190
	v_mul_f32_e32 v186, v175, v183
	v_mul_f32_e32 v187, v176, v183
	v_fma_f32 v188, v176, v182, -v186
	v_fma_f32 v189, v175, v182, v187
	v_mul_f32_e32 v186, v219, v185
	v_mul_f32_e32 v187, v245, v185
	v_fma_f32 v190, v245, v184, -v186
	v_fma_f32 v191, v219, v184, v187
	v_cvt_pk_bf16_f32 v192, v188, v189
	v_cvt_pk_bf16_f32 v193, v190, v191
	ds_write_b16 v170, v192 offset:2736
	ds_write_b16_d16_hi v170, v192 offset:2768
	ds_write_b16 v170, v193 offset:2800
; template <int EPI>
; DI void gemm_phase(const P& p, int l, const u16* __restrict__ A, const u16* __restrict__ Bt, int mpx, char* lds) {
;     ...
;           } else if (tr == 3) {
;             if (donorm) {
;               float ss = v0 * v0 + v1 * v1 + v2 * v2 + v3 * v3;
;               ss += __shfl_xor(ss, 1);
;               ss += __shfl_xor(ss, 2);
;               ss += __shfl_xor(ss, 4);
;               ss += __shfl_xor(ss, 8);
;               const float inv = rsqrtf(ss * (1.f / 64.f) + 1e-6f);
;               v0 *= inv * gv0; v1 *= inv * gv1; v2 *= inv * gv2; v3 *= inv * gv3;
;             }
;             if (dorope) {
;               float sr, cr, sc, cc;
;               sincos_rev((float)(s >> 6) * invf64, sr, cr);
;               sincos_rev((float)(s & 63) * invf64, sc, cc);
;               const float a1 = v0, a2 = v1, b1 = v2, b2 = v3;
;               v0 = a1 * cr - a2 * sr;
;               v1 = a2 * cr + a1 * sr;
;               v2 = b1 * cc - b2 * sc;
;               v3 = b2 * cc + b1 * sc;
;             }
;           } else if (tr == 4) {
;             float sr, cr, sc, cc;
;             sincos_rev((float)(s >> 6) * invf32, sr, cr);
;             sincos_rev((float)(s & 63) * invf32, sc, cc);
;             const float p0 = __shfl_xor(v0, 8), p1 = __shfl_xor(v1, 8), p2 = __shfl_xor(v2, 8), p3 = __shfl_xor(v3, 8);
;             v0 = lo8 ? (v0 * cr - p0 * sr) : (v0 * cr + p0 * sr);
;             v1 = lo8 ? (v1 * cc - p1 * sc) : (v1 * cc + p1 * sc);
;             v2 = lo8 ? (v2 * cr - p2 * sr) : (v2 * cr + p2 * sr);
;             v3 = lo8 ? (v3 * cc - p3 * sc) : (v3 * cc + p3 * sc);
;           }
;           const unsigned u01 = pack2(v0, v1), u23 = pack2(v2, v3);
;           if (kind == 1) {
;             Tl[(0 * 16 + r) * 72 + rowl] = (u16)u01;
;             Tl[(1 * 16 + r) * 72 + rowl] = (u16)(u01 >> 16);
;             Tl[(2 * 16 + r) * 72 + rowl] = (u16)u23;
;             Tl[(3 * 16 + r) * 72 + rowl] = (u16)(u23 >> 16);
;           } else if (tr == 2) {
;             Tl[rowl * 72 + 0 * 16 + r] = f2h(v0);
;             Tl[rowl * 72 + 1 * 16 + r] = f2h(v1);
;             Tl[rowl * 72 + 2 * 16 + r] = f2h(v2);
;             Tl[rowl * 72 + 3 * 16 + r] = f2h(v3);
;           } else {
;             Tl[rowl * 72 + 0 * 16 + r] = (u16)u01;
;             Tl[rowl * 72 + 1 * 16 + r] = (u16)(u01 >> 16);
;             Tl[rowl * 72 + 2 * 16 + r] = (u16)u23;
	ds_write_b16_d16_hi v170, v193 offset:2832
	v_mul_f32_e32 v182, v38, v38
	v_mul_f32_e32 v183, v42, v42
	v_mul_f32_e32 v184, v46, v46
	v_mul_f32_e32 v185, v50, v50
	v_add_f32_e32 v186, v182, v183
	v_add_f32_e32 v186, v186, v184
	v_add_f32_e32 v186, v186, v185
	s_nop 1
	v_add_f32_dpp v186, v186, v186 quad_perm:[1,0,3,2] row_mask:0xf bank_mask:0xf
	s_nop 1
	v_add_f32_dpp v186, v186, v186 quad_perm:[2,3,0,1] row_mask:0xf bank_mask:0xf
	s_nop 1
	v_add_f32_dpp v186, v186, v186 row_half_mirror row_mask:0xf bank_mask:0xf
	s_nop 1
	v_add_f32_dpp v186, v186, v186 row_mirror row_mask:0xf bank_mask:0xf
	v_fmamk_f32 v186, v186, 0x3c800000, v173
	v_rsq_f32_e32 v186, v186
	s_nop 0
	v_mul_f32_e32 v187, v178, v186
	v_mul_f32_e32 v188, v179, v186
	v_mul_f32_e32 v189, v180, v186
	v_mul_f32_e32 v190, v181, v186
	v_mul_f32_e32 v182, v38, v187
	v_mul_f32_e32 v183, v42, v188
	v_mul_f32_e32 v184, v46, v189
	v_mul_f32_e32 v185, v50, v190
	v_mul_f32_e32 v186, v175, v183
	v_mul_f32_e32 v187, v176, v183
	v_fma_f32 v188, v176, v182, -v186
	v_fma_f32 v189, v175, v182, v187
	v_mul_f32_e32 v186, v220, v185
	v_mul_f32_e32 v187, v246, v185
	v_fma_f32 v190, v246, v184, -v186
	v_fma_f32 v191, v220, v184, v187
	v_cvt_pk_bf16_f32 v192, v188, v189
	v_cvt_pk_bf16_f32 v193, v190, v191
	ds_write_b16 v170, v192 offset:4608
	ds_write_b16_d16_hi v170, v192 offset:4640
	ds_write_b16 v170, v193 offset:4672
	ds_write_b16_d16_hi v170, v193 offset:4704
	v_mul_f32_e32 v182, v39, v39
	v_mul_f32_e32 v183, v43, v43
	v_mul_f32_e32 v184, v47, v47
	v_mul_f32_e32 v185, v51, v51
	v_add_f32_e32 v186, v182, v183
	v_add_f32_e32 v186, v186, v184
	v_add_f32_e32 v186, v186, v185
	s_nop 1
	v_add_f32_dpp v186, v186, v186 quad_perm:[1,0,3,2] row_mask:0xf bank_mask:0xf
	s_nop 1
	v_add_f32_dpp v186, v186, v186 quad_perm:[2,3,0,1] row_mask:0xf bank_mask:0xf
	s_nop 1
	v_add_f32_dpp v186, v186, v186 row_half_mirror row_mask:0xf bank_mask:0xf
	s_nop 1
	v_add_f32_dpp v186, v186, v186 row_mirror row_mask:0xf bank_mask:0xf
	v_fmamk_f32 v186, v186, 0x3c800000, v173
	v_rsq_f32_e32 v186, v186
	s_nop 0
	v_mul_f32_e32 v187, v178, v186
	v_mul_f32_e32 v188, v179, v186
	v_mul_f32_e32 v189, v180, v186
	v_mul_f32_e32 v190, v181, v186
	v_mul_f32_e32 v182, v39, v187
	v_mul_f32_e32 v183, v43, v188
	v_mul_f32_e32 v184, v47, v189
	v_mul_f32_e32 v185, v51, v190
	v_mul_f32_e32 v186, v175, v183
	v_mul_f32_e32 v187, v176, v183
	v_fma_f32 v188, v176, v182, -v186
	v_fma_f32 v189, v175, v182, v187
	v_mul_f32_e32 v186, v221, v185
	v_mul_f32_e32 v187, v247, v185
	v_fma_f32 v190, v247, v184, -v186
	v_fma_f32 v191, v221, v184, v187
	v_cvt_pk_bf16_f32 v192, v188, v189
	v_cvt_pk_bf16_f32 v193, v190, v191
	ds_write_b16 v170, v192 offset:4752
	ds_write_b16_d16_hi v170, v192 offset:4784
	ds_write_b16 v170, v193 offset:4816
	ds_write_b16_d16_hi v170, v193 offset:4848
	v_mul_f32_e32 v182, v40, v40
	v_mul_f32_e32 v183, v44, v44
	v_mul_f32_e32 v184, v48, v48
	v_mul_f32_e32 v185, v52, v52
	v_add_f32_e32 v186, v182, v183
	v_add_f32_e32 v186, v186, v184
	v_add_f32_e32 v186, v186, v185
	s_nop 1
	v_add_f32_dpp v186, v186, v186 quad_perm:[1,0,3,2] row_mask:0xf bank_mask:0xf
	s_nop 1
	v_add_f32_dpp v186, v186, v186 quad_perm:[2,3,0,1] row_mask:0xf bank_mask:0xf
	s_nop 1
	v_add_f32_dpp v186, v186, v186 row_half_mirror row_mask:0xf bank_mask:0xf
	s_nop 1
	v_add_f32_dpp v186, v186, v186 row_mirror row_mask:0xf bank_mask:0xf
	v_fmamk_f32 v186, v186, 0x3c800000, v173
	v_rsq_f32_e32 v186, v186
	s_nop 0
	v_mul_f32_e32 v187, v178, v186
	v_mul_f32_e32 v188, v179, v186
	v_mul_f32_e32 v189, v180, v186
	v_mul_f32_e32 v190, v181, v186
	v_mul_f32_e32 v182, v40, v187
	v_mul_f32_e32 v183, v44, v188
	v_mul_f32_e32 v184, v48, v189
	v_mul_f32_e32 v185, v52, v190
	v_mul_f32_e32 v186, v175, v183
	v_mul_f32_e32 v187, v176, v183
	v_fma_f32 v188, v176, v182, -v186
	v_fma_f32 v189, v175, v182, v187
	v_mul_f32_e32 v186, v222, v185
	v_mul_f32_e32 v187, v248, v185
	v_fma_f32 v190, v248, v184, -v186
	v_fma_f32 v191, v222, v184, v187
	v_cvt_pk_bf16_f32 v192, v188, v189
	v_cvt_pk_bf16_f32 v193, v190, v191
	ds_write_b16 v170, v192 offset:4896
	ds_write_b16_d16_hi v170, v192 offset:4928
	ds_write_b16 v170, v193 offset:4960
	ds_write_b16_d16_hi v170, v193 offset:4992
	v_mul_f32_e32 v182, v41, v41
	v_mul_f32_e32 v183, v45, v45
	v_mul_f32_e32 v184, v49, v49
	v_mul_f32_e32 v185, v53, v53
	v_add_f32_e32 v186, v182, v183
	v_add_f32_e32 v186, v186, v184
	v_add_f32_e32 v186, v186, v185
	s_nop 1
	v_add_f32_dpp v186, v186, v186 quad_perm:[1,0,3,2] row_mask:0xf bank_mask:0xf
	s_nop 1
	v_add_f32_dpp v186, v186, v186 quad_perm:[2,3,0,1] row_mask:0xf bank_mask:0xf
	s_nop 1
	v_add_f32_dpp v186, v186, v186 row_half_mirror row_mask:0xf bank_mask:0xf
	s_nop 1
	v_add_f32_dpp v186, v186, v186 row_mirror row_mask:0xf bank_mask:0xf
	v_fmamk_f32 v186, v186, 0x3c800000, v173
	v_rsq_f32_e32 v186, v186
	s_nop 0
	v_mul_f32_e32 v187, v178, v186
	v_mul_f32_e32 v188, v179, v186
	v_mul_f32_e32 v189, v180, v186
	v_mul_f32_e32 v190, v181, v186
	v_mul_f32_e32 v182, v41, v187
	v_mul_f32_e32 v183, v45, v188
	v_mul_f32_e32 v184, v49, v189
	v_mul_f32_e32 v185, v53, v190
	v_mul_f32_e32 v186, v175, v183
	v_mul_f32_e32 v187, v176, v183
	v_fma_f32 v188, v176, v182, -v186
	v_fma_f32 v189, v175, v182, v187
	v_mul_f32_e32 v186, v223, v185
	v_mul_f32_e32 v187, v249, v185
	v_fma_f32 v190, v249, v184, -v186
	v_fma_f32 v191, v223, v184, v187
	v_cvt_pk_bf16_f32 v192, v188, v189
	v_cvt_pk_bf16_f32 v193, v190, v191
	ds_write_b16 v170, v192 offset:5040
	ds_write_b16_d16_hi v170, v192 offset:5072
	ds_write_b16 v170, v193 offset:5104
	ds_write_b16_d16_hi v170, v193 offset:5136
	v_mul_f32_e32 v182, v54, v54
	v_mul_f32_e32 v183, v58, v58
; template <int EPI>
; DI void gemm_phase(const P& p, int l, const u16* __restrict__ A, const u16* __restrict__ Bt, int mpx, char* lds) {
;     ...
;           } else if (tr == 3) {
;             if (donorm) {
;               float ss = v0 * v0 + v1 * v1 + v2 * v2 + v3 * v3;
;               ss += __shfl_xor(ss, 1);
;               ss += __shfl_xor(ss, 2);
;               ss += __shfl_xor(ss, 4);
;               ss += __shfl_xor(ss, 8);
;               const float inv = rsqrtf(ss * (1.f / 64.f) + 1e-6f);
;               v0 *= inv * gv0; v1 *= inv * gv1; v2 *= inv * gv2; v3 *= inv * gv3;
;             }
;             if (dorope) {
;               float sr, cr, sc, cc;
;               sincos_rev((float)(s >> 6) * invf64, sr, cr);
;               sincos_rev((float)(s & 63) * invf64, sc, cc);
;               const float a1 = v0, a2 = v1, b1 = v2, b2 = v3;
;               v0 = a1 * cr - a2 * sr;
;               v1 = a2 * cr + a1 * sr;
;               v2 = b1 * cc - b2 * sc;
;               v3 = b2 * cc + b1 * sc;
;             }
;           } else if (tr == 4) {
;             float sr, cr, sc, cc;
;             sincos_rev((float)(s >> 6) * invf32, sr, cr);
;             sincos_rev((float)(s & 63) * invf32, sc, cc);
;             const float p0 = __shfl_xor(v0, 8), p1 = __shfl_xor(v1, 8), p2 = __shfl_xor(v2, 8), p3 = __shfl_xor(v3, 8);
;             v0 = lo8 ? (v0 * cr - p0 * sr) : (v0 * cr + p0 * sr);
;             v1 = lo8 ? (v1 * cc - p1 * sc) : (v1 * cc + p1 * sc);
;             v2 = lo8 ? (v2 * cr - p2 * sr) : (v2 * cr + p2 * sr);
;             v3 = lo8 ? (v3 * cc - p3 * sc) : (v3 * cc + p3 * sc);
;           }
;           const unsigned u01 = pack2(v0, v1), u23 = pack2(v2, v3);
;           if (kind == 1) {
;             Tl[(0 * 16 + r) * 72 + rowl] = (u16)u01;
;             Tl[(1 * 16 + r) * 72 + rowl] = (u16)(u01 >> 16);
;             Tl[(2 * 16 + r) * 72 + rowl] = (u16)u23;
;             Tl[(3 * 16 + r) * 72 + rowl] = (u16)(u23 >> 16);
;           } else if (tr == 2) {
;             Tl[rowl * 72 + 0 * 16 + r] = f2h(v0);
;             Tl[rowl * 72 + 1 * 16 + r] = f2h(v1);
;             Tl[rowl * 72 + 2 * 16 + r] = f2h(v2);
;             Tl[rowl * 72 + 3 * 16 + r] = f2h(v3);
;           } else {
;             Tl[rowl * 72 + 0 * 16 + r] = (u16)u01;
;             Tl[rowl * 72 + 1 * 16 + r] = (u16)(u01 >> 16);
;             Tl[rowl * 72 + 2 * 16 + r] = (u16)u23;
	v_mul_f32_e32 v184, v62, v62
	v_mul_f32_e32 v185, v66, v66
	v_add_f32_e32 v186, v182, v183
	v_add_f32_e32 v186, v186, v184
	v_add_f32_e32 v186, v186, v185
	s_nop 1
	v_add_f32_dpp v186, v186, v186 quad_perm:[1,0,3,2] row_mask:0xf bank_mask:0xf
	s_nop 1
	v_add_f32_dpp v186, v186, v186 quad_perm:[2,3,0,1] row_mask:0xf bank_mask:0xf
	s_nop 1
	v_add_f32_dpp v186, v186, v186 row_half_mirror row_mask:0xf bank_mask:0xf
	s_nop 1
	v_add_f32_dpp v186, v186, v186 row_mirror row_mask:0xf bank_mask:0xf
	v_fmamk_f32 v186, v186, 0x3c800000, v173
	v_rsq_f32_e32 v186, v186
	s_nop 0
	v_mul_f32_e32 v187, v178, v186
	v_mul_f32_e32 v188, v179, v186
	v_mul_f32_e32 v189, v180, v186
	v_mul_f32_e32 v190, v181, v186
	v_mul_f32_e32 v182, v54, v187
	v_mul_f32_e32 v183, v58, v188
	v_mul_f32_e32 v184, v62, v189
	v_mul_f32_e32 v185, v66, v190
	v_mul_f32_e32 v186, v175, v183
	v_mul_f32_e32 v187, v176, v183
	v_fma_f32 v188, v176, v182, -v186
	v_fma_f32 v189, v175, v182, v187
	v_mul_f32_e32 v186, v234, v185
	v_mul_f32_e32 v187, v250, v185
	v_fma_f32 v190, v250, v184, -v186
	v_fma_f32 v191, v234, v184, v187
	v_cvt_pk_bf16_f32 v192, v188, v189
	v_cvt_pk_bf16_f32 v193, v190, v191
	ds_write_b16 v170, v192 offset:6912
	ds_write_b16_d16_hi v170, v192 offset:6944
	ds_write_b16 v170, v193 offset:6976
	ds_write_b16_d16_hi v170, v193 offset:7008
	v_mul_f32_e32 v182, v55, v55
	v_mul_f32_e32 v183, v59, v59
	v_mul_f32_e32 v184, v63, v63
	v_mul_f32_e32 v185, v67, v67
	v_add_f32_e32 v186, v182, v183
	v_add_f32_e32 v186, v186, v184
	v_add_f32_e32 v186, v186, v185
	s_nop 1
	v_add_f32_dpp v186, v186, v186 quad_perm:[1,0,3,2] row_mask:0xf bank_mask:0xf
	s_nop 1
	v_add_f32_dpp v186, v186, v186 quad_perm:[2,3,0,1] row_mask:0xf bank_mask:0xf
	s_nop 1
	v_add_f32_dpp v186, v186, v186 row_half_mirror row_mask:0xf bank_mask:0xf
	s_nop 1
	v_add_f32_dpp v186, v186, v186 row_mirror row_mask:0xf bank_mask:0xf
	v_fmamk_f32 v186, v186, 0x3c800000, v173
	v_rsq_f32_e32 v186, v186
	s_nop 0
	v_mul_f32_e32 v187, v178, v186
	v_mul_f32_e32 v188, v179, v186
	v_mul_f32_e32 v189, v180, v186
	v_mul_f32_e32 v190, v181, v186
	v_mul_f32_e32 v182, v55, v187
	v_mul_f32_e32 v183, v59, v188
	v_mul_f32_e32 v184, v63, v189
	v_mul_f32_e32 v185, v67, v190
	v_mul_f32_e32 v186, v175, v183
	v_mul_f32_e32 v187, v176, v183
	v_fma_f32 v188, v176, v182, -v186
	v_fma_f32 v189, v175, v182, v187
	v_mul_f32_e32 v186, v235, v185
	v_mul_f32_e32 v187, v251, v185
	v_fma_f32 v190, v251, v184, -v186
	v_fma_f32 v191, v235, v184, v187
	v_cvt_pk_bf16_f32 v192, v188, v189
	v_cvt_pk_bf16_f32 v193, v190, v191
	ds_write_b16 v170, v192 offset:7056
	ds_write_b16_d16_hi v170, v192 offset:7088
	ds_write_b16 v170, v193 offset:7120
	ds_write_b16_d16_hi v170, v193 offset:7152
	v_mul_f32_e32 v182, v56, v56
	v_mul_f32_e32 v183, v60, v60
	v_mul_f32_e32 v184, v64, v64
	v_mul_f32_e32 v185, v68, v68
	v_add_f32_e32 v186, v182, v183
	v_add_f32_e32 v186, v186, v184
	v_add_f32_e32 v186, v186, v185
	s_nop 1
	v_add_f32_dpp v186, v186, v186 quad_perm:[1,0,3,2] row_mask:0xf bank_mask:0xf
	s_nop 1
	v_add_f32_dpp v186, v186, v186 quad_perm:[2,3,0,1] row_mask:0xf bank_mask:0xf
	s_nop 1
	v_add_f32_dpp v186, v186, v186 row_half_mirror row_mask:0xf bank_mask:0xf
	s_nop 1
	v_add_f32_dpp v186, v186, v186 row_mirror row_mask:0xf bank_mask:0xf
	v_fmamk_f32 v186, v186, 0x3c800000, v173
	v_rsq_f32_e32 v186, v186
	s_nop 0
	v_mul_f32_e32 v187, v178, v186
	v_mul_f32_e32 v188, v179, v186
	v_mul_f32_e32 v189, v180, v186
	v_mul_f32_e32 v190, v181, v186
	v_mul_f32_e32 v182, v56, v187
	v_mul_f32_e32 v183, v60, v188
	v_mul_f32_e32 v184, v64, v189
	v_mul_f32_e32 v185, v68, v190
	v_mul_f32_e32 v186, v175, v183
	v_mul_f32_e32 v187, v176, v183
	v_fma_f32 v188, v176, v182, -v186
	v_fma_f32 v189, v175, v182, v187
	v_mul_f32_e32 v186, v236, v185
	v_mul_f32_e32 v187, v252, v185
	v_fma_f32 v190, v252, v184, -v186
	v_fma_f32 v191, v236, v184, v187
	v_cvt_pk_bf16_f32 v192, v188, v189
	v_cvt_pk_bf16_f32 v193, v190, v191
	ds_write_b16 v170, v192 offset:7200
	ds_write_b16_d16_hi v170, v192 offset:7232
	ds_write_b16 v170, v193 offset:7264
	ds_write_b16_d16_hi v170, v193 offset:7296
	v_mul_f32_e32 v182, v57, v57
	v_mul_f32_e32 v183, v61, v61
	v_mul_f32_e32 v184, v65, v65
	v_mul_f32_e32 v185, v69, v69
	v_add_f32_e32 v186, v182, v183
	v_add_f32_e32 v186, v186, v184
	v_add_f32_e32 v186, v186, v185
	s_nop 1
	v_add_f32_dpp v186, v186, v186 quad_perm:[1,0,3,2] row_mask:0xf bank_mask:0xf
	s_nop 1
	v_add_f32_dpp v186, v186, v186 quad_perm:[2,3,0,1] row_mask:0xf bank_mask:0xf
	s_nop 1
	v_add_f32_dpp v186, v186, v186 row_half_mirror row_mask:0xf bank_mask:0xf
	s_nop 1
	v_add_f32_dpp v186, v186, v186 row_mirror row_mask:0xf bank_mask:0xf
	v_fmamk_f32 v186, v186, 0x3c800000, v173
	v_rsq_f32_e32 v186, v186
	s_nop 0
	v_mul_f32_e32 v187, v178, v186
	v_mul_f32_e32 v188, v179, v186
	v_mul_f32_e32 v189, v180, v186
	v_mul_f32_e32 v190, v181, v186
	v_mul_f32_e32 v182, v57, v187
	v_mul_f32_e32 v183, v61, v188
	v_mul_f32_e32 v184, v65, v189
	v_mul_f32_e32 v185, v69, v190
	v_mul_f32_e32 v186, v175, v183
	v_mul_f32_e32 v187, v176, v183
	v_fma_f32 v188, v176, v182, -v186
	v_fma_f32 v189, v175, v182, v187
	v_mul_f32_e32 v186, v237, v185
	v_mul_f32_e32 v187, v253, v185
	v_fma_f32 v190, v253, v184, -v186
	v_fma_f32 v191, v237, v184, v187
	v_cvt_pk_bf16_f32 v192, v188, v189
	v_cvt_pk_bf16_f32 v193, v190, v191
	ds_write_b16 v170, v192 offset:7344
	ds_write_b16_d16_hi v170, v192 offset:7376
	ds_write_b16 v170, v193 offset:7408
	ds_write_b16_d16_hi v170, v193 offset:7440
	ds_read_b128 v[130:133], v171 offset:0
	ds_read_b128 v[134:137], v171 offset:1152
	ds_read_b128 v[138:141], v171 offset:2304
	ds_read_b128 v[142:145], v171 offset:3456
	ds_read_b128 v[146:149], v171 offset:4608
	ds_read_b128 v[150:153], v171 offset:5760
	ds_read_b128 v[154:157], v171 offset:6912
	ds_read_b128 v[158:161], v171 offset:8064
	s_waitcnt lgkmcnt(7)
; template <int EPI>
; DI void gemm_phase(const P& p, int l, const u16* __restrict__ A, const u16* __restrict__ Bt, int mpx, char* lds) {
;     ...
;           } else if (tr == 3) {
;             if (donorm) {
;               float ss = v0 * v0 + v1 * v1 + v2 * v2 + v3 * v3;
;               ss += __shfl_xor(ss, 1);
;               ss += __shfl_xor(ss, 2);
;               ss += __shfl_xor(ss, 4);
;               ss += __shfl_xor(ss, 8);
;               const float inv = rsqrtf(ss * (1.f / 64.f) + 1e-6f);
;               v0 *= inv * gv0; v1 *= inv * gv1; v2 *= inv * gv2; v3 *= inv * gv3;
;             }
;             if (dorope) {
;               float sr, cr, sc, cc;
;               sincos_rev((float)(s >> 6) * invf64, sr, cr);
;               sincos_rev((float)(s & 63) * invf64, sc, cc);
;               const float a1 = v0, a2 = v1, b1 = v2, b2 = v3;
;               v0 = a1 * cr - a2 * sr;
;               v1 = a2 * cr + a1 * sr;
;               v2 = b1 * cc - b2 * sc;
;               v3 = b2 * cc + b1 * sc;
;             }
;           } else if (tr == 4) {
;             float sr, cr, sc, cc;
;             sincos_rev((float)(s >> 6) * invf32, sr, cr);
;             sincos_rev((float)(s & 63) * invf32, sc, cc);
;             const float p0 = __shfl_xor(v0, 8), p1 = __shfl_xor(v1, 8), p2 = __shfl_xor(v2, 8), p3 = __shfl_xor(v3, 8);
;             v0 = lo8 ? (v0 * cr - p0 * sr) : (v0 * cr + p0 * sr);
;             v1 = lo8 ? (v1 * cc - p1 * sc) : (v1 * cc + p1 * sc);
;             v2 = lo8 ? (v2 * cr - p2 * sr) : (v2 * cr + p2 * sr);
;             v3 = lo8 ? (v3 * cc - p3 * sc) : (v3 * cc + p3 * sc);
;           }
;           const unsigned u01 = pack2(v0, v1), u23 = pack2(v2, v3);
;           if (kind == 1) {
;             Tl[(0 * 16 + r) * 72 + rowl] = (u16)u01;
;             Tl[(1 * 16 + r) * 72 + rowl] = (u16)(u01 >> 16);
;             Tl[(2 * 16 + r) * 72 + rowl] = (u16)u23;
;             Tl[(3 * 16 + r) * 72 + rowl] = (u16)(u23 >> 16);
;           } else if (tr == 2) {
;             Tl[rowl * 72 + 0 * 16 + r] = f2h(v0);
;             Tl[rowl * 72 + 1 * 16 + r] = f2h(v1);
;             Tl[rowl * 72 + 2 * 16 + r] = f2h(v2);
;             Tl[rowl * 72 + 3 * 16 + r] = f2h(v3);
;           } else {
;             Tl[rowl * 72 + 0 * 16 + r] = (u16)u01;
;             Tl[rowl * 72 + 1 * 16 + r] = (u16)(u01 >> 16);
;             Tl[rowl * 72 + 2 * 16 + r] = (u16)u23;
	global_store_dwordx4 v172, v[130:133], s[44:45] offset:0 sc1
	s_waitcnt lgkmcnt(6)
	global_store_dwordx4 v172, v[134:137], s[44:45] offset:1024 sc1
	s_waitcnt lgkmcnt(5)
	global_store_dwordx4 v172, v[138:141], s[44:45] offset:2048 sc1
	s_waitcnt lgkmcnt(4)
	global_store_dwordx4 v172, v[142:145], s[44:45] offset:3072 sc1
	s_waitcnt lgkmcnt(3)
	global_store_dwordx4 v172, v[146:149], s[62:63] offset:0 sc1
	s_waitcnt lgkmcnt(2)
	global_store_dwordx4 v172, v[150:153], s[62:63] offset:1024 sc1
	s_waitcnt lgkmcnt(1)
	global_store_dwordx4 v172, v[154:157], s[62:63] offset:2048 sc1
	s_waitcnt lgkmcnt(0)
	global_store_dwordx4 v172, v[158:161], s[62:63] offset:3072 sc1
	s_add_u32 s44, s44, 0x2000
	s_addc_u32 s45, s45, 0
	s_add_u32 s62, s62, 0x2000
	s_addc_u32 s63, s63, 0
	s_lshr_b32 s70, s69, 6
	s_add_i32 s70, s70, 1
	v_cvt_f32_i32_e32 v182, s70
	v_mul_f32_e32 v182, v174, v182
	v_mul_f32_e32 v183, 0.15915494, v182
	v_rndne_f32_e32 v183, v183
	v_fma_f32 v183, v182, 0.15915494, -v183
	v_sin_f32_e32 v175, v183
	v_cos_f32_e32 v176, v183
	v_mul_f32_e32 v182, v70, v70
	v_mul_f32_e32 v183, v74, v74
	v_mul_f32_e32 v184, v78, v78
	v_mul_f32_e32 v185, v82, v82
	v_add_f32_e32 v186, v182, v183
	v_add_f32_e32 v186, v186, v184
	v_add_f32_e32 v186, v186, v185
	s_nop 1
	v_add_f32_dpp v186, v186, v186 quad_perm:[1,0,3,2] row_mask:0xf bank_mask:0xf
	s_nop 1
	v_add_f32_dpp v186, v186, v186 quad_perm:[2,3,0,1] row_mask:0xf bank_mask:0xf
	s_nop 1
	v_add_f32_dpp v186, v186, v186 row_half_mirror row_mask:0xf bank_mask:0xf
	s_nop 1
	v_add_f32_dpp v186, v186, v186 row_mirror row_mask:0xf bank_mask:0xf
	v_fmamk_f32 v186, v186, 0x3c800000, v173
	v_rsq_f32_e32 v186, v186
	s_nop 0
	v_mul_f32_e32 v187, v178, v186
	v_mul_f32_e32 v188, v179, v186
	v_mul_f32_e32 v189, v180, v186
	v_mul_f32_e32 v190, v181, v186
	v_mul_f32_e32 v182, v70, v187
	v_mul_f32_e32 v183, v74, v188
	v_mul_f32_e32 v184, v78, v189
	v_mul_f32_e32 v185, v82, v190
	v_mul_f32_e32 v186, v175, v183
	v_mul_f32_e32 v187, v176, v183
	v_fma_f32 v188, v176, v182, -v186
	v_fma_f32 v189, v175, v182, v187
	v_mul_f32_e32 v186, v212, v185
	v_mul_f32_e32 v187, v238, v185
	v_fma_f32 v190, v238, v184, -v186
	v_fma_f32 v191, v212, v184, v187
	v_cvt_pk_bf16_f32 v192, v188, v189
	v_cvt_pk_bf16_f32 v193, v190, v191
	ds_write_b16 v170, v192 offset:0
	ds_write_b16_d16_hi v170, v192 offset:32
	ds_write_b16 v170, v193 offset:64
	ds_write_b16_d16_hi v170, v193 offset:96
	v_mul_f32_e32 v182, v71, v71
	v_mul_f32_e32 v183, v75, v75
	v_mul_f32_e32 v184, v79, v79
	v_mul_f32_e32 v185, v83, v83
	v_add_f32_e32 v186, v182, v183
	v_add_f32_e32 v186, v186, v184
	v_add_f32_e32 v186, v186, v185
	s_nop 1
	v_add_f32_dpp v186, v186, v186 quad_perm:[1,0,3,2] row_mask:0xf bank_mask:0xf
	s_nop 1
	v_add_f32_dpp v186, v186, v186 quad_perm:[2,3,0,1] row_mask:0xf bank_mask:0xf
	s_nop 1
	v_add_f32_dpp v186, v186, v186 row_half_mirror row_mask:0xf bank_mask:0xf
	s_nop 1
	v_add_f32_dpp v186, v186, v186 row_mirror row_mask:0xf bank_mask:0xf
	v_fmamk_f32 v186, v186, 0x3c800000, v173
	v_rsq_f32_e32 v186, v186
	s_nop 0
	v_mul_f32_e32 v187, v178, v186
	v_mul_f32_e32 v188, v179, v186
	v_mul_f32_e32 v189, v180, v186
	v_mul_f32_e32 v190, v181, v186
	v_mul_f32_e32 v182, v71, v187
	v_mul_f32_e32 v183, v75, v188
	v_mul_f32_e32 v184, v79, v189
	v_mul_f32_e32 v185, v83, v190
	v_mul_f32_e32 v186, v175, v183
	v_mul_f32_e32 v187, v176, v183
	v_fma_f32 v188, v176, v182, -v186
	v_fma_f32 v189, v175, v182, v187
	v_mul_f32_e32 v186, v213, v185
	v_mul_f32_e32 v187, v239, v185
	v_fma_f32 v190, v239, v184, -v186
	v_fma_f32 v191, v213, v184, v187
	v_cvt_pk_bf16_f32 v192, v188, v189
	v_cvt_pk_bf16_f32 v193, v190, v191
	ds_write_b16 v170, v192 offset:144
	ds_write_b16_d16_hi v170, v192 offset:176
	ds_write_b16 v170, v193 offset:208
	ds_write_b16_d16_hi v170, v193 offset:240
	v_mul_f32_e32 v182, v72, v72
	v_mul_f32_e32 v183, v76, v76
	v_mul_f32_e32 v184, v80, v80
	v_mul_f32_e32 v185, v84, v84
	v_add_f32_e32 v186, v182, v183
	v_add_f32_e32 v186, v186, v184
	v_add_f32_e32 v186, v186, v185
	s_nop 1
	v_add_f32_dpp v186, v186, v186 quad_perm:[1,0,3,2] row_mask:0xf bank_mask:0xf
	s_nop 1
	v_add_f32_dpp v186, v186, v186 quad_perm:[2,3,0,1] row_mask:0xf bank_mask:0xf
	s_nop 1
	v_add_f32_dpp v186, v186, v186 row_half_mirror row_mask:0xf bank_mask:0xf
	s_nop 1
	v_add_f32_dpp v186, v186, v186 row_mirror row_mask:0xf bank_mask:0xf
	v_fmamk_f32 v186, v186, 0x3c800000, v173
	v_rsq_f32_e32 v186, v186
	s_nop 0
	v_mul_f32_e32 v187, v178, v186
	v_mul_f32_e32 v188, v179, v186
	v_mul_f32_e32 v189, v180, v186
	v_mul_f32_e32 v190, v181, v186
	v_mul_f32_e32 v182, v72, v187
	v_mul_f32_e32 v183, v76, v188
	v_mul_f32_e32 v184, v80, v189
	v_mul_f32_e32 v185, v84, v190
	v_mul_f32_e32 v186, v175, v183
	v_mul_f32_e32 v187, v176, v183
	v_fma_f32 v188, v176, v182, -v186
	v_fma_f32 v189, v175, v182, v187
	v_mul_f32_e32 v186, v214, v185
	v_mul_f32_e32 v187, v240, v185
	v_fma_f32 v190, v240, v184, -v186
	v_fma_f32 v191, v214, v184, v187
	v_cvt_pk_bf16_f32 v192, v188, v189
	v_cvt_pk_bf16_f32 v193, v190, v191
	ds_write_b16 v170, v192 offset:288
	ds_write_b16_d16_hi v170, v192 offset:320
	ds_write_b16 v170, v193 offset:352
	ds_write_b16_d16_hi v170, v193 offset:384
	v_mul_f32_e32 v182, v73, v73
	v_mul_f32_e32 v183, v77, v77
	v_mul_f32_e32 v184, v81, v81
	v_mul_f32_e32 v185, v85, v85
	v_add_f32_e32 v186, v182, v183
	v_add_f32_e32 v186, v186, v184
	v_add_f32_e32 v186, v186, v185
	s_nop 1
	v_add_f32_dpp v186, v186, v186 quad_perm:[1,0,3,2] row_mask:0xf bank_mask:0xf
	s_nop 1
	v_add_f32_dpp v186, v186, v186 quad_perm:[2,3,0,1] row_mask:0xf bank_mask:0xf
	s_nop 1
	v_add_f32_dpp v186, v186, v186 row_half_mirror row_mask:0xf bank_mask:0xf
; template <int EPI>
; DI void gemm_phase(const P& p, int l, const u16* __restrict__ A, const u16* __restrict__ Bt, int mpx, char* lds) {
;     ...
;           } else if (tr == 3) {
;             if (donorm) {
;               float ss = v0 * v0 + v1 * v1 + v2 * v2 + v3 * v3;
;               ss += __shfl_xor(ss, 1);
;               ss += __shfl_xor(ss, 2);
;               ss += __shfl_xor(ss, 4);
;               ss += __shfl_xor(ss, 8);
;               const float inv = rsqrtf(ss * (1.f / 64.f) + 1e-6f);
;               v0 *= inv * gv0; v1 *= inv * gv1; v2 *= inv * gv2; v3 *= inv * gv3;
;             }
;             if (dorope) {
;               float sr, cr, sc, cc;
;               sincos_rev((float)(s >> 6) * invf64, sr, cr);
;               sincos_rev((float)(s & 63) * invf64, sc, cc);
;               const float a1 = v0, a2 = v1, b1 = v2, b2 = v3;
;               v0 = a1 * cr - a2 * sr;
;               v1 = a2 * cr + a1 * sr;
;               v2 = b1 * cc - b2 * sc;
;               v3 = b2 * cc + b1 * sc;
;             }
;           } else if (tr == 4) {
;             float sr, cr, sc, cc;
;             sincos_rev((float)(s >> 6) * invf32, sr, cr);
;             sincos_rev((float)(s & 63) * invf32, sc, cc);
;             const float p0 = __shfl_xor(v0, 8), p1 = __shfl_xor(v1, 8), p2 = __shfl_xor(v2, 8), p3 = __shfl_xor(v3, 8);
;             v0 = lo8 ? (v0 * cr - p0 * sr) : (v0 * cr + p0 * sr);
;             v1 = lo8 ? (v1 * cc - p1 * sc) : (v1 * cc + p1 * sc);
;             v2 = lo8 ? (v2 * cr - p2 * sr) : (v2 * cr + p2 * sr);
;             v3 = lo8 ? (v3 * cc - p3 * sc) : (v3 * cc + p3 * sc);
;           }
;           const unsigned u01 = pack2(v0, v1), u23 = pack2(v2, v3);
;           if (kind == 1) {
;             Tl[(0 * 16 + r) * 72 + rowl] = (u16)u01;
;             Tl[(1 * 16 + r) * 72 + rowl] = (u16)(u01 >> 16);
;             Tl[(2 * 16 + r) * 72 + rowl] = (u16)u23;
;             Tl[(3 * 16 + r) * 72 + rowl] = (u16)(u23 >> 16);
;           } else if (tr == 2) {
;             Tl[rowl * 72 + 0 * 16 + r] = f2h(v0);
;             Tl[rowl * 72 + 1 * 16 + r] = f2h(v1);
;             Tl[rowl * 72 + 2 * 16 + r] = f2h(v2);
;             Tl[rowl * 72 + 3 * 16 + r] = f2h(v3);
;           } else {
;             Tl[rowl * 72 + 0 * 16 + r] = (u16)u01;
;             Tl[rowl * 72 + 1 * 16 + r] = (u16)(u01 >> 16);
;             Tl[rowl * 72 + 2 * 16 + r] = (u16)u23;
	s_nop 1
	v_add_f32_dpp v186, v186, v186 row_mirror row_mask:0xf bank_mask:0xf
	v_fmamk_f32 v186, v186, 0x3c800000, v173
	v_rsq_f32_e32 v186, v186
	s_nop 0
	v_mul_f32_e32 v187, v178, v186
	v_mul_f32_e32 v188, v179, v186
	v_mul_f32_e32 v189, v180, v186
	v_mul_f32_e32 v190, v181, v186
	v_mul_f32_e32 v182, v73, v187
	v_mul_f32_e32 v183, v77, v188
	v_mul_f32_e32 v184, v81, v189
	v_mul_f32_e32 v185, v85, v190
	v_mul_f32_e32 v186, v175, v183
	v_mul_f32_e32 v187, v176, v183
	v_fma_f32 v188, v176, v182, -v186
	v_fma_f32 v189, v175, v182, v187
	v_mul_f32_e32 v186, v215, v185
	v_mul_f32_e32 v187, v241, v185
	v_fma_f32 v190, v241, v184, -v186
	v_fma_f32 v191, v215, v184, v187
	v_cvt_pk_bf16_f32 v192, v188, v189
	v_cvt_pk_bf16_f32 v193, v190, v191
	ds_write_b16 v170, v192 offset:432
	ds_write_b16_d16_hi v170, v192 offset:464
	ds_write_b16 v170, v193 offset:496
	ds_write_b16_d16_hi v170, v193 offset:528
	v_mul_f32_e32 v182, v86, v86
	v_mul_f32_e32 v183, v90, v90
	v_mul_f32_e32 v184, v94, v94
	v_mul_f32_e32 v185, v98, v98
	v_add_f32_e32 v186, v182, v183
	v_add_f32_e32 v186, v186, v184
	v_add_f32_e32 v186, v186, v185
	s_nop 1
	v_add_f32_dpp v186, v186, v186 quad_perm:[1,0,3,2] row_mask:0xf bank_mask:0xf
	s_nop 1
	v_add_f32_dpp v186, v186, v186 quad_perm:[2,3,0,1] row_mask:0xf bank_mask:0xf
	s_nop 1
	v_add_f32_dpp v186, v186, v186 row_half_mirror row_mask:0xf bank_mask:0xf
	s_nop 1
	v_add_f32_dpp v186, v186, v186 row_mirror row_mask:0xf bank_mask:0xf
	v_fmamk_f32 v186, v186, 0x3c800000, v173
	v_rsq_f32_e32 v186, v186
	s_nop 0
	v_mul_f32_e32 v187, v178, v186
	v_mul_f32_e32 v188, v179, v186
	v_mul_f32_e32 v189, v180, v186
	v_mul_f32_e32 v190, v181, v186
	v_mul_f32_e32 v182, v86, v187
	v_mul_f32_e32 v183, v90, v188
	v_mul_f32_e32 v184, v94, v189
	v_mul_f32_e32 v185, v98, v190
	v_mul_f32_e32 v186, v175, v183
	v_mul_f32_e32 v187, v176, v183
	v_fma_f32 v188, v176, v182, -v186
	v_fma_f32 v189, v175, v182, v187
	v_mul_f32_e32 v186, v216, v185
	v_mul_f32_e32 v187, v242, v185
	v_fma_f32 v190, v242, v184, -v186
	v_fma_f32 v191, v216, v184, v187
	v_cvt_pk_bf16_f32 v192, v188, v189
	v_cvt_pk_bf16_f32 v193, v190, v191
	ds_write_b16 v170, v192 offset:2304
	ds_write_b16_d16_hi v170, v192 offset:2336
	ds_write_b16 v170, v193 offset:2368
	ds_write_b16_d16_hi v170, v193 offset:2400
	v_mul_f32_e32 v182, v87, v87
	v_mul_f32_e32 v183, v91, v91
	v_mul_f32_e32 v184, v95, v95
	v_mul_f32_e32 v185, v99, v99
	v_add_f32_e32 v186, v182, v183
	v_add_f32_e32 v186, v186, v184
	v_add_f32_e32 v186, v186, v185
	s_nop 1
	v_add_f32_dpp v186, v186, v186 quad_perm:[1,0,3,2] row_mask:0xf bank_mask:0xf
	s_nop 1
	v_add_f32_dpp v186, v186, v186 quad_perm:[2,3,0,1] row_mask:0xf bank_mask:0xf
	s_nop 1
	v_add_f32_dpp v186, v186, v186 row_half_mirror row_mask:0xf bank_mask:0xf
	s_nop 1
	v_add_f32_dpp v186, v186, v186 row_mirror row_mask:0xf bank_mask:0xf
	v_fmamk_f32 v186, v186, 0x3c800000, v173
	v_rsq_f32_e32 v186, v186
	s_nop 0
	v_mul_f32_e32 v187, v178, v186
	v_mul_f32_e32 v188, v179, v186
	v_mul_f32_e32 v189, v180, v186
	v_mul_f32_e32 v190, v181, v186
	v_mul_f32_e32 v182, v87, v187
	v_mul_f32_e32 v183, v91, v188
	v_mul_f32_e32 v184, v95, v189
	v_mul_f32_e32 v185, v99, v190
	v_mul_f32_e32 v186, v175, v183
	v_mul_f32_e32 v187, v176, v183
	v_fma_f32 v188, v176, v182, -v186
	v_fma_f32 v189, v175, v182, v187
	v_mul_f32_e32 v186, v217, v185
	v_mul_f32_e32 v187, v243, v185
	v_fma_f32 v190, v243, v184, -v186
	v_fma_f32 v191, v217, v184, v187
	v_cvt_pk_bf16_f32 v192, v188, v189
	v_cvt_pk_bf16_f32 v193, v190, v191
	ds_write_b16 v170, v192 offset:2448
	ds_write_b16_d16_hi v170, v192 offset:2480
	ds_write_b16 v170, v193 offset:2512
	ds_write_b16_d16_hi v170, v193 offset:2544
	v_mul_f32_e32 v182, v88, v88
	v_mul_f32_e32 v183, v92, v92
	v_mul_f32_e32 v184, v96, v96
	v_mul_f32_e32 v185, v100, v100
	v_add_f32_e32 v186, v182, v183
	v_add_f32_e32 v186, v186, v184
	v_add_f32_e32 v186, v186, v185
	s_nop 1
	v_add_f32_dpp v186, v186, v186 quad_perm:[1,0,3,2] row_mask:0xf bank_mask:0xf
	s_nop 1
	v_add_f32_dpp v186, v186, v186 quad_perm:[2,3,0,1] row_mask:0xf bank_mask:0xf
	s_nop 1
	v_add_f32_dpp v186, v186, v186 row_half_mirror row_mask:0xf bank_mask:0xf
	s_nop 1
	v_add_f32_dpp v186, v186, v186 row_mirror row_mask:0xf bank_mask:0xf
	v_fmamk_f32 v186, v186, 0x3c800000, v173
	v_rsq_f32_e32 v186, v186
	s_nop 0
	v_mul_f32_e32 v187, v178, v186
	v_mul_f32_e32 v188, v179, v186
	v_mul_f32_e32 v189, v180, v186
	v_mul_f32_e32 v190, v181, v186
	v_mul_f32_e32 v182, v88, v187
	v_mul_f32_e32 v183, v92, v188
	v_mul_f32_e32 v184, v96, v189
	v_mul_f32_e32 v185, v100, v190
	v_mul_f32_e32 v186, v175, v183
	v_mul_f32_e32 v187, v176, v183
	v_fma_f32 v188, v176, v182, -v186
	v_fma_f32 v189, v175, v182, v187
	v_mul_f32_e32 v186, v218, v185
	v_mul_f32_e32 v187, v244, v185
	v_fma_f32 v190, v244, v184, -v186
	v_fma_f32 v191, v218, v184, v187
	v_cvt_pk_bf16_f32 v192, v188, v189
	v_cvt_pk_bf16_f32 v193, v190, v191
	ds_write_b16 v170, v192 offset:2592
	ds_write_b16_d16_hi v170, v192 offset:2624
	ds_write_b16 v170, v193 offset:2656
	ds_write_b16_d16_hi v170, v193 offset:2688
	v_mul_f32_e32 v182, v89, v89
	v_mul_f32_e32 v183, v93, v93
	v_mul_f32_e32 v184, v97, v97
	v_mul_f32_e32 v185, v101, v101
	v_add_f32_e32 v186, v182, v183
	v_add_f32_e32 v186, v186, v184
	v_add_f32_e32 v186, v186, v185
	s_nop 1
	v_add_f32_dpp v186, v186, v186 quad_perm:[1,0,3,2] row_mask:0xf bank_mask:0xf
	s_nop 1
	v_add_f32_dpp v186, v186, v186 quad_perm:[2,3,0,1] row_mask:0xf bank_mask:0xf
	s_nop 1
	v_add_f32_dpp v186, v186, v186 row_half_mirror row_mask:0xf bank_mask:0xf
	s_nop 1
	v_add_f32_dpp v186, v186, v186 row_mirror row_mask:0xf bank_mask:0xf
	v_fmamk_f32 v186, v186, 0x3c800000, v173
; template <int EPI>
; DI void gemm_phase(const P& p, int l, const u16* __restrict__ A, const u16* __restrict__ Bt, int mpx, char* lds) {
;     ...
;           } else if (tr == 3) {
;             if (donorm) {
;               float ss = v0 * v0 + v1 * v1 + v2 * v2 + v3 * v3;
;               ss += __shfl_xor(ss, 1);
;               ss += __shfl_xor(ss, 2);
;               ss += __shfl_xor(ss, 4);
;               ss += __shfl_xor(ss, 8);
;               const float inv = rsqrtf(ss * (1.f / 64.f) + 1e-6f);
;               v0 *= inv * gv0; v1 *= inv * gv1; v2 *= inv * gv2; v3 *= inv * gv3;
;             }
;             if (dorope) {
;               float sr, cr, sc, cc;
;               sincos_rev((float)(s >> 6) * invf64, sr, cr);
;               sincos_rev((float)(s & 63) * invf64, sc, cc);
;               const float a1 = v0, a2 = v1, b1 = v2, b2 = v3;
;               v0 = a1 * cr - a2 * sr;
;               v1 = a2 * cr + a1 * sr;
;               v2 = b1 * cc - b2 * sc;
;               v3 = b2 * cc + b1 * sc;
;             }
;           } else if (tr == 4) {
;             float sr, cr, sc, cc;
;             sincos_rev((float)(s >> 6) * invf32, sr, cr);
;             sincos_rev((float)(s & 63) * invf32, sc, cc);
;             const float p0 = __shfl_xor(v0, 8), p1 = __shfl_xor(v1, 8), p2 = __shfl_xor(v2, 8), p3 = __shfl_xor(v3, 8);
;             v0 = lo8 ? (v0 * cr - p0 * sr) : (v0 * cr + p0 * sr);
;             v1 = lo8 ? (v1 * cc - p1 * sc) : (v1 * cc + p1 * sc);
;             v2 = lo8 ? (v2 * cr - p2 * sr) : (v2 * cr + p2 * sr);
;             v3 = lo8 ? (v3 * cc - p3 * sc) : (v3 * cc + p3 * sc);
;           }
;           const unsigned u01 = pack2(v0, v1), u23 = pack2(v2, v3);
;           if (kind == 1) {
;             Tl[(0 * 16 + r) * 72 + rowl] = (u16)u01;
;             Tl[(1 * 16 + r) * 72 + rowl] = (u16)(u01 >> 16);
;             Tl[(2 * 16 + r) * 72 + rowl] = (u16)u23;
;             Tl[(3 * 16 + r) * 72 + rowl] = (u16)(u23 >> 16);
;           } else if (tr == 2) {
;             Tl[rowl * 72 + 0 * 16 + r] = f2h(v0);
;             Tl[rowl * 72 + 1 * 16 + r] = f2h(v1);
;             Tl[rowl * 72 + 2 * 16 + r] = f2h(v2);
;             Tl[rowl * 72 + 3 * 16 + r] = f2h(v3);
;           } else {
;             Tl[rowl * 72 + 0 * 16 + r] = (u16)u01;
;             Tl[rowl * 72 + 1 * 16 + r] = (u16)(u01 >> 16);
;             Tl[rowl * 72 + 2 * 16 + r] = (u16)u23;
	v_rsq_f32_e32 v186, v186
	s_nop 0
	v_mul_f32_e32 v187, v178, v186
	v_mul_f32_e32 v188, v179, v186
	v_mul_f32_e32 v189, v180, v186
	v_mul_f32_e32 v190, v181, v186
	v_mul_f32_e32 v182, v89, v187
	v_mul_f32_e32 v183, v93, v188
	v_mul_f32_e32 v184, v97, v189
	v_mul_f32_e32 v185, v101, v190
	v_mul_f32_e32 v186, v175, v183
	v_mul_f32_e32 v187, v176, v183
	v_fma_f32 v188, v176, v182, -v186
	v_fma_f32 v189, v175, v182, v187
	v_mul_f32_e32 v186, v219, v185
	v_mul_f32_e32 v187, v245, v185
	v_fma_f32 v190, v245, v184, -v186
	v_fma_f32 v191, v219, v184, v187
	v_cvt_pk_bf16_f32 v192, v188, v189
	v_cvt_pk_bf16_f32 v193, v190, v191
	ds_write_b16 v170, v192 offset:2736
	ds_write_b16_d16_hi v170, v192 offset:2768
	ds_write_b16 v170, v193 offset:2800
	ds_write_b16_d16_hi v170, v193 offset:2832
	v_mul_f32_e32 v182, v102, v102
	v_mul_f32_e32 v183, v106, v106
	v_mul_f32_e32 v184, v110, v110
	v_mul_f32_e32 v185, v114, v114
	v_add_f32_e32 v186, v182, v183
	v_add_f32_e32 v186, v186, v184
	v_add_f32_e32 v186, v186, v185
	s_nop 1
	v_add_f32_dpp v186, v186, v186 quad_perm:[1,0,3,2] row_mask:0xf bank_mask:0xf
	s_nop 1
	v_add_f32_dpp v186, v186, v186 quad_perm:[2,3,0,1] row_mask:0xf bank_mask:0xf
	s_nop 1
	v_add_f32_dpp v186, v186, v186 row_half_mirror row_mask:0xf bank_mask:0xf
	s_nop 1
	v_add_f32_dpp v186, v186, v186 row_mirror row_mask:0xf bank_mask:0xf
	v_fmamk_f32 v186, v186, 0x3c800000, v173
	v_rsq_f32_e32 v186, v186
	s_nop 0
	v_mul_f32_e32 v187, v178, v186
	v_mul_f32_e32 v188, v179, v186
	v_mul_f32_e32 v189, v180, v186
	v_mul_f32_e32 v190, v181, v186
	v_mul_f32_e32 v182, v102, v187
	v_mul_f32_e32 v183, v106, v188
	v_mul_f32_e32 v184, v110, v189
	v_mul_f32_e32 v185, v114, v190
	v_mul_f32_e32 v186, v175, v183
	v_mul_f32_e32 v187, v176, v183
	v_fma_f32 v188, v176, v182, -v186
	v_fma_f32 v189, v175, v182, v187
	v_mul_f32_e32 v186, v220, v185
	v_mul_f32_e32 v187, v246, v185
	v_fma_f32 v190, v246, v184, -v186
	v_fma_f32 v191, v220, v184, v187
	v_cvt_pk_bf16_f32 v192, v188, v189
	v_cvt_pk_bf16_f32 v193, v190, v191
	ds_write_b16 v170, v192 offset:4608
	ds_write_b16_d16_hi v170, v192 offset:4640
	ds_write_b16 v170, v193 offset:4672
	ds_write_b16_d16_hi v170, v193 offset:4704
	v_mul_f32_e32 v182, v103, v103
	v_mul_f32_e32 v183, v107, v107
	v_mul_f32_e32 v184, v111, v111
	v_mul_f32_e32 v185, v115, v115
	v_add_f32_e32 v186, v182, v183
	v_add_f32_e32 v186, v186, v184
	v_add_f32_e32 v186, v186, v185
	s_nop 1
	v_add_f32_dpp v186, v186, v186 quad_perm:[1,0,3,2] row_mask:0xf bank_mask:0xf
	s_nop 1
	v_add_f32_dpp v186, v186, v186 quad_perm:[2,3,0,1] row_mask:0xf bank_mask:0xf
	s_nop 1
	v_add_f32_dpp v186, v186, v186 row_half_mirror row_mask:0xf bank_mask:0xf
	s_nop 1
	v_add_f32_dpp v186, v186, v186 row_mirror row_mask:0xf bank_mask:0xf
	v_fmamk_f32 v186, v186, 0x3c800000, v173
	v_rsq_f32_e32 v186, v186
	s_nop 0
	v_mul_f32_e32 v187, v178, v186
	v_mul_f32_e32 v188, v179, v186
	v_mul_f32_e32 v189, v180, v186
	v_mul_f32_e32 v190, v181, v186
	v_mul_f32_e32 v182, v103, v187
	v_mul_f32_e32 v183, v107, v188
	v_mul_f32_e32 v184, v111, v189
	v_mul_f32_e32 v185, v115, v190
	v_mul_f32_e32 v186, v175, v183
	v_mul_f32_e32 v187, v176, v183
	v_fma_f32 v188, v176, v182, -v186
	v_fma_f32 v189, v175, v182, v187
	v_mul_f32_e32 v186, v221, v185
	v_mul_f32_e32 v187, v247, v185
	v_fma_f32 v190, v247, v184, -v186
	v_fma_f32 v191, v221, v184, v187
	v_cvt_pk_bf16_f32 v192, v188, v189
	v_cvt_pk_bf16_f32 v193, v190, v191
	ds_write_b16 v170, v192 offset:4752
	ds_write_b16_d16_hi v170, v192 offset:4784
	ds_write_b16 v170, v193 offset:4816
	ds_write_b16_d16_hi v170, v193 offset:4848
	v_mul_f32_e32 v182, v104, v104
	v_mul_f32_e32 v183, v108, v108
	v_mul_f32_e32 v184, v112, v112
	v_mul_f32_e32 v185, v116, v116
	v_add_f32_e32 v186, v182, v183
	v_add_f32_e32 v186, v186, v184
	v_add_f32_e32 v186, v186, v185
	s_nop 1
	v_add_f32_dpp v186, v186, v186 quad_perm:[1,0,3,2] row_mask:0xf bank_mask:0xf
	s_nop 1
	v_add_f32_dpp v186, v186, v186 quad_perm:[2,3,0,1] row_mask:0xf bank_mask:0xf
	s_nop 1
	v_add_f32_dpp v186, v186, v186 row_half_mirror row_mask:0xf bank_mask:0xf
	s_nop 1
	v_add_f32_dpp v186, v186, v186 row_mirror row_mask:0xf bank_mask:0xf
	v_fmamk_f32 v186, v186, 0x3c800000, v173
	v_rsq_f32_e32 v186, v186
	s_nop 0
	v_mul_f32_e32 v187, v178, v186
	v_mul_f32_e32 v188, v179, v186
	v_mul_f32_e32 v189, v180, v186
	v_mul_f32_e32 v190, v181, v186
	v_mul_f32_e32 v182, v104, v187
	v_mul_f32_e32 v183, v108, v188
	v_mul_f32_e32 v184, v112, v189
	v_mul_f32_e32 v185, v116, v190
	v_mul_f32_e32 v186, v175, v183
	v_mul_f32_e32 v187, v176, v183
	v_fma_f32 v188, v176, v182, -v186
	v_fma_f32 v189, v175, v182, v187
	v_mul_f32_e32 v186, v222, v185
	v_mul_f32_e32 v187, v248, v185
	v_fma_f32 v190, v248, v184, -v186
	v_fma_f32 v191, v222, v184, v187
	v_cvt_pk_bf16_f32 v192, v188, v189
	v_cvt_pk_bf16_f32 v193, v190, v191
	ds_write_b16 v170, v192 offset:4896
	ds_write_b16_d16_hi v170, v192 offset:4928
	ds_write_b16 v170, v193 offset:4960
	ds_write_b16_d16_hi v170, v193 offset:4992
	v_mul_f32_e32 v182, v105, v105
	v_mul_f32_e32 v183, v109, v109
	v_mul_f32_e32 v184, v113, v113
	v_mul_f32_e32 v185, v117, v117
	v_add_f32_e32 v186, v182, v183
	v_add_f32_e32 v186, v186, v184
	v_add_f32_e32 v186, v186, v185
	s_nop 1
	v_add_f32_dpp v186, v186, v186 quad_perm:[1,0,3,2] row_mask:0xf bank_mask:0xf
	s_nop 1
	v_add_f32_dpp v186, v186, v186 quad_perm:[2,3,0,1] row_mask:0xf bank_mask:0xf
	s_nop 1
	v_add_f32_dpp v186, v186, v186 row_half_mirror row_mask:0xf bank_mask:0xf
	s_nop 1
	v_add_f32_dpp v186, v186, v186 row_mirror row_mask:0xf bank_mask:0xf
	v_fmamk_f32 v186, v186, 0x3c800000, v173
	v_rsq_f32_e32 v186, v186
	s_nop 0
	v_mul_f32_e32 v187, v178, v186
; template <int EPI>
; DI void gemm_phase(const P& p, int l, const u16* __restrict__ A, const u16* __restrict__ Bt, int mpx, char* lds) {
;     ...
;           } else if (tr == 3) {
;             if (donorm) {
;               float ss = v0 * v0 + v1 * v1 + v2 * v2 + v3 * v3;
;               ss += __shfl_xor(ss, 1);
;               ss += __shfl_xor(ss, 2);
;               ss += __shfl_xor(ss, 4);
;               ss += __shfl_xor(ss, 8);
;               const float inv = rsqrtf(ss * (1.f / 64.f) + 1e-6f);
;               v0 *= inv * gv0; v1 *= inv * gv1; v2 *= inv * gv2; v3 *= inv * gv3;
;             }
;             if (dorope) {
;               float sr, cr, sc, cc;
;               sincos_rev((float)(s >> 6) * invf64, sr, cr);
;               sincos_rev((float)(s & 63) * invf64, sc, cc);
;               const float a1 = v0, a2 = v1, b1 = v2, b2 = v3;
;               v0 = a1 * cr - a2 * sr;
;               v1 = a2 * cr + a1 * sr;
;               v2 = b1 * cc - b2 * sc;
;               v3 = b2 * cc + b1 * sc;
;             }
;           } else if (tr == 4) {
;             float sr, cr, sc, cc;
;             sincos_rev((float)(s >> 6) * invf32, sr, cr);
;             sincos_rev((float)(s & 63) * invf32, sc, cc);
;             const float p0 = __shfl_xor(v0, 8), p1 = __shfl_xor(v1, 8), p2 = __shfl_xor(v2, 8), p3 = __shfl_xor(v3, 8);
;             v0 = lo8 ? (v0 * cr - p0 * sr) : (v0 * cr + p0 * sr);
;             v1 = lo8 ? (v1 * cc - p1 * sc) : (v1 * cc + p1 * sc);
;             v2 = lo8 ? (v2 * cr - p2 * sr) : (v2 * cr + p2 * sr);
;             v3 = lo8 ? (v3 * cc - p3 * sc) : (v3 * cc + p3 * sc);
;           }
;           const unsigned u01 = pack2(v0, v1), u23 = pack2(v2, v3);
;           if (kind == 1) {
;             Tl[(0 * 16 + r) * 72 + rowl] = (u16)u01;
;             Tl[(1 * 16 + r) * 72 + rowl] = (u16)(u01 >> 16);
;             Tl[(2 * 16 + r) * 72 + rowl] = (u16)u23;
;             Tl[(3 * 16 + r) * 72 + rowl] = (u16)(u23 >> 16);
;           } else if (tr == 2) {
;             Tl[rowl * 72 + 0 * 16 + r] = f2h(v0);
;             Tl[rowl * 72 + 1 * 16 + r] = f2h(v1);
;             Tl[rowl * 72 + 2 * 16 + r] = f2h(v2);
;             Tl[rowl * 72 + 3 * 16 + r] = f2h(v3);
;           } else {
;             Tl[rowl * 72 + 0 * 16 + r] = (u16)u01;
;             Tl[rowl * 72 + 1 * 16 + r] = (u16)(u01 >> 16);
;             Tl[rowl * 72 + 2 * 16 + r] = (u16)u23;
	v_mul_f32_e32 v188, v179, v186
	v_mul_f32_e32 v189, v180, v186
	v_mul_f32_e32 v190, v181, v186
	v_mul_f32_e32 v182, v105, v187
	v_mul_f32_e32 v183, v109, v188
	v_mul_f32_e32 v184, v113, v189
	v_mul_f32_e32 v185, v117, v190
	v_mul_f32_e32 v186, v175, v183
	v_mul_f32_e32 v187, v176, v183
	v_fma_f32 v188, v176, v182, -v186
	v_fma_f32 v189, v175, v182, v187
	v_mul_f32_e32 v186, v223, v185
	v_mul_f32_e32 v187, v249, v185
	v_fma_f32 v190, v249, v184, -v186
	v_fma_f32 v191, v223, v184, v187
	v_cvt_pk_bf16_f32 v192, v188, v189
	v_cvt_pk_bf16_f32 v193, v190, v191
	ds_write_b16 v170, v192 offset:5040
	ds_write_b16_d16_hi v170, v192 offset:5072
	ds_write_b16 v170, v193 offset:5104
	ds_write_b16_d16_hi v170, v193 offset:5136
	v_mul_f32_e32 v182, v118, v118
	v_mul_f32_e32 v183, v122, v122
	v_mul_f32_e32 v184, v126, v126
	v_mul_f32_e32 v185, v2, v2
	v_add_f32_e32 v186, v182, v183
	v_add_f32_e32 v186, v186, v184
	v_add_f32_e32 v186, v186, v185
	s_nop 1
	v_add_f32_dpp v186, v186, v186 quad_perm:[1,0,3,2] row_mask:0xf bank_mask:0xf
	s_nop 1
	v_add_f32_dpp v186, v186, v186 quad_perm:[2,3,0,1] row_mask:0xf bank_mask:0xf
	s_nop 1
	v_add_f32_dpp v186, v186, v186 row_half_mirror row_mask:0xf bank_mask:0xf
	s_nop 1
	v_add_f32_dpp v186, v186, v186 row_mirror row_mask:0xf bank_mask:0xf
	v_fmamk_f32 v186, v186, 0x3c800000, v173
	v_rsq_f32_e32 v186, v186
	s_nop 0
	v_mul_f32_e32 v187, v178, v186
	v_mul_f32_e32 v188, v179, v186
	v_mul_f32_e32 v189, v180, v186
	v_mul_f32_e32 v190, v181, v186
	v_mul_f32_e32 v182, v118, v187
	v_mul_f32_e32 v183, v122, v188
	v_mul_f32_e32 v184, v126, v189
	v_mul_f32_e32 v185, v2, v190
	v_mul_f32_e32 v186, v175, v183
	v_mul_f32_e32 v187, v176, v183
	v_fma_f32 v188, v176, v182, -v186
	v_fma_f32 v189, v175, v182, v187
	v_mul_f32_e32 v186, v234, v185
	v_mul_f32_e32 v187, v250, v185
	v_fma_f32 v190, v250, v184, -v186
	v_fma_f32 v191, v234, v184, v187
	v_cvt_pk_bf16_f32 v192, v188, v189
	v_cvt_pk_bf16_f32 v193, v190, v191
	ds_write_b16 v170, v192 offset:6912
	ds_write_b16_d16_hi v170, v192 offset:6944
	ds_write_b16 v170, v193 offset:6976
	ds_write_b16_d16_hi v170, v193 offset:7008
	v_mul_f32_e32 v182, v119, v119
	v_mul_f32_e32 v183, v123, v123
	v_mul_f32_e32 v184, v127, v127
	v_mul_f32_e32 v185, v3, v3
	v_add_f32_e32 v186, v182, v183
	v_add_f32_e32 v186, v186, v184
	v_add_f32_e32 v186, v186, v185
	s_nop 1
	v_add_f32_dpp v186, v186, v186 quad_perm:[1,0,3,2] row_mask:0xf bank_mask:0xf
	s_nop 1
	v_add_f32_dpp v186, v186, v186 quad_perm:[2,3,0,1] row_mask:0xf bank_mask:0xf
	s_nop 1
	v_add_f32_dpp v186, v186, v186 row_half_mirror row_mask:0xf bank_mask:0xf
	s_nop 1
	v_add_f32_dpp v186, v186, v186 row_mirror row_mask:0xf bank_mask:0xf
	v_fmamk_f32 v186, v186, 0x3c800000, v173
	v_rsq_f32_e32 v186, v186
	s_nop 0
	v_mul_f32_e32 v187, v178, v186
	v_mul_f32_e32 v188, v179, v186
	v_mul_f32_e32 v189, v180, v186
	v_mul_f32_e32 v190, v181, v186
	v_mul_f32_e32 v182, v119, v187
	v_mul_f32_e32 v183, v123, v188
	v_mul_f32_e32 v184, v127, v189
	v_mul_f32_e32 v185, v3, v190
	v_mul_f32_e32 v186, v175, v183
	v_mul_f32_e32 v187, v176, v183
	v_fma_f32 v188, v176, v182, -v186
	v_fma_f32 v189, v175, v182, v187
	v_mul_f32_e32 v186, v235, v185
	v_mul_f32_e32 v187, v251, v185
	v_fma_f32 v190, v251, v184, -v186
	v_fma_f32 v191, v235, v184, v187
	v_cvt_pk_bf16_f32 v192, v188, v189
	v_cvt_pk_bf16_f32 v193, v190, v191
	ds_write_b16 v170, v192 offset:7056
	ds_write_b16_d16_hi v170, v192 offset:7088
	ds_write_b16 v170, v193 offset:7120
	ds_write_b16_d16_hi v170, v193 offset:7152
	v_mul_f32_e32 v182, v120, v120
	v_mul_f32_e32 v183, v124, v124
	v_mul_f32_e32 v184, v128, v128
	v_mul_f32_e32 v185, v4, v4
	v_add_f32_e32 v186, v182, v183
	v_add_f32_e32 v186, v186, v184
	v_add_f32_e32 v186, v186, v185
	s_nop 1
	v_add_f32_dpp v186, v186, v186 quad_perm:[1,0,3,2] row_mask:0xf bank_mask:0xf
	s_nop 1
	v_add_f32_dpp v186, v186, v186 quad_perm:[2,3,0,1] row_mask:0xf bank_mask:0xf
	s_nop 1
	v_add_f32_dpp v186, v186, v186 row_half_mirror row_mask:0xf bank_mask:0xf
	s_nop 1
	v_add_f32_dpp v186, v186, v186 row_mirror row_mask:0xf bank_mask:0xf
	v_fmamk_f32 v186, v186, 0x3c800000, v173
	v_rsq_f32_e32 v186, v186
	s_nop 0
	v_mul_f32_e32 v187, v178, v186
	v_mul_f32_e32 v188, v179, v186
	v_mul_f32_e32 v189, v180, v186
	v_mul_f32_e32 v190, v181, v186
	v_mul_f32_e32 v182, v120, v187
	v_mul_f32_e32 v183, v124, v188
	v_mul_f32_e32 v184, v128, v189
	v_mul_f32_e32 v185, v4, v190
	v_mul_f32_e32 v186, v175, v183
	v_mul_f32_e32 v187, v176, v183
	v_fma_f32 v188, v176, v182, -v186
	v_fma_f32 v189, v175, v182, v187
	v_mul_f32_e32 v186, v236, v185
	v_mul_f32_e32 v187, v252, v185
	v_fma_f32 v190, v252, v184, -v186
	v_fma_f32 v191, v236, v184, v187
	v_cvt_pk_bf16_f32 v192, v188, v189
	v_cvt_pk_bf16_f32 v193, v190, v191
	ds_write_b16 v170, v192 offset:7200
	ds_write_b16_d16_hi v170, v192 offset:7232
	ds_write_b16 v170, v193 offset:7264
	ds_write_b16_d16_hi v170, v193 offset:7296
	v_mul_f32_e32 v182, v121, v121
	v_mul_f32_e32 v183, v125, v125
	v_mul_f32_e32 v184, v129, v129
	v_mul_f32_e32 v185, v5, v5
	v_add_f32_e32 v186, v182, v183
	v_add_f32_e32 v186, v186, v184
	v_add_f32_e32 v186, v186, v185
	s_nop 1
	v_add_f32_dpp v186, v186, v186 quad_perm:[1,0,3,2] row_mask:0xf bank_mask:0xf
	s_nop 1
	v_add_f32_dpp v186, v186, v186 quad_perm:[2,3,0,1] row_mask:0xf bank_mask:0xf
	s_nop 1
	v_add_f32_dpp v186, v186, v186 row_half_mirror row_mask:0xf bank_mask:0xf
	s_nop 1
	v_add_f32_dpp v186, v186, v186 row_mirror row_mask:0xf bank_mask:0xf
	v_fmamk_f32 v186, v186, 0x3c800000, v173
	v_rsq_f32_e32 v186, v186
	s_nop 0
	v_mul_f32_e32 v187, v178, v186
	v_mul_f32_e32 v188, v179, v186
	v_mul_f32_e32 v189, v180, v186
	v_mul_f32_e32 v190, v181, v186
	v_mul_f32_e32 v182, v121, v187
	v_mul_f32_e32 v183, v125, v188
	v_mul_f32_e32 v184, v129, v189
	v_mul_f32_e32 v185, v5, v190
	v_mul_f32_e32 v186, v175, v183
	v_mul_f32_e32 v187, v176, v183
	v_fma_f32 v188, v176, v182, -v186
	v_fma_f32 v189, v175, v182, v187
	v_mul_f32_e32 v186, v237, v185
	v_mul_f32_e32 v187, v253, v185
	v_fma_f32 v190, v253, v184, -v186
	v_fma_f32 v191, v237, v184, v187
	v_cvt_pk_bf16_f32 v192, v188, v189
	v_cvt_pk_bf16_f32 v193, v190, v191
	ds_write_b16 v170, v192 offset:7344
	ds_write_b16_d16_hi v170, v192 offset:7376
	ds_write_b16 v170, v193 offset:7408
	ds_write_b16_d16_hi v170, v193 offset:7440
	ds_read_b128 v[130:133], v171 offset:0
	ds_read_b128 v[134:137], v171 offset:1152
	ds_read_b128 v[138:141], v171 offset:2304
	ds_read_b128 v[142:145], v171 offset:3456
	ds_read_b128 v[146:149], v171 offset:4608
	ds_read_b128 v[150:153], v171 offset:5760
	ds_read_b128 v[154:157], v171 offset:6912
	ds_read_b128 v[158:161], v171 offset:8064
	s_waitcnt lgkmcnt(7)
; template <int EPI>
; DI void gemm_phase(const P& p, int l, const u16* __restrict__ A, const u16* __restrict__ Bt, int mpx, char* lds) {
;     ...
;           } else if (tr == 3) {
;             if (donorm) {
;               float ss = v0 * v0 + v1 * v1 + v2 * v2 + v3 * v3;
;               ss += __shfl_xor(ss, 1);
;               ss += __shfl_xor(ss, 2);
;               ss += __shfl_xor(ss, 4);
;               ss += __shfl_xor(ss, 8);
;               const float inv = rsqrtf(ss * (1.f / 64.f) + 1e-6f);
;               v0 *= inv * gv0; v1 *= inv * gv1; v2 *= inv * gv2; v3 *= inv * gv3;
;             }
;             if (dorope) {
;               float sr, cr, sc, cc;
;               sincos_rev((float)(s >> 6) * invf64, sr, cr);
;               sincos_rev((float)(s & 63) * invf64, sc, cc);
;               const float a1 = v0, a2 = v1, b1 = v2, b2 = v3;
;               v0 = a1 * cr - a2 * sr;
;               v1 = a2 * cr + a1 * sr;
;               v2 = b1 * cc - b2 * sc;
;               v3 = b2 * cc + b1 * sc;
;             }
;           } else if (tr == 4) {
;             float sr, cr, sc, cc;
;             sincos_rev((float)(s >> 6) * invf32, sr, cr);
;             sincos_rev((float)(s & 63) * invf32, sc, cc);
;             const float p0 = __shfl_xor(v0, 8), p1 = __shfl_xor(v1, 8), p2 = __shfl_xor(v2, 8), p3 = __shfl_xor(v3, 8);
;             v0 = lo8 ? (v0 * cr - p0 * sr) : (v0 * cr + p0 * sr);
;             v1 = lo8 ? (v1 * cc - p1 * sc) : (v1 * cc + p1 * sc);
;             v2 = lo8 ? (v2 * cr - p2 * sr) : (v2 * cr + p2 * sr);
;             v3 = lo8 ? (v3 * cc - p3 * sc) : (v3 * cc + p3 * sc);
;           }
;           const unsigned u01 = pack2(v0, v1), u23 = pack2(v2, v3);
;           if (kind == 1) {
;             Tl[(0 * 16 + r) * 72 + rowl] = (u16)u01;
;             Tl[(1 * 16 + r) * 72 + rowl] = (u16)(u01 >> 16);
;             Tl[(2 * 16 + r) * 72 + rowl] = (u16)u23;
;             Tl[(3 * 16 + r) * 72 + rowl] = (u16)(u23 >> 16);
;           } else if (tr == 2) {
;             Tl[rowl * 72 + 0 * 16 + r] = f2h(v0);
;             Tl[rowl * 72 + 1 * 16 + r] = f2h(v1);
;             Tl[rowl * 72 + 2 * 16 + r] = f2h(v2);
;             Tl[rowl * 72 + 3 * 16 + r] = f2h(v3);
;           } else {
;             Tl[rowl * 72 + 0 * 16 + r] = (u16)u01;
;             Tl[rowl * 72 + 1 * 16 + r] = (u16)(u01 >> 16);
;             Tl[rowl * 72 + 2 * 16 + r] = (u16)u23;
	global_store_dwordx4 v172, v[130:133], s[44:45] offset:0 sc1
	s_waitcnt lgkmcnt(6)
	global_store_dwordx4 v172, v[134:137], s[44:45] offset:1024 sc1
	s_waitcnt lgkmcnt(5)
	global_store_dwordx4 v172, v[138:141], s[44:45] offset:2048 sc1
	s_waitcnt lgkmcnt(4)
	global_store_dwordx4 v172, v[142:145], s[44:45] offset:3072 sc1
	s_waitcnt lgkmcnt(3)
	global_store_dwordx4 v172, v[146:149], s[62:63] offset:0 sc1
	s_waitcnt lgkmcnt(2)
	global_store_dwordx4 v172, v[150:153], s[62:63] offset:1024 sc1
	s_waitcnt lgkmcnt(1)
	global_store_dwordx4 v172, v[154:157], s[62:63] offset:2048 sc1
	s_waitcnt lgkmcnt(0)
	global_store_dwordx4 v172, v[158:161], s[62:63] offset:3072 sc1
	s_branch .Lfe_done
.Lfe_k0_norm:
	s_cmp_lt_u32 s43, 20
	s_movk_i32 s70, 0x68
	s_cselect_b32 s70, 0x60, s70
	s_add_u32 s70, s96, s70
	s_addc_u32 s71, s97, 0
	s_load_dwordx2 s[70:71], s[70:71], 0x0
	v_and_b32_e32 v0, 15, v226
	v_lshlrev_b32_e32 v0, 2, v0
	v_mov_b32_e32 v173, 0x358637bd
	s_waitcnt lgkmcnt(0)
	s_lshl_b32 s63, s52, 2
	s_add_u32 s70, s70, s63
	s_addc_u32 s71, s71, 0
	global_load_dword v178, v0, s[70:71] offset:0
	global_load_dword v179, v0, s[70:71] offset:64
	global_load_dword v180, v0, s[70:71] offset:128
	global_load_dword v181, v0, s[70:71] offset:192
	s_waitcnt vmcnt(0)
	s_add_u32 s62, s44, 0x1000
	s_addc_u32 s63, s45, 0
	v_mul_f32_e32 v182, v6, v6
	v_mul_f32_e32 v183, v10, v10
	v_mul_f32_e32 v184, v14, v14
	v_mul_f32_e32 v185, v18, v18
	v_add_f32_e32 v186, v182, v183
	v_add_f32_e32 v186, v186, v184
	v_add_f32_e32 v186, v186, v185
	s_nop 1
	v_add_f32_dpp v186, v186, v186 quad_perm:[1,0,3,2] row_mask:0xf bank_mask:0xf
	s_nop 1
	v_add_f32_dpp v186, v186, v186 quad_perm:[2,3,0,1] row_mask:0xf bank_mask:0xf
	s_nop 1
	v_add_f32_dpp v186, v186, v186 row_half_mirror row_mask:0xf bank_mask:0xf
	s_nop 1
	v_add_f32_dpp v186, v186, v186 row_mirror row_mask:0xf bank_mask:0xf
	v_fmamk_f32 v186, v186, 0x3c800000, v173
	v_rsq_f32_e32 v186, v186
	s_nop 0
	v_mul_f32_e32 v187, v178, v186
	v_mul_f32_e32 v188, v179, v186
	v_mul_f32_e32 v189, v180, v186
	v_mul_f32_e32 v190, v181, v186
	v_mul_f32_e32 v182, v6, v187
	v_mul_f32_e32 v183, v10, v188
	v_mul_f32_e32 v184, v14, v189
	v_mul_f32_e32 v185, v18, v190
	v_cvt_pk_bf16_f32 v192, v182, v183
	v_cvt_pk_bf16_f32 v193, v184, v185
	ds_write_b16 v170, v192 offset:0
	ds_write_b16_d16_hi v170, v192 offset:32
	ds_write_b16 v170, v193 offset:64
	ds_write_b16_d16_hi v170, v193 offset:96
	v_mul_f32_e32 v182, v7, v7
	v_mul_f32_e32 v183, v11, v11
	v_mul_f32_e32 v184, v15, v15
	v_mul_f32_e32 v185, v19, v19
	v_add_f32_e32 v186, v182, v183
	v_add_f32_e32 v186, v186, v184
	v_add_f32_e32 v186, v186, v185
	s_nop 1
	v_add_f32_dpp v186, v186, v186 quad_perm:[1,0,3,2] row_mask:0xf bank_mask:0xf
	s_nop 1
	v_add_f32_dpp v186, v186, v186 quad_perm:[2,3,0,1] row_mask:0xf bank_mask:0xf
	s_nop 1
	v_add_f32_dpp v186, v186, v186 row_half_mirror row_mask:0xf bank_mask:0xf
	s_nop 1
	v_add_f32_dpp v186, v186, v186 row_mirror row_mask:0xf bank_mask:0xf
	v_fmamk_f32 v186, v186, 0x3c800000, v173
	v_rsq_f32_e32 v186, v186
	s_nop 0
	v_mul_f32_e32 v187, v178, v186
	v_mul_f32_e32 v188, v179, v186
	v_mul_f32_e32 v189, v180, v186
	v_mul_f32_e32 v190, v181, v186
	v_mul_f32_e32 v182, v7, v187
	v_mul_f32_e32 v183, v11, v188
	v_mul_f32_e32 v184, v15, v189
	v_mul_f32_e32 v185, v19, v190
	v_cvt_pk_bf16_f32 v192, v182, v183
	v_cvt_pk_bf16_f32 v193, v184, v185
	ds_write_b16 v170, v192 offset:144
	ds_write_b16_d16_hi v170, v192 offset:176
	ds_write_b16 v170, v193 offset:208
	ds_write_b16_d16_hi v170, v193 offset:240
	v_mul_f32_e32 v182, v8, v8
	v_mul_f32_e32 v183, v12, v12
	v_mul_f32_e32 v184, v16, v16
	v_mul_f32_e32 v185, v20, v20
	v_add_f32_e32 v186, v182, v183
	v_add_f32_e32 v186, v186, v184
	v_add_f32_e32 v186, v186, v185
	s_nop 1
	v_add_f32_dpp v186, v186, v186 quad_perm:[1,0,3,2] row_mask:0xf bank_mask:0xf
	s_nop 1
	v_add_f32_dpp v186, v186, v186 quad_perm:[2,3,0,1] row_mask:0xf bank_mask:0xf
	s_nop 1
	v_add_f32_dpp v186, v186, v186 row_half_mirror row_mask:0xf bank_mask:0xf
	s_nop 1
	v_add_f32_dpp v186, v186, v186 row_mirror row_mask:0xf bank_mask:0xf
	v_fmamk_f32 v186, v186, 0x3c800000, v173
	v_rsq_f32_e32 v186, v186
	s_nop 0
	v_mul_f32_e32 v187, v178, v186
	v_mul_f32_e32 v188, v179, v186
	v_mul_f32_e32 v189, v180, v186
	v_mul_f32_e32 v190, v181, v186
	v_mul_f32_e32 v182, v8, v187
	v_mul_f32_e32 v183, v12, v188
	v_mul_f32_e32 v184, v16, v189
	v_mul_f32_e32 v185, v20, v190
	v_cvt_pk_bf16_f32 v192, v182, v183
	v_cvt_pk_bf16_f32 v193, v184, v185
	ds_write_b16 v170, v192 offset:288
	ds_write_b16_d16_hi v170, v192 offset:320
	ds_write_b16 v170, v193 offset:352
	ds_write_b16_d16_hi v170, v193 offset:384
	v_mul_f32_e32 v182, v9, v9
	v_mul_f32_e32 v183, v13, v13
	v_mul_f32_e32 v184, v17, v17
	v_mul_f32_e32 v185, v21, v21
	v_add_f32_e32 v186, v182, v183
	v_add_f32_e32 v186, v186, v184
	v_add_f32_e32 v186, v186, v185
	s_nop 1
	v_add_f32_dpp v186, v186, v186 quad_perm:[1,0,3,2] row_mask:0xf bank_mask:0xf
	s_nop 1
	v_add_f32_dpp v186, v186, v186 quad_perm:[2,3,0,1] row_mask:0xf bank_mask:0xf
	s_nop 1
	v_add_f32_dpp v186, v186, v186 row_half_mirror row_mask:0xf bank_mask:0xf
	s_nop 1
	v_add_f32_dpp v186, v186, v186 row_mirror row_mask:0xf bank_mask:0xf
	v_fmamk_f32 v186, v186, 0x3c800000, v173
	v_rsq_f32_e32 v186, v186
	s_nop 0
	v_mul_f32_e32 v187, v178, v186
	v_mul_f32_e32 v188, v179, v186
	v_mul_f32_e32 v189, v180, v186
	v_mul_f32_e32 v190, v181, v186
	v_mul_f32_e32 v182, v9, v187
	v_mul_f32_e32 v183, v13, v188
	v_mul_f32_e32 v184, v17, v189
	v_mul_f32_e32 v185, v21, v190
	v_cvt_pk_bf16_f32 v192, v182, v183
	v_cvt_pk_bf16_f32 v193, v184, v185
	ds_write_b16 v170, v192 offset:432
; template <int EPI>
; DI void gemm_phase(const P& p, int l, const u16* __restrict__ A, const u16* __restrict__ Bt, int mpx, char* lds) {
;     ...
;           } else if (tr == 3) {
;             if (donorm) {
;               float ss = v0 * v0 + v1 * v1 + v2 * v2 + v3 * v3;
;               ss += __shfl_xor(ss, 1);
;               ss += __shfl_xor(ss, 2);
;               ss += __shfl_xor(ss, 4);
;               ss += __shfl_xor(ss, 8);
;               const float inv = rsqrtf(ss * (1.f / 64.f) + 1e-6f);
;               v0 *= inv * gv0; v1 *= inv * gv1; v2 *= inv * gv2; v3 *= inv * gv3;
;             }
;             if (dorope) {
;               float sr, cr, sc, cc;
;               sincos_rev((float)(s >> 6) * invf64, sr, cr);
;               sincos_rev((float)(s & 63) * invf64, sc, cc);
;               const float a1 = v0, a2 = v1, b1 = v2, b2 = v3;
;               v0 = a1 * cr - a2 * sr;
;               v1 = a2 * cr + a1 * sr;
;               v2 = b1 * cc - b2 * sc;
;               v3 = b2 * cc + b1 * sc;
;             }
;           } else if (tr == 4) {
;             float sr, cr, sc, cc;
;             sincos_rev((float)(s >> 6) * invf32, sr, cr);
;             sincos_rev((float)(s & 63) * invf32, sc, cc);
;             const float p0 = __shfl_xor(v0, 8), p1 = __shfl_xor(v1, 8), p2 = __shfl_xor(v2, 8), p3 = __shfl_xor(v3, 8);
;             v0 = lo8 ? (v0 * cr - p0 * sr) : (v0 * cr + p0 * sr);
;             v1 = lo8 ? (v1 * cc - p1 * sc) : (v1 * cc + p1 * sc);
;             v2 = lo8 ? (v2 * cr - p2 * sr) : (v2 * cr + p2 * sr);
;             v3 = lo8 ? (v3 * cc - p3 * sc) : (v3 * cc + p3 * sc);
;           }
;           const unsigned u01 = pack2(v0, v1), u23 = pack2(v2, v3);
;           if (kind == 1) {
;             Tl[(0 * 16 + r) * 72 + rowl] = (u16)u01;
;             Tl[(1 * 16 + r) * 72 + rowl] = (u16)(u01 >> 16);
;             Tl[(2 * 16 + r) * 72 + rowl] = (u16)u23;
;             Tl[(3 * 16 + r) * 72 + rowl] = (u16)(u23 >> 16);
;           } else if (tr == 2) {
;             Tl[rowl * 72 + 0 * 16 + r] = f2h(v0);
;             Tl[rowl * 72 + 1 * 16 + r] = f2h(v1);
;             Tl[rowl * 72 + 2 * 16 + r] = f2h(v2);
;             Tl[rowl * 72 + 3 * 16 + r] = f2h(v3);
;           } else {
;             Tl[rowl * 72 + 0 * 16 + r] = (u16)u01;
;             Tl[rowl * 72 + 1 * 16 + r] = (u16)(u01 >> 16);
;             Tl[rowl * 72 + 2 * 16 + r] = (u16)u23;
	ds_write_b16_d16_hi v170, v192 offset:464
	ds_write_b16 v170, v193 offset:496
	ds_write_b16_d16_hi v170, v193 offset:528
	v_mul_f32_e32 v182, v22, v22
	v_mul_f32_e32 v183, v26, v26
	v_mul_f32_e32 v184, v30, v30
	v_mul_f32_e32 v185, v34, v34
	v_add_f32_e32 v186, v182, v183
	v_add_f32_e32 v186, v186, v184
	v_add_f32_e32 v186, v186, v185
	s_nop 1
	v_add_f32_dpp v186, v186, v186 quad_perm:[1,0,3,2] row_mask:0xf bank_mask:0xf
	s_nop 1
	v_add_f32_dpp v186, v186, v186 quad_perm:[2,3,0,1] row_mask:0xf bank_mask:0xf
	s_nop 1
	v_add_f32_dpp v186, v186, v186 row_half_mirror row_mask:0xf bank_mask:0xf
	s_nop 1
	v_add_f32_dpp v186, v186, v186 row_mirror row_mask:0xf bank_mask:0xf
	v_fmamk_f32 v186, v186, 0x3c800000, v173
	v_rsq_f32_e32 v186, v186
	s_nop 0
	v_mul_f32_e32 v187, v178, v186
	v_mul_f32_e32 v188, v179, v186
	v_mul_f32_e32 v189, v180, v186
	v_mul_f32_e32 v190, v181, v186
	v_mul_f32_e32 v182, v22, v187
	v_mul_f32_e32 v183, v26, v188
	v_mul_f32_e32 v184, v30, v189
	v_mul_f32_e32 v185, v34, v190
	v_cvt_pk_bf16_f32 v192, v182, v183
	v_cvt_pk_bf16_f32 v193, v184, v185
	ds_write_b16 v170, v192 offset:2304
	ds_write_b16_d16_hi v170, v192 offset:2336
	ds_write_b16 v170, v193 offset:2368
	ds_write_b16_d16_hi v170, v193 offset:2400
	v_mul_f32_e32 v182, v23, v23
	v_mul_f32_e32 v183, v27, v27
	v_mul_f32_e32 v184, v31, v31
	v_mul_f32_e32 v185, v35, v35
	v_add_f32_e32 v186, v182, v183
	v_add_f32_e32 v186, v186, v184
	v_add_f32_e32 v186, v186, v185
	s_nop 1
	v_add_f32_dpp v186, v186, v186 quad_perm:[1,0,3,2] row_mask:0xf bank_mask:0xf
	s_nop 1
	v_add_f32_dpp v186, v186, v186 quad_perm:[2,3,0,1] row_mask:0xf bank_mask:0xf
	s_nop 1
	v_add_f32_dpp v186, v186, v186 row_half_mirror row_mask:0xf bank_mask:0xf
	s_nop 1
	v_add_f32_dpp v186, v186, v186 row_mirror row_mask:0xf bank_mask:0xf
	v_fmamk_f32 v186, v186, 0x3c800000, v173
	v_rsq_f32_e32 v186, v186
	s_nop 0
	v_mul_f32_e32 v187, v178, v186
	v_mul_f32_e32 v188, v179, v186
	v_mul_f32_e32 v189, v180, v186
	v_mul_f32_e32 v190, v181, v186
	v_mul_f32_e32 v182, v23, v187
	v_mul_f32_e32 v183, v27, v188
	v_mul_f32_e32 v184, v31, v189
	v_mul_f32_e32 v185, v35, v190
	v_cvt_pk_bf16_f32 v192, v182, v183
	v_cvt_pk_bf16_f32 v193, v184, v185
	ds_write_b16 v170, v192 offset:2448
	ds_write_b16_d16_hi v170, v192 offset:2480
	ds_write_b16 v170, v193 offset:2512
	ds_write_b16_d16_hi v170, v193 offset:2544
	v_mul_f32_e32 v182, v24, v24
	v_mul_f32_e32 v183, v28, v28
	v_mul_f32_e32 v184, v32, v32
	v_mul_f32_e32 v185, v36, v36
	v_add_f32_e32 v186, v182, v183
	v_add_f32_e32 v186, v186, v184
	v_add_f32_e32 v186, v186, v185
	s_nop 1
	v_add_f32_dpp v186, v186, v186 quad_perm:[1,0,3,2] row_mask:0xf bank_mask:0xf
	s_nop 1
	v_add_f32_dpp v186, v186, v186 quad_perm:[2,3,0,1] row_mask:0xf bank_mask:0xf
	s_nop 1
	v_add_f32_dpp v186, v186, v186 row_half_mirror row_mask:0xf bank_mask:0xf
	s_nop 1
	v_add_f32_dpp v186, v186, v186 row_mirror row_mask:0xf bank_mask:0xf
	v_fmamk_f32 v186, v186, 0x3c800000, v173
	v_rsq_f32_e32 v186, v186
	s_nop 0
	v_mul_f32_e32 v187, v178, v186
	v_mul_f32_e32 v188, v179, v186
	v_mul_f32_e32 v189, v180, v186
	v_mul_f32_e32 v190, v181, v186
	v_mul_f32_e32 v182, v24, v187
	v_mul_f32_e32 v183, v28, v188
	v_mul_f32_e32 v184, v32, v189
	v_mul_f32_e32 v185, v36, v190
	v_cvt_pk_bf16_f32 v192, v182, v183
	v_cvt_pk_bf16_f32 v193, v184, v185
	ds_write_b16 v170, v192 offset:2592
	ds_write_b16_d16_hi v170, v192 offset:2624
	ds_write_b16 v170, v193 offset:2656
	ds_write_b16_d16_hi v170, v193 offset:2688
	v_mul_f32_e32 v182, v25, v25
	v_mul_f32_e32 v183, v29, v29
	v_mul_f32_e32 v184, v33, v33
	v_mul_f32_e32 v185, v37, v37
	v_add_f32_e32 v186, v182, v183
	v_add_f32_e32 v186, v186, v184
	v_add_f32_e32 v186, v186, v185
	s_nop 1
	v_add_f32_dpp v186, v186, v186 quad_perm:[1,0,3,2] row_mask:0xf bank_mask:0xf
	s_nop 1
	v_add_f32_dpp v186, v186, v186 quad_perm:[2,3,0,1] row_mask:0xf bank_mask:0xf
	s_nop 1
	v_add_f32_dpp v186, v186, v186 row_half_mirror row_mask:0xf bank_mask:0xf
	s_nop 1
	v_add_f32_dpp v186, v186, v186 row_mirror row_mask:0xf bank_mask:0xf
	v_fmamk_f32 v186, v186, 0x3c800000, v173
	v_rsq_f32_e32 v186, v186
	s_nop 0
	v_mul_f32_e32 v187, v178, v186
	v_mul_f32_e32 v188, v179, v186
	v_mul_f32_e32 v189, v180, v186
	v_mul_f32_e32 v190, v181, v186
	v_mul_f32_e32 v182, v25, v187
	v_mul_f32_e32 v183, v29, v188
	v_mul_f32_e32 v184, v33, v189
	v_mul_f32_e32 v185, v37, v190
	v_cvt_pk_bf16_f32 v192, v182, v183
	v_cvt_pk_bf16_f32 v193, v184, v185
	ds_write_b16 v170, v192 offset:2736
	ds_write_b16_d16_hi v170, v192 offset:2768
	ds_write_b16 v170, v193 offset:2800
	ds_write_b16_d16_hi v170, v193 offset:2832
	v_mul_f32_e32 v182, v38, v38
	v_mul_f32_e32 v183, v42, v42
	v_mul_f32_e32 v184, v46, v46
	v_mul_f32_e32 v185, v50, v50
	v_add_f32_e32 v186, v182, v183
	v_add_f32_e32 v186, v186, v184
	v_add_f32_e32 v186, v186, v185
	s_nop 1
	v_add_f32_dpp v186, v186, v186 quad_perm:[1,0,3,2] row_mask:0xf bank_mask:0xf
	s_nop 1
	v_add_f32_dpp v186, v186, v186 quad_perm:[2,3,0,1] row_mask:0xf bank_mask:0xf
	s_nop 1
	v_add_f32_dpp v186, v186, v186 row_half_mirror row_mask:0xf bank_mask:0xf
	s_nop 1
	v_add_f32_dpp v186, v186, v186 row_mirror row_mask:0xf bank_mask:0xf
	v_fmamk_f32 v186, v186, 0x3c800000, v173
	v_rsq_f32_e32 v186, v186
	s_nop 0
	v_mul_f32_e32 v187, v178, v186
	v_mul_f32_e32 v188, v179, v186
	v_mul_f32_e32 v189, v180, v186
	v_mul_f32_e32 v190, v181, v186
	v_mul_f32_e32 v182, v38, v187
	v_mul_f32_e32 v183, v42, v188
	v_mul_f32_e32 v184, v46, v189
	v_mul_f32_e32 v185, v50, v190
	v_cvt_pk_bf16_f32 v192, v182, v183
	v_cvt_pk_bf16_f32 v193, v184, v185
	ds_write_b16 v170, v192 offset:4608
	ds_write_b16_d16_hi v170, v192 offset:4640
; template <int EPI>
; DI void gemm_phase(const P& p, int l, const u16* __restrict__ A, const u16* __restrict__ Bt, int mpx, char* lds) {
;     ...
;           } else if (tr == 3) {
;             if (donorm) {
;               float ss = v0 * v0 + v1 * v1 + v2 * v2 + v3 * v3;
;               ss += __shfl_xor(ss, 1);
;               ss += __shfl_xor(ss, 2);
;               ss += __shfl_xor(ss, 4);
;               ss += __shfl_xor(ss, 8);
;               const float inv = rsqrtf(ss * (1.f / 64.f) + 1e-6f);
;               v0 *= inv * gv0; v1 *= inv * gv1; v2 *= inv * gv2; v3 *= inv * gv3;
;             }
;             if (dorope) {
;               float sr, cr, sc, cc;
;               sincos_rev((float)(s >> 6) * invf64, sr, cr);
;               sincos_rev((float)(s & 63) * invf64, sc, cc);
;               const float a1 = v0, a2 = v1, b1 = v2, b2 = v3;
;               v0 = a1 * cr - a2 * sr;
;               v1 = a2 * cr + a1 * sr;
;               v2 = b1 * cc - b2 * sc;
;               v3 = b2 * cc + b1 * sc;
;             }
;           } else if (tr == 4) {
;             float sr, cr, sc, cc;
;             sincos_rev((float)(s >> 6) * invf32, sr, cr);
;             sincos_rev((float)(s & 63) * invf32, sc, cc);
;             const float p0 = __shfl_xor(v0, 8), p1 = __shfl_xor(v1, 8), p2 = __shfl_xor(v2, 8), p3 = __shfl_xor(v3, 8);
;             v0 = lo8 ? (v0 * cr - p0 * sr) : (v0 * cr + p0 * sr);
;             v1 = lo8 ? (v1 * cc - p1 * sc) : (v1 * cc + p1 * sc);
;             v2 = lo8 ? (v2 * cr - p2 * sr) : (v2 * cr + p2 * sr);
;             v3 = lo8 ? (v3 * cc - p3 * sc) : (v3 * cc + p3 * sc);
;           }
;           const unsigned u01 = pack2(v0, v1), u23 = pack2(v2, v3);
;           if (kind == 1) {
;             Tl[(0 * 16 + r) * 72 + rowl] = (u16)u01;
;             Tl[(1 * 16 + r) * 72 + rowl] = (u16)(u01 >> 16);
;             Tl[(2 * 16 + r) * 72 + rowl] = (u16)u23;
;             Tl[(3 * 16 + r) * 72 + rowl] = (u16)(u23 >> 16);
;           } else if (tr == 2) {
;             Tl[rowl * 72 + 0 * 16 + r] = f2h(v0);
;             Tl[rowl * 72 + 1 * 16 + r] = f2h(v1);
;             Tl[rowl * 72 + 2 * 16 + r] = f2h(v2);
;             Tl[rowl * 72 + 3 * 16 + r] = f2h(v3);
;           } else {
;             Tl[rowl * 72 + 0 * 16 + r] = (u16)u01;
;             Tl[rowl * 72 + 1 * 16 + r] = (u16)(u01 >> 16);
;             Tl[rowl * 72 + 2 * 16 + r] = (u16)u23;
	ds_write_b16 v170, v193 offset:4672
	ds_write_b16_d16_hi v170, v193 offset:4704
	v_mul_f32_e32 v182, v39, v39
	v_mul_f32_e32 v183, v43, v43
	v_mul_f32_e32 v184, v47, v47
	v_mul_f32_e32 v185, v51, v51
	v_add_f32_e32 v186, v182, v183
	v_add_f32_e32 v186, v186, v184
	v_add_f32_e32 v186, v186, v185
	s_nop 1
	v_add_f32_dpp v186, v186, v186 quad_perm:[1,0,3,2] row_mask:0xf bank_mask:0xf
	s_nop 1
	v_add_f32_dpp v186, v186, v186 quad_perm:[2,3,0,1] row_mask:0xf bank_mask:0xf
	s_nop 1
	v_add_f32_dpp v186, v186, v186 row_half_mirror row_mask:0xf bank_mask:0xf
	s_nop 1
	v_add_f32_dpp v186, v186, v186 row_mirror row_mask:0xf bank_mask:0xf
	v_fmamk_f32 v186, v186, 0x3c800000, v173
	v_rsq_f32_e32 v186, v186
	s_nop 0
	v_mul_f32_e32 v187, v178, v186
	v_mul_f32_e32 v188, v179, v186
	v_mul_f32_e32 v189, v180, v186
	v_mul_f32_e32 v190, v181, v186
	v_mul_f32_e32 v182, v39, v187
	v_mul_f32_e32 v183, v43, v188
	v_mul_f32_e32 v184, v47, v189
	v_mul_f32_e32 v185, v51, v190
	v_cvt_pk_bf16_f32 v192, v182, v183
	v_cvt_pk_bf16_f32 v193, v184, v185
	ds_write_b16 v170, v192 offset:4752
	ds_write_b16_d16_hi v170, v192 offset:4784
	ds_write_b16 v170, v193 offset:4816
	ds_write_b16_d16_hi v170, v193 offset:4848
	v_mul_f32_e32 v182, v40, v40
	v_mul_f32_e32 v183, v44, v44
	v_mul_f32_e32 v184, v48, v48
	v_mul_f32_e32 v185, v52, v52
	v_add_f32_e32 v186, v182, v183
	v_add_f32_e32 v186, v186, v184
	v_add_f32_e32 v186, v186, v185
	s_nop 1
	v_add_f32_dpp v186, v186, v186 quad_perm:[1,0,3,2] row_mask:0xf bank_mask:0xf
	s_nop 1
	v_add_f32_dpp v186, v186, v186 quad_perm:[2,3,0,1] row_mask:0xf bank_mask:0xf
	s_nop 1
	v_add_f32_dpp v186, v186, v186 row_half_mirror row_mask:0xf bank_mask:0xf
	s_nop 1
	v_add_f32_dpp v186, v186, v186 row_mirror row_mask:0xf bank_mask:0xf
	v_fmamk_f32 v186, v186, 0x3c800000, v173
	v_rsq_f32_e32 v186, v186
	s_nop 0
	v_mul_f32_e32 v187, v178, v186
	v_mul_f32_e32 v188, v179, v186
	v_mul_f32_e32 v189, v180, v186
	v_mul_f32_e32 v190, v181, v186
	v_mul_f32_e32 v182, v40, v187
	v_mul_f32_e32 v183, v44, v188
	v_mul_f32_e32 v184, v48, v189
	v_mul_f32_e32 v185, v52, v190
	v_cvt_pk_bf16_f32 v192, v182, v183
	v_cvt_pk_bf16_f32 v193, v184, v185
	ds_write_b16 v170, v192 offset:4896
	ds_write_b16_d16_hi v170, v192 offset:4928
	ds_write_b16 v170, v193 offset:4960
	ds_write_b16_d16_hi v170, v193 offset:4992
	v_mul_f32_e32 v182, v41, v41
	v_mul_f32_e32 v183, v45, v45
	v_mul_f32_e32 v184, v49, v49
	v_mul_f32_e32 v185, v53, v53
	v_add_f32_e32 v186, v182, v183
	v_add_f32_e32 v186, v186, v184
	v_add_f32_e32 v186, v186, v185
	s_nop 1
	v_add_f32_dpp v186, v186, v186 quad_perm:[1,0,3,2] row_mask:0xf bank_mask:0xf
	s_nop 1
	v_add_f32_dpp v186, v186, v186 quad_perm:[2,3,0,1] row_mask:0xf bank_mask:0xf
	s_nop 1
	v_add_f32_dpp v186, v186, v186 row_half_mirror row_mask:0xf bank_mask:0xf
	s_nop 1
	v_add_f32_dpp v186, v186, v186 row_mirror row_mask:0xf bank_mask:0xf
	v_fmamk_f32 v186, v186, 0x3c800000, v173
	v_rsq_f32_e32 v186, v186
	s_nop 0
	v_mul_f32_e32 v187, v178, v186
	v_mul_f32_e32 v188, v179, v186
	v_mul_f32_e32 v189, v180, v186
	v_mul_f32_e32 v190, v181, v186
	v_mul_f32_e32 v182, v41, v187
	v_mul_f32_e32 v183, v45, v188
	v_mul_f32_e32 v184, v49, v189
	v_mul_f32_e32 v185, v53, v190
	v_cvt_pk_bf16_f32 v192, v182, v183
	v_cvt_pk_bf16_f32 v193, v184, v185
	ds_write_b16 v170, v192 offset:5040
	ds_write_b16_d16_hi v170, v192 offset:5072
	ds_write_b16 v170, v193 offset:5104
	ds_write_b16_d16_hi v170, v193 offset:5136
	v_mul_f32_e32 v182, v54, v54
	v_mul_f32_e32 v183, v58, v58
	v_mul_f32_e32 v184, v62, v62
	v_mul_f32_e32 v185, v66, v66
	v_add_f32_e32 v186, v182, v183
	v_add_f32_e32 v186, v186, v184
	v_add_f32_e32 v186, v186, v185
	s_nop 1
	v_add_f32_dpp v186, v186, v186 quad_perm:[1,0,3,2] row_mask:0xf bank_mask:0xf
	s_nop 1
	v_add_f32_dpp v186, v186, v186 quad_perm:[2,3,0,1] row_mask:0xf bank_mask:0xf
	s_nop 1
	v_add_f32_dpp v186, v186, v186 row_half_mirror row_mask:0xf bank_mask:0xf
	s_nop 1
	v_add_f32_dpp v186, v186, v186 row_mirror row_mask:0xf bank_mask:0xf
	v_fmamk_f32 v186, v186, 0x3c800000, v173
	v_rsq_f32_e32 v186, v186
	s_nop 0
	v_mul_f32_e32 v187, v178, v186
	v_mul_f32_e32 v188, v179, v186
	v_mul_f32_e32 v189, v180, v186
	v_mul_f32_e32 v190, v181, v186
	v_mul_f32_e32 v182, v54, v187
	v_mul_f32_e32 v183, v58, v188
	v_mul_f32_e32 v184, v62, v189
	v_mul_f32_e32 v185, v66, v190
	v_cvt_pk_bf16_f32 v192, v182, v183
	v_cvt_pk_bf16_f32 v193, v184, v185
	ds_write_b16 v170, v192 offset:6912
	ds_write_b16_d16_hi v170, v192 offset:6944
	ds_write_b16 v170, v193 offset:6976
	ds_write_b16_d16_hi v170, v193 offset:7008
	v_mul_f32_e32 v182, v55, v55
	v_mul_f32_e32 v183, v59, v59
	v_mul_f32_e32 v184, v63, v63
	v_mul_f32_e32 v185, v67, v67
	v_add_f32_e32 v186, v182, v183
	v_add_f32_e32 v186, v186, v184
	v_add_f32_e32 v186, v186, v185
	s_nop 1
	v_add_f32_dpp v186, v186, v186 quad_perm:[1,0,3,2] row_mask:0xf bank_mask:0xf
	s_nop 1
	v_add_f32_dpp v186, v186, v186 quad_perm:[2,3,0,1] row_mask:0xf bank_mask:0xf
	s_nop 1
	v_add_f32_dpp v186, v186, v186 row_half_mirror row_mask:0xf bank_mask:0xf
	s_nop 1
	v_add_f32_dpp v186, v186, v186 row_mirror row_mask:0xf bank_mask:0xf
	v_fmamk_f32 v186, v186, 0x3c800000, v173
	v_rsq_f32_e32 v186, v186
	s_nop 0
	v_mul_f32_e32 v187, v178, v186
	v_mul_f32_e32 v188, v179, v186
	v_mul_f32_e32 v189, v180, v186
	v_mul_f32_e32 v190, v181, v186
	v_mul_f32_e32 v182, v55, v187
	v_mul_f32_e32 v183, v59, v188
	v_mul_f32_e32 v184, v63, v189
	v_mul_f32_e32 v185, v67, v190
	v_cvt_pk_bf16_f32 v192, v182, v183
	v_cvt_pk_bf16_f32 v193, v184, v185
	ds_write_b16 v170, v192 offset:7056
	ds_write_b16_d16_hi v170, v192 offset:7088
	ds_write_b16 v170, v193 offset:7120
; template <int EPI>
; DI void gemm_phase(const P& p, int l, const u16* __restrict__ A, const u16* __restrict__ Bt, int mpx, char* lds) {
;     ...
;           } else if (tr == 3) {
;             if (donorm) {
;               float ss = v0 * v0 + v1 * v1 + v2 * v2 + v3 * v3;
;               ss += __shfl_xor(ss, 1);
;               ss += __shfl_xor(ss, 2);
;               ss += __shfl_xor(ss, 4);
;               ss += __shfl_xor(ss, 8);
;               const float inv = rsqrtf(ss * (1.f / 64.f) + 1e-6f);
;               v0 *= inv * gv0; v1 *= inv * gv1; v2 *= inv * gv2; v3 *= inv * gv3;
;             }
;             if (dorope) {
;               float sr, cr, sc, cc;
;               sincos_rev((float)(s >> 6) * invf64, sr, cr);
;               sincos_rev((float)(s & 63) * invf64, sc, cc);
;               const float a1 = v0, a2 = v1, b1 = v2, b2 = v3;
;               v0 = a1 * cr - a2 * sr;
;               v1 = a2 * cr + a1 * sr;
;               v2 = b1 * cc - b2 * sc;
;               v3 = b2 * cc + b1 * sc;
;             }
;           } else if (tr == 4) {
;             float sr, cr, sc, cc;
;             sincos_rev((float)(s >> 6) * invf32, sr, cr);
;             sincos_rev((float)(s & 63) * invf32, sc, cc);
;             const float p0 = __shfl_xor(v0, 8), p1 = __shfl_xor(v1, 8), p2 = __shfl_xor(v2, 8), p3 = __shfl_xor(v3, 8);
;             v0 = lo8 ? (v0 * cr - p0 * sr) : (v0 * cr + p0 * sr);
;             v1 = lo8 ? (v1 * cc - p1 * sc) : (v1 * cc + p1 * sc);
;             v2 = lo8 ? (v2 * cr - p2 * sr) : (v2 * cr + p2 * sr);
;             v3 = lo8 ? (v3 * cc - p3 * sc) : (v3 * cc + p3 * sc);
;           }
;           const unsigned u01 = pack2(v0, v1), u23 = pack2(v2, v3);
;           if (kind == 1) {
;             Tl[(0 * 16 + r) * 72 + rowl] = (u16)u01;
;             Tl[(1 * 16 + r) * 72 + rowl] = (u16)(u01 >> 16);
;             Tl[(2 * 16 + r) * 72 + rowl] = (u16)u23;
;             Tl[(3 * 16 + r) * 72 + rowl] = (u16)(u23 >> 16);
;           } else if (tr == 2) {
;             Tl[rowl * 72 + 0 * 16 + r] = f2h(v0);
;             Tl[rowl * 72 + 1 * 16 + r] = f2h(v1);
;             Tl[rowl * 72 + 2 * 16 + r] = f2h(v2);
;             Tl[rowl * 72 + 3 * 16 + r] = f2h(v3);
;           } else {
;             Tl[rowl * 72 + 0 * 16 + r] = (u16)u01;
;             Tl[rowl * 72 + 1 * 16 + r] = (u16)(u01 >> 16);
;             Tl[rowl * 72 + 2 * 16 + r] = (u16)u23;
	ds_write_b16_d16_hi v170, v193 offset:7152
	v_mul_f32_e32 v182, v56, v56
	v_mul_f32_e32 v183, v60, v60
	v_mul_f32_e32 v184, v64, v64
	v_mul_f32_e32 v185, v68, v68
	v_add_f32_e32 v186, v182, v183
	v_add_f32_e32 v186, v186, v184
	v_add_f32_e32 v186, v186, v185
	s_nop 1
	v_add_f32_dpp v186, v186, v186 quad_perm:[1,0,3,2] row_mask:0xf bank_mask:0xf
	s_nop 1
	v_add_f32_dpp v186, v186, v186 quad_perm:[2,3,0,1] row_mask:0xf bank_mask:0xf
	s_nop 1
	v_add_f32_dpp v186, v186, v186 row_half_mirror row_mask:0xf bank_mask:0xf
	s_nop 1
	v_add_f32_dpp v186, v186, v186 row_mirror row_mask:0xf bank_mask:0xf
	v_fmamk_f32 v186, v186, 0x3c800000, v173
	v_rsq_f32_e32 v186, v186
	s_nop 0
	v_mul_f32_e32 v187, v178, v186
	v_mul_f32_e32 v188, v179, v186
	v_mul_f32_e32 v189, v180, v186
	v_mul_f32_e32 v190, v181, v186
	v_mul_f32_e32 v182, v56, v187
	v_mul_f32_e32 v183, v60, v188
	v_mul_f32_e32 v184, v64, v189
	v_mul_f32_e32 v185, v68, v190
	v_cvt_pk_bf16_f32 v192, v182, v183
	v_cvt_pk_bf16_f32 v193, v184, v185
	ds_write_b16 v170, v192 offset:7200
	ds_write_b16_d16_hi v170, v192 offset:7232
	ds_write_b16 v170, v193 offset:7264
	ds_write_b16_d16_hi v170, v193 offset:7296
	v_mul_f32_e32 v182, v57, v57
	v_mul_f32_e32 v183, v61, v61
	v_mul_f32_e32 v184, v65, v65
	v_mul_f32_e32 v185, v69, v69
	v_add_f32_e32 v186, v182, v183
	v_add_f32_e32 v186, v186, v184
	v_add_f32_e32 v186, v186, v185
	s_nop 1
	v_add_f32_dpp v186, v186, v186 quad_perm:[1,0,3,2] row_mask:0xf bank_mask:0xf
	s_nop 1
	v_add_f32_dpp v186, v186, v186 quad_perm:[2,3,0,1] row_mask:0xf bank_mask:0xf
	s_nop 1
	v_add_f32_dpp v186, v186, v186 row_half_mirror row_mask:0xf bank_mask:0xf
	s_nop 1
	v_add_f32_dpp v186, v186, v186 row_mirror row_mask:0xf bank_mask:0xf
	v_fmamk_f32 v186, v186, 0x3c800000, v173
	v_rsq_f32_e32 v186, v186
	s_nop 0
	v_mul_f32_e32 v187, v178, v186
	v_mul_f32_e32 v188, v179, v186
	v_mul_f32_e32 v189, v180, v186
	v_mul_f32_e32 v190, v181, v186
	v_mul_f32_e32 v182, v57, v187
	v_mul_f32_e32 v183, v61, v188
	v_mul_f32_e32 v184, v65, v189
	v_mul_f32_e32 v185, v69, v190
	v_cvt_pk_bf16_f32 v192, v182, v183
	v_cvt_pk_bf16_f32 v193, v184, v185
	ds_write_b16 v170, v192 offset:7344
	ds_write_b16_d16_hi v170, v192 offset:7376
	ds_write_b16 v170, v193 offset:7408
	ds_write_b16_d16_hi v170, v193 offset:7440
	ds_read_b128 v[130:133], v171 offset:0
	ds_read_b128 v[134:137], v171 offset:1152
	ds_read_b128 v[138:141], v171 offset:2304
	ds_read_b128 v[142:145], v171 offset:3456
	ds_read_b128 v[146:149], v171 offset:4608
	ds_read_b128 v[150:153], v171 offset:5760
	ds_read_b128 v[154:157], v171 offset:6912
	ds_read_b128 v[158:161], v171 offset:8064
	s_waitcnt lgkmcnt(7)
	global_store_dwordx4 v172, v[130:133], s[44:45] offset:0 sc1
	s_waitcnt lgkmcnt(6)
	global_store_dwordx4 v172, v[134:137], s[44:45] offset:1024 sc1
	s_waitcnt lgkmcnt(5)
	global_store_dwordx4 v172, v[138:141], s[44:45] offset:2048 sc1
	s_waitcnt lgkmcnt(4)
	global_store_dwordx4 v172, v[142:145], s[44:45] offset:3072 sc1
	s_waitcnt lgkmcnt(3)
	global_store_dwordx4 v172, v[146:149], s[62:63] offset:0 sc1
	s_waitcnt lgkmcnt(2)
	global_store_dwordx4 v172, v[150:153], s[62:63] offset:1024 sc1
	s_waitcnt lgkmcnt(1)
	global_store_dwordx4 v172, v[154:157], s[62:63] offset:2048 sc1
	s_waitcnt lgkmcnt(0)
	global_store_dwordx4 v172, v[158:161], s[62:63] offset:3072 sc1
	s_add_u32 s44, s44, 0x2000
	s_addc_u32 s45, s45, 0
	s_add_u32 s62, s62, 0x2000
	s_addc_u32 s63, s63, 0
	v_mul_f32_e32 v182, v70, v70
	v_mul_f32_e32 v183, v74, v74
	v_mul_f32_e32 v184, v78, v78
	v_mul_f32_e32 v185, v82, v82
	v_add_f32_e32 v186, v182, v183
	v_add_f32_e32 v186, v186, v184
	v_add_f32_e32 v186, v186, v185
	s_nop 1
	v_add_f32_dpp v186, v186, v186 quad_perm:[1,0,3,2] row_mask:0xf bank_mask:0xf
	s_nop 1
	v_add_f32_dpp v186, v186, v186 quad_perm:[2,3,0,1] row_mask:0xf bank_mask:0xf
	s_nop 1
	v_add_f32_dpp v186, v186, v186 row_half_mirror row_mask:0xf bank_mask:0xf
	s_nop 1
	v_add_f32_dpp v186, v186, v186 row_mirror row_mask:0xf bank_mask:0xf
	v_fmamk_f32 v186, v186, 0x3c800000, v173
	v_rsq_f32_e32 v186, v186
	s_nop 0
	v_mul_f32_e32 v187, v178, v186
	v_mul_f32_e32 v188, v179, v186
	v_mul_f32_e32 v189, v180, v186
	v_mul_f32_e32 v190, v181, v186
	v_mul_f32_e32 v182, v70, v187
	v_mul_f32_e32 v183, v74, v188
	v_mul_f32_e32 v184, v78, v189
	v_mul_f32_e32 v185, v82, v190
	v_cvt_pk_bf16_f32 v192, v182, v183
	v_cvt_pk_bf16_f32 v193, v184, v185
	ds_write_b16 v170, v192 offset:0
	ds_write_b16_d16_hi v170, v192 offset:32
	ds_write_b16 v170, v193 offset:64
	ds_write_b16_d16_hi v170, v193 offset:96
	v_mul_f32_e32 v182, v71, v71
	v_mul_f32_e32 v183, v75, v75
	v_mul_f32_e32 v184, v79, v79
	v_mul_f32_e32 v185, v83, v83
	v_add_f32_e32 v186, v182, v183
	v_add_f32_e32 v186, v186, v184
	v_add_f32_e32 v186, v186, v185
	s_nop 1
	v_add_f32_dpp v186, v186, v186 quad_perm:[1,0,3,2] row_mask:0xf bank_mask:0xf
	s_nop 1
	v_add_f32_dpp v186, v186, v186 quad_perm:[2,3,0,1] row_mask:0xf bank_mask:0xf
	s_nop 1
	v_add_f32_dpp v186, v186, v186 row_half_mirror row_mask:0xf bank_mask:0xf
	s_nop 1
	v_add_f32_dpp v186, v186, v186 row_mirror row_mask:0xf bank_mask:0xf
	v_fmamk_f32 v186, v186, 0x3c800000, v173
	v_rsq_f32_e32 v186, v186
	s_nop 0
	v_mul_f32_e32 v187, v178, v186
	v_mul_f32_e32 v188, v179, v186
	v_mul_f32_e32 v189, v180, v186
	v_mul_f32_e32 v190, v181, v186
	v_mul_f32_e32 v182, v71, v187
	v_mul_f32_e32 v183, v75, v188
	v_mul_f32_e32 v184, v79, v189
	v_mul_f32_e32 v185, v83, v190
	v_cvt_pk_bf16_f32 v192, v182, v183
	v_cvt_pk_bf16_f32 v193, v184, v185
	ds_write_b16 v170, v192 offset:144
	ds_write_b16_d16_hi v170, v192 offset:176
	ds_write_b16 v170, v193 offset:208
	ds_write_b16_d16_hi v170, v193 offset:240
; template <int EPI>
; DI void gemm_phase(const P& p, int l, const u16* __restrict__ A, const u16* __restrict__ Bt, int mpx, char* lds) {
;     ...
;           } else if (tr == 3) {
;             if (donorm) {
;               float ss = v0 * v0 + v1 * v1 + v2 * v2 + v3 * v3;
;               ss += __shfl_xor(ss, 1);
;               ss += __shfl_xor(ss, 2);
;               ss += __shfl_xor(ss, 4);
;               ss += __shfl_xor(ss, 8);
;               const float inv = rsqrtf(ss * (1.f / 64.f) + 1e-6f);
;               v0 *= inv * gv0; v1 *= inv * gv1; v2 *= inv * gv2; v3 *= inv * gv3;
;             }
;     ...
;           } else {
;             Tl[rowl * 72 + 0 * 16 + r] = (u16)u01;
;             Tl[rowl * 72 + 1 * 16 + r] = (u16)(u01 >> 16);
;             Tl[rowl * 72 + 2 * 16 + r] = (u16)u23;
;             Tl[rowl * 72 + 3 * 16 + r] = (u16)(u23 >> 16);
;           }
	v_mul_f32_e32 v182, v72, v72
	v_mul_f32_e32 v183, v76, v76
	v_mul_f32_e32 v184, v80, v80
	v_mul_f32_e32 v185, v84, v84
	v_add_f32_e32 v186, v182, v183
	v_add_f32_e32 v186, v186, v184
	v_add_f32_e32 v186, v186, v185
	s_nop 1
	v_add_f32_dpp v186, v186, v186 quad_perm:[1,0,3,2] row_mask:0xf bank_mask:0xf
	s_nop 1
	v_add_f32_dpp v186, v186, v186 quad_perm:[2,3,0,1] row_mask:0xf bank_mask:0xf
	s_nop 1
	v_add_f32_dpp v186, v186, v186 row_half_mirror row_mask:0xf bank_mask:0xf
	s_nop 1
	v_add_f32_dpp v186, v186, v186 row_mirror row_mask:0xf bank_mask:0xf
	v_fmamk_f32 v186, v186, 0x3c800000, v173
	v_rsq_f32_e32 v186, v186
	s_nop 0
	v_mul_f32_e32 v187, v178, v186
	v_mul_f32_e32 v188, v179, v186
	v_mul_f32_e32 v189, v180, v186
	v_mul_f32_e32 v190, v181, v186
	v_mul_f32_e32 v182, v72, v187
	v_mul_f32_e32 v183, v76, v188
	v_mul_f32_e32 v184, v80, v189
	v_mul_f32_e32 v185, v84, v190
	v_cvt_pk_bf16_f32 v192, v182, v183
	v_cvt_pk_bf16_f32 v193, v184, v185
	ds_write_b16 v170, v192 offset:288
	ds_write_b16_d16_hi v170, v192 offset:320
	ds_write_b16 v170, v193 offset:352
	ds_write_b16_d16_hi v170, v193 offset:384
	v_mul_f32_e32 v182, v73, v73
	v_mul_f32_e32 v183, v77, v77
	v_mul_f32_e32 v184, v81, v81
	v_mul_f32_e32 v185, v85, v85
	v_add_f32_e32 v186, v182, v183
	v_add_f32_e32 v186, v186, v184
	v_add_f32_e32 v186, v186, v185
	s_nop 1
	v_add_f32_dpp v186, v186, v186 quad_perm:[1,0,3,2] row_mask:0xf bank_mask:0xf
	s_nop 1
	v_add_f32_dpp v186, v186, v186 quad_perm:[2,3,0,1] row_mask:0xf bank_mask:0xf
	s_nop 1
	v_add_f32_dpp v186, v186, v186 row_half_mirror row_mask:0xf bank_mask:0xf
	s_nop 1
	v_add_f32_dpp v186, v186, v186 row_mirror row_mask:0xf bank_mask:0xf
	v_fmamk_f32 v186, v186, 0x3c800000, v173
	v_rsq_f32_e32 v186, v186
	s_nop 0
	v_mul_f32_e32 v187, v178, v186
	v_mul_f32_e32 v188, v179, v186
	v_mul_f32_e32 v189, v180, v186
	v_mul_f32_e32 v190, v181, v186
	v_mul_f32_e32 v182, v73, v187
	v_mul_f32_e32 v183, v77, v188
	v_mul_f32_e32 v184, v81, v189
	v_mul_f32_e32 v185, v85, v190
	v_cvt_pk_bf16_f32 v192, v182, v183
	v_cvt_pk_bf16_f32 v193, v184, v185
	ds_write_b16 v170, v192 offset:432
	ds_write_b16_d16_hi v170, v192 offset:464
	ds_write_b16 v170, v193 offset:496
	ds_write_b16_d16_hi v170, v193 offset:528
	v_mul_f32_e32 v182, v86, v86
	v_mul_f32_e32 v183, v90, v90
	v_mul_f32_e32 v184, v94, v94
	v_mul_f32_e32 v185, v98, v98
	v_add_f32_e32 v186, v182, v183
	v_add_f32_e32 v186, v186, v184
	v_add_f32_e32 v186, v186, v185
	s_nop 1
	v_add_f32_dpp v186, v186, v186 quad_perm:[1,0,3,2] row_mask:0xf bank_mask:0xf
	s_nop 1
	v_add_f32_dpp v186, v186, v186 quad_perm:[2,3,0,1] row_mask:0xf bank_mask:0xf
	s_nop 1
	v_add_f32_dpp v186, v186, v186 row_half_mirror row_mask:0xf bank_mask:0xf
	s_nop 1
	v_add_f32_dpp v186, v186, v186 row_mirror row_mask:0xf bank_mask:0xf
	v_fmamk_f32 v186, v186, 0x3c800000, v173
	v_rsq_f32_e32 v186, v186
	s_nop 0
	v_mul_f32_e32 v187, v178, v186
	v_mul_f32_e32 v188, v179, v186
	v_mul_f32_e32 v189, v180, v186
	v_mul_f32_e32 v190, v181, v186
	v_mul_f32_e32 v182, v86, v187
	v_mul_f32_e32 v183, v90, v188
	v_mul_f32_e32 v184, v94, v189
	v_mul_f32_e32 v185, v98, v190
	v_cvt_pk_bf16_f32 v192, v182, v183
	v_cvt_pk_bf16_f32 v193, v184, v185
	ds_write_b16 v170, v192 offset:2304
	ds_write_b16_d16_hi v170, v192 offset:2336
	ds_write_b16 v170, v193 offset:2368
	ds_write_b16_d16_hi v170, v193 offset:2400
	v_mul_f32_e32 v182, v87, v87
	v_mul_f32_e32 v183, v91, v91
	v_mul_f32_e32 v184, v95, v95
	v_mul_f32_e32 v185, v99, v99
	v_add_f32_e32 v186, v182, v183
	v_add_f32_e32 v186, v186, v184
	v_add_f32_e32 v186, v186, v185
	s_nop 1
	v_add_f32_dpp v186, v186, v186 quad_perm:[1,0,3,2] row_mask:0xf bank_mask:0xf
	s_nop 1
	v_add_f32_dpp v186, v186, v186 quad_perm:[2,3,0,1] row_mask:0xf bank_mask:0xf
	s_nop 1
	v_add_f32_dpp v186, v186, v186 row_half_mirror row_mask:0xf bank_mask:0xf
	s_nop 1
	v_add_f32_dpp v186, v186, v186 row_mirror row_mask:0xf bank_mask:0xf
	v_fmamk_f32 v186, v186, 0x3c800000, v173
	v_rsq_f32_e32 v186, v186
	s_nop 0
	v_mul_f32_e32 v187, v178, v186
	v_mul_f32_e32 v188, v179, v186
	v_mul_f32_e32 v189, v180, v186
	v_mul_f32_e32 v190, v181, v186
	v_mul_f32_e32 v182, v87, v187
	v_mul_f32_e32 v183, v91, v188
	v_mul_f32_e32 v184, v95, v189
	v_mul_f32_e32 v185, v99, v190
	v_cvt_pk_bf16_f32 v192, v182, v183
	v_cvt_pk_bf16_f32 v193, v184, v185
	ds_write_b16 v170, v192 offset:2448
	ds_write_b16_d16_hi v170, v192 offset:2480
	ds_write_b16 v170, v193 offset:2512
	ds_write_b16_d16_hi v170, v193 offset:2544
	v_mul_f32_e32 v182, v88, v88
	v_mul_f32_e32 v183, v92, v92
	v_mul_f32_e32 v184, v96, v96
	v_mul_f32_e32 v185, v100, v100
	v_add_f32_e32 v186, v182, v183
	v_add_f32_e32 v186, v186, v184
	v_add_f32_e32 v186, v186, v185
	s_nop 1
	v_add_f32_dpp v186, v186, v186 quad_perm:[1,0,3,2] row_mask:0xf bank_mask:0xf
	s_nop 1
	v_add_f32_dpp v186, v186, v186 quad_perm:[2,3,0,1] row_mask:0xf bank_mask:0xf
	s_nop 1
	v_add_f32_dpp v186, v186, v186 row_half_mirror row_mask:0xf bank_mask:0xf
	s_nop 1
	v_add_f32_dpp v186, v186, v186 row_mirror row_mask:0xf bank_mask:0xf
	v_fmamk_f32 v186, v186, 0x3c800000, v173
	v_rsq_f32_e32 v186, v186
	s_nop 0
	v_mul_f32_e32 v187, v178, v186
	v_mul_f32_e32 v188, v179, v186
	v_mul_f32_e32 v189, v180, v186
	v_mul_f32_e32 v190, v181, v186
	v_mul_f32_e32 v182, v88, v187
	v_mul_f32_e32 v183, v92, v188
	v_mul_f32_e32 v184, v96, v189
	v_mul_f32_e32 v185, v100, v190
	v_cvt_pk_bf16_f32 v192, v182, v183
	v_cvt_pk_bf16_f32 v193, v184, v185
	ds_write_b16 v170, v192 offset:2592
	ds_write_b16_d16_hi v170, v192 offset:2624
	ds_write_b16 v170, v193 offset:2656
	ds_write_b16_d16_hi v170, v193 offset:2688
	v_mul_f32_e32 v182, v89, v89
	v_mul_f32_e32 v183, v93, v93
; template <int EPI>
; DI void gemm_phase(const P& p, int l, const u16* __restrict__ A, const u16* __restrict__ Bt, int mpx, char* lds) {
;     ...
;           } else if (tr == 3) {
;             if (donorm) {
;               float ss = v0 * v0 + v1 * v1 + v2 * v2 + v3 * v3;
;               ss += __shfl_xor(ss, 1);
;               ss += __shfl_xor(ss, 2);
;               ss += __shfl_xor(ss, 4);
;               ss += __shfl_xor(ss, 8);
;               const float inv = rsqrtf(ss * (1.f / 64.f) + 1e-6f);
;               v0 *= inv * gv0; v1 *= inv * gv1; v2 *= inv * gv2; v3 *= inv * gv3;
;             }
;     ...
;           } else {
;             Tl[rowl * 72 + 0 * 16 + r] = (u16)u01;
;             Tl[rowl * 72 + 1 * 16 + r] = (u16)(u01 >> 16);
;             Tl[rowl * 72 + 2 * 16 + r] = (u16)u23;
;             Tl[rowl * 72 + 3 * 16 + r] = (u16)(u23 >> 16);
;           }
	v_mul_f32_e32 v184, v97, v97
	v_mul_f32_e32 v185, v101, v101
	v_add_f32_e32 v186, v182, v183
	v_add_f32_e32 v186, v186, v184
	v_add_f32_e32 v186, v186, v185
	s_nop 1
	v_add_f32_dpp v186, v186, v186 quad_perm:[1,0,3,2] row_mask:0xf bank_mask:0xf
	s_nop 1
	v_add_f32_dpp v186, v186, v186 quad_perm:[2,3,0,1] row_mask:0xf bank_mask:0xf
	s_nop 1
	v_add_f32_dpp v186, v186, v186 row_half_mirror row_mask:0xf bank_mask:0xf
	s_nop 1
	v_add_f32_dpp v186, v186, v186 row_mirror row_mask:0xf bank_mask:0xf
	v_fmamk_f32 v186, v186, 0x3c800000, v173
	v_rsq_f32_e32 v186, v186
	s_nop 0
	v_mul_f32_e32 v187, v178, v186
	v_mul_f32_e32 v188, v179, v186
	v_mul_f32_e32 v189, v180, v186
	v_mul_f32_e32 v190, v181, v186
	v_mul_f32_e32 v182, v89, v187
	v_mul_f32_e32 v183, v93, v188
	v_mul_f32_e32 v184, v97, v189
	v_mul_f32_e32 v185, v101, v190
	v_cvt_pk_bf16_f32 v192, v182, v183
	v_cvt_pk_bf16_f32 v193, v184, v185
	ds_write_b16 v170, v192 offset:2736
	ds_write_b16_d16_hi v170, v192 offset:2768
	ds_write_b16 v170, v193 offset:2800
	ds_write_b16_d16_hi v170, v193 offset:2832
	v_mul_f32_e32 v182, v102, v102
	v_mul_f32_e32 v183, v106, v106
	v_mul_f32_e32 v184, v110, v110
	v_mul_f32_e32 v185, v114, v114
	v_add_f32_e32 v186, v182, v183
	v_add_f32_e32 v186, v186, v184
	v_add_f32_e32 v186, v186, v185
	s_nop 1
	v_add_f32_dpp v186, v186, v186 quad_perm:[1,0,3,2] row_mask:0xf bank_mask:0xf
	s_nop 1
	v_add_f32_dpp v186, v186, v186 quad_perm:[2,3,0,1] row_mask:0xf bank_mask:0xf
	s_nop 1
	v_add_f32_dpp v186, v186, v186 row_half_mirror row_mask:0xf bank_mask:0xf
	s_nop 1
	v_add_f32_dpp v186, v186, v186 row_mirror row_mask:0xf bank_mask:0xf
	v_fmamk_f32 v186, v186, 0x3c800000, v173
	v_rsq_f32_e32 v186, v186
	s_nop 0
	v_mul_f32_e32 v187, v178, v186
	v_mul_f32_e32 v188, v179, v186
	v_mul_f32_e32 v189, v180, v186
	v_mul_f32_e32 v190, v181, v186
	v_mul_f32_e32 v182, v102, v187
	v_mul_f32_e32 v183, v106, v188
	v_mul_f32_e32 v184, v110, v189
	v_mul_f32_e32 v185, v114, v190
	v_cvt_pk_bf16_f32 v192, v182, v183
	v_cvt_pk_bf16_f32 v193, v184, v185
	ds_write_b16 v170, v192 offset:4608
	ds_write_b16_d16_hi v170, v192 offset:4640
	ds_write_b16 v170, v193 offset:4672
	ds_write_b16_d16_hi v170, v193 offset:4704
	v_mul_f32_e32 v182, v103, v103
	v_mul_f32_e32 v183, v107, v107
	v_mul_f32_e32 v184, v111, v111
	v_mul_f32_e32 v185, v115, v115
	v_add_f32_e32 v186, v182, v183
	v_add_f32_e32 v186, v186, v184
	v_add_f32_e32 v186, v186, v185
	s_nop 1
	v_add_f32_dpp v186, v186, v186 quad_perm:[1,0,3,2] row_mask:0xf bank_mask:0xf
	s_nop 1
	v_add_f32_dpp v186, v186, v186 quad_perm:[2,3,0,1] row_mask:0xf bank_mask:0xf
	s_nop 1
	v_add_f32_dpp v186, v186, v186 row_half_mirror row_mask:0xf bank_mask:0xf
	s_nop 1
	v_add_f32_dpp v186, v186, v186 row_mirror row_mask:0xf bank_mask:0xf
	v_fmamk_f32 v186, v186, 0x3c800000, v173
	v_rsq_f32_e32 v186, v186
	s_nop 0
	v_mul_f32_e32 v187, v178, v186
	v_mul_f32_e32 v188, v179, v186
	v_mul_f32_e32 v189, v180, v186
	v_mul_f32_e32 v190, v181, v186
	v_mul_f32_e32 v182, v103, v187
	v_mul_f32_e32 v183, v107, v188
	v_mul_f32_e32 v184, v111, v189
	v_mul_f32_e32 v185, v115, v190
	v_cvt_pk_bf16_f32 v192, v182, v183
	v_cvt_pk_bf16_f32 v193, v184, v185
	ds_write_b16 v170, v192 offset:4752
	ds_write_b16_d16_hi v170, v192 offset:4784
	ds_write_b16 v170, v193 offset:4816
	ds_write_b16_d16_hi v170, v193 offset:4848
	v_mul_f32_e32 v182, v104, v104
	v_mul_f32_e32 v183, v108, v108
	v_mul_f32_e32 v184, v112, v112
	v_mul_f32_e32 v185, v116, v116
	v_add_f32_e32 v186, v182, v183
	v_add_f32_e32 v186, v186, v184
	v_add_f32_e32 v186, v186, v185
	s_nop 1
	v_add_f32_dpp v186, v186, v186 quad_perm:[1,0,3,2] row_mask:0xf bank_mask:0xf
	s_nop 1
	v_add_f32_dpp v186, v186, v186 quad_perm:[2,3,0,1] row_mask:0xf bank_mask:0xf
	s_nop 1
	v_add_f32_dpp v186, v186, v186 row_half_mirror row_mask:0xf bank_mask:0xf
	s_nop 1
	v_add_f32_dpp v186, v186, v186 row_mirror row_mask:0xf bank_mask:0xf
	v_fmamk_f32 v186, v186, 0x3c800000, v173
	v_rsq_f32_e32 v186, v186
	s_nop 0
	v_mul_f32_e32 v187, v178, v186
	v_mul_f32_e32 v188, v179, v186
	v_mul_f32_e32 v189, v180, v186
	v_mul_f32_e32 v190, v181, v186
	v_mul_f32_e32 v182, v104, v187
	v_mul_f32_e32 v183, v108, v188
	v_mul_f32_e32 v184, v112, v189
	v_mul_f32_e32 v185, v116, v190
	v_cvt_pk_bf16_f32 v192, v182, v183
	v_cvt_pk_bf16_f32 v193, v184, v185
	ds_write_b16 v170, v192 offset:4896
	ds_write_b16_d16_hi v170, v192 offset:4928
	ds_write_b16 v170, v193 offset:4960
	ds_write_b16_d16_hi v170, v193 offset:4992
	v_mul_f32_e32 v182, v105, v105
	v_mul_f32_e32 v183, v109, v109
	v_mul_f32_e32 v184, v113, v113
	v_mul_f32_e32 v185, v117, v117
	v_add_f32_e32 v186, v182, v183
	v_add_f32_e32 v186, v186, v184
	v_add_f32_e32 v186, v186, v185
	s_nop 1
	v_add_f32_dpp v186, v186, v186 quad_perm:[1,0,3,2] row_mask:0xf bank_mask:0xf
	s_nop 1
	v_add_f32_dpp v186, v186, v186 quad_perm:[2,3,0,1] row_mask:0xf bank_mask:0xf
	s_nop 1
	v_add_f32_dpp v186, v186, v186 row_half_mirror row_mask:0xf bank_mask:0xf
	s_nop 1
	v_add_f32_dpp v186, v186, v186 row_mirror row_mask:0xf bank_mask:0xf
	v_fmamk_f32 v186, v186, 0x3c800000, v173
	v_rsq_f32_e32 v186, v186
	s_nop 0
	v_mul_f32_e32 v187, v178, v186
	v_mul_f32_e32 v188, v179, v186
	v_mul_f32_e32 v189, v180, v186
	v_mul_f32_e32 v190, v181, v186
	v_mul_f32_e32 v182, v105, v187
	v_mul_f32_e32 v183, v109, v188
	v_mul_f32_e32 v184, v113, v189
	v_mul_f32_e32 v185, v117, v190
	v_cvt_pk_bf16_f32 v192, v182, v183
	v_cvt_pk_bf16_f32 v193, v184, v185
	ds_write_b16 v170, v192 offset:5040
	ds_write_b16_d16_hi v170, v192 offset:5072
	ds_write_b16 v170, v193 offset:5104
	ds_write_b16_d16_hi v170, v193 offset:5136
; template <int EPI>
; DI void gemm_phase(const P& p, int l, const u16* __restrict__ A, const u16* __restrict__ Bt, int mpx, char* lds) {
;     ...
;           } else if (tr == 3) {
;             if (donorm) {
;               float ss = v0 * v0 + v1 * v1 + v2 * v2 + v3 * v3;
;               ss += __shfl_xor(ss, 1);
;               ss += __shfl_xor(ss, 2);
;               ss += __shfl_xor(ss, 4);
;               ss += __shfl_xor(ss, 8);
;               const float inv = rsqrtf(ss * (1.f / 64.f) + 1e-6f);
;               v0 *= inv * gv0; v1 *= inv * gv1; v2 *= inv * gv2; v3 *= inv * gv3;
;             }
;     ...
;       __builtin_amdgcn_fence(__ATOMIC_RELEASE, "wavefront");
;       u16* dh = (kind == 1) ? dst + hf * 64 : dst + (size_t)(hf * 64) * rstride;
; #pragma unroll
;       for (int i = 0; i < 8; ++i) {
;         const int c = lane + i * 64;
;         const int row = c >> 3, cc = c & 7;
;         uint4 v = *(const uint4*)&Tl[row * 72 + cc * 8];
;         *(uint4*)(dh + (size_t)row * rstride + cc * 8) = v;
;       }
	v_mul_f32_e32 v182, v118, v118
	v_mul_f32_e32 v183, v122, v122
	v_mul_f32_e32 v184, v126, v126
	v_mul_f32_e32 v185, v2, v2
	v_add_f32_e32 v186, v182, v183
	v_add_f32_e32 v186, v186, v184
	v_add_f32_e32 v186, v186, v185
	s_nop 1
	v_add_f32_dpp v186, v186, v186 quad_perm:[1,0,3,2] row_mask:0xf bank_mask:0xf
	s_nop 1
	v_add_f32_dpp v186, v186, v186 quad_perm:[2,3,0,1] row_mask:0xf bank_mask:0xf
	s_nop 1
	v_add_f32_dpp v186, v186, v186 row_half_mirror row_mask:0xf bank_mask:0xf
	s_nop 1
	v_add_f32_dpp v186, v186, v186 row_mirror row_mask:0xf bank_mask:0xf
	v_fmamk_f32 v186, v186, 0x3c800000, v173
	v_rsq_f32_e32 v186, v186
	s_nop 0
	v_mul_f32_e32 v187, v178, v186
	v_mul_f32_e32 v188, v179, v186
	v_mul_f32_e32 v189, v180, v186
	v_mul_f32_e32 v190, v181, v186
	v_mul_f32_e32 v182, v118, v187
	v_mul_f32_e32 v183, v122, v188
	v_mul_f32_e32 v184, v126, v189
	v_mul_f32_e32 v185, v2, v190
	v_cvt_pk_bf16_f32 v192, v182, v183
	v_cvt_pk_bf16_f32 v193, v184, v185
	ds_write_b16 v170, v192 offset:6912
	ds_write_b16_d16_hi v170, v192 offset:6944
	ds_write_b16 v170, v193 offset:6976
	ds_write_b16_d16_hi v170, v193 offset:7008
	v_mul_f32_e32 v182, v119, v119
	v_mul_f32_e32 v183, v123, v123
	v_mul_f32_e32 v184, v127, v127
	v_mul_f32_e32 v185, v3, v3
	v_add_f32_e32 v186, v182, v183
	v_add_f32_e32 v186, v186, v184
	v_add_f32_e32 v186, v186, v185
	s_nop 1
	v_add_f32_dpp v186, v186, v186 quad_perm:[1,0,3,2] row_mask:0xf bank_mask:0xf
	s_nop 1
	v_add_f32_dpp v186, v186, v186 quad_perm:[2,3,0,1] row_mask:0xf bank_mask:0xf
	s_nop 1
	v_add_f32_dpp v186, v186, v186 row_half_mirror row_mask:0xf bank_mask:0xf
	s_nop 1
	v_add_f32_dpp v186, v186, v186 row_mirror row_mask:0xf bank_mask:0xf
	v_fmamk_f32 v186, v186, 0x3c800000, v173
	v_rsq_f32_e32 v186, v186
	s_nop 0
	v_mul_f32_e32 v187, v178, v186
	v_mul_f32_e32 v188, v179, v186
	v_mul_f32_e32 v189, v180, v186
	v_mul_f32_e32 v190, v181, v186
	v_mul_f32_e32 v182, v119, v187
	v_mul_f32_e32 v183, v123, v188
	v_mul_f32_e32 v184, v127, v189
	v_mul_f32_e32 v185, v3, v190
	v_cvt_pk_bf16_f32 v192, v182, v183
	v_cvt_pk_bf16_f32 v193, v184, v185
	ds_write_b16 v170, v192 offset:7056
	ds_write_b16_d16_hi v170, v192 offset:7088
	ds_write_b16 v170, v193 offset:7120
	ds_write_b16_d16_hi v170, v193 offset:7152
	v_mul_f32_e32 v182, v120, v120
	v_mul_f32_e32 v183, v124, v124
	v_mul_f32_e32 v184, v128, v128
	v_mul_f32_e32 v185, v4, v4
	v_add_f32_e32 v186, v182, v183
	v_add_f32_e32 v186, v186, v184
	v_add_f32_e32 v186, v186, v185
	s_nop 1
	v_add_f32_dpp v186, v186, v186 quad_perm:[1,0,3,2] row_mask:0xf bank_mask:0xf
	s_nop 1
	v_add_f32_dpp v186, v186, v186 quad_perm:[2,3,0,1] row_mask:0xf bank_mask:0xf
	s_nop 1
	v_add_f32_dpp v186, v186, v186 row_half_mirror row_mask:0xf bank_mask:0xf
	s_nop 1
	v_add_f32_dpp v186, v186, v186 row_mirror row_mask:0xf bank_mask:0xf
	v_fmamk_f32 v186, v186, 0x3c800000, v173
	v_rsq_f32_e32 v186, v186
	s_nop 0
	v_mul_f32_e32 v187, v178, v186
	v_mul_f32_e32 v188, v179, v186
	v_mul_f32_e32 v189, v180, v186
	v_mul_f32_e32 v190, v181, v186
	v_mul_f32_e32 v182, v120, v187
	v_mul_f32_e32 v183, v124, v188
	v_mul_f32_e32 v184, v128, v189
	v_mul_f32_e32 v185, v4, v190
	v_cvt_pk_bf16_f32 v192, v182, v183
	v_cvt_pk_bf16_f32 v193, v184, v185
	ds_write_b16 v170, v192 offset:7200
	ds_write_b16_d16_hi v170, v192 offset:7232
	ds_write_b16 v170, v193 offset:7264
	ds_write_b16_d16_hi v170, v193 offset:7296
	v_mul_f32_e32 v182, v121, v121
	v_mul_f32_e32 v183, v125, v125
	v_mul_f32_e32 v184, v129, v129
	v_mul_f32_e32 v185, v5, v5
	v_add_f32_e32 v186, v182, v183
	v_add_f32_e32 v186, v186, v184
	v_add_f32_e32 v186, v186, v185
	s_nop 1
	v_add_f32_dpp v186, v186, v186 quad_perm:[1,0,3,2] row_mask:0xf bank_mask:0xf
	s_nop 1
	v_add_f32_dpp v186, v186, v186 quad_perm:[2,3,0,1] row_mask:0xf bank_mask:0xf
	s_nop 1
	v_add_f32_dpp v186, v186, v186 row_half_mirror row_mask:0xf bank_mask:0xf
	s_nop 1
	v_add_f32_dpp v186, v186, v186 row_mirror row_mask:0xf bank_mask:0xf
	v_fmamk_f32 v186, v186, 0x3c800000, v173
	v_rsq_f32_e32 v186, v186
	s_nop 0
	v_mul_f32_e32 v187, v178, v186
	v_mul_f32_e32 v188, v179, v186
	v_mul_f32_e32 v189, v180, v186
	v_mul_f32_e32 v190, v181, v186
	v_mul_f32_e32 v182, v121, v187
	v_mul_f32_e32 v183, v125, v188
	v_mul_f32_e32 v184, v129, v189
	v_mul_f32_e32 v185, v5, v190
	v_cvt_pk_bf16_f32 v192, v182, v183
	v_cvt_pk_bf16_f32 v193, v184, v185
	ds_write_b16 v170, v192 offset:7344
	ds_write_b16_d16_hi v170, v192 offset:7376
	ds_write_b16 v170, v193 offset:7408
	ds_write_b16_d16_hi v170, v193 offset:7440
	ds_read_b128 v[130:133], v171 offset:0
	ds_read_b128 v[134:137], v171 offset:1152
	ds_read_b128 v[138:141], v171 offset:2304
	ds_read_b128 v[142:145], v171 offset:3456
	ds_read_b128 v[146:149], v171 offset:4608
	ds_read_b128 v[150:153], v171 offset:5760
	ds_read_b128 v[154:157], v171 offset:6912
	ds_read_b128 v[158:161], v171 offset:8064
	s_waitcnt lgkmcnt(7)
	global_store_dwordx4 v172, v[130:133], s[44:45] offset:0 sc1
	s_waitcnt lgkmcnt(6)
	global_store_dwordx4 v172, v[134:137], s[44:45] offset:1024 sc1
	s_waitcnt lgkmcnt(5)
	global_store_dwordx4 v172, v[138:141], s[44:45] offset:2048 sc1
	s_waitcnt lgkmcnt(4)
	global_store_dwordx4 v172, v[142:145], s[44:45] offset:3072 sc1
	s_waitcnt lgkmcnt(3)
	global_store_dwordx4 v172, v[146:149], s[62:63] offset:0 sc1
	s_waitcnt lgkmcnt(2)
	global_store_dwordx4 v172, v[150:153], s[62:63] offset:1024 sc1
	s_waitcnt lgkmcnt(1)
	global_store_dwordx4 v172, v[154:157], s[62:63] offset:2048 sc1
	s_waitcnt lgkmcnt(0)
	global_store_dwordx4 v172, v[158:161], s[62:63] offset:3072 sc1
	s_branch .Lfe_done

; template <int EPI>
; DI void gemm_phase(const P& p, int l, const u16* __restrict__ A, const u16* __restrict__ Bt, int mpx, char* lds) {
;     ...
;           const unsigned u01 = pack2(v0, v1), u23 = pack2(v2, v3);
;           if (kind == 1) {
;             Tl[(0 * 16 + r) * 72 + rowl] = (u16)u01;
;             Tl[(1 * 16 + r) * 72 + rowl] = (u16)(u01 >> 16);
;             Tl[(2 * 16 + r) * 72 + rowl] = (u16)u23;
;             Tl[(3 * 16 + r) * 72 + rowl] = (u16)(u23 >> 16);
;     ...
;       __builtin_amdgcn_fence(__ATOMIC_RELEASE, "wavefront");
;       u16* dh = (kind == 1) ? dst + hf * 64 : dst + (size_t)(hf * 64) * rstride;
; #pragma unroll
;       for (int i = 0; i < 8; ++i) {
;         const int c = lane + i * 64;
;         const int row = c >> 3, cc = c & 7;
;         uint4 v = *(const uint4*)&Tl[row * 72 + cc * 8];
;         *(uint4*)(dh + (size_t)row * rstride + cc * 8) = v;
;       }
.Lfe_k1:
	s_mov_b64 s[62:63], s[44:45]
	v_cvt_pk_bf16_f32 v178, v6, v10
	v_cvt_pk_bf16_f32 v179, v14, v18
	ds_write_b16 v170, v178 offset:0
	ds_write_b16_d16_hi v170, v178 offset:2304
	ds_write_b16 v170, v179 offset:4608
	ds_write_b16_d16_hi v170, v179 offset:6912
	v_cvt_pk_bf16_f32 v184, v7, v11
	v_cvt_pk_bf16_f32 v185, v15, v19
	ds_write_b16 v170, v184 offset:2
	ds_write_b16_d16_hi v170, v184 offset:2306
	ds_write_b16 v170, v185 offset:4610
	ds_write_b16_d16_hi v170, v185 offset:6914
	v_cvt_pk_bf16_f32 v190, v8, v12
	v_cvt_pk_bf16_f32 v191, v16, v20
	ds_write_b16 v170, v190 offset:4
	ds_write_b16_d16_hi v170, v190 offset:2308
	ds_write_b16 v170, v191 offset:4612
	ds_write_b16_d16_hi v170, v191 offset:6916
	v_cvt_pk_bf16_f32 v176, v9, v13
	v_cvt_pk_bf16_f32 v177, v17, v21
	ds_write_b16 v170, v176 offset:6
	ds_write_b16_d16_hi v170, v176 offset:2310
	ds_write_b16 v170, v177 offset:4614
	ds_write_b16_d16_hi v170, v177 offset:6918
	v_cvt_pk_bf16_f32 v182, v22, v26
	v_cvt_pk_bf16_f32 v183, v30, v34
	ds_write_b16 v170, v182 offset:32
	ds_write_b16_d16_hi v170, v182 offset:2336
	ds_write_b16 v170, v183 offset:4640
	ds_write_b16_d16_hi v170, v183 offset:6944
	v_cvt_pk_bf16_f32 v188, v23, v27
	v_cvt_pk_bf16_f32 v189, v31, v35
	ds_write_b16 v170, v188 offset:34
	ds_write_b16_d16_hi v170, v188 offset:2338
	ds_write_b16 v170, v189 offset:4642
	ds_write_b16_d16_hi v170, v189 offset:6946
	v_cvt_pk_bf16_f32 v174, v24, v28
	v_cvt_pk_bf16_f32 v175, v32, v36
	ds_write_b16 v170, v174 offset:36
	ds_write_b16_d16_hi v170, v174 offset:2340
	ds_write_b16 v170, v175 offset:4644
	ds_write_b16_d16_hi v170, v175 offset:6948
	v_cvt_pk_bf16_f32 v180, v25, v29
	v_cvt_pk_bf16_f32 v181, v33, v37
	ds_write_b16 v170, v180 offset:38
	ds_write_b16_d16_hi v170, v180 offset:2342
	ds_write_b16 v170, v181 offset:4646
	ds_write_b16_d16_hi v170, v181 offset:6950
	v_cvt_pk_bf16_f32 v186, v38, v42
	v_cvt_pk_bf16_f32 v187, v46, v50
	ds_write_b16 v170, v186 offset:64
	ds_write_b16_d16_hi v170, v186 offset:2368
	ds_write_b16 v170, v187 offset:4672
	ds_write_b16_d16_hi v170, v187 offset:6976
	v_cvt_pk_bf16_f32 v192, v39, v43
	v_cvt_pk_bf16_f32 v193, v47, v51
	ds_write_b16 v170, v192 offset:66
	ds_write_b16_d16_hi v170, v192 offset:2370
	ds_write_b16 v170, v193 offset:4674
	ds_write_b16_d16_hi v170, v193 offset:6978
	v_cvt_pk_bf16_f32 v178, v40, v44
	v_cvt_pk_bf16_f32 v179, v48, v52
	ds_write_b16 v170, v178 offset:68
	ds_write_b16_d16_hi v170, v178 offset:2372
	ds_write_b16 v170, v179 offset:4676
	ds_write_b16_d16_hi v170, v179 offset:6980
	v_cvt_pk_bf16_f32 v184, v41, v45
	v_cvt_pk_bf16_f32 v185, v49, v53
	ds_write_b16 v170, v184 offset:70
	ds_write_b16_d16_hi v170, v184 offset:2374
	ds_write_b16 v170, v185 offset:4678
	ds_write_b16_d16_hi v170, v185 offset:6982
	v_cvt_pk_bf16_f32 v190, v54, v58
	v_cvt_pk_bf16_f32 v191, v62, v66
	ds_write_b16 v170, v190 offset:96
	ds_write_b16_d16_hi v170, v190 offset:2400
	ds_write_b16 v170, v191 offset:4704
	ds_write_b16_d16_hi v170, v191 offset:7008
	v_cvt_pk_bf16_f32 v176, v55, v59
	v_cvt_pk_bf16_f32 v177, v63, v67
	ds_write_b16 v170, v176 offset:98
	ds_write_b16_d16_hi v170, v176 offset:2402
	ds_write_b16 v170, v177 offset:4706
	ds_write_b16_d16_hi v170, v177 offset:7010
	v_cvt_pk_bf16_f32 v182, v56, v60
	v_cvt_pk_bf16_f32 v183, v64, v68
	ds_write_b16 v170, v182 offset:100
	ds_write_b16_d16_hi v170, v182 offset:2404
	ds_write_b16 v170, v183 offset:4708
	ds_write_b16_d16_hi v170, v183 offset:7012
	v_cvt_pk_bf16_f32 v188, v57, v61
	v_cvt_pk_bf16_f32 v189, v65, v69
	ds_write_b16 v170, v188 offset:102
	ds_write_b16_d16_hi v170, v188 offset:2406
	ds_write_b16 v170, v189 offset:4710
	ds_write_b16_d16_hi v170, v189 offset:7014
	ds_read_b128 v[130:133], v171 offset:0
	ds_read_b128 v[134:137], v171 offset:1152
	ds_read_b128 v[138:141], v171 offset:2304
	ds_read_b128 v[142:145], v171 offset:3456
	ds_read_b128 v[146:149], v171 offset:4608
	ds_read_b128 v[150:153], v171 offset:5760
	ds_read_b128 v[154:157], v171 offset:6912
	ds_read_b128 v[158:161], v171 offset:8064
	s_waitcnt lgkmcnt(7)
	global_store_dwordx4 v172, v[130:133], s[44:45] sc1
	s_add_u32 s44, s44, 0x9000
	s_addc_u32 s45, s45, 0
	s_waitcnt lgkmcnt(6)
	global_store_dwordx4 v172, v[134:137], s[44:45] sc1
	s_add_u32 s44, s44, 0x9000
	s_addc_u32 s45, s45, 0
	s_waitcnt lgkmcnt(5)
	global_store_dwordx4 v172, v[138:141], s[44:45] sc1
	s_add_u32 s44, s44, 0x9000
	s_addc_u32 s45, s45, 0
	s_waitcnt lgkmcnt(4)
	global_store_dwordx4 v172, v[142:145], s[44:45] sc1
	s_add_u32 s44, s44, 0x9000
	s_addc_u32 s45, s45, 0
	s_waitcnt lgkmcnt(3)
	global_store_dwordx4 v172, v[146:149], s[44:45] sc1
	s_add_u32 s44, s44, 0x9000
	s_addc_u32 s45, s45, 0
	s_waitcnt lgkmcnt(2)
	global_store_dwordx4 v172, v[150:153], s[44:45] sc1
	s_add_u32 s44, s44, 0x9000
	s_addc_u32 s45, s45, 0
	s_waitcnt lgkmcnt(1)
	global_store_dwordx4 v172, v[154:157], s[44:45] sc1
	s_add_u32 s44, s44, 0x9000
	s_addc_u32 s45, s45, 0
	s_waitcnt lgkmcnt(0)
; template <int EPI>
; DI void gemm_phase(const P& p, int l, const u16* __restrict__ A, const u16* __restrict__ Bt, int mpx, char* lds) {
;     ...
;           const unsigned u01 = pack2(v0, v1), u23 = pack2(v2, v3);
;           if (kind == 1) {
;             Tl[(0 * 16 + r) * 72 + rowl] = (u16)u01;
;             Tl[(1 * 16 + r) * 72 + rowl] = (u16)(u01 >> 16);
;             Tl[(2 * 16 + r) * 72 + rowl] = (u16)u23;
;             Tl[(3 * 16 + r) * 72 + rowl] = (u16)(u23 >> 16);
;     ...
;       __builtin_amdgcn_fence(__ATOMIC_RELEASE, "wavefront");
;       u16* dh = (kind == 1) ? dst + hf * 64 : dst + (size_t)(hf * 64) * rstride;
; #pragma unroll
;       for (int i = 0; i < 8; ++i) {
;         const int c = lane + i * 64;
;         const int row = c >> 3, cc = c & 7;
;         uint4 v = *(const uint4*)&Tl[row * 72 + cc * 8];
;         *(uint4*)(dh + (size_t)row * rstride + cc * 8) = v;
;       }
	global_store_dwordx4 v172, v[158:161], s[44:45] sc1
	s_add_u32 s44, s62, 0x80
	s_addc_u32 s45, s63, 0
	v_cvt_pk_bf16_f32 v178, v70, v74
	v_cvt_pk_bf16_f32 v179, v78, v82
	ds_write_b16 v170, v178 offset:0
	ds_write_b16_d16_hi v170, v178 offset:2304
	ds_write_b16 v170, v179 offset:4608
	ds_write_b16_d16_hi v170, v179 offset:6912
	v_cvt_pk_bf16_f32 v184, v71, v75
	v_cvt_pk_bf16_f32 v185, v79, v83
	ds_write_b16 v170, v184 offset:2
	ds_write_b16_d16_hi v170, v184 offset:2306
	ds_write_b16 v170, v185 offset:4610
	ds_write_b16_d16_hi v170, v185 offset:6914
	v_cvt_pk_bf16_f32 v190, v72, v76
	v_cvt_pk_bf16_f32 v191, v80, v84
	ds_write_b16 v170, v190 offset:4
	ds_write_b16_d16_hi v170, v190 offset:2308
	ds_write_b16 v170, v191 offset:4612
	ds_write_b16_d16_hi v170, v191 offset:6916
	v_cvt_pk_bf16_f32 v176, v73, v77
	v_cvt_pk_bf16_f32 v177, v81, v85
	ds_write_b16 v170, v176 offset:6
	ds_write_b16_d16_hi v170, v176 offset:2310
	ds_write_b16 v170, v177 offset:4614
	ds_write_b16_d16_hi v170, v177 offset:6918
	v_cvt_pk_bf16_f32 v182, v86, v90
	v_cvt_pk_bf16_f32 v183, v94, v98
	ds_write_b16 v170, v182 offset:32
	ds_write_b16_d16_hi v170, v182 offset:2336
	ds_write_b16 v170, v183 offset:4640
	ds_write_b16_d16_hi v170, v183 offset:6944
	v_cvt_pk_bf16_f32 v188, v87, v91
	v_cvt_pk_bf16_f32 v189, v95, v99
	ds_write_b16 v170, v188 offset:34
	ds_write_b16_d16_hi v170, v188 offset:2338
	ds_write_b16 v170, v189 offset:4642
	ds_write_b16_d16_hi v170, v189 offset:6946
	v_cvt_pk_bf16_f32 v174, v88, v92
	v_cvt_pk_bf16_f32 v175, v96, v100
	ds_write_b16 v170, v174 offset:36
	ds_write_b16_d16_hi v170, v174 offset:2340
	ds_write_b16 v170, v175 offset:4644
	ds_write_b16_d16_hi v170, v175 offset:6948
	v_cvt_pk_bf16_f32 v180, v89, v93
	v_cvt_pk_bf16_f32 v181, v97, v101
	ds_write_b16 v170, v180 offset:38
	ds_write_b16_d16_hi v170, v180 offset:2342
	ds_write_b16 v170, v181 offset:4646
	ds_write_b16_d16_hi v170, v181 offset:6950
	v_cvt_pk_bf16_f32 v186, v102, v106
	v_cvt_pk_bf16_f32 v187, v110, v114
	ds_write_b16 v170, v186 offset:64
	ds_write_b16_d16_hi v170, v186 offset:2368
	ds_write_b16 v170, v187 offset:4672
	ds_write_b16_d16_hi v170, v187 offset:6976
	v_cvt_pk_bf16_f32 v192, v103, v107
	v_cvt_pk_bf16_f32 v193, v111, v115
	ds_write_b16 v170, v192 offset:66
	ds_write_b16_d16_hi v170, v192 offset:2370
	ds_write_b16 v170, v193 offset:4674
	ds_write_b16_d16_hi v170, v193 offset:6978
	v_cvt_pk_bf16_f32 v178, v104, v108
	v_cvt_pk_bf16_f32 v179, v112, v116
	ds_write_b16 v170, v178 offset:68
	ds_write_b16_d16_hi v170, v178 offset:2372
	ds_write_b16 v170, v179 offset:4676
	ds_write_b16_d16_hi v170, v179 offset:6980
	v_cvt_pk_bf16_f32 v184, v105, v109
	v_cvt_pk_bf16_f32 v185, v113, v117
	ds_write_b16 v170, v184 offset:70
	ds_write_b16_d16_hi v170, v184 offset:2374
	ds_write_b16 v170, v185 offset:4678
	ds_write_b16_d16_hi v170, v185 offset:6982
	v_cvt_pk_bf16_f32 v190, v118, v122
	v_cvt_pk_bf16_f32 v191, v126, v2
	ds_write_b16 v170, v190 offset:96
	ds_write_b16_d16_hi v170, v190 offset:2400
	ds_write_b16 v170, v191 offset:4704
	ds_write_b16_d16_hi v170, v191 offset:7008
	v_cvt_pk_bf16_f32 v176, v119, v123
	v_cvt_pk_bf16_f32 v177, v127, v3
	ds_write_b16 v170, v176 offset:98
	ds_write_b16_d16_hi v170, v176 offset:2402
	ds_write_b16 v170, v177 offset:4706
	ds_write_b16_d16_hi v170, v177 offset:7010
	v_cvt_pk_bf16_f32 v182, v120, v124
	v_cvt_pk_bf16_f32 v183, v128, v4
	ds_write_b16 v170, v182 offset:100
	ds_write_b16_d16_hi v170, v182 offset:2404
	ds_write_b16 v170, v183 offset:4708
	ds_write_b16_d16_hi v170, v183 offset:7012
	v_cvt_pk_bf16_f32 v188, v121, v125
	v_cvt_pk_bf16_f32 v189, v129, v5
	ds_write_b16 v170, v188 offset:102
	ds_write_b16_d16_hi v170, v188 offset:2406
	ds_write_b16 v170, v189 offset:4710
	ds_write_b16_d16_hi v170, v189 offset:7014
	ds_read_b128 v[130:133], v171 offset:0
	ds_read_b128 v[134:137], v171 offset:1152
	ds_read_b128 v[138:141], v171 offset:2304
	ds_read_b128 v[142:145], v171 offset:3456
	ds_read_b128 v[146:149], v171 offset:4608
	ds_read_b128 v[150:153], v171 offset:5760
	ds_read_b128 v[154:157], v171 offset:6912
	ds_read_b128 v[158:161], v171 offset:8064
	s_waitcnt lgkmcnt(7)
	global_store_dwordx4 v172, v[130:133], s[44:45] sc1
	s_add_u32 s44, s44, 0x9000
	s_addc_u32 s45, s45, 0
	s_waitcnt lgkmcnt(6)
	global_store_dwordx4 v172, v[134:137], s[44:45] sc1
	s_add_u32 s44, s44, 0x9000
	s_addc_u32 s45, s45, 0
	s_waitcnt lgkmcnt(5)
	global_store_dwordx4 v172, v[138:141], s[44:45] sc1
	s_add_u32 s44, s44, 0x9000
	s_addc_u32 s45, s45, 0
	s_waitcnt lgkmcnt(4)
	global_store_dwordx4 v172, v[142:145], s[44:45] sc1
	s_add_u32 s44, s44, 0x9000
	s_addc_u32 s45, s45, 0
	s_waitcnt lgkmcnt(3)
	global_store_dwordx4 v172, v[146:149], s[44:45] sc1
	s_add_u32 s44, s44, 0x9000
	s_addc_u32 s45, s45, 0
	s_waitcnt lgkmcnt(2)
	global_store_dwordx4 v172, v[150:153], s[44:45] sc1
	s_add_u32 s44, s44, 0x9000
	s_addc_u32 s45, s45, 0
	s_waitcnt lgkmcnt(1)
	global_store_dwordx4 v172, v[154:157], s[44:45] sc1
	s_add_u32 s44, s44, 0x9000
	s_addc_u32 s45, s45, 0
	s_waitcnt lgkmcnt(0)
	global_store_dwordx4 v172, v[158:161], s[44:45] sc1
	s_branch .Lfe_done

; DI float silu(float v) { return v * __builtin_amdgcn_rcpf(1.f + __builtin_amdgcn_exp2f(-1.4426950408889634f * v)); }
; template <int EPI>
; DI void gemm_phase(const P& p, int l, const u16* __restrict__ A, const u16* __restrict__ Bt, int mpx, char* lds) {
;     ...
;           if (tr == 1) {
;             v0 = silu(v0); v1 = silu(v1); v2 = silu(v2); v3 = silu(v3);
;     ...
;           } else {
;             Tl[rowl * 72 + 0 * 16 + r] = (u16)u01;
;             Tl[rowl * 72 + 1 * 16 + r] = (u16)(u01 >> 16);
;             Tl[rowl * 72 + 2 * 16 + r] = (u16)u23;
;             Tl[rowl * 72 + 3 * 16 + r] = (u16)(u23 >> 16);
;           }
.Lfe_k2:
	s_mov_b64 s[62:63], s[44:45]
	v_mul_f32_e32 v174, 0xbfb8aa3b, v6
	v_mul_f32_e32 v175, 0xbfb8aa3b, v10
	v_mul_f32_e32 v176, 0xbfb8aa3b, v14
	v_mul_f32_e32 v177, 0xbfb8aa3b, v18
	v_exp_f32_e32 v174, v174
	v_exp_f32_e32 v175, v175
	v_exp_f32_e32 v176, v176
	v_exp_f32_e32 v177, v177
	v_add_f32_e32 v174, 1.0, v174
	v_add_f32_e32 v175, 1.0, v175
	v_add_f32_e32 v176, 1.0, v176
	v_add_f32_e32 v177, 1.0, v177
	v_rcp_f32_e32 v174, v174
	v_rcp_f32_e32 v175, v175
	v_rcp_f32_e32 v176, v176
	v_rcp_f32_e32 v177, v177
	v_mul_f32_e32 v174, v6, v174
	v_mul_f32_e32 v175, v10, v175
	v_mul_f32_e32 v176, v14, v176
	v_mul_f32_e32 v177, v18, v177
	v_cvt_pk_bf16_f32 v178, v174, v175
	v_cvt_pk_bf16_f32 v179, v176, v177
	ds_write_b16 v170, v178 offset:0
	ds_write_b16_d16_hi v170, v178 offset:32
	ds_write_b16 v170, v179 offset:64
	ds_write_b16_d16_hi v170, v179 offset:96
	v_mul_f32_e32 v180, 0xbfb8aa3b, v7
	v_mul_f32_e32 v181, 0xbfb8aa3b, v11
	v_mul_f32_e32 v182, 0xbfb8aa3b, v15
	v_mul_f32_e32 v183, 0xbfb8aa3b, v19
	v_exp_f32_e32 v180, v180
	v_exp_f32_e32 v181, v181
	v_exp_f32_e32 v182, v182
	v_exp_f32_e32 v183, v183
	v_add_f32_e32 v180, 1.0, v180
	v_add_f32_e32 v181, 1.0, v181
	v_add_f32_e32 v182, 1.0, v182
	v_add_f32_e32 v183, 1.0, v183
	v_rcp_f32_e32 v180, v180
	v_rcp_f32_e32 v181, v181
	v_rcp_f32_e32 v182, v182
	v_rcp_f32_e32 v183, v183
	v_mul_f32_e32 v180, v7, v180
	v_mul_f32_e32 v181, v11, v181
	v_mul_f32_e32 v182, v15, v182
	v_mul_f32_e32 v183, v19, v183
	v_cvt_pk_bf16_f32 v184, v180, v181
	v_cvt_pk_bf16_f32 v185, v182, v183
	ds_write_b16 v170, v184 offset:144
	ds_write_b16_d16_hi v170, v184 offset:176
	ds_write_b16 v170, v185 offset:208
	ds_write_b16_d16_hi v170, v185 offset:240
	v_mul_f32_e32 v186, 0xbfb8aa3b, v8
	v_mul_f32_e32 v187, 0xbfb8aa3b, v12
	v_mul_f32_e32 v188, 0xbfb8aa3b, v16
	v_mul_f32_e32 v189, 0xbfb8aa3b, v20
	v_exp_f32_e32 v186, v186
	v_exp_f32_e32 v187, v187
	v_exp_f32_e32 v188, v188
	v_exp_f32_e32 v189, v189
	v_add_f32_e32 v186, 1.0, v186
	v_add_f32_e32 v187, 1.0, v187
	v_add_f32_e32 v188, 1.0, v188
	v_add_f32_e32 v189, 1.0, v189
	v_rcp_f32_e32 v186, v186
	v_rcp_f32_e32 v187, v187
	v_rcp_f32_e32 v188, v188
	v_rcp_f32_e32 v189, v189
	v_mul_f32_e32 v186, v8, v186
	v_mul_f32_e32 v187, v12, v187
	v_mul_f32_e32 v188, v16, v188
	v_mul_f32_e32 v189, v20, v189
	v_cvt_pk_bf16_f32 v190, v186, v187
	v_cvt_pk_bf16_f32 v191, v188, v189
	ds_write_b16 v170, v190 offset:288
	ds_write_b16_d16_hi v170, v190 offset:320
	ds_write_b16 v170, v191 offset:352
	ds_write_b16_d16_hi v170, v191 offset:384
	v_mul_f32_e32 v192, 0xbfb8aa3b, v9
	v_mul_f32_e32 v193, 0xbfb8aa3b, v13
	v_mul_f32_e32 v174, 0xbfb8aa3b, v17
	v_mul_f32_e32 v175, 0xbfb8aa3b, v21
	v_exp_f32_e32 v192, v192
	v_exp_f32_e32 v193, v193
	v_exp_f32_e32 v174, v174
	v_exp_f32_e32 v175, v175
	v_add_f32_e32 v192, 1.0, v192
	v_add_f32_e32 v193, 1.0, v193
	v_add_f32_e32 v174, 1.0, v174
	v_add_f32_e32 v175, 1.0, v175
	v_rcp_f32_e32 v192, v192
	v_rcp_f32_e32 v193, v193
	v_rcp_f32_e32 v174, v174
	v_rcp_f32_e32 v175, v175
	v_mul_f32_e32 v192, v9, v192
	v_mul_f32_e32 v193, v13, v193
	v_mul_f32_e32 v174, v17, v174
	v_mul_f32_e32 v175, v21, v175
	v_cvt_pk_bf16_f32 v176, v192, v193
	v_cvt_pk_bf16_f32 v177, v174, v175
	ds_write_b16 v170, v176 offset:432
	ds_write_b16_d16_hi v170, v176 offset:464
	ds_write_b16 v170, v177 offset:496
	ds_write_b16_d16_hi v170, v177 offset:528
	v_mul_f32_e32 v178, 0xbfb8aa3b, v22
	v_mul_f32_e32 v179, 0xbfb8aa3b, v26
	v_mul_f32_e32 v180, 0xbfb8aa3b, v30
	v_mul_f32_e32 v181, 0xbfb8aa3b, v34
	v_exp_f32_e32 v178, v178
	v_exp_f32_e32 v179, v179
	v_exp_f32_e32 v180, v180
	v_exp_f32_e32 v181, v181
	v_add_f32_e32 v178, 1.0, v178
	v_add_f32_e32 v179, 1.0, v179
	v_add_f32_e32 v180, 1.0, v180
	v_add_f32_e32 v181, 1.0, v181
	v_rcp_f32_e32 v178, v178
	v_rcp_f32_e32 v179, v179
	v_rcp_f32_e32 v180, v180
	v_rcp_f32_e32 v181, v181
	v_mul_f32_e32 v178, v22, v178
	v_mul_f32_e32 v179, v26, v179
	v_mul_f32_e32 v180, v30, v180
	v_mul_f32_e32 v181, v34, v181
	v_cvt_pk_bf16_f32 v182, v178, v179
	v_cvt_pk_bf16_f32 v183, v180, v181
	ds_write_b16 v170, v182 offset:2304
	ds_write_b16_d16_hi v170, v182 offset:2336
	ds_write_b16 v170, v183 offset:2368
	ds_write_b16_d16_hi v170, v183 offset:2400
	v_mul_f32_e32 v184, 0xbfb8aa3b, v23
	v_mul_f32_e32 v185, 0xbfb8aa3b, v27
	v_mul_f32_e32 v186, 0xbfb8aa3b, v31
	v_mul_f32_e32 v187, 0xbfb8aa3b, v35
	v_exp_f32_e32 v184, v184
	v_exp_f32_e32 v185, v185
	v_exp_f32_e32 v186, v186
	v_exp_f32_e32 v187, v187
	v_add_f32_e32 v184, 1.0, v184
	v_add_f32_e32 v185, 1.0, v185
	v_add_f32_e32 v186, 1.0, v186
	v_add_f32_e32 v187, 1.0, v187
	v_rcp_f32_e32 v184, v184
	v_rcp_f32_e32 v185, v185
	v_rcp_f32_e32 v186, v186
	v_rcp_f32_e32 v187, v187
	v_mul_f32_e32 v184, v23, v184
	v_mul_f32_e32 v185, v27, v185
	v_mul_f32_e32 v186, v31, v186
	v_mul_f32_e32 v187, v35, v187
	v_cvt_pk_bf16_f32 v188, v184, v185
	v_cvt_pk_bf16_f32 v189, v186, v187
	ds_write_b16 v170, v188 offset:2448
	ds_write_b16_d16_hi v170, v188 offset:2480
	ds_write_b16 v170, v189 offset:2512
	ds_write_b16_d16_hi v170, v189 offset:2544
	v_mul_f32_e32 v190, 0xbfb8aa3b, v24
	v_mul_f32_e32 v191, 0xbfb8aa3b, v28
	v_mul_f32_e32 v192, 0xbfb8aa3b, v32
	v_mul_f32_e32 v193, 0xbfb8aa3b, v36
	v_exp_f32_e32 v190, v190
	v_exp_f32_e32 v191, v191
	v_exp_f32_e32 v192, v192
	v_exp_f32_e32 v193, v193
	v_add_f32_e32 v190, 1.0, v190
	v_add_f32_e32 v191, 1.0, v191
	v_add_f32_e32 v192, 1.0, v192
	v_add_f32_e32 v193, 1.0, v193
	v_rcp_f32_e32 v190, v190
	v_rcp_f32_e32 v191, v191
	v_rcp_f32_e32 v192, v192
	v_rcp_f32_e32 v193, v193
	v_mul_f32_e32 v190, v24, v190
	v_mul_f32_e32 v191, v28, v191
	v_mul_f32_e32 v192, v32, v192
	v_mul_f32_e32 v193, v36, v193
; DI float silu(float v) { return v * __builtin_amdgcn_rcpf(1.f + __builtin_amdgcn_exp2f(-1.4426950408889634f * v)); }
; template <int EPI>
; DI void gemm_phase(const P& p, int l, const u16* __restrict__ A, const u16* __restrict__ Bt, int mpx, char* lds) {
;     ...
;           if (tr == 1) {
;             v0 = silu(v0); v1 = silu(v1); v2 = silu(v2); v3 = silu(v3);
;     ...
;           } else {
;             Tl[rowl * 72 + 0 * 16 + r] = (u16)u01;
;             Tl[rowl * 72 + 1 * 16 + r] = (u16)(u01 >> 16);
;             Tl[rowl * 72 + 2 * 16 + r] = (u16)u23;
;             Tl[rowl * 72 + 3 * 16 + r] = (u16)(u23 >> 16);
;           }
	v_cvt_pk_bf16_f32 v174, v190, v191
	v_cvt_pk_bf16_f32 v175, v192, v193
	ds_write_b16 v170, v174 offset:2592
	ds_write_b16_d16_hi v170, v174 offset:2624
	ds_write_b16 v170, v175 offset:2656
	ds_write_b16_d16_hi v170, v175 offset:2688
	v_mul_f32_e32 v176, 0xbfb8aa3b, v25
	v_mul_f32_e32 v177, 0xbfb8aa3b, v29
	v_mul_f32_e32 v178, 0xbfb8aa3b, v33
	v_mul_f32_e32 v179, 0xbfb8aa3b, v37
	v_exp_f32_e32 v176, v176
	v_exp_f32_e32 v177, v177
	v_exp_f32_e32 v178, v178
	v_exp_f32_e32 v179, v179
	v_add_f32_e32 v176, 1.0, v176
	v_add_f32_e32 v177, 1.0, v177
	v_add_f32_e32 v178, 1.0, v178
	v_add_f32_e32 v179, 1.0, v179
	v_rcp_f32_e32 v176, v176
	v_rcp_f32_e32 v177, v177
	v_rcp_f32_e32 v178, v178
	v_rcp_f32_e32 v179, v179
	v_mul_f32_e32 v176, v25, v176
	v_mul_f32_e32 v177, v29, v177
	v_mul_f32_e32 v178, v33, v178
	v_mul_f32_e32 v179, v37, v179
	v_cvt_pk_bf16_f32 v180, v176, v177
	v_cvt_pk_bf16_f32 v181, v178, v179
	ds_write_b16 v170, v180 offset:2736
	ds_write_b16_d16_hi v170, v180 offset:2768
	ds_write_b16 v170, v181 offset:2800
	ds_write_b16_d16_hi v170, v181 offset:2832
	v_mul_f32_e32 v182, 0xbfb8aa3b, v38
	v_mul_f32_e32 v183, 0xbfb8aa3b, v42
	v_mul_f32_e32 v184, 0xbfb8aa3b, v46
	v_mul_f32_e32 v185, 0xbfb8aa3b, v50
	v_exp_f32_e32 v182, v182
	v_exp_f32_e32 v183, v183
	v_exp_f32_e32 v184, v184
	v_exp_f32_e32 v185, v185
	v_add_f32_e32 v182, 1.0, v182
	v_add_f32_e32 v183, 1.0, v183
	v_add_f32_e32 v184, 1.0, v184
	v_add_f32_e32 v185, 1.0, v185
	v_rcp_f32_e32 v182, v182
	v_rcp_f32_e32 v183, v183
	v_rcp_f32_e32 v184, v184
	v_rcp_f32_e32 v185, v185
	v_mul_f32_e32 v182, v38, v182
	v_mul_f32_e32 v183, v42, v183
	v_mul_f32_e32 v184, v46, v184
	v_mul_f32_e32 v185, v50, v185
	v_cvt_pk_bf16_f32 v186, v182, v183
	v_cvt_pk_bf16_f32 v187, v184, v185
	ds_write_b16 v170, v186 offset:4608
	ds_write_b16_d16_hi v170, v186 offset:4640
	ds_write_b16 v170, v187 offset:4672
	ds_write_b16_d16_hi v170, v187 offset:4704
	v_mul_f32_e32 v188, 0xbfb8aa3b, v39
	v_mul_f32_e32 v189, 0xbfb8aa3b, v43
	v_mul_f32_e32 v190, 0xbfb8aa3b, v47
	v_mul_f32_e32 v191, 0xbfb8aa3b, v51
	v_exp_f32_e32 v188, v188
	v_exp_f32_e32 v189, v189
	v_exp_f32_e32 v190, v190
	v_exp_f32_e32 v191, v191
	v_add_f32_e32 v188, 1.0, v188
	v_add_f32_e32 v189, 1.0, v189
	v_add_f32_e32 v190, 1.0, v190
	v_add_f32_e32 v191, 1.0, v191
	v_rcp_f32_e32 v188, v188
	v_rcp_f32_e32 v189, v189
	v_rcp_f32_e32 v190, v190
	v_rcp_f32_e32 v191, v191
	v_mul_f32_e32 v188, v39, v188
	v_mul_f32_e32 v189, v43, v189
	v_mul_f32_e32 v190, v47, v190
	v_mul_f32_e32 v191, v51, v191
	v_cvt_pk_bf16_f32 v192, v188, v189
	v_cvt_pk_bf16_f32 v193, v190, v191
	ds_write_b16 v170, v192 offset:4752
	ds_write_b16_d16_hi v170, v192 offset:4784
	ds_write_b16 v170, v193 offset:4816
	ds_write_b16_d16_hi v170, v193 offset:4848
	v_mul_f32_e32 v174, 0xbfb8aa3b, v40
	v_mul_f32_e32 v175, 0xbfb8aa3b, v44
	v_mul_f32_e32 v176, 0xbfb8aa3b, v48
	v_mul_f32_e32 v177, 0xbfb8aa3b, v52
	v_exp_f32_e32 v174, v174
	v_exp_f32_e32 v175, v175
	v_exp_f32_e32 v176, v176
	v_exp_f32_e32 v177, v177
	v_add_f32_e32 v174, 1.0, v174
	v_add_f32_e32 v175, 1.0, v175
	v_add_f32_e32 v176, 1.0, v176
	v_add_f32_e32 v177, 1.0, v177
	v_rcp_f32_e32 v174, v174
	v_rcp_f32_e32 v175, v175
	v_rcp_f32_e32 v176, v176
	v_rcp_f32_e32 v177, v177
	v_mul_f32_e32 v174, v40, v174
	v_mul_f32_e32 v175, v44, v175
	v_mul_f32_e32 v176, v48, v176
	v_mul_f32_e32 v177, v52, v177
	v_cvt_pk_bf16_f32 v178, v174, v175
	v_cvt_pk_bf16_f32 v179, v176, v177
	ds_write_b16 v170, v178 offset:4896
	ds_write_b16_d16_hi v170, v178 offset:4928
	ds_write_b16 v170, v179 offset:4960
	ds_write_b16_d16_hi v170, v179 offset:4992
	v_mul_f32_e32 v180, 0xbfb8aa3b, v41
	v_mul_f32_e32 v181, 0xbfb8aa3b, v45
	v_mul_f32_e32 v182, 0xbfb8aa3b, v49
	v_mul_f32_e32 v183, 0xbfb8aa3b, v53
	v_exp_f32_e32 v180, v180
	v_exp_f32_e32 v181, v181
	v_exp_f32_e32 v182, v182
	v_exp_f32_e32 v183, v183
	v_add_f32_e32 v180, 1.0, v180
	v_add_f32_e32 v181, 1.0, v181
	v_add_f32_e32 v182, 1.0, v182
	v_add_f32_e32 v183, 1.0, v183
	v_rcp_f32_e32 v180, v180
	v_rcp_f32_e32 v181, v181
	v_rcp_f32_e32 v182, v182
	v_rcp_f32_e32 v183, v183
	v_mul_f32_e32 v180, v41, v180
	v_mul_f32_e32 v181, v45, v181
	v_mul_f32_e32 v182, v49, v182
	v_mul_f32_e32 v183, v53, v183
	v_cvt_pk_bf16_f32 v184, v180, v181
	v_cvt_pk_bf16_f32 v185, v182, v183
	ds_write_b16 v170, v184 offset:5040
	ds_write_b16_d16_hi v170, v184 offset:5072
	ds_write_b16 v170, v185 offset:5104
	ds_write_b16_d16_hi v170, v185 offset:5136
	v_mul_f32_e32 v186, 0xbfb8aa3b, v54
	v_mul_f32_e32 v187, 0xbfb8aa3b, v58
	v_mul_f32_e32 v188, 0xbfb8aa3b, v62
	v_mul_f32_e32 v189, 0xbfb8aa3b, v66
	v_exp_f32_e32 v186, v186
	v_exp_f32_e32 v187, v187
	v_exp_f32_e32 v188, v188
	v_exp_f32_e32 v189, v189
	v_add_f32_e32 v186, 1.0, v186
	v_add_f32_e32 v187, 1.0, v187
	v_add_f32_e32 v188, 1.0, v188
	v_add_f32_e32 v189, 1.0, v189
	v_rcp_f32_e32 v186, v186
	v_rcp_f32_e32 v187, v187
	v_rcp_f32_e32 v188, v188
	v_rcp_f32_e32 v189, v189
	v_mul_f32_e32 v186, v54, v186
	v_mul_f32_e32 v187, v58, v187
	v_mul_f32_e32 v188, v62, v188
	v_mul_f32_e32 v189, v66, v189
	v_cvt_pk_bf16_f32 v190, v186, v187
	v_cvt_pk_bf16_f32 v191, v188, v189
	ds_write_b16 v170, v190 offset:6912
	ds_write_b16_d16_hi v170, v190 offset:6944
	ds_write_b16 v170, v191 offset:6976
	ds_write_b16_d16_hi v170, v191 offset:7008
	v_mul_f32_e32 v192, 0xbfb8aa3b, v55
	v_mul_f32_e32 v193, 0xbfb8aa3b, v59
	v_mul_f32_e32 v174, 0xbfb8aa3b, v63
	v_mul_f32_e32 v175, 0xbfb8aa3b, v67
	v_exp_f32_e32 v192, v192
	v_exp_f32_e32 v193, v193
	v_exp_f32_e32 v174, v174
	v_exp_f32_e32 v175, v175
	v_add_f32_e32 v192, 1.0, v192
	v_add_f32_e32 v193, 1.0, v193
	v_add_f32_e32 v174, 1.0, v174
	v_add_f32_e32 v175, 1.0, v175
; DI float silu(float v) { return v * __builtin_amdgcn_rcpf(1.f + __builtin_amdgcn_exp2f(-1.4426950408889634f * v)); }
; template <int EPI>
; DI void gemm_phase(const P& p, int l, const u16* __restrict__ A, const u16* __restrict__ Bt, int mpx, char* lds) {
;     ...
;           if (tr == 1) {
;             v0 = silu(v0); v1 = silu(v1); v2 = silu(v2); v3 = silu(v3);
;     ...
;       __builtin_amdgcn_fence(__ATOMIC_RELEASE, "wavefront");
;       u16* dh = (kind == 1) ? dst + hf * 64 : dst + (size_t)(hf * 64) * rstride;
; #pragma unroll
;       for (int i = 0; i < 8; ++i) {
;         const int c = lane + i * 64;
;         const int row = c >> 3, cc = c & 7;
;         uint4 v = *(const uint4*)&Tl[row * 72 + cc * 8];
;         *(uint4*)(dh + (size_t)row * rstride + cc * 8) = v;
;       }
	v_rcp_f32_e32 v192, v192
	v_rcp_f32_e32 v193, v193
	v_rcp_f32_e32 v174, v174
	v_rcp_f32_e32 v175, v175
	v_mul_f32_e32 v192, v55, v192
	v_mul_f32_e32 v193, v59, v193
	v_mul_f32_e32 v174, v63, v174
	v_mul_f32_e32 v175, v67, v175
	v_cvt_pk_bf16_f32 v176, v192, v193
	v_cvt_pk_bf16_f32 v177, v174, v175
	ds_write_b16 v170, v176 offset:7056
	ds_write_b16_d16_hi v170, v176 offset:7088
	ds_write_b16 v170, v177 offset:7120
	ds_write_b16_d16_hi v170, v177 offset:7152
	v_mul_f32_e32 v178, 0xbfb8aa3b, v56
	v_mul_f32_e32 v179, 0xbfb8aa3b, v60
	v_mul_f32_e32 v180, 0xbfb8aa3b, v64
	v_mul_f32_e32 v181, 0xbfb8aa3b, v68
	v_exp_f32_e32 v178, v178
	v_exp_f32_e32 v179, v179
	v_exp_f32_e32 v180, v180
	v_exp_f32_e32 v181, v181
	v_add_f32_e32 v178, 1.0, v178
	v_add_f32_e32 v179, 1.0, v179
	v_add_f32_e32 v180, 1.0, v180
	v_add_f32_e32 v181, 1.0, v181
	v_rcp_f32_e32 v178, v178
	v_rcp_f32_e32 v179, v179
	v_rcp_f32_e32 v180, v180
	v_rcp_f32_e32 v181, v181
	v_mul_f32_e32 v178, v56, v178
	v_mul_f32_e32 v179, v60, v179
	v_mul_f32_e32 v180, v64, v180
	v_mul_f32_e32 v181, v68, v181
	v_cvt_pk_bf16_f32 v182, v178, v179
	v_cvt_pk_bf16_f32 v183, v180, v181
	ds_write_b16 v170, v182 offset:7200
	ds_write_b16_d16_hi v170, v182 offset:7232
	ds_write_b16 v170, v183 offset:7264
	ds_write_b16_d16_hi v170, v183 offset:7296
	v_mul_f32_e32 v184, 0xbfb8aa3b, v57
	v_mul_f32_e32 v185, 0xbfb8aa3b, v61
	v_mul_f32_e32 v186, 0xbfb8aa3b, v65
	v_mul_f32_e32 v187, 0xbfb8aa3b, v69
	v_exp_f32_e32 v184, v184
	v_exp_f32_e32 v185, v185
	v_exp_f32_e32 v186, v186
	v_exp_f32_e32 v187, v187
	v_add_f32_e32 v184, 1.0, v184
	v_add_f32_e32 v185, 1.0, v185
	v_add_f32_e32 v186, 1.0, v186
	v_add_f32_e32 v187, 1.0, v187
	v_rcp_f32_e32 v184, v184
	v_rcp_f32_e32 v185, v185
	v_rcp_f32_e32 v186, v186
	v_rcp_f32_e32 v187, v187
	v_mul_f32_e32 v184, v57, v184
	v_mul_f32_e32 v185, v61, v185
	v_mul_f32_e32 v186, v65, v186
	v_mul_f32_e32 v187, v69, v187
	v_cvt_pk_bf16_f32 v188, v184, v185
	v_cvt_pk_bf16_f32 v189, v186, v187
	ds_write_b16 v170, v188 offset:7344
	ds_write_b16_d16_hi v170, v188 offset:7376
	ds_write_b16 v170, v189 offset:7408
	ds_write_b16_d16_hi v170, v189 offset:7440
	ds_read_b128 v[130:133], v171 offset:0
	ds_read_b128 v[134:137], v171 offset:1152
	ds_read_b128 v[138:141], v171 offset:2304
	ds_read_b128 v[142:145], v171 offset:3456
	ds_read_b128 v[146:149], v171 offset:4608
	ds_read_b128 v[150:153], v171 offset:5760
	ds_read_b128 v[154:157], v171 offset:6912
	ds_read_b128 v[158:161], v171 offset:8064
	s_waitcnt lgkmcnt(7)
	global_store_dwordx4 v172, v[130:133], s[44:45] sc1
	s_add_u32 s44, s44, 0x4000
	s_addc_u32 s45, s45, 0
	s_waitcnt lgkmcnt(6)
	global_store_dwordx4 v172, v[134:137], s[44:45] sc1
	s_add_u32 s44, s44, 0x4000
	s_addc_u32 s45, s45, 0
	s_waitcnt lgkmcnt(5)
	global_store_dwordx4 v172, v[138:141], s[44:45] sc1
	s_add_u32 s44, s44, 0x4000
	s_addc_u32 s45, s45, 0
	s_waitcnt lgkmcnt(4)
	global_store_dwordx4 v172, v[142:145], s[44:45] sc1
	s_add_u32 s44, s44, 0x4000
	s_addc_u32 s45, s45, 0
	s_waitcnt lgkmcnt(3)
	global_store_dwordx4 v172, v[146:149], s[44:45] sc1
	s_add_u32 s44, s44, 0x4000
	s_addc_u32 s45, s45, 0
	s_waitcnt lgkmcnt(2)
	global_store_dwordx4 v172, v[150:153], s[44:45] sc1
	s_add_u32 s44, s44, 0x4000
	s_addc_u32 s45, s45, 0
	s_waitcnt lgkmcnt(1)
	global_store_dwordx4 v172, v[154:157], s[44:45] sc1
	s_add_u32 s44, s44, 0x4000
	s_addc_u32 s45, s45, 0
	s_waitcnt lgkmcnt(0)
	global_store_dwordx4 v172, v[158:161], s[44:45] sc1
	s_add_u32 s44, s62, 0x20000
	s_addc_u32 s45, s63, 0
	v_mul_f32_e32 v174, 0xbfb8aa3b, v70
	v_mul_f32_e32 v175, 0xbfb8aa3b, v74
	v_mul_f32_e32 v176, 0xbfb8aa3b, v78
	v_mul_f32_e32 v177, 0xbfb8aa3b, v82
	v_exp_f32_e32 v174, v174
	v_exp_f32_e32 v175, v175
	v_exp_f32_e32 v176, v176
	v_exp_f32_e32 v177, v177
	v_add_f32_e32 v174, 1.0, v174
	v_add_f32_e32 v175, 1.0, v175
	v_add_f32_e32 v176, 1.0, v176
	v_add_f32_e32 v177, 1.0, v177
	v_rcp_f32_e32 v174, v174
	v_rcp_f32_e32 v175, v175
	v_rcp_f32_e32 v176, v176
	v_rcp_f32_e32 v177, v177
	v_mul_f32_e32 v174, v70, v174
	v_mul_f32_e32 v175, v74, v175
	v_mul_f32_e32 v176, v78, v176
	v_mul_f32_e32 v177, v82, v177
	v_cvt_pk_bf16_f32 v178, v174, v175
	v_cvt_pk_bf16_f32 v179, v176, v177
	ds_write_b16 v170, v178 offset:0
	ds_write_b16_d16_hi v170, v178 offset:32
	ds_write_b16 v170, v179 offset:64
	ds_write_b16_d16_hi v170, v179 offset:96
	v_mul_f32_e32 v180, 0xbfb8aa3b, v71
	v_mul_f32_e32 v181, 0xbfb8aa3b, v75
	v_mul_f32_e32 v182, 0xbfb8aa3b, v79
	v_mul_f32_e32 v183, 0xbfb8aa3b, v83
	v_exp_f32_e32 v180, v180
	v_exp_f32_e32 v181, v181
	v_exp_f32_e32 v182, v182
	v_exp_f32_e32 v183, v183
	v_add_f32_e32 v180, 1.0, v180
	v_add_f32_e32 v181, 1.0, v181
	v_add_f32_e32 v182, 1.0, v182
	v_add_f32_e32 v183, 1.0, v183
	v_rcp_f32_e32 v180, v180
	v_rcp_f32_e32 v181, v181
	v_rcp_f32_e32 v182, v182
	v_rcp_f32_e32 v183, v183
	v_mul_f32_e32 v180, v71, v180
	v_mul_f32_e32 v181, v75, v181
	v_mul_f32_e32 v182, v79, v182
	v_mul_f32_e32 v183, v83, v183
	v_cvt_pk_bf16_f32 v184, v180, v181
	v_cvt_pk_bf16_f32 v185, v182, v183
	ds_write_b16 v170, v184 offset:144
	ds_write_b16_d16_hi v170, v184 offset:176
	ds_write_b16 v170, v185 offset:208
	ds_write_b16_d16_hi v170, v185 offset:240
	v_mul_f32_e32 v186, 0xbfb8aa3b, v72
	v_mul_f32_e32 v187, 0xbfb8aa3b, v76
	v_mul_f32_e32 v188, 0xbfb8aa3b, v80
	v_mul_f32_e32 v189, 0xbfb8aa3b, v84
	v_exp_f32_e32 v186, v186
	v_exp_f32_e32 v187, v187
	v_exp_f32_e32 v188, v188
	v_exp_f32_e32 v189, v189
	v_add_f32_e32 v186, 1.0, v186
	v_add_f32_e32 v187, 1.0, v187
	v_add_f32_e32 v188, 1.0, v188
	v_add_f32_e32 v189, 1.0, v189
	v_rcp_f32_e32 v186, v186
	v_rcp_f32_e32 v187, v187
	v_rcp_f32_e32 v188, v188
	v_rcp_f32_e32 v189, v189
; DI float silu(float v) { return v * __builtin_amdgcn_rcpf(1.f + __builtin_amdgcn_exp2f(-1.4426950408889634f * v)); }
; template <int EPI>
; DI void gemm_phase(const P& p, int l, const u16* __restrict__ A, const u16* __restrict__ Bt, int mpx, char* lds) {
;     ...
;           if (tr == 1) {
;             v0 = silu(v0); v1 = silu(v1); v2 = silu(v2); v3 = silu(v3);
;     ...
;           } else {
;             Tl[rowl * 72 + 0 * 16 + r] = (u16)u01;
;             Tl[rowl * 72 + 1 * 16 + r] = (u16)(u01 >> 16);
;             Tl[rowl * 72 + 2 * 16 + r] = (u16)u23;
;             Tl[rowl * 72 + 3 * 16 + r] = (u16)(u23 >> 16);
;           }
	v_mul_f32_e32 v186, v72, v186
	v_mul_f32_e32 v187, v76, v187
	v_mul_f32_e32 v188, v80, v188
	v_mul_f32_e32 v189, v84, v189
	v_cvt_pk_bf16_f32 v190, v186, v187
	v_cvt_pk_bf16_f32 v191, v188, v189
	ds_write_b16 v170, v190 offset:288
	ds_write_b16_d16_hi v170, v190 offset:320
	ds_write_b16 v170, v191 offset:352
	ds_write_b16_d16_hi v170, v191 offset:384
	v_mul_f32_e32 v192, 0xbfb8aa3b, v73
	v_mul_f32_e32 v193, 0xbfb8aa3b, v77
	v_mul_f32_e32 v174, 0xbfb8aa3b, v81
	v_mul_f32_e32 v175, 0xbfb8aa3b, v85
	v_exp_f32_e32 v192, v192
	v_exp_f32_e32 v193, v193
	v_exp_f32_e32 v174, v174
	v_exp_f32_e32 v175, v175
	v_add_f32_e32 v192, 1.0, v192
	v_add_f32_e32 v193, 1.0, v193
	v_add_f32_e32 v174, 1.0, v174
	v_add_f32_e32 v175, 1.0, v175
	v_rcp_f32_e32 v192, v192
	v_rcp_f32_e32 v193, v193
	v_rcp_f32_e32 v174, v174
	v_rcp_f32_e32 v175, v175
	v_mul_f32_e32 v192, v73, v192
	v_mul_f32_e32 v193, v77, v193
	v_mul_f32_e32 v174, v81, v174
	v_mul_f32_e32 v175, v85, v175
	v_cvt_pk_bf16_f32 v176, v192, v193
	v_cvt_pk_bf16_f32 v177, v174, v175
	ds_write_b16 v170, v176 offset:432
	ds_write_b16_d16_hi v170, v176 offset:464
	ds_write_b16 v170, v177 offset:496
	ds_write_b16_d16_hi v170, v177 offset:528
	v_mul_f32_e32 v178, 0xbfb8aa3b, v86
	v_mul_f32_e32 v179, 0xbfb8aa3b, v90
	v_mul_f32_e32 v180, 0xbfb8aa3b, v94
	v_mul_f32_e32 v181, 0xbfb8aa3b, v98
	v_exp_f32_e32 v178, v178
	v_exp_f32_e32 v179, v179
	v_exp_f32_e32 v180, v180
	v_exp_f32_e32 v181, v181
	v_add_f32_e32 v178, 1.0, v178
	v_add_f32_e32 v179, 1.0, v179
	v_add_f32_e32 v180, 1.0, v180
	v_add_f32_e32 v181, 1.0, v181
	v_rcp_f32_e32 v178, v178
	v_rcp_f32_e32 v179, v179
	v_rcp_f32_e32 v180, v180
	v_rcp_f32_e32 v181, v181
	v_mul_f32_e32 v178, v86, v178
	v_mul_f32_e32 v179, v90, v179
	v_mul_f32_e32 v180, v94, v180
	v_mul_f32_e32 v181, v98, v181
	v_cvt_pk_bf16_f32 v182, v178, v179
	v_cvt_pk_bf16_f32 v183, v180, v181
	ds_write_b16 v170, v182 offset:2304
	ds_write_b16_d16_hi v170, v182 offset:2336
	ds_write_b16 v170, v183 offset:2368
	ds_write_b16_d16_hi v170, v183 offset:2400
	v_mul_f32_e32 v184, 0xbfb8aa3b, v87
	v_mul_f32_e32 v185, 0xbfb8aa3b, v91
	v_mul_f32_e32 v186, 0xbfb8aa3b, v95
	v_mul_f32_e32 v187, 0xbfb8aa3b, v99
	v_exp_f32_e32 v184, v184
	v_exp_f32_e32 v185, v185
	v_exp_f32_e32 v186, v186
	v_exp_f32_e32 v187, v187
	v_add_f32_e32 v184, 1.0, v184
	v_add_f32_e32 v185, 1.0, v185
	v_add_f32_e32 v186, 1.0, v186
	v_add_f32_e32 v187, 1.0, v187
	v_rcp_f32_e32 v184, v184
	v_rcp_f32_e32 v185, v185
	v_rcp_f32_e32 v186, v186
	v_rcp_f32_e32 v187, v187
	v_mul_f32_e32 v184, v87, v184
	v_mul_f32_e32 v185, v91, v185
	v_mul_f32_e32 v186, v95, v186
	v_mul_f32_e32 v187, v99, v187
	v_cvt_pk_bf16_f32 v188, v184, v185
	v_cvt_pk_bf16_f32 v189, v186, v187
	ds_write_b16 v170, v188 offset:2448
	ds_write_b16_d16_hi v170, v188 offset:2480
	ds_write_b16 v170, v189 offset:2512
	ds_write_b16_d16_hi v170, v189 offset:2544
	v_mul_f32_e32 v190, 0xbfb8aa3b, v88
	v_mul_f32_e32 v191, 0xbfb8aa3b, v92
	v_mul_f32_e32 v192, 0xbfb8aa3b, v96
	v_mul_f32_e32 v193, 0xbfb8aa3b, v100
	v_exp_f32_e32 v190, v190
	v_exp_f32_e32 v191, v191
	v_exp_f32_e32 v192, v192
	v_exp_f32_e32 v193, v193
	v_add_f32_e32 v190, 1.0, v190
	v_add_f32_e32 v191, 1.0, v191
	v_add_f32_e32 v192, 1.0, v192
	v_add_f32_e32 v193, 1.0, v193
	v_rcp_f32_e32 v190, v190
	v_rcp_f32_e32 v191, v191
	v_rcp_f32_e32 v192, v192
	v_rcp_f32_e32 v193, v193
	v_mul_f32_e32 v190, v88, v190
	v_mul_f32_e32 v191, v92, v191
	v_mul_f32_e32 v192, v96, v192
	v_mul_f32_e32 v193, v100, v193
	v_cvt_pk_bf16_f32 v174, v190, v191
	v_cvt_pk_bf16_f32 v175, v192, v193
	ds_write_b16 v170, v174 offset:2592
	ds_write_b16_d16_hi v170, v174 offset:2624
	ds_write_b16 v170, v175 offset:2656
	ds_write_b16_d16_hi v170, v175 offset:2688
	v_mul_f32_e32 v176, 0xbfb8aa3b, v89
	v_mul_f32_e32 v177, 0xbfb8aa3b, v93
	v_mul_f32_e32 v178, 0xbfb8aa3b, v97
	v_mul_f32_e32 v179, 0xbfb8aa3b, v101
	v_exp_f32_e32 v176, v176
	v_exp_f32_e32 v177, v177
	v_exp_f32_e32 v178, v178
	v_exp_f32_e32 v179, v179
	v_add_f32_e32 v176, 1.0, v176
	v_add_f32_e32 v177, 1.0, v177
	v_add_f32_e32 v178, 1.0, v178
	v_add_f32_e32 v179, 1.0, v179
	v_rcp_f32_e32 v176, v176
	v_rcp_f32_e32 v177, v177
	v_rcp_f32_e32 v178, v178
	v_rcp_f32_e32 v179, v179
	v_mul_f32_e32 v176, v89, v176
	v_mul_f32_e32 v177, v93, v177
	v_mul_f32_e32 v178, v97, v178
	v_mul_f32_e32 v179, v101, v179
	v_cvt_pk_bf16_f32 v180, v176, v177
	v_cvt_pk_bf16_f32 v181, v178, v179
	ds_write_b16 v170, v180 offset:2736
	ds_write_b16_d16_hi v170, v180 offset:2768
	ds_write_b16 v170, v181 offset:2800
	ds_write_b16_d16_hi v170, v181 offset:2832
	v_mul_f32_e32 v182, 0xbfb8aa3b, v102
	v_mul_f32_e32 v183, 0xbfb8aa3b, v106
	v_mul_f32_e32 v184, 0xbfb8aa3b, v110
	v_mul_f32_e32 v185, 0xbfb8aa3b, v114
	v_exp_f32_e32 v182, v182
	v_exp_f32_e32 v183, v183
	v_exp_f32_e32 v184, v184
	v_exp_f32_e32 v185, v185
	v_add_f32_e32 v182, 1.0, v182
	v_add_f32_e32 v183, 1.0, v183
	v_add_f32_e32 v184, 1.0, v184
	v_add_f32_e32 v185, 1.0, v185
	v_rcp_f32_e32 v182, v182
	v_rcp_f32_e32 v183, v183
	v_rcp_f32_e32 v184, v184
	v_rcp_f32_e32 v185, v185
	v_mul_f32_e32 v182, v102, v182
	v_mul_f32_e32 v183, v106, v183
	v_mul_f32_e32 v184, v110, v184
	v_mul_f32_e32 v185, v114, v185
	v_cvt_pk_bf16_f32 v186, v182, v183
	v_cvt_pk_bf16_f32 v187, v184, v185
	ds_write_b16 v170, v186 offset:4608
	ds_write_b16_d16_hi v170, v186 offset:4640
	ds_write_b16 v170, v187 offset:4672
	ds_write_b16_d16_hi v170, v187 offset:4704
	v_mul_f32_e32 v188, 0xbfb8aa3b, v103
	v_mul_f32_e32 v189, 0xbfb8aa3b, v107
	v_mul_f32_e32 v190, 0xbfb8aa3b, v111
	v_mul_f32_e32 v191, 0xbfb8aa3b, v115
	v_exp_f32_e32 v188, v188
	v_exp_f32_e32 v189, v189
	v_exp_f32_e32 v190, v190
	v_exp_f32_e32 v191, v191
; DI float silu(float v) { return v * __builtin_amdgcn_rcpf(1.f + __builtin_amdgcn_exp2f(-1.4426950408889634f * v)); }
; template <int EPI>
; DI void gemm_phase(const P& p, int l, const u16* __restrict__ A, const u16* __restrict__ Bt, int mpx, char* lds) {
;     ...
;           if (tr == 1) {
;             v0 = silu(v0); v1 = silu(v1); v2 = silu(v2); v3 = silu(v3);
;     ...
;       __builtin_amdgcn_fence(__ATOMIC_RELEASE, "wavefront");
;       u16* dh = (kind == 1) ? dst + hf * 64 : dst + (size_t)(hf * 64) * rstride;
; #pragma unroll
;       for (int i = 0; i < 8; ++i) {
;         const int c = lane + i * 64;
;         const int row = c >> 3, cc = c & 7;
;         uint4 v = *(const uint4*)&Tl[row * 72 + cc * 8];
;         *(uint4*)(dh + (size_t)row * rstride + cc * 8) = v;
;       }
	v_add_f32_e32 v188, 1.0, v188
	v_add_f32_e32 v189, 1.0, v189
	v_add_f32_e32 v190, 1.0, v190
	v_add_f32_e32 v191, 1.0, v191
	v_rcp_f32_e32 v188, v188
	v_rcp_f32_e32 v189, v189
	v_rcp_f32_e32 v190, v190
	v_rcp_f32_e32 v191, v191
	v_mul_f32_e32 v188, v103, v188
	v_mul_f32_e32 v189, v107, v189
	v_mul_f32_e32 v190, v111, v190
	v_mul_f32_e32 v191, v115, v191
	v_cvt_pk_bf16_f32 v192, v188, v189
	v_cvt_pk_bf16_f32 v193, v190, v191
	ds_write_b16 v170, v192 offset:4752
	ds_write_b16_d16_hi v170, v192 offset:4784
	ds_write_b16 v170, v193 offset:4816
	ds_write_b16_d16_hi v170, v193 offset:4848
	v_mul_f32_e32 v174, 0xbfb8aa3b, v104
	v_mul_f32_e32 v175, 0xbfb8aa3b, v108
	v_mul_f32_e32 v176, 0xbfb8aa3b, v112
	v_mul_f32_e32 v177, 0xbfb8aa3b, v116
	v_exp_f32_e32 v174, v174
	v_exp_f32_e32 v175, v175
	v_exp_f32_e32 v176, v176
	v_exp_f32_e32 v177, v177
	v_add_f32_e32 v174, 1.0, v174
	v_add_f32_e32 v175, 1.0, v175
	v_add_f32_e32 v176, 1.0, v176
	v_add_f32_e32 v177, 1.0, v177
	v_rcp_f32_e32 v174, v174
	v_rcp_f32_e32 v175, v175
	v_rcp_f32_e32 v176, v176
	v_rcp_f32_e32 v177, v177
	v_mul_f32_e32 v174, v104, v174
	v_mul_f32_e32 v175, v108, v175
	v_mul_f32_e32 v176, v112, v176
	v_mul_f32_e32 v177, v116, v177
	v_cvt_pk_bf16_f32 v178, v174, v175
	v_cvt_pk_bf16_f32 v179, v176, v177
	ds_write_b16 v170, v178 offset:4896
	ds_write_b16_d16_hi v170, v178 offset:4928
	ds_write_b16 v170, v179 offset:4960
	ds_write_b16_d16_hi v170, v179 offset:4992
	v_mul_f32_e32 v180, 0xbfb8aa3b, v105
	v_mul_f32_e32 v181, 0xbfb8aa3b, v109
	v_mul_f32_e32 v182, 0xbfb8aa3b, v113
	v_mul_f32_e32 v183, 0xbfb8aa3b, v117
	v_exp_f32_e32 v180, v180
	v_exp_f32_e32 v181, v181
	v_exp_f32_e32 v182, v182
	v_exp_f32_e32 v183, v183
	v_add_f32_e32 v180, 1.0, v180
	v_add_f32_e32 v181, 1.0, v181
	v_add_f32_e32 v182, 1.0, v182
	v_add_f32_e32 v183, 1.0, v183
	v_rcp_f32_e32 v180, v180
	v_rcp_f32_e32 v181, v181
	v_rcp_f32_e32 v182, v182
	v_rcp_f32_e32 v183, v183
	v_mul_f32_e32 v180, v105, v180
	v_mul_f32_e32 v181, v109, v181
	v_mul_f32_e32 v182, v113, v182
	v_mul_f32_e32 v183, v117, v183
	v_cvt_pk_bf16_f32 v184, v180, v181
	v_cvt_pk_bf16_f32 v185, v182, v183
	ds_write_b16 v170, v184 offset:5040
	ds_write_b16_d16_hi v170, v184 offset:5072
	ds_write_b16 v170, v185 offset:5104
	ds_write_b16_d16_hi v170, v185 offset:5136
	v_mul_f32_e32 v186, 0xbfb8aa3b, v118
	v_mul_f32_e32 v187, 0xbfb8aa3b, v122
	v_mul_f32_e32 v188, 0xbfb8aa3b, v126
	v_mul_f32_e32 v189, 0xbfb8aa3b, v2
	v_exp_f32_e32 v186, v186
	v_exp_f32_e32 v187, v187
	v_exp_f32_e32 v188, v188
	v_exp_f32_e32 v189, v189
	v_add_f32_e32 v186, 1.0, v186
	v_add_f32_e32 v187, 1.0, v187
	v_add_f32_e32 v188, 1.0, v188
	v_add_f32_e32 v189, 1.0, v189
	v_rcp_f32_e32 v186, v186
	v_rcp_f32_e32 v187, v187
	v_rcp_f32_e32 v188, v188
	v_rcp_f32_e32 v189, v189
	v_mul_f32_e32 v186, v118, v186
	v_mul_f32_e32 v187, v122, v187
	v_mul_f32_e32 v188, v126, v188
	v_mul_f32_e32 v189, v2, v189
	v_cvt_pk_bf16_f32 v190, v186, v187
	v_cvt_pk_bf16_f32 v191, v188, v189
	ds_write_b16 v170, v190 offset:6912
	ds_write_b16_d16_hi v170, v190 offset:6944
	ds_write_b16 v170, v191 offset:6976
	ds_write_b16_d16_hi v170, v191 offset:7008
	v_mul_f32_e32 v192, 0xbfb8aa3b, v119
	v_mul_f32_e32 v193, 0xbfb8aa3b, v123
	v_mul_f32_e32 v174, 0xbfb8aa3b, v127
	v_mul_f32_e32 v175, 0xbfb8aa3b, v3
	v_exp_f32_e32 v192, v192
	v_exp_f32_e32 v193, v193
	v_exp_f32_e32 v174, v174
	v_exp_f32_e32 v175, v175
	v_add_f32_e32 v192, 1.0, v192
	v_add_f32_e32 v193, 1.0, v193
	v_add_f32_e32 v174, 1.0, v174
	v_add_f32_e32 v175, 1.0, v175
	v_rcp_f32_e32 v192, v192
	v_rcp_f32_e32 v193, v193
	v_rcp_f32_e32 v174, v174
	v_rcp_f32_e32 v175, v175
	v_mul_f32_e32 v192, v119, v192
	v_mul_f32_e32 v193, v123, v193
	v_mul_f32_e32 v174, v127, v174
	v_mul_f32_e32 v175, v3, v175
	v_cvt_pk_bf16_f32 v176, v192, v193
	v_cvt_pk_bf16_f32 v177, v174, v175
	ds_write_b16 v170, v176 offset:7056
	ds_write_b16_d16_hi v170, v176 offset:7088
	ds_write_b16 v170, v177 offset:7120
	ds_write_b16_d16_hi v170, v177 offset:7152
	v_mul_f32_e32 v178, 0xbfb8aa3b, v120
	v_mul_f32_e32 v179, 0xbfb8aa3b, v124
	v_mul_f32_e32 v180, 0xbfb8aa3b, v128
	v_mul_f32_e32 v181, 0xbfb8aa3b, v4
	v_exp_f32_e32 v178, v178
	v_exp_f32_e32 v179, v179
	v_exp_f32_e32 v180, v180
	v_exp_f32_e32 v181, v181
	v_add_f32_e32 v178, 1.0, v178
	v_add_f32_e32 v179, 1.0, v179
	v_add_f32_e32 v180, 1.0, v180
	v_add_f32_e32 v181, 1.0, v181
	v_rcp_f32_e32 v178, v178
	v_rcp_f32_e32 v179, v179
	v_rcp_f32_e32 v180, v180
	v_rcp_f32_e32 v181, v181
	v_mul_f32_e32 v178, v120, v178
	v_mul_f32_e32 v179, v124, v179
	v_mul_f32_e32 v180, v128, v180
	v_mul_f32_e32 v181, v4, v181
	v_cvt_pk_bf16_f32 v182, v178, v179
	v_cvt_pk_bf16_f32 v183, v180, v181
	ds_write_b16 v170, v182 offset:7200
	ds_write_b16_d16_hi v170, v182 offset:7232
	ds_write_b16 v170, v183 offset:7264
	ds_write_b16_d16_hi v170, v183 offset:7296
	v_mul_f32_e32 v184, 0xbfb8aa3b, v121
	v_mul_f32_e32 v185, 0xbfb8aa3b, v125
	v_mul_f32_e32 v186, 0xbfb8aa3b, v129
	v_mul_f32_e32 v187, 0xbfb8aa3b, v5
	v_exp_f32_e32 v184, v184
	v_exp_f32_e32 v185, v185
	v_exp_f32_e32 v186, v186
	v_exp_f32_e32 v187, v187
	v_add_f32_e32 v184, 1.0, v184
	v_add_f32_e32 v185, 1.0, v185
	v_add_f32_e32 v186, 1.0, v186
	v_add_f32_e32 v187, 1.0, v187
	v_rcp_f32_e32 v184, v184
	v_rcp_f32_e32 v185, v185
	v_rcp_f32_e32 v186, v186
	v_rcp_f32_e32 v187, v187
	v_mul_f32_e32 v184, v121, v184
	v_mul_f32_e32 v185, v125, v185
	v_mul_f32_e32 v186, v129, v186
	v_mul_f32_e32 v187, v5, v187
	v_cvt_pk_bf16_f32 v188, v184, v185
	v_cvt_pk_bf16_f32 v189, v186, v187
	ds_write_b16 v170, v188 offset:7344
	ds_write_b16_d16_hi v170, v188 offset:7376
	ds_write_b16 v170, v189 offset:7408
	ds_write_b16_d16_hi v170, v189 offset:7440
	ds_read_b128 v[130:133], v171 offset:0
	ds_read_b128 v[134:137], v171 offset:1152
	ds_read_b128 v[138:141], v171 offset:2304
	ds_read_b128 v[142:145], v171 offset:3456
	ds_read_b128 v[146:149], v171 offset:4608
	ds_read_b128 v[150:153], v171 offset:5760
	ds_read_b128 v[154:157], v171 offset:6912
	ds_read_b128 v[158:161], v171 offset:8064
	s_waitcnt lgkmcnt(7)
	global_store_dwordx4 v172, v[130:133], s[44:45] sc1
	s_add_u32 s44, s44, 0x4000
	s_addc_u32 s45, s45, 0
	s_waitcnt lgkmcnt(6)
	global_store_dwordx4 v172, v[134:137], s[44:45] sc1
	s_add_u32 s44, s44, 0x4000
	s_addc_u32 s45, s45, 0
	s_waitcnt lgkmcnt(5)
	global_store_dwordx4 v172, v[138:141], s[44:45] sc1
	s_add_u32 s44, s44, 0x4000
	s_addc_u32 s45, s45, 0
	s_waitcnt lgkmcnt(4)
	global_store_dwordx4 v172, v[142:145], s[44:45] sc1
	s_add_u32 s44, s44, 0x4000
	s_addc_u32 s45, s45, 0
	s_waitcnt lgkmcnt(3)
	global_store_dwordx4 v172, v[146:149], s[44:45] sc1
	s_add_u32 s44, s44, 0x4000
	s_addc_u32 s45, s45, 0
	s_waitcnt lgkmcnt(2)
	global_store_dwordx4 v172, v[150:153], s[44:45] sc1
	s_add_u32 s44, s44, 0x4000
	s_addc_u32 s45, s45, 0
	s_waitcnt lgkmcnt(1)
	global_store_dwordx4 v172, v[154:157], s[44:45] sc1
	s_add_u32 s44, s44, 0x4000
	s_addc_u32 s45, s45, 0
	s_waitcnt lgkmcnt(0)
	global_store_dwordx4 v172, v[158:161], s[44:45] sc1
	s_branch .Lfe_done
